# v054 + GEMM loops: per-phase s_setprio flips deleted, one static s_setprio 1 for waves 4-7 at kernel entry (asm guide 7.4)
# speedup vs baseline: 1.0117x; 1.0117x over previous
_Z6mk_fwd4Args:
	v_readfirstlane_b32 s100, v0
	s_nop 3
	s_and_b32 s100, s100, 0x3ff
	s_lshr_b32 s100, s100, 6
	s_cmp_ge_u32 s100, 4
	s_cbranch_scc0 .Lprio_done
	s_setprio 1
.Lprio_done:
	s_load_dwordx4 s[56:59], s[0:1], 0x140
	s_load_dword s82, s[0:1], 0x158
	s_mov_b32 s96, s2
	s_add_u32 s2, s0, 0x158
	s_addc_u32 s3, s1, 0
	v_cmp_gt_u32_e32 vcc, 64, v0
	v_writelane_b32 v250, s2, 0
	s_nop 1
	v_writelane_b32 v250, s3, 1
	s_and_saveexec_b64 s[4:5], vcc
	v_lshl_add_u32 v1, v0, 2, 0
	v_add_u32_e32 v1, 0x22000, v1
	v_mov_b32_e32 v2, 0
	ds_write_b32 v1, v2
	s_or_b64 exec, exec, s[4:5]
	s_load_dwordx2 s[2:3], s[0:1], 0x150
	s_waitcnt lgkmcnt(0)
	s_add_u32 s16, s58, 0x4000
	s_addc_u32 s17, s59, 0
	v_cmp_eq_u32_e32 vcc, 0, v0
	s_sub_i32 s3, s3, s2
	s_cmp_lt_i32 s3, 2
	s_mov_b32 s3, 0
	s_mov_b32 s2, 0
	v_writelane_b32 v250, s3, 2
	s_barrier
	s_cbranch_scc1 .LBB0_7
	s_getreg_b32 s2, hwreg(HW_REG_XCC_ID, 0, 4)
	s_and_b32 s2, s2, 15
	s_and_saveexec_b64 s[4:5], vcc
	s_cbranch_execz .LBB0_6
	s_mov_b64 s[6:7], exec
	v_mbcnt_lo_u32_b32 v1, s6, 0
	v_mbcnt_hi_u32_b32 v1, s7, v1
	v_cmp_eq_u32_e32 vcc, 0, v1
	s_and_b64 s[8:9], exec, vcc
	s_mov_b64 exec, s[8:9]
	s_cbranch_execz .LBB0_6
	s_lshl_b32 s3, s2, 8
	s_bcnt1_i32_b64 s6, s[6:7]
	v_mov_b32_e32 v1, s3
	v_mov_b32_e32 v2, s6
	global_atomic_add v1, v2, s[16:17] offset:1024

.LBB0_329:
	s_add_u32 s19, s16, 0xfff80080
	s_addc_u32 s26, s17, -1
	s_add_i32 s31, 0, 0x10000
	v_add_u32_e32 v2, s31, v158
	ds_read_b128 v[132:135], v2
	ds_read_b128 v[148:151], v2 offset:1024
	ds_read_b128 v[152:155], v2 offset:2048
	ds_read_b128 v[160:163], v2 offset:3072
	s_cmp_eq_u32 s15, 28
	s_cselect_b32 s39, s37, s26
	s_cselect_b32 s38, s36, s19
	s_cselect_b32 s27, s49, s14
	s_cselect_b32 s26, s48, s10
	v_lshl_add_u64 v[196:197], s[16:17], 0, v[144:145]
	s_add_i32 m0, s6, 0xc000
	ds_read_b128 v[164:167], v159
	ds_read_b128 v[168:171], v159 offset:1024
	ds_read_b128 v[172:175], v159 offset:2048
	ds_read_b128 v[176:179], v159 offset:3072
	ds_read_b128 v[180:183], v159 offset:4096
	ds_read_b128 v[184:187], v159 offset:5120
	ds_read_b128 v[188:191], v159 offset:6144
	ds_read_b128 v[192:195], v159 offset:7168
	global_load_lds_dwordx4 v[196:197], off
	v_lshl_add_u64 v[196:197], s[16:17], 0, v[146:147]
	s_add_i32 m0, s6, 0xe000
	s_nop 0
	global_load_lds_dwordx4 v[196:197], off
	s_waitcnt lgkmcnt(8)
	s_barrier
	s_waitcnt lgkmcnt(0)
	s_waitcnt lgkmcnt(0)
	v_mfma_f32_16x16x32_f16 v[128:131], v[132:135], v[164:167], v[128:131]
	v_mfma_f32_16x16x32_f16 v[124:127], v[152:155], v[164:167], v[124:127]
	v_mfma_f32_16x16x32_f16 v[112:115], v[132:135], v[172:175], v[112:115]
	v_mfma_f32_16x16x32_f16 v[108:111], v[152:155], v[172:175], v[108:111]
	v_mfma_f32_16x16x32_f16 v[96:99], v[132:135], v[180:183], v[96:99]
	v_mfma_f32_16x16x32_f16 v[92:95], v[152:155], v[180:183], v[92:95]
	v_mfma_f32_16x16x32_f16 v[80:83], v[132:135], v[188:191], v[80:83]
	v_mfma_f32_16x16x32_f16 v[76:79], v[152:155], v[188:191], v[76:79]
	v_mfma_f32_16x16x32_f16 v[128:131], v[148:151], v[168:171], v[128:131]
	v_mfma_f32_16x16x32_f16 v[124:127], v[160:163], v[168:171], v[124:127]
	v_mfma_f32_16x16x32_f16 v[112:115], v[148:151], v[176:179], v[112:115]
	v_mfma_f32_16x16x32_f16 v[108:111], v[160:163], v[176:179], v[108:111]
	v_mfma_f32_16x16x32_f16 v[96:99], v[148:151], v[184:187], v[96:99]
	v_mfma_f32_16x16x32_f16 v[92:95], v[160:163], v[184:187], v[92:95]
	v_mfma_f32_16x16x32_f16 v[80:83], v[148:151], v[192:195], v[80:83]
	v_mfma_f32_16x16x32_f16 v[76:79], v[160:163], v[192:195], v[76:79]
	s_barrier
	s_add_i32 s19, 0, 0x14000
	s_add_i32 s31, s31, s5
	v_add_u32_e32 v2, s19, v158
	v_lshl_add_u64 v[214:215], s[26:27], 0, v[138:139]
	s_mov_b32 m0, s31
	ds_read_b128 v[196:199], v2
	ds_read_b128 v[200:203], v2 offset:1024
	ds_read_b128 v[206:209], v2 offset:2048
	ds_read_b128 v[210:213], v2 offset:3072
	global_load_lds_dwordx4 v[214:215], off
	v_lshl_add_u64 v[216:217], s[26:27], 0, v[142:143]
	s_add_i32 m0, s31, 0x2000
	s_nop 0
	global_load_lds_dwordx4 v[216:217], off
	s_barrier
	s_waitcnt lgkmcnt(0)
	s_waitcnt lgkmcnt(0)
	v_mfma_f32_16x16x32_f16 v[120:123], v[196:199], v[164:167], v[120:123]
	v_mfma_f32_16x16x32_f16 v[116:119], v[206:209], v[164:167], v[116:119]
	v_mfma_f32_16x16x32_f16 v[104:107], v[196:199], v[172:175], v[104:107]
	v_mfma_f32_16x16x32_f16 v[100:103], v[206:209], v[172:175], v[100:103]
	v_mfma_f32_16x16x32_f16 v[88:91], v[196:199], v[180:183], v[88:91]
	v_mfma_f32_16x16x32_f16 v[84:87], v[206:209], v[180:183], v[84:87]
	v_mfma_f32_16x16x32_f16 v[72:75], v[196:199], v[188:191], v[72:75]
	v_mfma_f32_16x16x32_f16 v[68:71], v[206:209], v[188:191], v[68:71]
	v_mfma_f32_16x16x32_f16 v[120:123], v[200:203], v[168:171], v[120:123]
	v_mfma_f32_16x16x32_f16 v[116:119], v[210:213], v[168:171], v[116:119]
	v_mfma_f32_16x16x32_f16 v[104:107], v[200:203], v[176:179], v[104:107]
	v_mfma_f32_16x16x32_f16 v[100:103], v[210:213], v[176:179], v[100:103]
	v_mfma_f32_16x16x32_f16 v[88:91], v[200:203], v[184:187], v[88:91]
	v_mfma_f32_16x16x32_f16 v[84:87], v[210:213], v[184:187], v[84:87]
	v_mfma_f32_16x16x32_f16 v[72:75], v[200:203], v[192:195], v[72:75]
	v_mfma_f32_16x16x32_f16 v[68:71], v[210:213], v[192:195], v[68:71]
	s_mov_b32 m0, s6
	v_lshl_add_u64 v[218:219], s[38:39], 0, v[136:137]
	s_barrier
	ds_read_b128 v[164:167], v159 offset:16384
	ds_read_b128 v[168:171], v159 offset:17408
	ds_read_b128 v[172:175], v159 offset:18432
	ds_read_b128 v[176:179], v159 offset:19456
	ds_read_b128 v[180:183], v159 offset:20480
	ds_read_b128 v[184:187], v159 offset:21504
	ds_read_b128 v[188:191], v159 offset:22528
	ds_read_b128 v[192:195], v159 offset:23552
	global_load_lds_dwordx4 v[218:219], off
	v_lshl_add_u64 v[220:221], s[38:39], 0, v[140:141]
	s_mov_b32 m0, s7
	s_nop 0
	global_load_lds_dwordx4 v[220:221], off
	s_barrier
	s_waitcnt lgkmcnt(0)
	s_waitcnt lgkmcnt(0)
	v_mfma_f32_16x16x32_f16 v[64:67], v[132:135], v[164:167], v[64:67]
	v_mfma_f32_16x16x32_f16 v[60:63], v[152:155], v[164:167], v[60:63]
	v_mfma_f32_16x16x32_f16 v[48:51], v[132:135], v[172:175], v[48:51]
	v_mfma_f32_16x16x32_f16 v[44:47], v[152:155], v[172:175], v[44:47]
	v_mfma_f32_16x16x32_f16 v[32:35], v[132:135], v[180:183], v[32:35]
	v_mfma_f32_16x16x32_f16 v[28:31], v[152:155], v[180:183], v[28:31]
	v_mfma_f32_16x16x32_f16 v[16:19], v[132:135], v[188:191], v[16:19]
	v_mfma_f32_16x16x32_f16 v[12:15], v[152:155], v[188:191], v[12:15]
	v_mfma_f32_16x16x32_f16 v[64:67], v[148:151], v[168:171], v[64:67]
	v_mfma_f32_16x16x32_f16 v[60:63], v[160:163], v[168:171], v[60:63]
	v_mfma_f32_16x16x32_f16 v[48:51], v[148:151], v[176:179], v[48:51]
	v_mfma_f32_16x16x32_f16 v[44:47], v[160:163], v[176:179], v[44:47]
	v_mfma_f32_16x16x32_f16 v[32:35], v[148:151], v[184:187], v[32:35]
	v_mfma_f32_16x16x32_f16 v[28:31], v[160:163], v[184:187], v[28:31]
	v_mfma_f32_16x16x32_f16 v[16:19], v[148:151], v[192:195], v[16:19]
	v_mfma_f32_16x16x32_f16 v[12:15], v[160:163], v[192:195], v[12:15]
	s_barrier
	s_add_u32 s42, s26, 0x80000
	s_addc_u32 s43, s27, 0
	s_add_i32 s19, s19, s5
	v_lshl_add_u64 v[132:133], s[42:43], 0, v[138:139]
	s_mov_b32 m0, s19
	s_nop 0
	global_load_lds_dwordx4 v[132:133], off
	v_lshl_add_u64 v[132:133], s[42:43], 0, v[142:143]
	s_add_i32 m0, s19, 0x2000
	s_nop 0
	global_load_lds_dwordx4 v[132:133], off
	s_waitcnt vmcnt(6)
	s_barrier
	v_mfma_f32_16x16x32_f16 v[56:59], v[196:199], v[164:167], v[56:59]
	v_mfma_f32_16x16x32_f16 v[52:55], v[206:209], v[164:167], v[52:55]
	v_mfma_f32_16x16x32_f16 v[40:43], v[196:199], v[172:175], v[40:43]
	v_mfma_f32_16x16x32_f16 v[36:39], v[206:209], v[172:175], v[36:39]
	v_mfma_f32_16x16x32_f16 v[24:27], v[196:199], v[180:183], v[24:27]
	v_mfma_f32_16x16x32_f16 v[20:23], v[206:209], v[180:183], v[20:23]
	v_mfma_f32_16x16x32_f16 v[8:11], v[196:199], v[188:191], v[8:11]
	v_mfma_f32_16x16x32_f16 v[4:7], v[206:209], v[188:191], v[4:7]
	v_mfma_f32_16x16x32_f16 v[56:59], v[200:203], v[168:171], v[56:59]
	v_mfma_f32_16x16x32_f16 v[52:55], v[210:213], v[168:171], v[52:55]
	v_mfma_f32_16x16x32_f16 v[40:43], v[200:203], v[176:179], v[40:43]
	v_mfma_f32_16x16x32_f16 v[36:39], v[210:213], v[176:179], v[36:39]
	v_mfma_f32_16x16x32_f16 v[24:27], v[200:203], v[184:187], v[24:27]
	v_mfma_f32_16x16x32_f16 v[20:23], v[210:213], v[184:187], v[20:23]
	v_mfma_f32_16x16x32_f16 v[8:11], v[200:203], v[192:195], v[8:11]
	v_mfma_f32_16x16x32_f16 v[4:7], v[210:213], v[192:195], v[4:7]
	s_add_i32 s19, 0, 0x18000
	v_add_u32_e32 v2, s19, v158
	s_barrier
	ds_read_b128 v[132:135], v2
	ds_read_b128 v[148:151], v2 offset:1024
	ds_read_b128 v[152:155], v2 offset:2048
	ds_read_b128 v[160:163], v2 offset:3072
	s_add_u32 s38, s38, 0x80000
	s_addc_u32 s39, s39, 0
	s_mov_b32 m0, s8
	v_lshl_add_u64 v[196:197], s[38:39], 0, v[136:137]
	ds_read_b128 v[164:167], v159 offset:32768
	ds_read_b128 v[168:171], v159 offset:33792
	ds_read_b128 v[172:175], v159 offset:34816
	ds_read_b128 v[176:179], v159 offset:35840
	ds_read_b128 v[180:183], v159 offset:36864
	ds_read_b128 v[184:187], v159 offset:37888
	ds_read_b128 v[188:191], v159 offset:38912
	ds_read_b128 v[192:195], v159 offset:39936
	global_load_lds_dwordx4 v[196:197], off
	v_lshl_add_u64 v[196:197], s[38:39], 0, v[140:141]
	s_mov_b32 m0, s9
	s_nop 0
	global_load_lds_dwordx4 v[196:197], off
	s_waitcnt lgkmcnt(8)
	s_barrier
	s_waitcnt lgkmcnt(0)
	s_waitcnt lgkmcnt(0)
	v_mfma_f32_16x16x32_f16 v[128:131], v[132:135], v[164:167], v[128:131]
	v_mfma_f32_16x16x32_f16 v[124:127], v[152:155], v[164:167], v[124:127]
	v_mfma_f32_16x16x32_f16 v[112:115], v[132:135], v[172:175], v[112:115]
	v_mfma_f32_16x16x32_f16 v[108:111], v[152:155], v[172:175], v[108:111]
	v_mfma_f32_16x16x32_f16 v[96:99], v[132:135], v[180:183], v[96:99]
	v_mfma_f32_16x16x32_f16 v[92:95], v[152:155], v[180:183], v[92:95]
	v_mfma_f32_16x16x32_f16 v[80:83], v[132:135], v[188:191], v[80:83]
	v_mfma_f32_16x16x32_f16 v[76:79], v[152:155], v[188:191], v[76:79]
	v_mfma_f32_16x16x32_f16 v[128:131], v[148:151], v[168:171], v[128:131]
	v_mfma_f32_16x16x32_f16 v[124:127], v[160:163], v[168:171], v[124:127]
	v_mfma_f32_16x16x32_f16 v[112:115], v[148:151], v[176:179], v[112:115]
	v_mfma_f32_16x16x32_f16 v[108:111], v[160:163], v[176:179], v[108:111]
	v_mfma_f32_16x16x32_f16 v[96:99], v[148:151], v[184:187], v[96:99]
	v_mfma_f32_16x16x32_f16 v[92:95], v[160:163], v[184:187], v[92:95]
	v_mfma_f32_16x16x32_f16 v[80:83], v[148:151], v[192:195], v[80:83]
	v_mfma_f32_16x16x32_f16 v[76:79], v[160:163], v[192:195], v[76:79]
	s_barrier
	s_add_i32 s31, 0, 0x1c000
	s_add_i32 s19, s19, s5
	v_add_u32_e32 v2, s31, v158
	v_lshl_add_u64 v[214:215], v[214:215], 0, s[88:89]
	s_mov_b32 m0, s19
	ds_read_b128 v[196:199], v2
	ds_read_b128 v[200:203], v2 offset:1024
	ds_read_b128 v[206:209], v2 offset:2048
	ds_read_b128 v[210:213], v2 offset:3072
	global_load_lds_dwordx4 v[214:215], off
	v_lshl_add_u64 v[214:215], v[216:217], 0, s[88:89]
	s_add_i32 m0, s19, 0x2000
	s_nop 0
	global_load_lds_dwordx4 v[214:215], off
	s_barrier
	s_waitcnt lgkmcnt(0)
	s_waitcnt lgkmcnt(0)
	v_mfma_f32_16x16x32_f16 v[120:123], v[196:199], v[164:167], v[120:123]
	v_mfma_f32_16x16x32_f16 v[116:119], v[206:209], v[164:167], v[116:119]
	v_mfma_f32_16x16x32_f16 v[104:107], v[196:199], v[172:175], v[104:107]
	v_mfma_f32_16x16x32_f16 v[100:103], v[206:209], v[172:175], v[100:103]
	v_mfma_f32_16x16x32_f16 v[88:91], v[196:199], v[180:183], v[88:91]
	v_mfma_f32_16x16x32_f16 v[84:87], v[206:209], v[180:183], v[84:87]
	v_mfma_f32_16x16x32_f16 v[72:75], v[196:199], v[188:191], v[72:75]
	v_mfma_f32_16x16x32_f16 v[68:71], v[206:209], v[188:191], v[68:71]
	v_mfma_f32_16x16x32_f16 v[120:123], v[200:203], v[168:171], v[120:123]
	v_mfma_f32_16x16x32_f16 v[116:119], v[210:213], v[168:171], v[116:119]
	v_mfma_f32_16x16x32_f16 v[104:107], v[200:203], v[176:179], v[104:107]
	v_mfma_f32_16x16x32_f16 v[100:103], v[210:213], v[176:179], v[100:103]
	v_mfma_f32_16x16x32_f16 v[88:91], v[200:203], v[184:187], v[88:91]
	v_mfma_f32_16x16x32_f16 v[84:87], v[210:213], v[184:187], v[84:87]
	v_mfma_f32_16x16x32_f16 v[72:75], v[200:203], v[192:195], v[72:75]
	v_mfma_f32_16x16x32_f16 v[68:71], v[210:213], v[192:195], v[68:71]
	s_mov_b32 m0, s30
	v_lshl_add_u64 v[214:215], v[218:219], 0, s[88:89]
	s_barrier
	ds_read_b128 v[164:167], v159 offset:49152
	ds_read_b128 v[168:171], v159 offset:50176
	ds_read_b128 v[172:175], v159 offset:51200
	ds_read_b128 v[176:179], v159 offset:52224
	ds_read_b128 v[180:183], v159 offset:53248
	ds_read_b128 v[184:187], v159 offset:54272
	ds_read_b128 v[188:191], v159 offset:55296
	ds_read_b128 v[192:195], v159 offset:56320
	global_load_lds_dwordx4 v[214:215], off
	v_lshl_add_u64 v[214:215], v[220:221], 0, s[88:89]
	s_mov_b32 m0, s52
	s_nop 0
	global_load_lds_dwordx4 v[214:215], off
	s_barrier
	s_waitcnt lgkmcnt(0)
	s_waitcnt lgkmcnt(0)
	v_mfma_f32_16x16x32_f16 v[64:67], v[132:135], v[164:167], v[64:67]
	v_mfma_f32_16x16x32_f16 v[60:63], v[152:155], v[164:167], v[60:63]
	v_mfma_f32_16x16x32_f16 v[48:51], v[132:135], v[172:175], v[48:51]
	v_mfma_f32_16x16x32_f16 v[44:47], v[152:155], v[172:175], v[44:47]
	v_mfma_f32_16x16x32_f16 v[32:35], v[132:135], v[180:183], v[32:35]
	v_mfma_f32_16x16x32_f16 v[28:31], v[152:155], v[180:183], v[28:31]
	v_mfma_f32_16x16x32_f16 v[16:19], v[132:135], v[188:191], v[16:19]
	v_mfma_f32_16x16x32_f16 v[12:15], v[152:155], v[188:191], v[12:15]
	v_mfma_f32_16x16x32_f16 v[64:67], v[148:151], v[168:171], v[64:67]
	v_mfma_f32_16x16x32_f16 v[60:63], v[160:163], v[168:171], v[60:63]
	v_mfma_f32_16x16x32_f16 v[48:51], v[148:151], v[176:179], v[48:51]
	v_mfma_f32_16x16x32_f16 v[44:47], v[160:163], v[176:179], v[44:47]
	v_mfma_f32_16x16x32_f16 v[32:35], v[148:151], v[184:187], v[32:35]
	v_mfma_f32_16x16x32_f16 v[28:31], v[160:163], v[184:187], v[28:31]
	v_mfma_f32_16x16x32_f16 v[16:19], v[148:151], v[192:195], v[16:19]
	v_mfma_f32_16x16x32_f16 v[12:15], v[160:163], v[192:195], v[12:15]
	s_barrier
	s_add_u32 s26, s26, 0x80080
	s_addc_u32 s27, s27, 0
	s_add_i32 s19, s31, s5
	v_lshl_add_u64 v[132:133], s[26:27], 0, v[138:139]
	s_mov_b32 m0, s19
	s_nop 0
	global_load_lds_dwordx4 v[132:133], off
	v_lshl_add_u64 v[132:133], s[26:27], 0, v[142:143]
	s_add_i32 m0, s19, 0x2000
	s_nop 0
	global_load_lds_dwordx4 v[132:133], off
	s_waitcnt vmcnt(6)
	s_barrier
	v_mfma_f32_16x16x32_f16 v[56:59], v[196:199], v[164:167], v[56:59]
	v_mfma_f32_16x16x32_f16 v[52:55], v[206:209], v[164:167], v[52:55]
	v_mfma_f32_16x16x32_f16 v[40:43], v[196:199], v[172:175], v[40:43]
	v_mfma_f32_16x16x32_f16 v[36:39], v[206:209], v[172:175], v[36:39]
	v_mfma_f32_16x16x32_f16 v[24:27], v[196:199], v[180:183], v[24:27]
	v_mfma_f32_16x16x32_f16 v[20:23], v[206:209], v[180:183], v[20:23]
	v_mfma_f32_16x16x32_f16 v[8:11], v[196:199], v[188:191], v[8:11]
	v_mfma_f32_16x16x32_f16 v[4:7], v[206:209], v[188:191], v[4:7]
	v_mfma_f32_16x16x32_f16 v[56:59], v[200:203], v[168:171], v[56:59]
	v_mfma_f32_16x16x32_f16 v[52:55], v[210:213], v[168:171], v[52:55]
	v_mfma_f32_16x16x32_f16 v[40:43], v[200:203], v[176:179], v[40:43]
	v_mfma_f32_16x16x32_f16 v[36:39], v[210:213], v[176:179], v[36:39]
	v_mfma_f32_16x16x32_f16 v[24:27], v[200:203], v[184:187], v[24:27]
	v_mfma_f32_16x16x32_f16 v[20:23], v[210:213], v[184:187], v[20:23]
	v_mfma_f32_16x16x32_f16 v[8:11], v[200:203], v[192:195], v[8:11]
	v_mfma_f32_16x16x32_f16 v[4:7], v[210:213], v[192:195], v[4:7]
	s_add_i32 s15, s15, 2
	s_add_u32 s16, s16, 0x100
	s_addc_u32 s17, s17, 0
	s_add_u32 s10, s10, 0x100
	s_addc_u32 s14, s14, 0
	s_cmp_gt_u32 s15, 29
	s_barrier
	s_cbranch_scc0 .LBB0_329
	s_lshl_b32 s19, s11, 8
	v_mov_b32_e32 v2, v156
	s_add_i32 s10, s19, s12
	v_mov_b32_e32 v132, v157
	v_add_u32_e32 v161, s10, v2
	s_lshl_b32 s10, s29, 8
	s_or_b32 s14, s10, s13
	s_cmp_gt_i32 s29, 1
	v_lshlrev_b32_e32 v154, 3, v132
	v_add_u32_e32 v160, s14, v154
	s_cselect_b64 s[16:17], -1, 0
	s_add_i32 s14, s29, -14
	s_cmp_gt_u32 s14, 5
	s_cselect_b64 s[38:39], -1, 0
	s_sub_i32 s14, s29, 20
	s_cmp_gt_u32 s14, 23
	s_cselect_b64 s[50:51], -1, 0
	s_cmp_eq_u32 s29, 44
	s_mul_i32 s14, s29, 0x42
	s_cselect_b64 s[42:43], -1, 0
	s_addk_i32 s14, 0xfad8
	s_ashr_i32 s15, s14, 31
	s_ashr_i32 s26, s11, 31
	s_add_u32 s14, s14, s11
	s_addc_u32 s15, s15, s26
	v_lshlrev_b32_e32 v133, 7, v2
	s_lshl_b64 s[26:27], s[14:15], 17
	v_and_b32_e32 v132, 0xffffe000, v161
	v_and_b32_e32 v162, 0x1f80, v133
	v_bfe_u32 v133, v161, 6, 7
	s_movk_i32 s14, 0x4000
	v_or3_b32 v132, v132, v133, v162
	v_cmp_gt_i32_e32 vcc, s14, v161
	s_sub_i32 s29, s10, s19
	s_addk_i32 s29, 0xf200
	v_cndmask_b32_e32 v132, v161, v132, vcc
	v_mad_i64_i32 v[152:153], s[14:15], v132, s33, 0
	v_add_u32_e32 v132, s12, v2
	v_ashrrev_i32_e32 v133, 31, v132
	v_lshlrev_b64 v[150:151], 9, v[132:133]
	v_add_u32_e32 v132, s29, v161
	s_mov_b32 s14, 0x8400
	v_mad_i64_i32 v[148:149], s[14:15], v132, s14, 0
	s_sub_i32 s11, s19, s10
	v_cvt_pk_f16_f32 v135, v126, v127
	v_cvt_pk_f16_f32 v134, v124, v125
	v_cvt_pk_f16_f32 v133, v130, v131
	v_cvt_pk_f16_f32 v132, v128, v129
	s_mov_b64 s[14:15], -1
	s_and_b64 vcc, exec, s[16:17]
	s_cbranch_vccz .LBB0_340
	s_and_b64 vcc, exec, s[38:39]
	s_cbranch_vccz .LBB0_337
	s_and_b64 vcc, exec, s[50:51]
	s_cbranch_vccz .LBB0_334
	v_add_u32_e32 v155, 0xffffe200, v160
	v_cndmask_b32_e64 v166, v160, v155, s[42:43]
	v_lshl_add_u64 v[164:165], s[22:23], 0, v[152:153]
	v_ashrrev_i32_e32 v167, 31, v166
	v_lshl_add_u64 v[164:165], v[166:167], 1, v[164:165]
	global_store_dwordx4 v[164:165], v[132:135], off
	s_mov_b64 s[14:15], 0

.LBB0_885:
	s_add_i32 s37, 0, 0x10000
	v_add_u32_e32 v216, s37, v12
	ds_read_b128 v[14:17], v216
	ds_read_b128 v[18:21], v216 offset:1024
	ds_read_b128 v[22:25], v216 offset:2048
	ds_read_b128 v[26:29], v216 offset:3072
	s_add_u32 s30, s38, 0x400080
	s_addc_u32 s31, s39, 0
	s_add_i32 s42, s6, 0xc000
	v_lshl_add_u64 v[62:63], s[30:31], 0, v[8:9]
	s_mov_b32 m0, s42
	s_add_i32 s17, s6, 0xe000
	ds_read_b128 v[30:33], v13
	ds_read_b128 v[34:37], v13 offset:1024
	ds_read_b128 v[38:41], v13 offset:2048
	ds_read_b128 v[42:45], v13 offset:3072
	ds_read_b128 v[46:49], v13 offset:4096
	ds_read_b128 v[50:53], v13 offset:5120
	ds_read_b128 v[54:57], v13 offset:6144
	ds_read_b128 v[58:61], v13 offset:7168
	global_load_lds_dwordx4 v[62:63], off
	v_lshl_add_u64 v[62:63], s[30:31], 0, v[6:7]
	s_mov_b32 m0, s17
	s_nop 0
	global_load_lds_dwordx4 v[62:63], off
	s_waitcnt lgkmcnt(8)
	s_barrier
	s_waitcnt lgkmcnt(0)
	s_waitcnt lgkmcnt(0)
	v_mfma_f32_16x16x32_f16 v[62:65], v[14:17], v[30:33], 0
	v_mfma_f32_16x16x32_f16 v[66:69], v[22:25], v[30:33], 0
	v_mfma_f32_16x16x32_f16 v[70:73], v[14:17], v[38:41], 0
	v_mfma_f32_16x16x32_f16 v[74:77], v[22:25], v[38:41], 0
	v_mfma_f32_16x16x32_f16 v[78:81], v[14:17], v[46:49], 0
	v_mfma_f32_16x16x32_f16 v[82:85], v[22:25], v[46:49], 0
	v_mfma_f32_16x16x32_f16 v[86:89], v[14:17], v[54:57], 0
	v_mfma_f32_16x16x32_f16 v[90:93], v[22:25], v[54:57], 0
	v_mfma_f32_16x16x32_f16 v[62:65], v[18:21], v[34:37], v[62:65]
	v_mfma_f32_16x16x32_f16 v[66:69], v[26:29], v[34:37], v[66:69]
	v_mfma_f32_16x16x32_f16 v[70:73], v[18:21], v[42:45], v[70:73]
	v_mfma_f32_16x16x32_f16 v[74:77], v[26:29], v[42:45], v[74:77]
	v_mfma_f32_16x16x32_f16 v[78:81], v[18:21], v[50:53], v[78:81]
	v_mfma_f32_16x16x32_f16 v[82:85], v[26:29], v[50:53], v[82:85]
	v_mfma_f32_16x16x32_f16 v[86:89], v[18:21], v[58:61], v[86:89]
	v_mfma_f32_16x16x32_f16 v[90:93], v[26:29], v[58:61], v[90:93]
	s_barrier
	s_add_i32 s43, 0, 0x14000
	v_lshl_add_u64 v[202:203], s[40:41], 0, v[2:3]
	s_mov_b64 s[44:45], 0x100
	s_add_i32 s37, s37, s5
	v_add_u32_e32 v217, s43, v12
	v_lshl_add_u64 v[110:111], v[202:203], 0, s[44:45]
	s_mov_b32 m0, s37
	v_lshl_add_u64 v[210:211], s[40:41], 0, v[4:5]
	s_add_i32 s30, s37, 0x2000
	ds_read_b128 v[94:97], v217
	ds_read_b128 v[98:101], v217 offset:1024
	ds_read_b128 v[102:105], v217 offset:2048
	ds_read_b128 v[106:109], v217 offset:3072
	global_load_lds_dwordx4 v[110:111], off
	v_lshl_add_u64 v[110:111], v[210:211], 0, s[44:45]
	s_mov_b32 m0, s30
	s_nop 0
	global_load_lds_dwordx4 v[110:111], off
	s_barrier
	s_waitcnt lgkmcnt(0)
	s_waitcnt lgkmcnt(0)
	v_mfma_f32_16x16x32_f16 v[110:113], v[94:97], v[30:33], 0
	v_mfma_f32_16x16x32_f16 v[30:33], v[102:105], v[30:33], 0
	v_mfma_f32_16x16x32_f16 v[110:113], v[98:101], v[34:37], v[110:113]
	v_mfma_f32_16x16x32_f16 v[30:33], v[106:109], v[34:37], v[30:33]
	v_mfma_f32_16x16x32_f16 v[34:37], v[94:97], v[38:41], 0
	v_mfma_f32_16x16x32_f16 v[38:41], v[102:105], v[38:41], 0
	v_mfma_f32_16x16x32_f16 v[34:37], v[98:101], v[42:45], v[34:37]
	v_mfma_f32_16x16x32_f16 v[38:41], v[106:109], v[42:45], v[38:41]
	v_mfma_f32_16x16x32_f16 v[42:45], v[94:97], v[46:49], 0
	v_mfma_f32_16x16x32_f16 v[46:49], v[102:105], v[46:49], 0
	v_mfma_f32_16x16x32_f16 v[42:45], v[98:101], v[50:53], v[42:45]
	v_mfma_f32_16x16x32_f16 v[46:49], v[106:109], v[50:53], v[46:49]
	v_mfma_f32_16x16x32_f16 v[50:53], v[94:97], v[54:57], 0
	v_mfma_f32_16x16x32_f16 v[54:57], v[102:105], v[54:57], 0
	v_mfma_f32_16x16x32_f16 v[50:53], v[98:101], v[58:61], v[50:53]
	v_mfma_f32_16x16x32_f16 v[54:57], v[106:109], v[58:61], v[54:57]
	v_lshl_add_u64 v[212:213], s[38:39], 0, v[8:9]
	s_mov_b32 m0, s6
	v_lshl_add_u64 v[142:143], v[212:213], 0, s[44:45]
	v_lshl_add_u64 v[214:215], s[38:39], 0, v[6:7]
	s_barrier
	ds_read_b128 v[58:61], v13 offset:16384
	ds_read_b128 v[114:117], v13 offset:17408
	ds_read_b128 v[118:121], v13 offset:18432
	ds_read_b128 v[122:125], v13 offset:19456
	ds_read_b128 v[126:129], v13 offset:20480
	ds_read_b128 v[130:133], v13 offset:21504
	ds_read_b128 v[134:137], v13 offset:22528
	ds_read_b128 v[138:141], v13 offset:23552
	global_load_lds_dwordx4 v[142:143], off
	v_lshl_add_u64 v[142:143], v[214:215], 0, s[44:45]
	s_mov_b32 m0, s7
	s_nop 0
	global_load_lds_dwordx4 v[142:143], off
	s_barrier
	s_waitcnt lgkmcnt(0)
	s_waitcnt lgkmcnt(0)
	v_mfma_f32_16x16x32_f16 v[142:145], v[14:17], v[58:61], 0
	v_mfma_f32_16x16x32_f16 v[150:153], v[14:17], v[118:121], 0
	v_mfma_f32_16x16x32_f16 v[158:161], v[14:17], v[126:129], 0
	v_mfma_f32_16x16x32_f16 v[14:17], v[14:17], v[134:137], 0
	v_mfma_f32_16x16x32_f16 v[142:145], v[18:21], v[114:117], v[142:145]
	v_mfma_f32_16x16x32_f16 v[146:149], v[22:25], v[58:61], 0
	v_mfma_f32_16x16x32_f16 v[150:153], v[18:21], v[122:125], v[150:153]
	v_mfma_f32_16x16x32_f16 v[154:157], v[22:25], v[118:121], 0
	v_mfma_f32_16x16x32_f16 v[158:161], v[18:21], v[130:133], v[158:161]
	v_mfma_f32_16x16x32_f16 v[162:165], v[22:25], v[126:129], 0
	v_mfma_f32_16x16x32_f16 v[14:17], v[18:21], v[138:141], v[14:17]
	v_mfma_f32_16x16x32_f16 v[18:21], v[22:25], v[134:137], 0
	v_mfma_f32_16x16x32_f16 v[146:149], v[26:29], v[114:117], v[146:149]
	v_mfma_f32_16x16x32_f16 v[154:157], v[26:29], v[122:125], v[154:157]
	v_mfma_f32_16x16x32_f16 v[162:165], v[26:29], v[130:133], v[162:165]
	v_mfma_f32_16x16x32_f16 v[18:21], v[26:29], v[138:141], v[18:21]
	s_barrier
	s_add_u32 s44, s40, 0x10100
	s_addc_u32 s45, s41, 0
	s_add_i32 s43, s43, s5
	v_lshl_add_u64 v[22:23], s[44:45], 0, v[2:3]
	s_mov_b32 m0, s43
	s_add_i32 s31, s43, 0x2000
	global_load_lds_dwordx4 v[22:23], off
	v_lshl_add_u64 v[22:23], s[44:45], 0, v[4:5]
	s_mov_b32 m0, s31
	s_nop 0
	global_load_lds_dwordx4 v[22:23], off
	s_waitcnt vmcnt(6)
	s_barrier
	v_mfma_f32_16x16x32_f16 v[22:25], v[94:97], v[58:61], 0
	v_mfma_f32_16x16x32_f16 v[26:29], v[102:105], v[58:61], 0
	v_mfma_f32_16x16x32_f16 v[22:25], v[98:101], v[114:117], v[22:25]
	v_mfma_f32_16x16x32_f16 v[26:29], v[106:109], v[114:117], v[26:29]
	v_mfma_f32_16x16x32_f16 v[58:61], v[94:97], v[118:121], 0
	v_mfma_f32_16x16x32_f16 v[114:117], v[102:105], v[118:121], 0
	v_mfma_f32_16x16x32_f16 v[118:121], v[94:97], v[126:129], 0
	v_mfma_f32_16x16x32_f16 v[94:97], v[94:97], v[134:137], 0
	v_mfma_f32_16x16x32_f16 v[58:61], v[98:101], v[122:125], v[58:61]
	v_mfma_f32_16x16x32_f16 v[114:117], v[106:109], v[122:125], v[114:117]
	v_mfma_f32_16x16x32_f16 v[118:121], v[98:101], v[130:133], v[118:121]
	v_mfma_f32_16x16x32_f16 v[122:125], v[102:105], v[126:129], 0
	v_mfma_f32_16x16x32_f16 v[94:97], v[98:101], v[138:141], v[94:97]
	v_mfma_f32_16x16x32_f16 v[98:101], v[102:105], v[134:137], 0
	v_mfma_f32_16x16x32_f16 v[122:125], v[106:109], v[130:133], v[122:125]
	v_mfma_f32_16x16x32_f16 v[98:101], v[106:109], v[138:141], v[98:101]
	s_add_i32 s46, 0, 0x18000
	v_add_u32_e32 v218, s46, v12
	s_barrier
	ds_read_b128 v[102:105], v218
	ds_read_b128 v[106:109], v218 offset:1024
	ds_read_b128 v[126:129], v218 offset:2048
	ds_read_b128 v[130:133], v218 offset:3072
	s_add_u32 s44, s38, 0x400100
	s_addc_u32 s45, s39, 0
	s_mov_b32 m0, s8
	v_lshl_add_u64 v[190:191], s[44:45], 0, v[8:9]
	ds_read_b128 v[134:137], v13 offset:32768
	ds_read_b128 v[138:141], v13 offset:33792
	ds_read_b128 v[166:169], v13 offset:34816
	ds_read_b128 v[170:173], v13 offset:35840
	ds_read_b128 v[174:177], v13 offset:36864
	ds_read_b128 v[178:181], v13 offset:37888
	ds_read_b128 v[182:185], v13 offset:38912
	ds_read_b128 v[186:189], v13 offset:39936
	global_load_lds_dwordx4 v[190:191], off
	v_lshl_add_u64 v[190:191], s[44:45], 0, v[6:7]
	s_mov_b32 m0, s9
	s_nop 0
	global_load_lds_dwordx4 v[190:191], off
	s_waitcnt lgkmcnt(8)
	s_barrier
	s_waitcnt lgkmcnt(0)
	s_waitcnt lgkmcnt(0)
	v_mfma_f32_16x16x32_f16 v[62:65], v[102:105], v[134:137], v[62:65]
	v_mfma_f32_16x16x32_f16 v[66:69], v[126:129], v[134:137], v[66:69]
	v_mfma_f32_16x16x32_f16 v[70:73], v[102:105], v[166:169], v[70:73]
	v_mfma_f32_16x16x32_f16 v[74:77], v[126:129], v[166:169], v[74:77]
	v_mfma_f32_16x16x32_f16 v[78:81], v[102:105], v[174:177], v[78:81]
	v_mfma_f32_16x16x32_f16 v[82:85], v[126:129], v[174:177], v[82:85]
	v_mfma_f32_16x16x32_f16 v[86:89], v[102:105], v[182:185], v[86:89]
	v_mfma_f32_16x16x32_f16 v[90:93], v[126:129], v[182:185], v[90:93]
	v_mfma_f32_16x16x32_f16 v[62:65], v[106:109], v[138:141], v[62:65]
	v_mfma_f32_16x16x32_f16 v[66:69], v[130:133], v[138:141], v[66:69]
	v_mfma_f32_16x16x32_f16 v[70:73], v[106:109], v[170:173], v[70:73]
	v_mfma_f32_16x16x32_f16 v[74:77], v[130:133], v[170:173], v[74:77]
	v_mfma_f32_16x16x32_f16 v[78:81], v[106:109], v[178:181], v[78:81]
	v_mfma_f32_16x16x32_f16 v[82:85], v[130:133], v[178:181], v[82:85]
	v_mfma_f32_16x16x32_f16 v[86:89], v[106:109], v[186:189], v[86:89]
	v_mfma_f32_16x16x32_f16 v[90:93], v[130:133], v[186:189], v[90:93]
	s_barrier
	s_add_i32 s48, 0, 0x1c000
	s_mov_b64 s[50:51], 0x180
	s_add_i32 s45, s46, s5
	v_add_u32_e32 v219, s48, v12
	v_lshl_add_u64 v[202:203], v[202:203], 0, s[50:51]
	s_mov_b32 m0, s45
	s_add_i32 s44, s45, 0x2000
	ds_read_b128 v[190:193], v219
	ds_read_b128 v[194:197], v219 offset:1024
	ds_read_b128 v[198:201], v219 offset:2048
	ds_read_b128 v[206:209], v219 offset:3072
	global_load_lds_dwordx4 v[202:203], off
	v_lshl_add_u64 v[202:203], v[210:211], 0, s[50:51]
	s_mov_b32 m0, s44
	s_nop 0
	global_load_lds_dwordx4 v[202:203], off
	s_barrier
	s_waitcnt lgkmcnt(0)
	s_waitcnt lgkmcnt(0)
	v_mfma_f32_16x16x32_f16 v[110:113], v[190:193], v[134:137], v[110:113]
	v_mfma_f32_16x16x32_f16 v[30:33], v[198:201], v[134:137], v[30:33]
	v_mfma_f32_16x16x32_f16 v[34:37], v[190:193], v[166:169], v[34:37]
	v_mfma_f32_16x16x32_f16 v[38:41], v[198:201], v[166:169], v[38:41]
	v_mfma_f32_16x16x32_f16 v[42:45], v[190:193], v[174:177], v[42:45]
	v_mfma_f32_16x16x32_f16 v[46:49], v[198:201], v[174:177], v[46:49]
	v_mfma_f32_16x16x32_f16 v[50:53], v[190:193], v[182:185], v[50:53]
	v_mfma_f32_16x16x32_f16 v[54:57], v[198:201], v[182:185], v[54:57]
	v_mfma_f32_16x16x32_f16 v[110:113], v[194:197], v[138:141], v[110:113]
	v_mfma_f32_16x16x32_f16 v[30:33], v[206:209], v[138:141], v[30:33]
	v_mfma_f32_16x16x32_f16 v[34:37], v[194:197], v[170:173], v[34:37]
	v_mfma_f32_16x16x32_f16 v[38:41], v[206:209], v[170:173], v[38:41]
	v_mfma_f32_16x16x32_f16 v[42:45], v[194:197], v[178:181], v[42:45]
	v_mfma_f32_16x16x32_f16 v[46:49], v[206:209], v[178:181], v[46:49]
	v_mfma_f32_16x16x32_f16 v[50:53], v[194:197], v[186:189], v[50:53]
	v_mfma_f32_16x16x32_f16 v[54:57], v[206:209], v[186:189], v[54:57]
	s_mov_b32 m0, s10
	v_lshl_add_u64 v[202:203], v[212:213], 0, s[50:51]
	s_barrier
	ds_read_b128 v[134:137], v13 offset:49152
	ds_read_b128 v[138:141], v13 offset:50176
	ds_read_b128 v[166:169], v13 offset:51200
	ds_read_b128 v[170:173], v13 offset:52224
	ds_read_b128 v[174:177], v13 offset:53248
	ds_read_b128 v[178:181], v13 offset:54272
	ds_read_b128 v[182:185], v13 offset:55296
	ds_read_b128 v[186:189], v13 offset:56320
	global_load_lds_dwordx4 v[202:203], off
	v_lshl_add_u64 v[202:203], v[214:215], 0, s[50:51]
	s_mov_b32 m0, s11
	s_nop 0
	global_load_lds_dwordx4 v[202:203], off
	s_barrier
	s_waitcnt lgkmcnt(0)
	s_waitcnt lgkmcnt(0)
	v_mfma_f32_16x16x32_f16 v[142:145], v[102:105], v[134:137], v[142:145]
	v_mfma_f32_16x16x32_f16 v[146:149], v[126:129], v[134:137], v[146:149]
	v_mfma_f32_16x16x32_f16 v[150:153], v[102:105], v[166:169], v[150:153]
	v_mfma_f32_16x16x32_f16 v[154:157], v[126:129], v[166:169], v[154:157]
	v_mfma_f32_16x16x32_f16 v[158:161], v[102:105], v[174:177], v[158:161]
	v_mfma_f32_16x16x32_f16 v[162:165], v[126:129], v[174:177], v[162:165]
	v_mfma_f32_16x16x32_f16 v[14:17], v[102:105], v[182:185], v[14:17]
	v_mfma_f32_16x16x32_f16 v[18:21], v[126:129], v[182:185], v[18:21]
	v_mfma_f32_16x16x32_f16 v[142:145], v[106:109], v[138:141], v[142:145]
	v_mfma_f32_16x16x32_f16 v[146:149], v[130:133], v[138:141], v[146:149]
	v_mfma_f32_16x16x32_f16 v[150:153], v[106:109], v[170:173], v[150:153]
	v_mfma_f32_16x16x32_f16 v[154:157], v[130:133], v[170:173], v[154:157]
	v_mfma_f32_16x16x32_f16 v[158:161], v[106:109], v[178:181], v[158:161]
	v_mfma_f32_16x16x32_f16 v[162:165], v[130:133], v[178:181], v[162:165]
	v_mfma_f32_16x16x32_f16 v[14:17], v[106:109], v[186:189], v[14:17]
	v_mfma_f32_16x16x32_f16 v[18:21], v[130:133], v[186:189], v[18:21]
	s_barrier
	s_add_u32 s46, s40, 0x10180
	s_addc_u32 s47, s41, 0
	s_add_i32 s41, s48, s5
	v_lshl_add_u64 v[102:103], s[46:47], 0, v[2:3]
	s_mov_b32 m0, s41
	s_add_i32 s40, s41, 0x2000
	global_load_lds_dwordx4 v[102:103], off
	v_lshl_add_u64 v[102:103], s[46:47], 0, v[4:5]
	s_mov_b32 m0, s40
	s_nop 0
	global_load_lds_dwordx4 v[102:103], off
	s_waitcnt vmcnt(6)
	s_barrier
	v_mfma_f32_16x16x32_f16 v[22:25], v[190:193], v[134:137], v[22:25]
	v_mfma_f32_16x16x32_f16 v[26:29], v[198:201], v[134:137], v[26:29]
	v_mfma_f32_16x16x32_f16 v[58:61], v[190:193], v[166:169], v[58:61]
	v_mfma_f32_16x16x32_f16 v[102:105], v[198:201], v[166:169], v[114:117]
	v_mfma_f32_16x16x32_f16 v[106:109], v[190:193], v[174:177], v[118:121]
	v_mfma_f32_16x16x32_f16 v[114:117], v[198:201], v[174:177], v[122:125]
	v_mfma_f32_16x16x32_f16 v[94:97], v[190:193], v[182:185], v[94:97]
	v_mfma_f32_16x16x32_f16 v[98:101], v[198:201], v[182:185], v[98:101]
	v_mfma_f32_16x16x32_f16 v[22:25], v[194:197], v[138:141], v[22:25]
	v_mfma_f32_16x16x32_f16 v[26:29], v[206:209], v[138:141], v[26:29]
	v_mfma_f32_16x16x32_f16 v[58:61], v[194:197], v[170:173], v[58:61]
	v_mfma_f32_16x16x32_f16 v[102:105], v[206:209], v[170:173], v[102:105]
	v_mfma_f32_16x16x32_f16 v[106:109], v[194:197], v[178:181], v[106:109]
	v_mfma_f32_16x16x32_f16 v[114:117], v[206:209], v[178:181], v[114:117]
	v_mfma_f32_16x16x32_f16 v[94:97], v[194:197], v[186:189], v[94:97]
	v_mfma_f32_16x16x32_f16 v[98:101], v[206:209], v[186:189], v[98:101]
	s_barrier
	ds_read_b128 v[118:121], v216
	ds_read_b128 v[122:125], v216 offset:1024
	ds_read_b128 v[126:129], v216 offset:2048
	ds_read_b128 v[130:133], v216 offset:3072
	s_add_u32 s38, s38, 0x400180
	s_addc_u32 s39, s39, 0
	s_mov_b32 m0, s42
	v_lshl_add_u64 v[190:191], s[38:39], 0, v[8:9]
	ds_read_b128 v[134:137], v13
	ds_read_b128 v[138:141], v13 offset:1024
	ds_read_b128 v[166:169], v13 offset:2048
	ds_read_b128 v[170:173], v13 offset:3072
	ds_read_b128 v[174:177], v13 offset:4096
	ds_read_b128 v[178:181], v13 offset:5120
	ds_read_b128 v[182:185], v13 offset:6144
	ds_read_b128 v[186:189], v13 offset:7168
	global_load_lds_dwordx4 v[190:191], off
	v_lshl_add_u64 v[190:191], s[38:39], 0, v[6:7]
	s_mov_b32 m0, s17
	s_nop 0
	global_load_lds_dwordx4 v[190:191], off
	s_waitcnt lgkmcnt(8)
	s_barrier
	s_waitcnt lgkmcnt(0)
	s_waitcnt lgkmcnt(0)
	v_mfma_f32_16x16x32_f16 v[62:65], v[118:121], v[134:137], v[62:65]
	v_mfma_f32_16x16x32_f16 v[66:69], v[126:129], v[134:137], v[66:69]
	v_mfma_f32_16x16x32_f16 v[70:73], v[118:121], v[166:169], v[70:73]
	v_mfma_f32_16x16x32_f16 v[74:77], v[126:129], v[166:169], v[74:77]
	v_mfma_f32_16x16x32_f16 v[78:81], v[118:121], v[174:177], v[78:81]
	v_mfma_f32_16x16x32_f16 v[82:85], v[126:129], v[174:177], v[82:85]
	v_mfma_f32_16x16x32_f16 v[86:89], v[118:121], v[182:185], v[86:89]
	v_mfma_f32_16x16x32_f16 v[90:93], v[126:129], v[182:185], v[90:93]
	v_mfma_f32_16x16x32_f16 v[62:65], v[122:125], v[138:141], v[62:65]
	v_mfma_f32_16x16x32_f16 v[66:69], v[130:133], v[138:141], v[66:69]
	v_mfma_f32_16x16x32_f16 v[70:73], v[122:125], v[170:173], v[70:73]
	v_mfma_f32_16x16x32_f16 v[74:77], v[130:133], v[170:173], v[74:77]
	v_mfma_f32_16x16x32_f16 v[78:81], v[122:125], v[178:181], v[78:81]
	v_mfma_f32_16x16x32_f16 v[82:85], v[130:133], v[178:181], v[82:85]
	v_mfma_f32_16x16x32_f16 v[86:89], v[122:125], v[186:189], v[86:89]
	v_mfma_f32_16x16x32_f16 v[90:93], v[130:133], v[186:189], v[90:93]
	s_barrier
	s_mov_b32 m0, s37
	v_lshl_add_u64 v[202:203], s[26:27], 0, v[2:3]
	ds_read_b128 v[190:193], v217
	ds_read_b128 v[194:197], v217 offset:1024
	ds_read_b128 v[198:201], v217 offset:2048
	ds_read_b128 v[206:209], v217 offset:3072
	global_load_lds_dwordx4 v[202:203], off
	v_lshl_add_u64 v[210:211], s[26:27], 0, v[4:5]
	s_mov_b32 m0, s30
	s_nop 0
	global_load_lds_dwordx4 v[210:211], off
	s_barrier
	s_waitcnt lgkmcnt(0)
	s_waitcnt lgkmcnt(0)
	v_mfma_f32_16x16x32_f16 v[110:113], v[190:193], v[134:137], v[110:113]
	v_mfma_f32_16x16x32_f16 v[30:33], v[198:201], v[134:137], v[30:33]
	v_mfma_f32_16x16x32_f16 v[34:37], v[190:193], v[166:169], v[34:37]
	v_mfma_f32_16x16x32_f16 v[38:41], v[198:201], v[166:169], v[38:41]
	v_mfma_f32_16x16x32_f16 v[42:45], v[190:193], v[174:177], v[42:45]
	v_mfma_f32_16x16x32_f16 v[46:49], v[198:201], v[174:177], v[46:49]
	v_mfma_f32_16x16x32_f16 v[50:53], v[190:193], v[182:185], v[50:53]
	v_mfma_f32_16x16x32_f16 v[54:57], v[198:201], v[182:185], v[54:57]
	v_mfma_f32_16x16x32_f16 v[110:113], v[194:197], v[138:141], v[110:113]
	v_mfma_f32_16x16x32_f16 v[30:33], v[206:209], v[138:141], v[30:33]
	v_mfma_f32_16x16x32_f16 v[34:37], v[194:197], v[170:173], v[34:37]
	v_mfma_f32_16x16x32_f16 v[38:41], v[206:209], v[170:173], v[38:41]
	v_mfma_f32_16x16x32_f16 v[42:45], v[194:197], v[178:181], v[42:45]
	v_mfma_f32_16x16x32_f16 v[46:49], v[206:209], v[178:181], v[46:49]
	v_mfma_f32_16x16x32_f16 v[50:53], v[194:197], v[186:189], v[50:53]
	v_mfma_f32_16x16x32_f16 v[54:57], v[206:209], v[186:189], v[54:57]
	s_mov_b32 m0, s6
	v_lshl_add_u64 v[212:213], s[18:19], 0, v[8:9]
	s_barrier
	ds_read_b128 v[134:137], v13 offset:16384
	ds_read_b128 v[138:141], v13 offset:17408
	ds_read_b128 v[166:169], v13 offset:18432
	ds_read_b128 v[170:173], v13 offset:19456
	ds_read_b128 v[174:177], v13 offset:20480
	ds_read_b128 v[178:181], v13 offset:21504
	ds_read_b128 v[182:185], v13 offset:22528
	ds_read_b128 v[186:189], v13 offset:23552
	global_load_lds_dwordx4 v[212:213], off
	v_lshl_add_u64 v[214:215], s[18:19], 0, v[6:7]
	s_mov_b32 m0, s7
	s_nop 0
	global_load_lds_dwordx4 v[214:215], off
	s_barrier
	s_waitcnt lgkmcnt(0)
	s_waitcnt lgkmcnt(0)
	v_mfma_f32_16x16x32_f16 v[142:145], v[118:121], v[134:137], v[142:145]
	v_mfma_f32_16x16x32_f16 v[146:149], v[126:129], v[134:137], v[146:149]
	v_mfma_f32_16x16x32_f16 v[150:153], v[118:121], v[166:169], v[150:153]
	v_mfma_f32_16x16x32_f16 v[154:157], v[126:129], v[166:169], v[154:157]
	v_mfma_f32_16x16x32_f16 v[158:161], v[118:121], v[174:177], v[158:161]
	v_mfma_f32_16x16x32_f16 v[162:165], v[126:129], v[174:177], v[162:165]
	v_mfma_f32_16x16x32_f16 v[14:17], v[118:121], v[182:185], v[14:17]
	v_mfma_f32_16x16x32_f16 v[18:21], v[126:129], v[182:185], v[18:21]
	v_mfma_f32_16x16x32_f16 v[142:145], v[122:125], v[138:141], v[142:145]
	v_mfma_f32_16x16x32_f16 v[146:149], v[130:133], v[138:141], v[146:149]
	v_mfma_f32_16x16x32_f16 v[150:153], v[122:125], v[170:173], v[150:153]
	v_mfma_f32_16x16x32_f16 v[154:157], v[130:133], v[170:173], v[154:157]
	v_mfma_f32_16x16x32_f16 v[158:161], v[122:125], v[178:181], v[158:161]
	v_mfma_f32_16x16x32_f16 v[162:165], v[130:133], v[178:181], v[162:165]
	v_mfma_f32_16x16x32_f16 v[14:17], v[122:125], v[186:189], v[14:17]
	v_mfma_f32_16x16x32_f16 v[18:21], v[130:133], v[186:189], v[18:21]
	s_barrier
	s_add_u32 s38, s26, 0x10000
	s_addc_u32 s39, s27, 0
	s_mov_b32 m0, s43
	v_lshl_add_u64 v[118:119], s[38:39], 0, v[2:3]
	global_load_lds_dwordx4 v[118:119], off
	v_lshl_add_u64 v[118:119], s[38:39], 0, v[4:5]
	s_mov_b32 m0, s31
	s_nop 0
	global_load_lds_dwordx4 v[118:119], off
	s_waitcnt vmcnt(6)
	s_barrier
	v_mfma_f32_16x16x32_f16 v[22:25], v[190:193], v[134:137], v[22:25]
	v_mfma_f32_16x16x32_f16 v[26:29], v[198:201], v[134:137], v[26:29]
	v_mfma_f32_16x16x32_f16 v[58:61], v[190:193], v[166:169], v[58:61]
	v_mfma_f32_16x16x32_f16 v[102:105], v[198:201], v[166:169], v[102:105]
	v_mfma_f32_16x16x32_f16 v[106:109], v[190:193], v[174:177], v[106:109]
	v_mfma_f32_16x16x32_f16 v[114:117], v[198:201], v[174:177], v[114:117]
	v_mfma_f32_16x16x32_f16 v[94:97], v[190:193], v[182:185], v[94:97]
	v_mfma_f32_16x16x32_f16 v[98:101], v[198:201], v[182:185], v[98:101]
	v_mfma_f32_16x16x32_f16 v[22:25], v[194:197], v[138:141], v[22:25]
	v_mfma_f32_16x16x32_f16 v[26:29], v[206:209], v[138:141], v[26:29]
	v_mfma_f32_16x16x32_f16 v[58:61], v[194:197], v[170:173], v[58:61]
	v_mfma_f32_16x16x32_f16 v[102:105], v[206:209], v[170:173], v[102:105]
	v_mfma_f32_16x16x32_f16 v[106:109], v[194:197], v[178:181], v[106:109]
	v_mfma_f32_16x16x32_f16 v[114:117], v[206:209], v[178:181], v[114:117]
	v_mfma_f32_16x16x32_f16 v[94:97], v[194:197], v[186:189], v[94:97]
	v_mfma_f32_16x16x32_f16 v[98:101], v[206:209], v[186:189], v[98:101]
	s_barrier
	ds_read_b128 v[118:121], v218
	ds_read_b128 v[122:125], v218 offset:1024
	ds_read_b128 v[126:129], v218 offset:2048
	ds_read_b128 v[130:133], v218 offset:3072
	s_add_u32 s30, s18, 0x400000
	s_addc_u32 s31, s19, 0
	s_mov_b32 m0, s8
	v_lshl_add_u64 v[190:191], s[30:31], 0, v[8:9]
	ds_read_b128 v[134:137], v13 offset:32768
	ds_read_b128 v[138:141], v13 offset:33792
	ds_read_b128 v[166:169], v13 offset:34816
	ds_read_b128 v[170:173], v13 offset:35840
	ds_read_b128 v[174:177], v13 offset:36864
	ds_read_b128 v[178:181], v13 offset:37888
	ds_read_b128 v[182:185], v13 offset:38912
	ds_read_b128 v[186:189], v13 offset:39936
	global_load_lds_dwordx4 v[190:191], off
	v_lshl_add_u64 v[190:191], s[30:31], 0, v[6:7]
	s_mov_b32 m0, s9
	s_nop 0
	global_load_lds_dwordx4 v[190:191], off
	s_waitcnt lgkmcnt(8)
	s_barrier
	s_waitcnt lgkmcnt(0)
	s_waitcnt lgkmcnt(0)
	v_mfma_f32_16x16x32_f16 v[62:65], v[118:121], v[134:137], v[62:65]
	v_mfma_f32_16x16x32_f16 v[66:69], v[126:129], v[134:137], v[66:69]
	v_mfma_f32_16x16x32_f16 v[70:73], v[118:121], v[166:169], v[70:73]
	v_mfma_f32_16x16x32_f16 v[74:77], v[126:129], v[166:169], v[74:77]
	v_mfma_f32_16x16x32_f16 v[78:81], v[118:121], v[174:177], v[78:81]
	v_mfma_f32_16x16x32_f16 v[82:85], v[126:129], v[174:177], v[82:85]
	v_mfma_f32_16x16x32_f16 v[86:89], v[118:121], v[182:185], v[86:89]
	v_mfma_f32_16x16x32_f16 v[90:93], v[126:129], v[182:185], v[90:93]
	v_mfma_f32_16x16x32_f16 v[62:65], v[122:125], v[138:141], v[62:65]
	v_mfma_f32_16x16x32_f16 v[66:69], v[130:133], v[138:141], v[66:69]
	v_mfma_f32_16x16x32_f16 v[70:73], v[122:125], v[170:173], v[70:73]
	v_mfma_f32_16x16x32_f16 v[74:77], v[130:133], v[170:173], v[74:77]
	v_mfma_f32_16x16x32_f16 v[78:81], v[122:125], v[178:181], v[78:81]
	v_mfma_f32_16x16x32_f16 v[82:85], v[130:133], v[178:181], v[82:85]
	v_mfma_f32_16x16x32_f16 v[86:89], v[122:125], v[186:189], v[86:89]
	v_mfma_f32_16x16x32_f16 v[90:93], v[130:133], v[186:189], v[90:93]
	s_barrier
	s_mov_b32 m0, s45
	v_lshl_add_u64 v[202:203], v[202:203], 0, s[88:89]
	ds_read_b128 v[190:193], v219
	ds_read_b128 v[194:197], v219 offset:1024
	ds_read_b128 v[198:201], v219 offset:2048
	ds_read_b128 v[206:209], v219 offset:3072
	global_load_lds_dwordx4 v[202:203], off
	v_lshl_add_u64 v[202:203], v[210:211], 0, s[88:89]
	s_mov_b32 m0, s44
	s_nop 0
	global_load_lds_dwordx4 v[202:203], off
	s_barrier
	s_waitcnt lgkmcnt(0)
	s_waitcnt lgkmcnt(0)
	v_mfma_f32_16x16x32_f16 v[110:113], v[190:193], v[134:137], v[110:113]
	v_mfma_f32_16x16x32_f16 v[30:33], v[198:201], v[134:137], v[30:33]
	v_mfma_f32_16x16x32_f16 v[34:37], v[190:193], v[166:169], v[34:37]
	v_mfma_f32_16x16x32_f16 v[38:41], v[198:201], v[166:169], v[38:41]
	v_mfma_f32_16x16x32_f16 v[42:45], v[190:193], v[174:177], v[42:45]
	v_mfma_f32_16x16x32_f16 v[46:49], v[198:201], v[174:177], v[46:49]
	v_mfma_f32_16x16x32_f16 v[50:53], v[190:193], v[182:185], v[50:53]
	v_mfma_f32_16x16x32_f16 v[54:57], v[198:201], v[182:185], v[54:57]
	v_mfma_f32_16x16x32_f16 v[110:113], v[194:197], v[138:141], v[110:113]
	v_mfma_f32_16x16x32_f16 v[30:33], v[206:209], v[138:141], v[30:33]
	v_mfma_f32_16x16x32_f16 v[34:37], v[194:197], v[170:173], v[34:37]
	v_mfma_f32_16x16x32_f16 v[38:41], v[206:209], v[170:173], v[38:41]
	v_mfma_f32_16x16x32_f16 v[42:45], v[194:197], v[178:181], v[42:45]
	v_mfma_f32_16x16x32_f16 v[46:49], v[206:209], v[178:181], v[46:49]
	v_mfma_f32_16x16x32_f16 v[50:53], v[194:197], v[186:189], v[50:53]
	v_mfma_f32_16x16x32_f16 v[54:57], v[206:209], v[186:189], v[54:57]
	s_mov_b32 m0, s10
	v_lshl_add_u64 v[202:203], v[212:213], 0, s[88:89]
	s_barrier
	ds_read_b128 v[134:137], v13 offset:49152
	ds_read_b128 v[138:141], v13 offset:50176
	ds_read_b128 v[166:169], v13 offset:51200
	ds_read_b128 v[170:173], v13 offset:52224
	ds_read_b128 v[174:177], v13 offset:53248
	ds_read_b128 v[178:181], v13 offset:54272
	ds_read_b128 v[182:185], v13 offset:55296
	ds_read_b128 v[186:189], v13 offset:56320
	global_load_lds_dwordx4 v[202:203], off
	v_lshl_add_u64 v[202:203], v[214:215], 0, s[88:89]
	s_mov_b32 m0, s11
	s_nop 0
	global_load_lds_dwordx4 v[202:203], off
	s_barrier
	s_waitcnt lgkmcnt(0)
	s_waitcnt lgkmcnt(0)
	v_mfma_f32_16x16x32_f16 v[142:145], v[118:121], v[134:137], v[142:145]
	v_mfma_f32_16x16x32_f16 v[146:149], v[126:129], v[134:137], v[146:149]
	v_mfma_f32_16x16x32_f16 v[150:153], v[118:121], v[166:169], v[150:153]
	v_mfma_f32_16x16x32_f16 v[154:157], v[126:129], v[166:169], v[154:157]
	v_mfma_f32_16x16x32_f16 v[158:161], v[118:121], v[174:177], v[158:161]
	v_mfma_f32_16x16x32_f16 v[162:165], v[126:129], v[174:177], v[162:165]
	v_mfma_f32_16x16x32_f16 v[14:17], v[118:121], v[182:185], v[14:17]
	v_mfma_f32_16x16x32_f16 v[18:21], v[126:129], v[182:185], v[18:21]
	v_mfma_f32_16x16x32_f16 v[142:145], v[122:125], v[138:141], v[142:145]
	v_mfma_f32_16x16x32_f16 v[146:149], v[130:133], v[138:141], v[146:149]
	v_mfma_f32_16x16x32_f16 v[150:153], v[122:125], v[170:173], v[150:153]
	v_mfma_f32_16x16x32_f16 v[154:157], v[130:133], v[170:173], v[154:157]
	v_mfma_f32_16x16x32_f16 v[158:161], v[122:125], v[178:181], v[158:161]
	v_mfma_f32_16x16x32_f16 v[162:165], v[130:133], v[178:181], v[162:165]
	v_mfma_f32_16x16x32_f16 v[14:17], v[122:125], v[186:189], v[14:17]
	v_mfma_f32_16x16x32_f16 v[18:21], v[130:133], v[186:189], v[18:21]
	s_barrier
	s_add_u32 s30, s26, 0x10080
	s_addc_u32 s31, s27, 0
	s_mov_b32 m0, s41
	v_lshl_add_u64 v[118:119], s[30:31], 0, v[2:3]
	global_load_lds_dwordx4 v[118:119], off
	v_lshl_add_u64 v[118:119], s[30:31], 0, v[4:5]
	s_mov_b32 m0, s40
	s_nop 0
	global_load_lds_dwordx4 v[118:119], off
	s_waitcnt vmcnt(6)
	s_barrier
	v_mfma_f32_16x16x32_f16 v[22:25], v[190:193], v[134:137], v[22:25]
	v_mfma_f32_16x16x32_f16 v[26:29], v[198:201], v[134:137], v[26:29]
	v_mfma_f32_16x16x32_f16 v[58:61], v[190:193], v[166:169], v[58:61]
	v_mfma_f32_16x16x32_f16 v[102:105], v[198:201], v[166:169], v[102:105]
	v_mfma_f32_16x16x32_f16 v[106:109], v[190:193], v[174:177], v[106:109]
	v_mfma_f32_16x16x32_f16 v[114:117], v[198:201], v[174:177], v[114:117]
	v_mfma_f32_16x16x32_f16 v[94:97], v[190:193], v[182:185], v[94:97]
	v_mfma_f32_16x16x32_f16 v[98:101], v[198:201], v[182:185], v[98:101]
	v_mfma_f32_16x16x32_f16 v[22:25], v[194:197], v[138:141], v[22:25]
	v_mfma_f32_16x16x32_f16 v[26:29], v[206:209], v[138:141], v[26:29]
	v_mfma_f32_16x16x32_f16 v[58:61], v[194:197], v[170:173], v[58:61]
	v_mfma_f32_16x16x32_f16 v[102:105], v[206:209], v[170:173], v[102:105]
	v_mfma_f32_16x16x32_f16 v[106:109], v[194:197], v[178:181], v[106:109]
	v_mfma_f32_16x16x32_f16 v[114:117], v[206:209], v[178:181], v[114:117]
	v_mfma_f32_16x16x32_f16 v[94:97], v[194:197], v[186:189], v[94:97]
	v_mfma_f32_16x16x32_f16 v[98:101], v[206:209], v[186:189], v[98:101]
	v_mov_b32_e32 v118, v10
	s_lshl_b32 s17, s29, 8
	s_barrier
	v_mov_b32_e32 v119, v11
	s_add_i32 s17, s17, s12
	v_add_u32_e32 v118, s17, v118
	s_ashr_i32 s37, s36, 31
	v_lshl_add_u32 v120, v119, 2, s13
	s_lshl_b64 s[30:31], s[36:37], 10
	v_ashrrev_i32_e32 v119, 31, v118
	v_readlane_b32 s36, v252, 62
	v_lshlrev_b64 v[118:119], 15, v[118:119]
	v_readlane_b32 s37, v252, 63
	v_ashrrev_i32_e32 v121, 31, v120
	s_mov_b32 s17, 0x80000
	v_lshl_add_u64 v[118:119], s[36:37], 0, v[118:119]
	v_lshl_add_u64 v[118:119], v[118:119], 0, s[30:31]
	v_lshl_add_u64 v[118:119], v[120:121], 2, v[118:119]
	global_store_dwordx4 v[118:119], v[62:65], off
	global_store_dwordx4 v[118:119], v[66:69], off offset:64
	global_store_dwordx4 v[118:119], v[110:113], off offset:512
	global_store_dwordx4 v[118:119], v[30:33], off offset:576
	s_mov_b64 s[30:31], 0x80000
	s_mov_b32 s36, s15
	v_add_co_u32_e32 v32, vcc, s17, v118
	s_mov_b32 s17, 0x100000
	s_nop 0
	v_addc_co_u32_e32 v33, vcc, 0, v119, vcc
	v_lshl_add_u64 v[30:31], v[118:119], 0, s[30:31]
	global_store_dwordx4 v[32:33], v[70:73], off
	global_store_dwordx4 v[30:31], v[74:77], off offset:64
	global_store_dwordx4 v[30:31], v[34:37], off offset:512
	global_store_dwordx4 v[30:31], v[38:41], off offset:576
	v_add_co_u32_e32 v32, vcc, s17, v118
	s_mov_b64 s[30:31], 0x100000
	s_nop 0
	v_addc_co_u32_e32 v33, vcc, 0, v119, vcc
	s_mov_b32 s17, 0x180000
	v_lshl_add_u64 v[30:31], v[118:119], 0, s[30:31]
	global_store_dwordx4 v[32:33], v[78:81], off
	global_store_dwordx4 v[30:31], v[82:85], off offset:64
	global_store_dwordx4 v[30:31], v[42:45], off offset:512
	global_store_dwordx4 v[30:31], v[46:49], off offset:576
	v_add_co_u32_e32 v32, vcc, s17, v118
	s_mov_b64 s[30:31], 0x180000
	s_nop 0
	v_addc_co_u32_e32 v33, vcc, 0, v119, vcc
	s_mov_b32 s17, 0x400000
	v_lshl_add_u64 v[30:31], v[118:119], 0, s[30:31]
	global_store_dwordx4 v[32:33], v[86:89], off
	global_store_dwordx4 v[30:31], v[90:93], off offset:64
	global_store_dwordx4 v[30:31], v[50:53], off offset:512
	global_store_dwordx4 v[30:31], v[54:57], off offset:576
	v_add_co_u32_e32 v32, vcc, s17, v118
	s_mov_b64 s[30:31], 0x400000
	s_nop 0
	v_addc_co_u32_e32 v33, vcc, 0, v119, vcc
	s_mov_b32 s17, 0x480000
	v_lshl_add_u64 v[30:31], v[118:119], 0, s[30:31]
	global_store_dwordx4 v[32:33], v[142:145], off
	global_store_dwordx4 v[30:31], v[146:149], off offset:64
	global_store_dwordx4 v[30:31], v[22:25], off offset:512
	global_store_dwordx4 v[30:31], v[26:29], off offset:576
	s_mov_b64 s[30:31], 0x480000
	v_add_co_u32_e32 v24, vcc, s17, v118
	s_mov_b32 s17, 0x500000
	s_nop 0
	v_addc_co_u32_e32 v25, vcc, 0, v119, vcc
	v_lshl_add_u64 v[22:23], v[118:119], 0, s[30:31]
	global_store_dwordx4 v[24:25], v[150:153], off
	global_store_dwordx4 v[22:23], v[154:157], off offset:64
	global_store_dwordx4 v[22:23], v[58:61], off offset:512
	global_store_dwordx4 v[22:23], v[102:105], off offset:576
	v_add_co_u32_e32 v24, vcc, s17, v118
	s_mov_b64 s[30:31], 0x500000
	s_nop 0
	v_addc_co_u32_e32 v25, vcc, 0, v119, vcc
	v_lshl_add_u64 v[22:23], v[118:119], 0, s[30:31]
	global_store_dwordx4 v[24:25], v[158:161], off
	global_store_dwordx4 v[22:23], v[162:165], off offset:64
	global_store_dwordx4 v[22:23], v[106:109], off offset:512
	global_store_dwordx4 v[22:23], v[114:117], off offset:576
	v_add_co_u32_e32 v24, vcc, 0x580000, v118
	s_mov_b64 s[30:31], 0x580000
	s_nop 0
	v_addc_co_u32_e32 v25, vcc, 0, v119, vcc
	s_andn2_b64 vcc, exec, s[34:35]
	s_mov_b32 s29, s16
	s_mov_b64 s[40:41], s[26:27]
	s_mov_b64 s[38:39], s[18:19]
	v_lshl_add_u64 v[22:23], v[118:119], 0, s[30:31]
	global_store_dwordx4 v[24:25], v[14:17], off
	global_store_dwordx4 v[22:23], v[18:21], off offset:64
	global_store_dwordx4 v[22:23], v[94:97], off offset:512
	global_store_dwordx4 v[22:23], v[98:101], off offset:576
	s_cbranch_vccz .LBB0_888

.LBB0_1341:
	s_add_u32 s29, s26, 0xffc00080
	s_addc_u32 s31, s27, -1
	s_add_i32 s48, 0, 0x10000
	v_add_u32_e32 v2, s48, v190
	ds_read_b128 v[28:31], v2
	ds_read_b128 v[32:35], v2 offset:1024
	ds_read_b128 v[100:103], v2 offset:2048
	ds_read_b128 v[112:115], v2 offset:3072
	s_cmp_eq_u32 s19, 4
	s_cselect_b32 s43, s35, s31
	s_cselect_b32 s42, s34, s29
	s_cselect_b32 s39, s37, s17
	s_cselect_b32 s38, s36, s11
	v_lshl_add_u64 v[196:197], s[26:27], 0, v[180:181]
	s_add_i32 m0, s7, 0xc000
	ds_read_b128 v[124:127], v191
	ds_read_b128 v[136:139], v191 offset:1024
	ds_read_b128 v[148:151], v191 offset:2048
	ds_read_b128 v[156:159], v191 offset:3072
	ds_read_b128 v[164:167], v191 offset:4096
	ds_read_b128 v[168:171], v191 offset:5120
	ds_read_b128 v[184:187], v191 offset:6144
	ds_read_b128 v[192:195], v191 offset:7168
	global_load_lds_dwordx4 v[196:197], off
	v_lshl_add_u64 v[196:197], s[26:27], 0, v[182:183]
	s_add_i32 m0, s7, 0xe000
	s_nop 0
	global_load_lds_dwordx4 v[196:197], off
	s_waitcnt lgkmcnt(8)
	s_barrier
	s_waitcnt lgkmcnt(0)
	s_waitcnt lgkmcnt(0)
	v_mfma_f32_16x16x32_f16 v[160:163], v[28:31], v[124:127], v[160:163]
	v_mfma_f32_16x16x32_f16 v[152:155], v[100:103], v[124:127], v[152:155]
	v_mfma_f32_16x16x32_f16 v[132:135], v[28:31], v[148:151], v[132:135]
	v_mfma_f32_16x16x32_f16 v[128:131], v[100:103], v[148:151], v[128:131]
	v_mfma_f32_16x16x32_f16 v[108:111], v[28:31], v[164:167], v[108:111]
	v_mfma_f32_16x16x32_f16 v[104:107], v[100:103], v[164:167], v[104:107]
	v_mfma_f32_16x16x32_f16 v[88:91], v[28:31], v[184:187], v[88:91]
	v_mfma_f32_16x16x32_f16 v[84:87], v[100:103], v[184:187], v[84:87]
	v_mfma_f32_16x16x32_f16 v[160:163], v[32:35], v[136:139], v[160:163]
	v_mfma_f32_16x16x32_f16 v[152:155], v[112:115], v[136:139], v[152:155]
	v_mfma_f32_16x16x32_f16 v[132:135], v[32:35], v[156:159], v[132:135]
	v_mfma_f32_16x16x32_f16 v[128:131], v[112:115], v[156:159], v[128:131]
	v_mfma_f32_16x16x32_f16 v[108:111], v[32:35], v[168:171], v[108:111]
	v_mfma_f32_16x16x32_f16 v[104:107], v[112:115], v[168:171], v[104:107]
	v_mfma_f32_16x16x32_f16 v[88:91], v[32:35], v[192:195], v[88:91]
	v_mfma_f32_16x16x32_f16 v[84:87], v[112:115], v[192:195], v[84:87]
	s_barrier
	s_add_i32 s29, 0, 0x14000
	s_add_i32 s31, s48, s6
	v_add_u32_e32 v2, s29, v190
	v_lshl_add_u64 v[214:215], s[38:39], 0, v[176:177]
	s_mov_b32 m0, s31
	ds_read_b128 v[196:199], v2
	ds_read_b128 v[200:203], v2 offset:1024
	ds_read_b128 v[206:209], v2 offset:2048
	ds_read_b128 v[210:213], v2 offset:3072
	global_load_lds_dwordx4 v[214:215], off
	v_lshl_add_u64 v[216:217], s[38:39], 0, v[172:173]
	s_add_i32 m0, s31, 0x2000
	s_nop 0
	global_load_lds_dwordx4 v[216:217], off
	s_barrier
	s_waitcnt lgkmcnt(0)
	s_waitcnt lgkmcnt(0)
	v_mfma_f32_16x16x32_f16 v[144:147], v[196:199], v[124:127], v[144:147]
	v_mfma_f32_16x16x32_f16 v[120:123], v[196:199], v[148:151], v[120:123]
	v_mfma_f32_16x16x32_f16 v[116:119], v[206:209], v[148:151], v[116:119]
	v_mfma_f32_16x16x32_f16 v[96:99], v[196:199], v[164:167], v[96:99]
	v_mfma_f32_16x16x32_f16 v[92:95], v[206:209], v[164:167], v[92:95]
	v_mfma_f32_16x16x32_f16 v[80:83], v[196:199], v[184:187], v[80:83]
	v_mfma_f32_16x16x32_f16 v[76:79], v[206:209], v[184:187], v[76:79]
	v_mfma_f32_16x16x32_f16 v[144:147], v[200:203], v[136:139], v[144:147]
	v_mfma_f32_16x16x32_f16 v[124:127], v[206:209], v[124:127], v[140:143]
	v_mfma_f32_16x16x32_f16 v[120:123], v[200:203], v[156:159], v[120:123]
	v_mfma_f32_16x16x32_f16 v[116:119], v[210:213], v[156:159], v[116:119]
	v_mfma_f32_16x16x32_f16 v[96:99], v[200:203], v[168:171], v[96:99]
	v_mfma_f32_16x16x32_f16 v[92:95], v[210:213], v[168:171], v[92:95]
	v_mfma_f32_16x16x32_f16 v[80:83], v[200:203], v[192:195], v[80:83]
	v_mfma_f32_16x16x32_f16 v[76:79], v[210:213], v[192:195], v[76:79]
	v_mfma_f32_16x16x32_f16 v[124:127], v[210:213], v[136:139], v[124:127]
	s_mov_b32 m0, s7
	v_lshl_add_u64 v[218:219], s[42:43], 0, v[178:179]
	s_barrier
	ds_read_b128 v[136:139], v191 offset:16384
	ds_read_b128 v[140:143], v191 offset:17408
	ds_read_b128 v[148:151], v191 offset:18432
	ds_read_b128 v[156:159], v191 offset:19456
	ds_read_b128 v[164:167], v191 offset:20480
	ds_read_b128 v[168:171], v191 offset:21504
	ds_read_b128 v[184:187], v191 offset:22528
	ds_read_b128 v[192:195], v191 offset:23552
	global_load_lds_dwordx4 v[218:219], off
	v_lshl_add_u64 v[220:221], s[42:43], 0, v[174:175]
	s_mov_b32 m0, s8
	s_nop 0
	global_load_lds_dwordx4 v[220:221], off
	s_barrier
	s_waitcnt lgkmcnt(0)
	s_waitcnt lgkmcnt(0)
	v_mfma_f32_16x16x32_f16 v[72:75], v[28:31], v[136:139], v[72:75]
	v_mfma_f32_16x16x32_f16 v[68:71], v[100:103], v[136:139], v[68:71]
	v_mfma_f32_16x16x32_f16 v[56:59], v[28:31], v[148:151], v[56:59]
	v_mfma_f32_16x16x32_f16 v[52:55], v[100:103], v[148:151], v[52:55]
	v_mfma_f32_16x16x32_f16 v[40:43], v[28:31], v[164:167], v[40:43]
	v_mfma_f32_16x16x32_f16 v[36:39], v[100:103], v[164:167], v[36:39]
	v_mfma_f32_16x16x32_f16 v[16:19], v[28:31], v[184:187], v[16:19]
	v_mfma_f32_16x16x32_f16 v[12:15], v[100:103], v[184:187], v[12:15]
	v_mfma_f32_16x16x32_f16 v[72:75], v[32:35], v[140:143], v[72:75]
	v_mfma_f32_16x16x32_f16 v[68:71], v[112:115], v[140:143], v[68:71]
	v_mfma_f32_16x16x32_f16 v[56:59], v[32:35], v[156:159], v[56:59]
	v_mfma_f32_16x16x32_f16 v[52:55], v[112:115], v[156:159], v[52:55]
	v_mfma_f32_16x16x32_f16 v[40:43], v[32:35], v[168:171], v[40:43]
	v_mfma_f32_16x16x32_f16 v[36:39], v[112:115], v[168:171], v[36:39]
	v_mfma_f32_16x16x32_f16 v[16:19], v[32:35], v[192:195], v[16:19]
	v_mfma_f32_16x16x32_f16 v[12:15], v[112:115], v[192:195], v[12:15]
	s_barrier
	s_add_u32 s48, s38, 0x20000
	s_addc_u32 s49, s39, 0
	s_add_i32 s29, s29, s6
	v_lshl_add_u64 v[28:29], s[48:49], 0, v[176:177]
	s_mov_b32 m0, s29
	s_nop 0
	global_load_lds_dwordx4 v[28:29], off
	v_lshl_add_u64 v[28:29], s[48:49], 0, v[172:173]
	s_add_i32 m0, s29, 0x2000
	s_nop 0
	global_load_lds_dwordx4 v[28:29], off
	s_waitcnt vmcnt(6)
	s_barrier
	v_mfma_f32_16x16x32_f16 v[48:51], v[196:199], v[148:151], v[48:51]
	v_mfma_f32_16x16x32_f16 v[44:47], v[206:209], v[148:151], v[44:47]
	v_mfma_f32_16x16x32_f16 v[24:27], v[196:199], v[164:167], v[24:27]
	v_mfma_f32_16x16x32_f16 v[20:23], v[206:209], v[164:167], v[20:23]
	v_mfma_f32_16x16x32_f16 v[8:11], v[196:199], v[184:187], v[8:11]
	v_mfma_f32_16x16x32_f16 v[4:7], v[206:209], v[184:187], v[4:7]
	v_mfma_f32_16x16x32_f16 v[28:31], v[196:199], v[136:139], v[64:67]
	v_mfma_f32_16x16x32_f16 v[32:35], v[206:209], v[136:139], v[60:63]
	v_mfma_f32_16x16x32_f16 v[48:51], v[200:203], v[156:159], v[48:51]
	v_mfma_f32_16x16x32_f16 v[44:47], v[210:213], v[156:159], v[44:47]
	v_mfma_f32_16x16x32_f16 v[24:27], v[200:203], v[168:171], v[24:27]
	v_mfma_f32_16x16x32_f16 v[20:23], v[210:213], v[168:171], v[20:23]
	v_mfma_f32_16x16x32_f16 v[8:11], v[200:203], v[192:195], v[8:11]
	v_mfma_f32_16x16x32_f16 v[4:7], v[210:213], v[192:195], v[4:7]
	v_mfma_f32_16x16x32_f16 v[28:31], v[200:203], v[140:143], v[28:31]
	v_mfma_f32_16x16x32_f16 v[32:35], v[210:213], v[140:143], v[32:35]
	s_add_i32 s29, 0, 0x18000
	v_add_u32_e32 v2, s29, v190
	s_barrier
	ds_read_b128 v[60:63], v2
	ds_read_b128 v[64:67], v2 offset:1024
	ds_read_b128 v[100:103], v2 offset:2048
	ds_read_b128 v[112:115], v2 offset:3072
	s_add_u32 s42, s42, 0x400000
	s_addc_u32 s43, s43, 0
	s_mov_b32 m0, s9
	v_lshl_add_u64 v[196:197], s[42:43], 0, v[178:179]
	ds_read_b128 v[136:139], v191 offset:32768
	ds_read_b128 v[140:143], v191 offset:33792
	ds_read_b128 v[148:151], v191 offset:34816
	ds_read_b128 v[156:159], v191 offset:35840
	ds_read_b128 v[164:167], v191 offset:36864
	ds_read_b128 v[168:171], v191 offset:37888
	ds_read_b128 v[184:187], v191 offset:38912
	ds_read_b128 v[192:195], v191 offset:39936
	global_load_lds_dwordx4 v[196:197], off
	v_lshl_add_u64 v[196:197], s[42:43], 0, v[174:175]
	s_mov_b32 m0, s12
	s_nop 0
	global_load_lds_dwordx4 v[196:197], off
	s_waitcnt lgkmcnt(8)
	s_barrier
	s_waitcnt lgkmcnt(0)
	s_waitcnt lgkmcnt(0)
	v_mfma_f32_16x16x32_f16 v[160:163], v[60:63], v[136:139], v[160:163]
	v_mfma_f32_16x16x32_f16 v[152:155], v[100:103], v[136:139], v[152:155]
	v_mfma_f32_16x16x32_f16 v[132:135], v[60:63], v[148:151], v[132:135]
	v_mfma_f32_16x16x32_f16 v[128:131], v[100:103], v[148:151], v[128:131]
	v_mfma_f32_16x16x32_f16 v[108:111], v[60:63], v[164:167], v[108:111]
	v_mfma_f32_16x16x32_f16 v[104:107], v[100:103], v[164:167], v[104:107]
	v_mfma_f32_16x16x32_f16 v[88:91], v[60:63], v[184:187], v[88:91]
	v_mfma_f32_16x16x32_f16 v[84:87], v[100:103], v[184:187], v[84:87]
	v_mfma_f32_16x16x32_f16 v[160:163], v[64:67], v[140:143], v[160:163]
	v_mfma_f32_16x16x32_f16 v[152:155], v[112:115], v[140:143], v[152:155]
	v_mfma_f32_16x16x32_f16 v[132:135], v[64:67], v[156:159], v[132:135]
	v_mfma_f32_16x16x32_f16 v[128:131], v[112:115], v[156:159], v[128:131]
	v_mfma_f32_16x16x32_f16 v[108:111], v[64:67], v[168:171], v[108:111]
	v_mfma_f32_16x16x32_f16 v[104:107], v[112:115], v[168:171], v[104:107]
	v_mfma_f32_16x16x32_f16 v[88:91], v[64:67], v[192:195], v[88:91]
	v_mfma_f32_16x16x32_f16 v[84:87], v[112:115], v[192:195], v[84:87]
	s_barrier
	s_add_i32 s31, 0, 0x1c000
	s_add_i32 s29, s29, s6
	v_add_u32_e32 v2, s31, v190
	v_lshl_add_u64 v[214:215], v[214:215], 0, s[88:89]
	s_mov_b32 m0, s29
	ds_read_b128 v[196:199], v2
	ds_read_b128 v[200:203], v2 offset:1024
	ds_read_b128 v[206:209], v2 offset:2048
	ds_read_b128 v[210:213], v2 offset:3072
	global_load_lds_dwordx4 v[214:215], off
	v_lshl_add_u64 v[214:215], v[216:217], 0, s[88:89]
	s_add_i32 m0, s29, 0x2000
	s_nop 0
	global_load_lds_dwordx4 v[214:215], off
	s_barrier
	s_waitcnt lgkmcnt(0)
	s_waitcnt lgkmcnt(0)
	v_mfma_f32_16x16x32_f16 v[144:147], v[196:199], v[136:139], v[144:147]
	v_mfma_f32_16x16x32_f16 v[124:127], v[206:209], v[136:139], v[124:127]
	v_mfma_f32_16x16x32_f16 v[120:123], v[196:199], v[148:151], v[120:123]
	v_mfma_f32_16x16x32_f16 v[116:119], v[206:209], v[148:151], v[116:119]
	v_mfma_f32_16x16x32_f16 v[96:99], v[196:199], v[164:167], v[96:99]
	v_mfma_f32_16x16x32_f16 v[92:95], v[206:209], v[164:167], v[92:95]
	v_mfma_f32_16x16x32_f16 v[80:83], v[196:199], v[184:187], v[80:83]
	v_mfma_f32_16x16x32_f16 v[76:79], v[206:209], v[184:187], v[76:79]
	v_mfma_f32_16x16x32_f16 v[144:147], v[200:203], v[140:143], v[144:147]
	v_mfma_f32_16x16x32_f16 v[140:143], v[210:213], v[140:143], v[124:127]
	v_mfma_f32_16x16x32_f16 v[120:123], v[200:203], v[156:159], v[120:123]
	v_mfma_f32_16x16x32_f16 v[116:119], v[210:213], v[156:159], v[116:119]
	v_mfma_f32_16x16x32_f16 v[96:99], v[200:203], v[168:171], v[96:99]
	v_mfma_f32_16x16x32_f16 v[92:95], v[210:213], v[168:171], v[92:95]
	v_mfma_f32_16x16x32_f16 v[80:83], v[200:203], v[192:195], v[80:83]
	v_mfma_f32_16x16x32_f16 v[76:79], v[210:213], v[192:195], v[76:79]
	s_mov_b32 m0, s15
	v_lshl_add_u64 v[214:215], v[218:219], 0, s[88:89]
	s_barrier
	ds_read_b128 v[124:127], v191 offset:49152
	ds_read_b128 v[136:139], v191 offset:50176
	ds_read_b128 v[148:151], v191 offset:51200
	ds_read_b128 v[156:159], v191 offset:52224
	ds_read_b128 v[164:167], v191 offset:53248
	ds_read_b128 v[168:171], v191 offset:54272
	ds_read_b128 v[184:187], v191 offset:55296
	ds_read_b128 v[192:195], v191 offset:56320
	global_load_lds_dwordx4 v[214:215], off
	v_lshl_add_u64 v[214:215], v[220:221], 0, s[88:89]
	s_mov_b32 m0, s30
	s_nop 0
	global_load_lds_dwordx4 v[214:215], off
	s_barrier
	s_waitcnt lgkmcnt(0)
	s_waitcnt lgkmcnt(0)
	v_mfma_f32_16x16x32_f16 v[72:75], v[60:63], v[124:127], v[72:75]
	v_mfma_f32_16x16x32_f16 v[68:71], v[100:103], v[124:127], v[68:71]
	v_mfma_f32_16x16x32_f16 v[56:59], v[60:63], v[148:151], v[56:59]
	v_mfma_f32_16x16x32_f16 v[52:55], v[100:103], v[148:151], v[52:55]
	v_mfma_f32_16x16x32_f16 v[40:43], v[60:63], v[164:167], v[40:43]
	v_mfma_f32_16x16x32_f16 v[36:39], v[100:103], v[164:167], v[36:39]
	v_mfma_f32_16x16x32_f16 v[16:19], v[60:63], v[184:187], v[16:19]
	v_mfma_f32_16x16x32_f16 v[12:15], v[100:103], v[184:187], v[12:15]
	v_mfma_f32_16x16x32_f16 v[72:75], v[64:67], v[136:139], v[72:75]
	v_mfma_f32_16x16x32_f16 v[68:71], v[112:115], v[136:139], v[68:71]
	v_mfma_f32_16x16x32_f16 v[56:59], v[64:67], v[156:159], v[56:59]
	v_mfma_f32_16x16x32_f16 v[52:55], v[112:115], v[156:159], v[52:55]
	v_mfma_f32_16x16x32_f16 v[40:43], v[64:67], v[168:171], v[40:43]
	v_mfma_f32_16x16x32_f16 v[36:39], v[112:115], v[168:171], v[36:39]
	v_mfma_f32_16x16x32_f16 v[16:19], v[64:67], v[192:195], v[16:19]
	v_mfma_f32_16x16x32_f16 v[12:15], v[112:115], v[192:195], v[12:15]
	s_barrier
	s_add_u32 s38, s38, 0x20080
	s_addc_u32 s39, s39, 0
	s_add_i32 s29, s31, s6
	v_lshl_add_u64 v[60:61], s[38:39], 0, v[176:177]
	s_mov_b32 m0, s29
	s_nop 0
	global_load_lds_dwordx4 v[60:61], off
	v_lshl_add_u64 v[60:61], s[38:39], 0, v[172:173]
	s_add_i32 m0, s29, 0x2000
	s_nop 0
	global_load_lds_dwordx4 v[60:61], off
	s_waitcnt vmcnt(6)
	s_barrier
	v_mfma_f32_16x16x32_f16 v[28:31], v[196:199], v[124:127], v[28:31]
	v_mfma_f32_16x16x32_f16 v[64:67], v[200:203], v[136:139], v[28:31]
	v_mfma_f32_16x16x32_f16 v[28:31], v[206:209], v[124:127], v[32:35]
	v_mfma_f32_16x16x32_f16 v[60:63], v[210:213], v[136:139], v[28:31]
	v_mfma_f32_16x16x32_f16 v[28:31], v[196:199], v[148:151], v[48:51]
	v_mfma_f32_16x16x32_f16 v[48:51], v[200:203], v[156:159], v[28:31]
	v_mfma_f32_16x16x32_f16 v[28:31], v[206:209], v[148:151], v[44:47]
	v_mfma_f32_16x16x32_f16 v[24:27], v[196:199], v[164:167], v[24:27]
	v_mfma_f32_16x16x32_f16 v[20:23], v[206:209], v[164:167], v[20:23]
	v_mfma_f32_16x16x32_f16 v[8:11], v[196:199], v[184:187], v[8:11]
	v_mfma_f32_16x16x32_f16 v[4:7], v[206:209], v[184:187], v[4:7]
	v_mfma_f32_16x16x32_f16 v[44:47], v[210:213], v[156:159], v[28:31]
	v_mfma_f32_16x16x32_f16 v[24:27], v[200:203], v[168:171], v[24:27]
	v_mfma_f32_16x16x32_f16 v[20:23], v[210:213], v[168:171], v[20:23]
	v_mfma_f32_16x16x32_f16 v[8:11], v[200:203], v[192:195], v[8:11]
	v_mfma_f32_16x16x32_f16 v[4:7], v[210:213], v[192:195], v[4:7]
	s_add_i32 s19, s19, 2
	s_add_u32 s26, s26, 0x100
	s_addc_u32 s27, s27, 0
	s_add_u32 s11, s11, 0x100
	s_addc_u32 s17, s17, 0
	s_cmp_gt_u32 s19, 5
	s_barrier
	s_cbranch_scc0 .LBB0_1341
	v_mov_b32_e32 v2, v188
	s_lshl_b32 s10, s10, 8
	s_lshl_b32 s26, s16, 4
	v_mov_b32_e32 v28, v189
	s_add_i32 s10, s10, s44
	s_ashr_i32 s27, s26, 31
	v_add_u32_e32 v100, s10, v2
	v_lshlrev_b32_e32 v2, 3, v28
	s_lshl_b64 s[10:11], s[26:27], 2
	v_and_b32_e32 v193, 8, v2
	s_add_u32 s10, s13, s10
	v_add_u32_e32 v186, s45, v2
	s_addc_u32 s11, s14, s11
	v_lshlrev_b32_e32 v2, 2, v193
	s_ashr_i32 s17, s16, 31
	v_lshl_add_u64 v[28:29], s[10:11], 0, v[2:3]
	s_lshl_b64 s[10:11], s[16:17], 10
	v_readlane_b32 s16, v253, 2
	v_readlane_b32 s17, v253, 3
	s_add_u32 s10, s16, s10
	v_ashrrev_i32_e32 v187, 31, v186
	s_addc_u32 s11, s17, s11
	v_ashrrev_i32_e32 v101, 31, v100
	v_lshlrev_b32_e32 v192, 4, v100
	v_lshl_add_u64 v[102:103], v[186:187], 1, s[10:11]
	v_lshlrev_b64 v[100:101], 15, v[100:101]
	v_lshl_add_u64 v[184:185], v[102:103], 0, v[100:101]
	s_mov_b64 s[10:11], 0x80000
	v_lshl_add_u64 v[148:149], v[184:185], 0, s[10:11]
	s_mov_b64 s[10:11], 0x100000
	v_lshl_add_u64 v[124:125], v[184:185], 0, s[10:11]
	s_mov_b64 s[10:11], 0x180000
	v_lshl_add_u64 v[100:101], v[184:185], 0, s[10:11]
	s_mov_b32 s10, 0x180000
	v_add_co_u32_e32 v102, vcc, s10, v184
	s_mov_b32 s10, 0x100000
	s_nop 0
	v_addc_co_u32_e32 v103, vcc, 0, v185, vcc
	flat_load_dwordx4 v[32:35], v[28:29]
	s_nop 0
	flat_load_dwordx4 v[28:31], v[28:29] offset:16
	s_mov_b32 s38, 0x3a800000
	global_load_dwordx4 v[112:115], v[102:103], off
	v_add_co_u32_e32 v102, vcc, s10, v184
	s_mov_b32 s10, 0x80000
	s_nop 0
	v_addc_co_u32_e32 v103, vcc, 0, v185, vcc
	global_load_dwordx4 v[136:139], v[102:103], off
	v_add_co_u32_e32 v102, vcc, s10, v184
	v_readlane_b32 s16, v253, 25
	s_nop 0
	v_addc_co_u32_e32 v103, vcc, 0, v185, vcc
	global_load_dwordx4 v[156:159], v[102:103], off
	global_load_dwordx4 v[164:167], v[184:185], off offset:256
	global_load_dwordx4 v[168:171], v[184:185], off
	s_nop 0
	global_load_dwordx4 v[100:103], v[100:101], off offset:256
	s_nop 0
	global_load_dwordx4 v[124:127], v[124:125], off offset:256
	s_nop 0
	global_load_dwordx4 v[148:151], v[148:149], off offset:256
	v_readlane_b32 s17, v253, 26
	s_lshl_b64 s[42:43], s[26:27], 1
	s_mov_b64 s[10:11], 0x400000
	s_mov_b64 s[26:27], s[34:35]
	s_waitcnt vmcnt(0)
	s_nop 0
	v_cvt_f32_f16_e32 v194, v168
	v_cvt_f32_f16_sdwa v195, v168 dst_sel:DWORD dst_unused:UNUSED_PAD src0_sel:WORD_1
	s_waitcnt lgkmcnt(0)
	v_pk_mul_f32 v[194:195], v[32:33], v[194:195]
	s_nop 0
	v_pk_fma_f32 v[160:161], v[160:161], s[38:39], v[194:195] op_sel_hi:[1,0,1]
	s_nop 0
	v_mul_f32_e32 v2, 0x3d372713, v160
	v_mul_f32_e32 v2, v160, v2
	v_fma_f32 v2, v160, v2, v160
	v_mul_f32_e32 v2, 0x3f4c422a, v2
	v_mul_f32_e32 v2, -2.0, v2
	v_mul_f32_e32 v2, 0x3fb8aa3b, v2
	v_exp_f32_e32 v2, v2
	s_nop 0
	v_add_f32_e32 v2, 1.0, v2
	v_rcp_f32_e32 v194, v2
	v_mul_f32_e32 v2, 0x3d372713, v161
	v_mul_f32_e32 v2, v161, v2
	v_fma_f32 v2, v161, v2, v161
	v_mul_f32_e32 v2, 0x3f4c422a, v2
	v_mul_f32_e32 v2, -2.0, v2
	v_mul_f32_e32 v2, 0x3fb8aa3b, v2
	v_exp_f32_e32 v2, v2
	s_nop 0
	v_add_f32_e32 v2, 1.0, v2
	v_rcp_f32_e32 v195, v2
	s_nop 0
	v_pk_mul_f32 v[160:161], v[160:161], v[194:195]
	s_nop 0
	v_cvt_pk_f16_f32 v2, v160, v161
	v_cvt_f32_f16_e32 v160, v170
	v_cvt_f32_f16_sdwa v161, v170 dst_sel:DWORD dst_unused:UNUSED_PAD src0_sel:WORD_1
	v_pk_mul_f32 v[160:161], v[28:29], v[160:161]
	s_nop 0
	v_pk_fma_f32 v[152:153], v[152:153], s[38:39], v[160:161] op_sel_hi:[1,0,1]
	s_nop 0
	v_mul_f32_e32 v160, 0x3d372713, v152
	v_mul_f32_e32 v161, 0x3d372713, v153
	v_mul_f32_e32 v160, v152, v160
	v_mul_f32_e32 v161, v153, v161
	v_fma_f32 v160, v152, v160, v152
	v_fma_f32 v161, v153, v161, v153
	v_mul_f32_e32 v160, 0x3f4c422a, v160
	v_mul_f32_e32 v161, 0x3f4c422a, v161
	v_mul_f32_e32 v160, -2.0, v160
	v_mul_f32_e32 v161, -2.0, v161
	v_mul_f32_e32 v160, 0x3fb8aa3b, v160
	v_mul_f32_e32 v161, 0x3fb8aa3b, v161
	v_exp_f32_e32 v160, v160
	v_exp_f32_e32 v161, v161
	v_add_f32_e32 v160, 1.0, v160
	v_add_f32_e32 v161, 1.0, v161
	v_rcp_f32_e32 v160, v160
	v_rcp_f32_e32 v161, v161
	s_nop 0
	v_pk_mul_f32 v[152:153], v[152:153], v[160:161]
	s_nop 0
	v_cvt_pk_f16_f32 v168, v152, v153
	v_cvt_f32_f16_e32 v152, v169
	v_cvt_f32_f16_sdwa v153, v169 dst_sel:DWORD dst_unused:UNUSED_PAD src0_sel:WORD_1
	v_pk_mul_f32 v[152:153], v[34:35], v[152:153]
	s_nop 0
	v_pk_fma_f32 v[152:153], v[162:163], s[38:39], v[152:153] op_sel_hi:[1,0,1]
	s_nop 0
	v_mul_f32_e32 v160, 0x3d372713, v152
	v_mul_f32_e32 v161, 0x3d372713, v153
	v_mul_f32_e32 v160, v152, v160
	v_mul_f32_e32 v161, v153, v161
	v_fma_f32 v160, v152, v160, v152
	v_fma_f32 v161, v153, v161, v153
	v_mul_f32_e32 v160, 0x3f4c422a, v160
	v_mul_f32_e32 v161, 0x3f4c422a, v161
	v_mul_f32_e32 v160, -2.0, v160
	v_mul_f32_e32 v161, -2.0, v161
	v_mul_f32_e32 v160, 0x3fb8aa3b, v160
	v_mul_f32_e32 v161, 0x3fb8aa3b, v161
	v_exp_f32_e32 v160, v160
	v_exp_f32_e32 v161, v161
	v_add_f32_e32 v160, 1.0, v160
	v_add_f32_e32 v161, 1.0, v161
	v_rcp_f32_e32 v160, v160
	v_rcp_f32_e32 v161, v161
	s_nop 0
	v_pk_mul_f32 v[152:153], v[152:153], v[160:161]
	s_nop 0
	v_cvt_pk_f16_f32 v161, v152, v153
	v_cvt_f32_f16_e32 v152, v171
	v_cvt_f32_f16_sdwa v153, v171 dst_sel:DWORD dst_unused:UNUSED_PAD src0_sel:WORD_1
	v_pk_mul_f32 v[152:153], v[30:31], v[152:153]
	s_nop 0
	v_pk_fma_f32 v[152:153], v[154:155], s[38:39], v[152:153] op_sel_hi:[1,0,1]
	s_nop 0
	v_mul_f32_e32 v154, 0x3d372713, v152
	v_mul_f32_e32 v155, 0x3d372713, v153
	v_mul_f32_e32 v154, v152, v154
	v_mul_f32_e32 v155, v153, v155
	v_fma_f32 v154, v152, v154, v152
	v_fma_f32 v155, v153, v155, v153
	v_mul_f32_e32 v154, 0x3f4c422a, v154
	v_mul_f32_e32 v155, 0x3f4c422a, v155
	v_mul_f32_e32 v154, -2.0, v154
	v_mul_f32_e32 v155, -2.0, v155
	v_mul_f32_e32 v154, 0x3fb8aa3b, v154
	v_mul_f32_e32 v155, 0x3fb8aa3b, v155
	v_exp_f32_e32 v154, v154
	v_exp_f32_e32 v155, v155
	v_add_f32_e32 v154, 1.0, v154
	v_add_f32_e32 v155, 1.0, v155
	v_rcp_f32_e32 v154, v154
	v_rcp_f32_e32 v155, v155
	s_nop 0
	v_pk_mul_f32 v[152:153], v[152:153], v[154:155]
	v_lshrrev_b32_e32 v154, 4, v2
	v_and_b32_e32 v154, 0x10001, v154
	v_add3_u32 v2, v2, v154, s21
	v_and_b32_e32 v160, 0xfff0fff0, v2
	v_lshrrev_b32_e32 v2, 4, v161
	v_and_b32_e32 v2, 0x10001, v2
	v_add3_u32 v2, v161, v2, s21
	v_and_b32_e32 v161, 0xfff0fff0, v2
	v_lshrrev_b32_e32 v2, 4, v168
	v_cvt_pk_f16_f32 v153, v152, v153
	v_ashrrev_i32_e32 v152, 4, v186
	v_and_b32_e32 v2, 0x10001, v2
	v_add3_u32 v2, v168, v2, s21
	v_add_u32_e32 v154, v152, v192
	v_and_b32_e32 v162, 0xfff0fff0, v2
	v_lshrrev_b32_e32 v2, 4, v153
	v_ashrrev_i32_e32 v155, 31, v154
	v_and_b32_e32 v2, 0x10001, v2
	v_lshlrev_b64 v[154:155], 10, v[154:155]
	v_add3_u32 v2, v153, v2, s21
	v_lshl_add_u64 v[154:155], s[16:17], 0, v[154:155]
	v_and_b32_e32 v163, 0xfff0fff0, v2
	v_lshl_add_u64 v[154:155], v[154:155], 0, s[42:43]
	v_lshlrev_b32_e32 v2, 1, v193
	v_lshl_add_u64 v[154:155], v[154:155], 0, v[2:3]
	global_store_dwordx4 v[154:155], v[160:163], off
	v_cvt_f32_f16_e32 v154, v164
	v_cvt_f32_f16_sdwa v155, v164 dst_sel:DWORD dst_unused:UNUSED_PAD src0_sel:WORD_1
	v_add_u32_e32 v153, 0x80, v186
	v_pk_mul_f32 v[154:155], v[32:33], v[154:155]
	s_nop 0
	v_pk_fma_f32 v[144:145], v[144:145], s[38:39], v[154:155] op_sel_hi:[1,0,1]
	s_nop 0
	v_mul_f32_e32 v154, 0x3d372713, v144
	v_mul_f32_e32 v155, 0x3d372713, v145
	v_mul_f32_e32 v154, v144, v154
	v_mul_f32_e32 v155, v145, v155
	v_fma_f32 v154, v144, v154, v144
	v_fma_f32 v155, v145, v155, v145
	v_mul_f32_e32 v154, 0x3f4c422a, v154
	v_mul_f32_e32 v155, 0x3f4c422a, v155
	v_mul_f32_e32 v154, -2.0, v154
	v_mul_f32_e32 v155, -2.0, v155
	v_mul_f32_e32 v154, 0x3fb8aa3b, v154
	v_mul_f32_e32 v155, 0x3fb8aa3b, v155
	v_exp_f32_e32 v154, v154
	v_exp_f32_e32 v155, v155
	v_add_f32_e32 v154, 1.0, v154
	v_add_f32_e32 v155, 1.0, v155
	v_rcp_f32_e32 v154, v154
	v_rcp_f32_e32 v155, v155
	s_nop 0
	v_pk_mul_f32 v[144:145], v[144:145], v[154:155]
	s_nop 0
	v_cvt_pk_f16_f32 v154, v144, v145
	v_cvt_f32_f16_e32 v144, v166
	v_cvt_f32_f16_sdwa v145, v166 dst_sel:DWORD dst_unused:UNUSED_PAD src0_sel:WORD_1
	v_pk_mul_f32 v[144:145], v[28:29], v[144:145]
	s_nop 0
	v_pk_fma_f32 v[140:141], v[140:141], s[38:39], v[144:145] op_sel_hi:[1,0,1]
	s_nop 0
	v_mul_f32_e32 v144, 0x3d372713, v140
	v_mul_f32_e32 v145, 0x3d372713, v141
	v_mul_f32_e32 v144, v140, v144
	v_mul_f32_e32 v145, v141, v145
	v_fma_f32 v144, v140, v144, v140
	v_fma_f32 v145, v141, v145, v141
	v_mul_f32_e32 v144, 0x3f4c422a, v144
	v_mul_f32_e32 v145, 0x3f4c422a, v145
	v_mul_f32_e32 v144, -2.0, v144
	v_mul_f32_e32 v145, -2.0, v145
	v_mul_f32_e32 v144, 0x3fb8aa3b, v144
	v_mul_f32_e32 v145, 0x3fb8aa3b, v145
	v_exp_f32_e32 v144, v144
	v_exp_f32_e32 v145, v145
	v_add_f32_e32 v144, 1.0, v144
	v_add_f32_e32 v145, 1.0, v145
	v_rcp_f32_e32 v144, v144
	v_rcp_f32_e32 v145, v145
	s_nop 0
	v_pk_mul_f32 v[140:141], v[140:141], v[144:145]
	s_nop 0
	v_cvt_pk_f16_f32 v155, v140, v141
	v_cvt_f32_f16_e32 v140, v165
	v_cvt_f32_f16_sdwa v141, v165 dst_sel:DWORD dst_unused:UNUSED_PAD src0_sel:WORD_1
	v_pk_mul_f32 v[140:141], v[34:35], v[140:141]
	s_nop 0
	v_pk_fma_f32 v[140:141], v[146:147], s[38:39], v[140:141] op_sel_hi:[1,0,1]
	s_nop 0
	v_mul_f32_e32 v144, 0x3d372713, v140
	v_mul_f32_e32 v145, 0x3d372713, v141
	v_mul_f32_e32 v144, v140, v144
	v_mul_f32_e32 v145, v141, v145
	v_fma_f32 v144, v140, v144, v140
	v_fma_f32 v145, v141, v145, v141
	v_mul_f32_e32 v144, 0x3f4c422a, v144
	v_mul_f32_e32 v145, 0x3f4c422a, v145
	v_mul_f32_e32 v144, -2.0, v144
	v_mul_f32_e32 v145, -2.0, v145
	v_mul_f32_e32 v144, 0x3fb8aa3b, v144
	v_mul_f32_e32 v145, 0x3fb8aa3b, v145
	v_exp_f32_e32 v144, v144
	v_exp_f32_e32 v145, v145
	v_add_f32_e32 v144, 1.0, v144
	v_add_f32_e32 v145, 1.0, v145
	v_rcp_f32_e32 v144, v144
	v_rcp_f32_e32 v145, v145
	s_nop 0
	v_pk_mul_f32 v[140:141], v[140:141], v[144:145]
	s_nop 0
	v_cvt_pk_f16_f32 v144, v140, v141
	v_cvt_f32_f16_e32 v140, v167
	v_cvt_f32_f16_sdwa v141, v167 dst_sel:DWORD dst_unused:UNUSED_PAD src0_sel:WORD_1
	v_pk_mul_f32 v[140:141], v[30:31], v[140:141]
	s_nop 0
	v_pk_fma_f32 v[140:141], v[142:143], s[38:39], v[140:141] op_sel_hi:[1,0,1]
	s_nop 0
	v_mul_f32_e32 v142, 0x3d372713, v140
	v_mul_f32_e32 v143, 0x3d372713, v141
	v_mul_f32_e32 v142, v140, v142
	v_mul_f32_e32 v143, v141, v143
	v_fma_f32 v142, v140, v142, v140
	v_fma_f32 v143, v141, v143, v141
	v_mul_f32_e32 v142, 0x3f4c422a, v142
	v_mul_f32_e32 v143, 0x3f4c422a, v143
	v_mul_f32_e32 v142, -2.0, v142
	v_mul_f32_e32 v143, -2.0, v143
	v_mul_f32_e32 v142, 0x3fb8aa3b, v142
	v_mul_f32_e32 v143, 0x3fb8aa3b, v143
	v_exp_f32_e32 v142, v142
	v_exp_f32_e32 v143, v143
	v_add_f32_e32 v142, 1.0, v142
	v_add_f32_e32 v143, 1.0, v143
	v_rcp_f32_e32 v142, v142
	v_rcp_f32_e32 v143, v143
	s_nop 0
	v_pk_mul_f32 v[140:141], v[140:141], v[142:143]
	s_nop 0
	v_cvt_pk_f16_f32 v141, v140, v141
	v_ashrrev_i32_e32 v140, 4, v153
	v_lshrrev_b32_e32 v143, 4, v144
	v_add_u32_e32 v146, v140, v192
	v_and_b32_e32 v143, 0x10001, v143
	v_ashrrev_i32_e32 v147, 31, v146
	v_lshrrev_b32_e32 v142, 4, v154
	v_add3_u32 v143, v144, v143, s21
	v_lshrrev_b32_e32 v144, 4, v155
	v_lshrrev_b32_e32 v145, 4, v141
	v_lshlrev_b64 v[146:147], 10, v[146:147]
	v_and_b32_e32 v142, 0x10001, v142
	v_and_b32_e32 v144, 0x10001, v144
	v_and_b32_e32 v145, 0x10001, v145
	v_lshl_add_u64 v[146:147], s[16:17], 0, v[146:147]
	v_add3_u32 v142, v154, v142, s21
	v_add3_u32 v144, v155, v144, s21
	v_add3_u32 v141, v141, v145, s21
	v_lshl_add_u64 v[146:147], v[146:147], 0, s[42:43]
	v_and_b32_e32 v142, 0xfff0fff0, v142
	v_and_b32_e32 v143, 0xfff0fff0, v143
	v_and_b32_e32 v144, 0xfff0fff0, v144
	v_and_b32_e32 v145, 0xfff0fff0, v141
	v_lshl_add_u64 v[146:147], v[146:147], 0, v[2:3]
	global_store_dwordx4 v[146:147], v[142:145], off
	v_add_u32_e32 v141, 0x100, v192
	s_nop 0
	v_cvt_f32_f16_e32 v142, v156
	v_cvt_f32_f16_sdwa v143, v156 dst_sel:DWORD dst_unused:UNUSED_PAD src0_sel:WORD_1
	v_pk_mul_f32 v[142:143], v[32:33], v[142:143]
	s_nop 0
	v_pk_fma_f32 v[132:133], v[132:133], s[38:39], v[142:143] op_sel_hi:[1,0,1]
	s_nop 0
	v_mul_f32_e32 v142, 0x3d372713, v132
	v_mul_f32_e32 v143, 0x3d372713, v133
	v_mul_f32_e32 v142, v132, v142
	v_mul_f32_e32 v143, v133, v143
	v_fma_f32 v142, v132, v142, v132
	v_fma_f32 v143, v133, v143, v133
	v_mul_f32_e32 v142, 0x3f4c422a, v142
	v_mul_f32_e32 v143, 0x3f4c422a, v143
	v_mul_f32_e32 v142, -2.0, v142
	v_mul_f32_e32 v143, -2.0, v143
	v_mul_f32_e32 v142, 0x3fb8aa3b, v142
	v_mul_f32_e32 v143, 0x3fb8aa3b, v143
	v_exp_f32_e32 v142, v142
	v_exp_f32_e32 v143, v143
	v_add_f32_e32 v142, 1.0, v142
	v_add_f32_e32 v143, 1.0, v143
	v_rcp_f32_e32 v142, v142
	v_rcp_f32_e32 v143, v143
	s_nop 0
	v_pk_mul_f32 v[132:133], v[132:133], v[142:143]
	s_nop 0
	v_cvt_pk_f16_f32 v142, v132, v133
	v_cvt_f32_f16_e32 v132, v158
	v_cvt_f32_f16_sdwa v133, v158 dst_sel:DWORD dst_unused:UNUSED_PAD src0_sel:WORD_1
	v_pk_mul_f32 v[132:133], v[28:29], v[132:133]
	s_nop 0
	v_pk_fma_f32 v[128:129], v[128:129], s[38:39], v[132:133] op_sel_hi:[1,0,1]
	s_nop 0
	v_mul_f32_e32 v132, 0x3d372713, v128
	v_mul_f32_e32 v133, 0x3d372713, v129
	v_mul_f32_e32 v132, v128, v132
	v_mul_f32_e32 v133, v129, v133
	v_fma_f32 v132, v128, v132, v128
	v_fma_f32 v133, v129, v133, v129
	v_mul_f32_e32 v132, 0x3f4c422a, v132
	v_mul_f32_e32 v133, 0x3f4c422a, v133
	v_mul_f32_e32 v132, -2.0, v132
	v_mul_f32_e32 v133, -2.0, v133
	v_mul_f32_e32 v132, 0x3fb8aa3b, v132
	v_mul_f32_e32 v133, 0x3fb8aa3b, v133
	v_exp_f32_e32 v132, v132
	v_exp_f32_e32 v133, v133
	v_add_f32_e32 v132, 1.0, v132
	v_add_f32_e32 v133, 1.0, v133
	v_rcp_f32_e32 v132, v132
	v_rcp_f32_e32 v133, v133
	s_nop 0
	v_pk_mul_f32 v[128:129], v[128:129], v[132:133]
	s_nop 0
	v_cvt_pk_f16_f32 v143, v128, v129
	v_cvt_f32_f16_e32 v128, v157
	v_cvt_f32_f16_sdwa v129, v157 dst_sel:DWORD dst_unused:UNUSED_PAD src0_sel:WORD_1
	v_pk_mul_f32 v[128:129], v[34:35], v[128:129]
	s_nop 0
	v_pk_fma_f32 v[128:129], v[134:135], s[38:39], v[128:129] op_sel_hi:[1,0,1]
	s_nop 0
	v_mul_f32_e32 v132, 0x3d372713, v128
	v_mul_f32_e32 v133, 0x3d372713, v129
	v_mul_f32_e32 v132, v128, v132
	v_mul_f32_e32 v133, v129, v133
	v_fma_f32 v132, v128, v132, v128
	v_fma_f32 v133, v129, v133, v129
	v_mul_f32_e32 v132, 0x3f4c422a, v132
	v_mul_f32_e32 v133, 0x3f4c422a, v133
	v_mul_f32_e32 v132, -2.0, v132
	v_mul_f32_e32 v133, -2.0, v133
	v_mul_f32_e32 v132, 0x3fb8aa3b, v132
	v_mul_f32_e32 v133, 0x3fb8aa3b, v133
	v_exp_f32_e32 v132, v132
	v_exp_f32_e32 v133, v133
	v_add_f32_e32 v132, 1.0, v132
	v_add_f32_e32 v133, 1.0, v133
	v_rcp_f32_e32 v132, v132
	v_rcp_f32_e32 v133, v133
	s_nop 0
	v_pk_mul_f32 v[128:129], v[128:129], v[132:133]
	s_nop 0
	v_cvt_pk_f16_f32 v132, v128, v129
	v_cvt_f32_f16_e32 v128, v159
	v_cvt_f32_f16_sdwa v129, v159 dst_sel:DWORD dst_unused:UNUSED_PAD src0_sel:WORD_1
	v_pk_mul_f32 v[128:129], v[30:31], v[128:129]
	s_nop 0
	v_pk_fma_f32 v[128:129], v[130:131], s[38:39], v[128:129] op_sel_hi:[1,0,1]
	s_nop 0
	v_mul_f32_e32 v130, 0x3d372713, v128
	v_mul_f32_e32 v131, 0x3d372713, v129
	v_mul_f32_e32 v130, v128, v130
	v_mul_f32_e32 v131, v129, v131
	v_fma_f32 v130, v128, v130, v128
	v_fma_f32 v131, v129, v131, v129
	v_mul_f32_e32 v130, 0x3f4c422a, v130
	v_mul_f32_e32 v131, 0x3f4c422a, v131
	v_mul_f32_e32 v130, -2.0, v130
	v_mul_f32_e32 v131, -2.0, v131
	v_mul_f32_e32 v130, 0x3fb8aa3b, v130
	v_mul_f32_e32 v131, 0x3fb8aa3b, v131
	v_exp_f32_e32 v130, v130
	v_exp_f32_e32 v131, v131
	v_add_f32_e32 v130, 1.0, v130
	v_add_f32_e32 v131, 1.0, v131
	v_rcp_f32_e32 v130, v130
	v_rcp_f32_e32 v131, v131
	s_nop 0
	v_pk_mul_f32 v[128:129], v[128:129], v[130:131]
	s_nop 0
	v_cvt_pk_f16_f32 v131, v128, v129
	v_lshrrev_b32_e32 v129, 4, v132
	v_and_b32_e32 v129, 0x10001, v129
	v_add3_u32 v129, v132, v129, s21
	v_lshrrev_b32_e32 v132, 4, v131
	v_and_b32_e32 v132, 0x10001, v132
	v_add3_u32 v131, v131, v132, s21
	v_add_u32_e32 v132, v152, v141
	v_ashrrev_i32_e32 v133, 31, v132
	v_lshrrev_b32_e32 v128, 4, v142
	v_lshrrev_b32_e32 v130, 4, v143
	v_lshlrev_b64 v[132:133], 10, v[132:133]
	v_and_b32_e32 v128, 0x10001, v128
	v_and_b32_e32 v130, 0x10001, v130
	v_lshl_add_u64 v[132:133], s[16:17], 0, v[132:133]
	v_add3_u32 v128, v142, v128, s21
	v_add3_u32 v130, v143, v130, s21
	v_lshl_add_u64 v[132:133], v[132:133], 0, s[42:43]
	v_and_b32_e32 v128, 0xfff0fff0, v128
	v_and_b32_e32 v129, 0xfff0fff0, v129
	v_and_b32_e32 v130, 0xfff0fff0, v130
	v_and_b32_e32 v131, 0xfff0fff0, v131
	v_lshl_add_u64 v[132:133], v[132:133], 0, v[2:3]
	global_store_dwordx4 v[132:133], v[128:131], off
	s_nop 1
	v_cvt_f32_f16_e32 v128, v148
	v_cvt_f32_f16_sdwa v129, v148 dst_sel:DWORD dst_unused:UNUSED_PAD src0_sel:WORD_1
	v_pk_mul_f32 v[128:129], v[32:33], v[128:129]
	s_nop 0
	v_pk_fma_f32 v[120:121], v[120:121], s[38:39], v[128:129] op_sel_hi:[1,0,1]
	s_nop 0
	v_mul_f32_e32 v128, 0x3d372713, v120
	v_mul_f32_e32 v129, 0x3d372713, v121
	v_mul_f32_e32 v128, v120, v128
	v_mul_f32_e32 v129, v121, v129
	v_fma_f32 v128, v120, v128, v120
	v_fma_f32 v129, v121, v129, v121
	v_mul_f32_e32 v128, 0x3f4c422a, v128
	v_mul_f32_e32 v129, 0x3f4c422a, v129
	v_mul_f32_e32 v128, -2.0, v128
	v_mul_f32_e32 v129, -2.0, v129
	v_mul_f32_e32 v128, 0x3fb8aa3b, v128
	v_mul_f32_e32 v129, 0x3fb8aa3b, v129
	v_exp_f32_e32 v128, v128
	v_exp_f32_e32 v129, v129
	v_add_f32_e32 v128, 1.0, v128
	v_add_f32_e32 v129, 1.0, v129
	v_rcp_f32_e32 v128, v128
	v_rcp_f32_e32 v129, v129
	s_nop 0
	v_pk_mul_f32 v[120:121], v[120:121], v[128:129]
	s_nop 0
	v_cvt_pk_f16_f32 v128, v120, v121
	v_cvt_f32_f16_e32 v120, v150
	v_cvt_f32_f16_sdwa v121, v150 dst_sel:DWORD dst_unused:UNUSED_PAD src0_sel:WORD_1
	v_pk_mul_f32 v[120:121], v[28:29], v[120:121]
	s_nop 0
	v_pk_fma_f32 v[116:117], v[116:117], s[38:39], v[120:121] op_sel_hi:[1,0,1]
	s_nop 0
	v_mul_f32_e32 v120, 0x3d372713, v116
	v_mul_f32_e32 v121, 0x3d372713, v117
	v_mul_f32_e32 v120, v116, v120
	v_mul_f32_e32 v121, v117, v121
	v_fma_f32 v120, v116, v120, v116
	v_fma_f32 v121, v117, v121, v117
	v_mul_f32_e32 v120, 0x3f4c422a, v120
	v_mul_f32_e32 v121, 0x3f4c422a, v121
	v_mul_f32_e32 v120, -2.0, v120
	v_mul_f32_e32 v121, -2.0, v121
	v_mul_f32_e32 v120, 0x3fb8aa3b, v120
	v_mul_f32_e32 v121, 0x3fb8aa3b, v121
	v_exp_f32_e32 v120, v120
	v_exp_f32_e32 v121, v121
	v_add_f32_e32 v120, 1.0, v120
	v_add_f32_e32 v121, 1.0, v121
	v_rcp_f32_e32 v120, v120
	v_rcp_f32_e32 v121, v121
	s_nop 0
	v_pk_mul_f32 v[116:117], v[116:117], v[120:121]
	s_nop 0
	v_cvt_pk_f16_f32 v129, v116, v117
	v_cvt_f32_f16_e32 v116, v149
	v_cvt_f32_f16_sdwa v117, v149 dst_sel:DWORD dst_unused:UNUSED_PAD src0_sel:WORD_1
	v_pk_mul_f32 v[116:117], v[34:35], v[116:117]
	s_nop 0
	v_pk_fma_f32 v[116:117], v[122:123], s[38:39], v[116:117] op_sel_hi:[1,0,1]
	s_nop 0
	v_mul_f32_e32 v120, 0x3d372713, v116
	v_mul_f32_e32 v121, 0x3d372713, v117
	v_mul_f32_e32 v120, v116, v120
	v_mul_f32_e32 v121, v117, v121
	v_fma_f32 v120, v116, v120, v116
	v_fma_f32 v121, v117, v121, v117
	v_mul_f32_e32 v120, 0x3f4c422a, v120
	v_mul_f32_e32 v121, 0x3f4c422a, v121
	v_mul_f32_e32 v120, -2.0, v120
	v_mul_f32_e32 v121, -2.0, v121
	v_mul_f32_e32 v120, 0x3fb8aa3b, v120
	v_mul_f32_e32 v121, 0x3fb8aa3b, v121
	v_exp_f32_e32 v120, v120
	v_exp_f32_e32 v121, v121
	v_add_f32_e32 v120, 1.0, v120
	v_add_f32_e32 v121, 1.0, v121
	v_rcp_f32_e32 v120, v120
	v_rcp_f32_e32 v121, v121
	s_nop 0
	v_pk_mul_f32 v[116:117], v[116:117], v[120:121]
	s_nop 0
	v_cvt_pk_f16_f32 v120, v116, v117
	v_cvt_f32_f16_e32 v116, v151
	v_cvt_f32_f16_sdwa v117, v151 dst_sel:DWORD dst_unused:UNUSED_PAD src0_sel:WORD_1
	v_pk_mul_f32 v[116:117], v[30:31], v[116:117]
	s_nop 0
	v_pk_fma_f32 v[116:117], v[118:119], s[38:39], v[116:117] op_sel_hi:[1,0,1]
	s_nop 0
	v_mul_f32_e32 v118, 0x3d372713, v116
	v_mul_f32_e32 v119, 0x3d372713, v117
	v_mul_f32_e32 v118, v116, v118
	v_mul_f32_e32 v119, v117, v119
	v_fma_f32 v118, v116, v118, v116
	v_fma_f32 v119, v117, v119, v117
	v_mul_f32_e32 v118, 0x3f4c422a, v118
	v_mul_f32_e32 v119, 0x3f4c422a, v119
	v_mul_f32_e32 v118, -2.0, v118
	v_mul_f32_e32 v119, -2.0, v119
	v_mul_f32_e32 v118, 0x3fb8aa3b, v118
	v_mul_f32_e32 v119, 0x3fb8aa3b, v119
	v_exp_f32_e32 v118, v118
	v_exp_f32_e32 v119, v119
	v_add_f32_e32 v118, 1.0, v118
	v_add_f32_e32 v119, 1.0, v119
	v_rcp_f32_e32 v118, v118
	v_rcp_f32_e32 v119, v119
	s_nop 0
	v_pk_mul_f32 v[116:117], v[116:117], v[118:119]
	s_nop 0
	v_cvt_pk_f16_f32 v119, v116, v117
	v_lshrrev_b32_e32 v117, 4, v120
	v_and_b32_e32 v117, 0x10001, v117
	v_add3_u32 v117, v120, v117, s21
	v_lshrrev_b32_e32 v120, 4, v119
	v_and_b32_e32 v120, 0x10001, v120
	v_add3_u32 v119, v119, v120, s21
	v_add_u32_e32 v120, v140, v141
	v_ashrrev_i32_e32 v121, 31, v120
	v_lshrrev_b32_e32 v116, 4, v128
	v_lshrrev_b32_e32 v118, 4, v129
	v_lshlrev_b64 v[120:121], 10, v[120:121]
	v_and_b32_e32 v116, 0x10001, v116
	v_and_b32_e32 v118, 0x10001, v118
	v_lshl_add_u64 v[120:121], s[16:17], 0, v[120:121]
	v_add3_u32 v116, v128, v116, s21
	v_add3_u32 v118, v129, v118, s21
	v_lshl_add_u64 v[120:121], v[120:121], 0, s[42:43]
	v_and_b32_e32 v116, 0xfff0fff0, v116
	v_and_b32_e32 v117, 0xfff0fff0, v117
	v_and_b32_e32 v118, 0xfff0fff0, v118
	v_and_b32_e32 v119, 0xfff0fff0, v119
	v_lshl_add_u64 v[120:121], v[120:121], 0, v[2:3]
	global_store_dwordx4 v[120:121], v[116:119], off
	s_nop 1
	v_cvt_f32_f16_e32 v118, v136
	v_cvt_f32_f16_sdwa v119, v136 dst_sel:DWORD dst_unused:UNUSED_PAD src0_sel:WORD_1
	v_add_u32_e32 v116, 0x200, v192
	v_pk_mul_f32 v[118:119], v[32:33], v[118:119]
	s_nop 0
	v_pk_fma_f32 v[108:109], v[108:109], s[38:39], v[118:119] op_sel_hi:[1,0,1]
	s_nop 0
	v_mul_f32_e32 v117, 0x3d372713, v108
	v_mul_f32_e32 v117, v108, v117
	v_fma_f32 v117, v108, v117, v108
	v_mul_f32_e32 v117, 0x3f4c422a, v117
	v_mul_f32_e32 v117, -2.0, v117
	v_mul_f32_e32 v117, 0x3fb8aa3b, v117
	v_exp_f32_e32 v117, v117
	s_nop 0
	v_add_f32_e32 v117, 1.0, v117
	v_rcp_f32_e32 v118, v117
	v_mul_f32_e32 v117, 0x3d372713, v109
	v_mul_f32_e32 v117, v109, v117
	v_fma_f32 v117, v109, v117, v109
	v_mul_f32_e32 v117, 0x3f4c422a, v117
	v_mul_f32_e32 v117, -2.0, v117
	v_mul_f32_e32 v117, 0x3fb8aa3b, v117
	v_exp_f32_e32 v117, v117
	s_nop 0
	v_add_f32_e32 v117, 1.0, v117
	v_rcp_f32_e32 v119, v117
	s_nop 0
	v_pk_mul_f32 v[108:109], v[108:109], v[118:119]
	s_nop 0
	v_cvt_pk_f16_f32 v117, v108, v109
	v_cvt_f32_f16_e32 v108, v138
	v_cvt_f32_f16_sdwa v109, v138 dst_sel:DWORD dst_unused:UNUSED_PAD src0_sel:WORD_1
	v_pk_mul_f32 v[108:109], v[28:29], v[108:109]
	s_nop 0
	v_pk_fma_f32 v[104:105], v[104:105], s[38:39], v[108:109] op_sel_hi:[1,0,1]
	s_nop 0
	v_mul_f32_e32 v108, 0x3d372713, v104
	v_mul_f32_e32 v109, 0x3d372713, v105
	v_mul_f32_e32 v108, v104, v108
	v_mul_f32_e32 v109, v105, v109
	v_fma_f32 v108, v104, v108, v104
	v_fma_f32 v109, v105, v109, v105
	v_mul_f32_e32 v108, 0x3f4c422a, v108
	v_mul_f32_e32 v109, 0x3f4c422a, v109
	v_mul_f32_e32 v108, -2.0, v108
	v_mul_f32_e32 v109, -2.0, v109
	v_mul_f32_e32 v108, 0x3fb8aa3b, v108
	v_mul_f32_e32 v109, 0x3fb8aa3b, v109
	v_exp_f32_e32 v108, v108
	v_exp_f32_e32 v109, v109
	v_add_f32_e32 v108, 1.0, v108
	v_add_f32_e32 v109, 1.0, v109
	v_rcp_f32_e32 v108, v108
	v_rcp_f32_e32 v109, v109
	s_nop 0
	v_pk_mul_f32 v[104:105], v[104:105], v[108:109]
	s_nop 0
	v_cvt_pk_f16_f32 v118, v104, v105
	v_cvt_f32_f16_e32 v104, v137
	v_cvt_f32_f16_sdwa v105, v137 dst_sel:DWORD dst_unused:UNUSED_PAD src0_sel:WORD_1
	v_pk_mul_f32 v[104:105], v[34:35], v[104:105]
	s_nop 0
	v_pk_fma_f32 v[104:105], v[110:111], s[38:39], v[104:105] op_sel_hi:[1,0,1]
	s_nop 0
	v_mul_f32_e32 v108, 0x3d372713, v104
	v_mul_f32_e32 v109, 0x3d372713, v105
	v_mul_f32_e32 v108, v104, v108
	v_mul_f32_e32 v109, v105, v109
	v_fma_f32 v108, v104, v108, v104
	v_fma_f32 v109, v105, v109, v105
	v_mul_f32_e32 v108, 0x3f4c422a, v108
	v_mul_f32_e32 v109, 0x3f4c422a, v109
	v_mul_f32_e32 v108, -2.0, v108
	v_mul_f32_e32 v109, -2.0, v109
	v_mul_f32_e32 v108, 0x3fb8aa3b, v108
	v_mul_f32_e32 v109, 0x3fb8aa3b, v109
	v_exp_f32_e32 v108, v108
	v_exp_f32_e32 v109, v109
	v_add_f32_e32 v108, 1.0, v108
	v_add_f32_e32 v109, 1.0, v109
	v_rcp_f32_e32 v108, v108
	v_rcp_f32_e32 v109, v109
	s_nop 0
	v_pk_mul_f32 v[104:105], v[104:105], v[108:109]
	s_nop 0
	v_cvt_pk_f16_f32 v108, v104, v105
	v_cvt_f32_f16_e32 v104, v139
	v_cvt_f32_f16_sdwa v105, v139 dst_sel:DWORD dst_unused:UNUSED_PAD src0_sel:WORD_1
	v_pk_mul_f32 v[104:105], v[30:31], v[104:105]
	s_nop 0
	v_pk_fma_f32 v[104:105], v[106:107], s[38:39], v[104:105] op_sel_hi:[1,0,1]
	s_nop 0
	v_mul_f32_e32 v106, 0x3d372713, v104
	v_mul_f32_e32 v107, 0x3d372713, v105
	v_mul_f32_e32 v106, v104, v106
	v_mul_f32_e32 v107, v105, v107
	v_fma_f32 v106, v104, v106, v104
	v_fma_f32 v107, v105, v107, v105
	v_mul_f32_e32 v106, 0x3f4c422a, v106
	v_mul_f32_e32 v107, 0x3f4c422a, v107
	v_mul_f32_e32 v106, -2.0, v106
	v_mul_f32_e32 v107, -2.0, v107
	v_mul_f32_e32 v106, 0x3fb8aa3b, v106
	v_mul_f32_e32 v107, 0x3fb8aa3b, v107
	v_exp_f32_e32 v106, v106
	v_exp_f32_e32 v107, v107
	v_add_f32_e32 v106, 1.0, v106
	v_add_f32_e32 v107, 1.0, v107
	v_rcp_f32_e32 v106, v106
	v_rcp_f32_e32 v107, v107
	s_nop 0
	v_pk_mul_f32 v[104:105], v[104:105], v[106:107]
	s_nop 0
	v_cvt_pk_f16_f32 v107, v104, v105
	v_lshrrev_b32_e32 v105, 4, v108
	v_and_b32_e32 v105, 0x10001, v105
	v_add3_u32 v105, v108, v105, s21
	v_lshrrev_b32_e32 v108, 4, v107
	v_and_b32_e32 v108, 0x10001, v108
	v_add3_u32 v107, v107, v108, s21
	v_add_u32_e32 v108, v152, v116
	v_ashrrev_i32_e32 v109, 31, v108
	v_lshrrev_b32_e32 v104, 4, v117
	v_lshrrev_b32_e32 v106, 4, v118
	v_lshlrev_b64 v[108:109], 10, v[108:109]
	v_and_b32_e32 v104, 0x10001, v104
	v_and_b32_e32 v106, 0x10001, v106
	v_lshl_add_u64 v[108:109], s[16:17], 0, v[108:109]
	v_add3_u32 v104, v117, v104, s21
	v_add3_u32 v106, v118, v106, s21
	v_lshl_add_u64 v[108:109], v[108:109], 0, s[42:43]
	v_and_b32_e32 v104, 0xfff0fff0, v104
	v_and_b32_e32 v105, 0xfff0fff0, v105
	v_and_b32_e32 v106, 0xfff0fff0, v106
	v_and_b32_e32 v107, 0xfff0fff0, v107
	v_lshl_add_u64 v[108:109], v[108:109], 0, v[2:3]
	global_store_dwordx4 v[108:109], v[104:107], off
	s_nop 1
	v_cvt_f32_f16_e32 v104, v124
	v_cvt_f32_f16_sdwa v105, v124 dst_sel:DWORD dst_unused:UNUSED_PAD src0_sel:WORD_1
	v_pk_mul_f32 v[104:105], v[32:33], v[104:105]
	s_nop 0
	v_pk_fma_f32 v[96:97], v[96:97], s[38:39], v[104:105] op_sel_hi:[1,0,1]
	s_nop 0
	v_mul_f32_e32 v104, 0x3d372713, v96
	v_mul_f32_e32 v105, 0x3d372713, v97
	v_mul_f32_e32 v104, v96, v104
	v_mul_f32_e32 v105, v97, v105
	v_fma_f32 v104, v96, v104, v96
	v_fma_f32 v105, v97, v105, v97
	v_mul_f32_e32 v104, 0x3f4c422a, v104
	v_mul_f32_e32 v105, 0x3f4c422a, v105
	v_mul_f32_e32 v104, -2.0, v104
	v_mul_f32_e32 v105, -2.0, v105
	v_mul_f32_e32 v104, 0x3fb8aa3b, v104
	v_mul_f32_e32 v105, 0x3fb8aa3b, v105
	v_exp_f32_e32 v104, v104
	v_exp_f32_e32 v105, v105
	v_add_f32_e32 v104, 1.0, v104
	v_add_f32_e32 v105, 1.0, v105
	v_rcp_f32_e32 v104, v104
	v_rcp_f32_e32 v105, v105
	s_nop 0
	v_pk_mul_f32 v[96:97], v[96:97], v[104:105]
	s_nop 0
	v_cvt_pk_f16_f32 v104, v96, v97
	v_cvt_f32_f16_e32 v96, v126
	v_cvt_f32_f16_sdwa v97, v126 dst_sel:DWORD dst_unused:UNUSED_PAD src0_sel:WORD_1
	v_pk_mul_f32 v[96:97], v[28:29], v[96:97]
	s_nop 0
	v_pk_fma_f32 v[92:93], v[92:93], s[38:39], v[96:97] op_sel_hi:[1,0,1]
	s_nop 0
	v_mul_f32_e32 v96, 0x3d372713, v92
	v_mul_f32_e32 v97, 0x3d372713, v93
	v_mul_f32_e32 v96, v92, v96
	v_mul_f32_e32 v97, v93, v97
	v_fma_f32 v96, v92, v96, v92
	v_fma_f32 v97, v93, v97, v93
	v_mul_f32_e32 v96, 0x3f4c422a, v96
	v_mul_f32_e32 v97, 0x3f4c422a, v97
	v_mul_f32_e32 v96, -2.0, v96
	v_mul_f32_e32 v97, -2.0, v97
	v_mul_f32_e32 v96, 0x3fb8aa3b, v96
	v_mul_f32_e32 v97, 0x3fb8aa3b, v97
	v_exp_f32_e32 v96, v96
	v_exp_f32_e32 v97, v97
	v_add_f32_e32 v96, 1.0, v96
	v_add_f32_e32 v97, 1.0, v97
	v_rcp_f32_e32 v96, v96
	v_rcp_f32_e32 v97, v97
	s_nop 0
	v_pk_mul_f32 v[92:93], v[92:93], v[96:97]
	s_nop 0
	v_cvt_pk_f16_f32 v105, v92, v93
	v_cvt_f32_f16_e32 v92, v125
	v_cvt_f32_f16_sdwa v93, v125 dst_sel:DWORD dst_unused:UNUSED_PAD src0_sel:WORD_1
	v_pk_mul_f32 v[92:93], v[34:35], v[92:93]
	s_nop 0
	v_pk_fma_f32 v[92:93], v[98:99], s[38:39], v[92:93] op_sel_hi:[1,0,1]
	s_nop 0
	v_mul_f32_e32 v96, 0x3d372713, v92
	v_mul_f32_e32 v97, 0x3d372713, v93
	v_mul_f32_e32 v96, v92, v96
	v_mul_f32_e32 v97, v93, v97
	v_fma_f32 v96, v92, v96, v92
	v_fma_f32 v97, v93, v97, v93
	v_mul_f32_e32 v96, 0x3f4c422a, v96
	v_mul_f32_e32 v97, 0x3f4c422a, v97
	v_mul_f32_e32 v96, -2.0, v96
	v_mul_f32_e32 v97, -2.0, v97
	v_mul_f32_e32 v96, 0x3fb8aa3b, v96
	v_mul_f32_e32 v97, 0x3fb8aa3b, v97
	v_exp_f32_e32 v96, v96
	v_exp_f32_e32 v97, v97
	v_add_f32_e32 v96, 1.0, v96
	v_add_f32_e32 v97, 1.0, v97
	v_rcp_f32_e32 v96, v96
	v_rcp_f32_e32 v97, v97
	s_nop 0
	v_pk_mul_f32 v[92:93], v[92:93], v[96:97]
	s_nop 0
	v_cvt_pk_f16_f32 v96, v92, v93
	v_cvt_f32_f16_e32 v92, v127
	v_cvt_f32_f16_sdwa v93, v127 dst_sel:DWORD dst_unused:UNUSED_PAD src0_sel:WORD_1
	v_pk_mul_f32 v[92:93], v[30:31], v[92:93]
	s_nop 0
	v_pk_fma_f32 v[92:93], v[94:95], s[38:39], v[92:93] op_sel_hi:[1,0,1]
	s_nop 0
	v_mul_f32_e32 v94, 0x3d372713, v92
	v_mul_f32_e32 v95, 0x3d372713, v93
	v_mul_f32_e32 v94, v92, v94
	v_mul_f32_e32 v95, v93, v95
	v_fma_f32 v94, v92, v94, v92
	v_fma_f32 v95, v93, v95, v93
	v_mul_f32_e32 v94, 0x3f4c422a, v94
	v_mul_f32_e32 v95, 0x3f4c422a, v95
	v_mul_f32_e32 v94, -2.0, v94
	v_mul_f32_e32 v95, -2.0, v95
	v_mul_f32_e32 v94, 0x3fb8aa3b, v94
	v_mul_f32_e32 v95, 0x3fb8aa3b, v95
	v_exp_f32_e32 v94, v94
	v_exp_f32_e32 v95, v95
	v_add_f32_e32 v94, 1.0, v94
	v_add_f32_e32 v95, 1.0, v95
	v_rcp_f32_e32 v94, v94
	v_rcp_f32_e32 v95, v95
	s_nop 0
	v_pk_mul_f32 v[92:93], v[92:93], v[94:95]
	s_nop 0
	v_cvt_pk_f16_f32 v95, v92, v93
	v_lshrrev_b32_e32 v93, 4, v96
	v_and_b32_e32 v93, 0x10001, v93
	v_add3_u32 v93, v96, v93, s21
	v_lshrrev_b32_e32 v96, 4, v95
	v_and_b32_e32 v96, 0x10001, v96
	v_add3_u32 v95, v95, v96, s21
	v_add_u32_e32 v96, v140, v116
	v_ashrrev_i32_e32 v97, 31, v96
	v_lshrrev_b32_e32 v92, 4, v104
	v_lshrrev_b32_e32 v94, 4, v105
	v_lshlrev_b64 v[96:97], 10, v[96:97]
	v_and_b32_e32 v92, 0x10001, v92
	v_and_b32_e32 v94, 0x10001, v94
	v_lshl_add_u64 v[96:97], s[16:17], 0, v[96:97]
	v_add3_u32 v92, v104, v92, s21
	v_add3_u32 v94, v105, v94, s21
	v_lshl_add_u64 v[96:97], v[96:97], 0, s[42:43]
	v_and_b32_e32 v92, 0xfff0fff0, v92
	v_and_b32_e32 v93, 0xfff0fff0, v93
	v_and_b32_e32 v94, 0xfff0fff0, v94
	v_and_b32_e32 v95, 0xfff0fff0, v95
	v_lshl_add_u64 v[96:97], v[96:97], 0, v[2:3]
	global_store_dwordx4 v[96:97], v[92:95], off
	v_add_u32_e32 v104, 0x800, v192
	s_nop 0
	v_cvt_f32_f16_e32 v94, v112
	v_cvt_f32_f16_sdwa v95, v112 dst_sel:DWORD dst_unused:UNUSED_PAD src0_sel:WORD_1
	v_add_u32_e32 v92, 0x300, v192
	v_pk_mul_f32 v[94:95], v[32:33], v[94:95]
	s_nop 0
	v_pk_fma_f32 v[88:89], v[88:89], s[38:39], v[94:95] op_sel_hi:[1,0,1]
	s_nop 0
	v_mul_f32_e32 v93, 0x3d372713, v88
	v_mul_f32_e32 v93, v88, v93
	v_fma_f32 v93, v88, v93, v88
	v_mul_f32_e32 v93, 0x3f4c422a, v93
	v_mul_f32_e32 v93, -2.0, v93
	v_mul_f32_e32 v93, 0x3fb8aa3b, v93
	v_exp_f32_e32 v93, v93
	s_nop 0
	v_add_f32_e32 v93, 1.0, v93
	v_rcp_f32_e32 v94, v93
	v_mul_f32_e32 v93, 0x3d372713, v89
	v_mul_f32_e32 v93, v89, v93
	v_fma_f32 v93, v89, v93, v89
	v_mul_f32_e32 v93, 0x3f4c422a, v93
	v_mul_f32_e32 v93, -2.0, v93
	v_mul_f32_e32 v93, 0x3fb8aa3b, v93
	v_exp_f32_e32 v93, v93
	s_nop 0
	v_add_f32_e32 v93, 1.0, v93
	v_rcp_f32_e32 v95, v93
	s_nop 0
	v_pk_mul_f32 v[88:89], v[88:89], v[94:95]
	s_nop 0
	v_cvt_pk_f16_f32 v93, v88, v89
	v_cvt_f32_f16_e32 v88, v114
	v_cvt_f32_f16_sdwa v89, v114 dst_sel:DWORD dst_unused:UNUSED_PAD src0_sel:WORD_1
	v_pk_mul_f32 v[88:89], v[28:29], v[88:89]
	s_nop 0
	v_pk_fma_f32 v[84:85], v[84:85], s[38:39], v[88:89] op_sel_hi:[1,0,1]
	s_nop 0
	v_mul_f32_e32 v88, 0x3d372713, v84
	v_mul_f32_e32 v89, 0x3d372713, v85
	v_mul_f32_e32 v88, v84, v88
	v_mul_f32_e32 v89, v85, v89
	v_fma_f32 v88, v84, v88, v84
	v_fma_f32 v89, v85, v89, v85
	v_mul_f32_e32 v88, 0x3f4c422a, v88
	v_mul_f32_e32 v89, 0x3f4c422a, v89
	v_mul_f32_e32 v88, -2.0, v88
	v_mul_f32_e32 v89, -2.0, v89
	v_mul_f32_e32 v88, 0x3fb8aa3b, v88
	v_mul_f32_e32 v89, 0x3fb8aa3b, v89
	v_exp_f32_e32 v88, v88
	v_exp_f32_e32 v89, v89
	v_add_f32_e32 v88, 1.0, v88
	v_add_f32_e32 v89, 1.0, v89
	v_rcp_f32_e32 v88, v88
	v_rcp_f32_e32 v89, v89
	s_nop 0
	v_pk_mul_f32 v[84:85], v[84:85], v[88:89]
	s_nop 0
	v_cvt_pk_f16_f32 v94, v84, v85
	v_cvt_f32_f16_e32 v84, v113
	v_cvt_f32_f16_sdwa v85, v113 dst_sel:DWORD dst_unused:UNUSED_PAD src0_sel:WORD_1
	v_pk_mul_f32 v[84:85], v[34:35], v[84:85]
	s_nop 0
	v_pk_fma_f32 v[84:85], v[90:91], s[38:39], v[84:85] op_sel_hi:[1,0,1]
	s_nop 0
	v_mul_f32_e32 v88, 0x3d372713, v84
	v_mul_f32_e32 v89, 0x3d372713, v85
	v_mul_f32_e32 v88, v84, v88
	v_mul_f32_e32 v89, v85, v89
	v_fma_f32 v88, v84, v88, v84
	v_fma_f32 v89, v85, v89, v85
	v_mul_f32_e32 v88, 0x3f4c422a, v88
	v_mul_f32_e32 v89, 0x3f4c422a, v89
	v_mul_f32_e32 v88, -2.0, v88
	v_mul_f32_e32 v89, -2.0, v89
	v_mul_f32_e32 v88, 0x3fb8aa3b, v88
	v_mul_f32_e32 v89, 0x3fb8aa3b, v89
	v_exp_f32_e32 v88, v88
	v_exp_f32_e32 v89, v89
	v_add_f32_e32 v88, 1.0, v88
	v_add_f32_e32 v89, 1.0, v89
	v_rcp_f32_e32 v88, v88
	v_rcp_f32_e32 v89, v89
	s_nop 0
	v_pk_mul_f32 v[84:85], v[84:85], v[88:89]
	s_nop 0
	v_cvt_pk_f16_f32 v88, v84, v85
	v_cvt_f32_f16_e32 v84, v115
	v_cvt_f32_f16_sdwa v85, v115 dst_sel:DWORD dst_unused:UNUSED_PAD src0_sel:WORD_1
	v_pk_mul_f32 v[84:85], v[30:31], v[84:85]
	s_nop 0
	v_pk_fma_f32 v[84:85], v[86:87], s[38:39], v[84:85] op_sel_hi:[1,0,1]
	s_nop 0
	v_mul_f32_e32 v86, 0x3d372713, v84
	v_mul_f32_e32 v87, 0x3d372713, v85
	v_mul_f32_e32 v86, v84, v86
	v_mul_f32_e32 v87, v85, v87
	v_fma_f32 v86, v84, v86, v84
	v_fma_f32 v87, v85, v87, v85
	v_mul_f32_e32 v86, 0x3f4c422a, v86
	v_mul_f32_e32 v87, 0x3f4c422a, v87
	v_mul_f32_e32 v86, -2.0, v86
	v_mul_f32_e32 v87, -2.0, v87
	v_mul_f32_e32 v86, 0x3fb8aa3b, v86
	v_mul_f32_e32 v87, 0x3fb8aa3b, v87
	v_exp_f32_e32 v86, v86
	v_exp_f32_e32 v87, v87
	v_add_f32_e32 v86, 1.0, v86
	v_add_f32_e32 v87, 1.0, v87
	v_rcp_f32_e32 v86, v86
	v_rcp_f32_e32 v87, v87
	s_nop 0
	v_pk_mul_f32 v[84:85], v[84:85], v[86:87]
	s_nop 0
	v_cvt_pk_f16_f32 v87, v84, v85
	v_lshrrev_b32_e32 v85, 4, v88
	v_and_b32_e32 v85, 0x10001, v85
	v_add3_u32 v85, v88, v85, s21
	v_lshrrev_b32_e32 v88, 4, v87
	v_and_b32_e32 v88, 0x10001, v88
	v_add3_u32 v87, v87, v88, s21
	v_add_u32_e32 v88, v152, v92
	v_ashrrev_i32_e32 v89, 31, v88
	v_lshrrev_b32_e32 v84, 4, v93
	v_lshrrev_b32_e32 v86, 4, v94
	v_lshlrev_b64 v[88:89], 10, v[88:89]
	v_and_b32_e32 v84, 0x10001, v84
	v_and_b32_e32 v86, 0x10001, v86
	v_lshl_add_u64 v[88:89], s[16:17], 0, v[88:89]
	v_add3_u32 v84, v93, v84, s21
	v_add3_u32 v86, v94, v86, s21
	v_lshl_add_u64 v[88:89], v[88:89], 0, s[42:43]
	v_and_b32_e32 v84, 0xfff0fff0, v84
	v_and_b32_e32 v85, 0xfff0fff0, v85
	v_and_b32_e32 v86, 0xfff0fff0, v86
	v_and_b32_e32 v87, 0xfff0fff0, v87
	v_lshl_add_u64 v[88:89], v[88:89], 0, v[2:3]
	global_store_dwordx4 v[88:89], v[84:87], off
	s_nop 1
	v_cvt_f32_f16_e32 v84, v100
	v_cvt_f32_f16_sdwa v85, v100 dst_sel:DWORD dst_unused:UNUSED_PAD src0_sel:WORD_1
	v_pk_mul_f32 v[84:85], v[32:33], v[84:85]
	s_nop 0
	v_pk_fma_f32 v[80:81], v[80:81], s[38:39], v[84:85] op_sel_hi:[1,0,1]
	s_nop 0
	v_mul_f32_e32 v84, 0x3d372713, v80
	v_mul_f32_e32 v85, 0x3d372713, v81
	v_mul_f32_e32 v84, v80, v84
	v_mul_f32_e32 v85, v81, v85
	v_fma_f32 v84, v80, v84, v80
	v_fma_f32 v85, v81, v85, v81
	v_mul_f32_e32 v84, 0x3f4c422a, v84
	v_mul_f32_e32 v85, 0x3f4c422a, v85
	v_mul_f32_e32 v84, -2.0, v84
	v_mul_f32_e32 v85, -2.0, v85
	v_mul_f32_e32 v84, 0x3fb8aa3b, v84
	v_mul_f32_e32 v85, 0x3fb8aa3b, v85
	v_exp_f32_e32 v84, v84
	v_exp_f32_e32 v85, v85
	v_add_f32_e32 v84, 1.0, v84
	v_add_f32_e32 v85, 1.0, v85
	v_rcp_f32_e32 v84, v84
	v_rcp_f32_e32 v85, v85
	s_nop 0
	v_pk_mul_f32 v[80:81], v[80:81], v[84:85]
	s_nop 0
	v_cvt_pk_f16_f32 v84, v80, v81
	v_cvt_f32_f16_e32 v80, v102
	v_cvt_f32_f16_sdwa v81, v102 dst_sel:DWORD dst_unused:UNUSED_PAD src0_sel:WORD_1
	v_pk_mul_f32 v[80:81], v[28:29], v[80:81]
	s_nop 0
	v_pk_fma_f32 v[76:77], v[76:77], s[38:39], v[80:81] op_sel_hi:[1,0,1]
	s_nop 0
	v_mul_f32_e32 v80, 0x3d372713, v76
	v_mul_f32_e32 v81, 0x3d372713, v77
	v_mul_f32_e32 v80, v76, v80
	v_mul_f32_e32 v81, v77, v81
	v_fma_f32 v80, v76, v80, v76
	v_fma_f32 v81, v77, v81, v77
	v_mul_f32_e32 v80, 0x3f4c422a, v80
	v_mul_f32_e32 v81, 0x3f4c422a, v81
	v_mul_f32_e32 v80, -2.0, v80
	v_mul_f32_e32 v81, -2.0, v81
	v_mul_f32_e32 v80, 0x3fb8aa3b, v80
	v_mul_f32_e32 v81, 0x3fb8aa3b, v81
	v_exp_f32_e32 v80, v80
	v_exp_f32_e32 v81, v81
	v_add_f32_e32 v80, 1.0, v80
	v_add_f32_e32 v81, 1.0, v81
	v_rcp_f32_e32 v80, v80
	v_rcp_f32_e32 v81, v81
	s_nop 0
	v_pk_mul_f32 v[76:77], v[76:77], v[80:81]
	s_nop 0
	v_cvt_pk_f16_f32 v85, v76, v77
	v_cvt_f32_f16_e32 v76, v101
	v_cvt_f32_f16_sdwa v77, v101 dst_sel:DWORD dst_unused:UNUSED_PAD src0_sel:WORD_1
	v_lshl_add_u64 v[100:101], v[184:185], 0, s[10:11]
	s_mov_b64 s[10:11], 0x480000
	v_pk_mul_f32 v[76:77], v[34:35], v[76:77]
	s_nop 0
	v_pk_fma_f32 v[76:77], v[82:83], s[38:39], v[76:77] op_sel_hi:[1,0,1]
	s_nop 0
	v_mul_f32_e32 v80, 0x3d372713, v76
	v_mul_f32_e32 v81, 0x3d372713, v77
	v_mul_f32_e32 v80, v76, v80
	v_mul_f32_e32 v81, v77, v81
	v_fma_f32 v80, v76, v80, v76
	v_fma_f32 v81, v77, v81, v77
	v_mul_f32_e32 v80, 0x3f4c422a, v80
	v_mul_f32_e32 v81, 0x3f4c422a, v81
	v_mul_f32_e32 v80, -2.0, v80
	v_mul_f32_e32 v81, -2.0, v81
	v_mul_f32_e32 v80, 0x3fb8aa3b, v80
	v_mul_f32_e32 v81, 0x3fb8aa3b, v81
	v_exp_f32_e32 v80, v80
	v_exp_f32_e32 v81, v81
	v_add_f32_e32 v80, 1.0, v80
	v_add_f32_e32 v81, 1.0, v81
	v_rcp_f32_e32 v80, v80
	v_rcp_f32_e32 v81, v81
	s_nop 0
	v_pk_mul_f32 v[76:77], v[76:77], v[80:81]
	s_nop 0
	v_cvt_pk_f16_f32 v80, v76, v77
	v_cvt_f32_f16_e32 v76, v103
	v_cvt_f32_f16_sdwa v77, v103 dst_sel:DWORD dst_unused:UNUSED_PAD src0_sel:WORD_1
	v_pk_mul_f32 v[76:77], v[30:31], v[76:77]
	s_nop 0
	v_pk_fma_f32 v[76:77], v[78:79], s[38:39], v[76:77] op_sel_hi:[1,0,1]
	s_nop 0
	v_mul_f32_e32 v78, 0x3d372713, v76
	v_mul_f32_e32 v79, 0x3d372713, v77
	v_mul_f32_e32 v78, v76, v78
	v_mul_f32_e32 v79, v77, v79
	v_fma_f32 v78, v76, v78, v76
	v_fma_f32 v79, v77, v79, v77
	v_mul_f32_e32 v78, 0x3f4c422a, v78
	v_mul_f32_e32 v79, 0x3f4c422a, v79
	v_mul_f32_e32 v78, -2.0, v78
	v_mul_f32_e32 v79, -2.0, v79
	v_mul_f32_e32 v78, 0x3fb8aa3b, v78
	v_mul_f32_e32 v79, 0x3fb8aa3b, v79
	v_exp_f32_e32 v78, v78
	v_exp_f32_e32 v79, v79
	v_add_f32_e32 v78, 1.0, v78
	v_add_f32_e32 v79, 1.0, v79
	v_rcp_f32_e32 v78, v78
	v_rcp_f32_e32 v79, v79
	s_nop 0
	v_pk_mul_f32 v[76:77], v[76:77], v[78:79]
	s_nop 0
	v_cvt_pk_f16_f32 v79, v76, v77
	v_lshrrev_b32_e32 v77, 4, v80
	v_and_b32_e32 v77, 0x10001, v77
	v_add3_u32 v77, v80, v77, s21
	v_lshrrev_b32_e32 v80, 4, v79
	v_and_b32_e32 v80, 0x10001, v80
	v_add3_u32 v79, v79, v80, s21
	v_add_u32_e32 v80, v140, v92
	v_ashrrev_i32_e32 v81, 31, v80
	v_lshrrev_b32_e32 v76, 4, v84
	v_lshrrev_b32_e32 v78, 4, v85
	v_lshlrev_b64 v[80:81], 10, v[80:81]
	v_and_b32_e32 v76, 0x10001, v76
	v_and_b32_e32 v78, 0x10001, v78
	v_lshl_add_u64 v[80:81], s[16:17], 0, v[80:81]
	v_add3_u32 v76, v84, v76, s21
	v_add3_u32 v78, v85, v78, s21
	v_lshl_add_u64 v[80:81], v[80:81], 0, s[42:43]
	v_lshl_add_u64 v[92:93], v[184:185], 0, s[10:11]
	s_mov_b64 s[10:11], 0x500000
	v_and_b32_e32 v76, 0xfff0fff0, v76
	v_and_b32_e32 v77, 0xfff0fff0, v77
	v_and_b32_e32 v78, 0xfff0fff0, v78
	v_and_b32_e32 v79, 0xfff0fff0, v79
	v_lshl_add_u64 v[80:81], v[80:81], 0, v[2:3]
	v_lshl_add_u64 v[84:85], v[184:185], 0, s[10:11]
	s_mov_b64 s[10:11], 0x580000
	global_store_dwordx4 v[80:81], v[76:79], off
	s_nop 1
	v_lshl_add_u64 v[76:77], v[184:185], 0, s[10:11]
	s_mov_b32 s10, 0x580000
	v_add_co_u32_e32 v78, vcc, s10, v184
	s_mov_b32 s10, 0x500000
	s_nop 0
	v_addc_co_u32_e32 v79, vcc, 0, v185, vcc
	global_load_dwordx4 v[80:83], v[78:79], off
	v_add_co_u32_e32 v78, vcc, s10, v184
	s_mov_b32 s10, 0x480000
	s_nop 0
	v_addc_co_u32_e32 v79, vcc, 0, v185, vcc
	global_load_dwordx4 v[88:91], v[78:79], off
	v_add_co_u32_e32 v78, vcc, s10, v184
	s_mov_b32 s10, 0x400000
	s_nop 0
	v_addc_co_u32_e32 v79, vcc, 0, v185, vcc
	global_load_dwordx4 v[96:99], v[78:79], off
	v_add_co_u32_e32 v78, vcc, s10, v184
	s_mov_b32 s10, s18
	s_nop 0
	v_addc_co_u32_e32 v79, vcc, 0, v185, vcc
	global_load_dwordx4 v[106:109], v[78:79], off
	s_nop 0
	global_load_dwordx4 v[76:79], v[76:77], off offset:256
	s_nop 0
	global_load_dwordx4 v[84:87], v[84:85], off offset:256
	s_nop 0
	global_load_dwordx4 v[92:95], v[92:93], off offset:256
	s_nop 0
	global_load_dwordx4 v[100:103], v[100:101], off offset:256
	s_waitcnt vmcnt(0)
	s_nop 0
	v_cvt_f32_f16_e32 v110, v106
	v_cvt_f32_f16_sdwa v111, v106 dst_sel:DWORD dst_unused:UNUSED_PAD src0_sel:WORD_1
	s_and_b64 vcc, exec, s[40:41]
	v_pk_mul_f32 v[110:111], v[32:33], v[110:111]
	s_nop 0
	v_pk_fma_f32 v[72:73], v[72:73], s[38:39], v[110:111] op_sel_hi:[1,0,1]
	s_nop 0
	v_mul_f32_e32 v105, 0x3d372713, v72
	v_mul_f32_e32 v105, v72, v105
	v_fma_f32 v105, v72, v105, v72
	v_mul_f32_e32 v105, 0x3f4c422a, v105
	v_mul_f32_e32 v105, -2.0, v105
	v_mul_f32_e32 v105, 0x3fb8aa3b, v105
	v_exp_f32_e32 v105, v105
	s_nop 0
	v_add_f32_e32 v105, 1.0, v105
	v_rcp_f32_e32 v110, v105
	v_mul_f32_e32 v105, 0x3d372713, v73
	v_mul_f32_e32 v105, v73, v105
	v_fma_f32 v105, v73, v105, v73
	v_mul_f32_e32 v105, 0x3f4c422a, v105
	v_mul_f32_e32 v105, -2.0, v105
	v_mul_f32_e32 v105, 0x3fb8aa3b, v105
	v_exp_f32_e32 v105, v105
	s_nop 0
	v_add_f32_e32 v105, 1.0, v105
	v_rcp_f32_e32 v111, v105
	s_nop 0
	v_pk_mul_f32 v[72:73], v[72:73], v[110:111]
	s_nop 0
	v_cvt_pk_f16_f32 v105, v72, v73
	v_cvt_f32_f16_e32 v72, v108
	v_cvt_f32_f16_sdwa v73, v108 dst_sel:DWORD dst_unused:UNUSED_PAD src0_sel:WORD_1
	v_pk_mul_f32 v[72:73], v[28:29], v[72:73]
	s_nop 0
	v_pk_fma_f32 v[68:69], v[68:69], s[38:39], v[72:73] op_sel_hi:[1,0,1]
	s_nop 0
	v_mul_f32_e32 v72, 0x3d372713, v68
	v_mul_f32_e32 v73, 0x3d372713, v69
	v_mul_f32_e32 v72, v68, v72
	v_mul_f32_e32 v73, v69, v73
	v_fma_f32 v72, v68, v72, v68
	v_fma_f32 v73, v69, v73, v69
	v_mul_f32_e32 v72, 0x3f4c422a, v72
	v_mul_f32_e32 v73, 0x3f4c422a, v73
	v_mul_f32_e32 v72, -2.0, v72
	v_mul_f32_e32 v73, -2.0, v73
	v_mul_f32_e32 v72, 0x3fb8aa3b, v72
	v_mul_f32_e32 v73, 0x3fb8aa3b, v73
	v_exp_f32_e32 v72, v72
	v_exp_f32_e32 v73, v73
	v_add_f32_e32 v72, 1.0, v72
	v_add_f32_e32 v73, 1.0, v73
	v_rcp_f32_e32 v72, v72
	v_rcp_f32_e32 v73, v73
	s_nop 0
	v_pk_mul_f32 v[68:69], v[68:69], v[72:73]
	s_nop 0
	v_cvt_pk_f16_f32 v106, v68, v69
	v_cvt_f32_f16_e32 v68, v107
	v_cvt_f32_f16_sdwa v69, v107 dst_sel:DWORD dst_unused:UNUSED_PAD src0_sel:WORD_1
	v_pk_mul_f32 v[68:69], v[34:35], v[68:69]
	s_nop 0
	v_pk_fma_f32 v[68:69], v[74:75], s[38:39], v[68:69] op_sel_hi:[1,0,1]
	s_nop 0
	v_mul_f32_e32 v72, 0x3d372713, v68
	v_mul_f32_e32 v73, 0x3d372713, v69
	v_mul_f32_e32 v72, v68, v72
	v_mul_f32_e32 v73, v69, v73
	v_fma_f32 v72, v68, v72, v68
	v_fma_f32 v73, v69, v73, v69
	v_mul_f32_e32 v72, 0x3f4c422a, v72
	v_mul_f32_e32 v73, 0x3f4c422a, v73
	v_mul_f32_e32 v72, -2.0, v72
	v_mul_f32_e32 v73, -2.0, v73
	v_mul_f32_e32 v72, 0x3fb8aa3b, v72
	v_mul_f32_e32 v73, 0x3fb8aa3b, v73
	v_exp_f32_e32 v72, v72
	v_exp_f32_e32 v73, v73
	v_add_f32_e32 v72, 1.0, v72
	v_add_f32_e32 v73, 1.0, v73
	v_rcp_f32_e32 v72, v72
	v_rcp_f32_e32 v73, v73
	s_nop 0
	v_pk_mul_f32 v[68:69], v[68:69], v[72:73]
	s_nop 0
	v_cvt_pk_f16_f32 v72, v68, v69
	v_cvt_f32_f16_e32 v68, v109
	v_cvt_f32_f16_sdwa v69, v109 dst_sel:DWORD dst_unused:UNUSED_PAD src0_sel:WORD_1
	v_pk_mul_f32 v[68:69], v[30:31], v[68:69]
	s_nop 0
	v_pk_fma_f32 v[68:69], v[70:71], s[38:39], v[68:69] op_sel_hi:[1,0,1]
	s_nop 0
	v_mul_f32_e32 v70, 0x3d372713, v68
	v_mul_f32_e32 v71, 0x3d372713, v69
	v_mul_f32_e32 v70, v68, v70
	v_mul_f32_e32 v71, v69, v71
	v_fma_f32 v70, v68, v70, v68
	v_fma_f32 v71, v69, v71, v69
	v_mul_f32_e32 v70, 0x3f4c422a, v70
	v_mul_f32_e32 v71, 0x3f4c422a, v71
	v_mul_f32_e32 v70, -2.0, v70
	v_mul_f32_e32 v71, -2.0, v71
	v_mul_f32_e32 v70, 0x3fb8aa3b, v70
	v_mul_f32_e32 v71, 0x3fb8aa3b, v71
	v_exp_f32_e32 v70, v70
	v_exp_f32_e32 v71, v71
	v_add_f32_e32 v70, 1.0, v70
	v_add_f32_e32 v71, 1.0, v71
	v_rcp_f32_e32 v70, v70
	v_rcp_f32_e32 v71, v71
	s_nop 0
	v_pk_mul_f32 v[68:69], v[68:69], v[70:71]
	s_nop 0
	v_cvt_pk_f16_f32 v71, v68, v69
	v_lshrrev_b32_e32 v69, 4, v72
	v_and_b32_e32 v69, 0x10001, v69
	v_add3_u32 v69, v72, v69, s21
	v_lshrrev_b32_e32 v72, 4, v71
	v_and_b32_e32 v72, 0x10001, v72
	v_add3_u32 v71, v71, v72, s21
	v_add_u32_e32 v72, v152, v104
	v_ashrrev_i32_e32 v73, 31, v72
	v_lshrrev_b32_e32 v68, 4, v105
	v_lshrrev_b32_e32 v70, 4, v106
	v_lshlrev_b64 v[72:73], 10, v[72:73]
	v_and_b32_e32 v68, 0x10001, v68
	v_and_b32_e32 v70, 0x10001, v70
	v_lshl_add_u64 v[72:73], s[16:17], 0, v[72:73]
	v_add3_u32 v68, v105, v68, s21
	v_add3_u32 v70, v106, v70, s21
	v_lshl_add_u64 v[72:73], v[72:73], 0, s[42:43]
	v_and_b32_e32 v68, 0xfff0fff0, v68
	v_and_b32_e32 v69, 0xfff0fff0, v69
	v_and_b32_e32 v70, 0xfff0fff0, v70
	v_and_b32_e32 v71, 0xfff0fff0, v71
	v_lshl_add_u64 v[72:73], v[72:73], 0, v[2:3]
	global_store_dwordx4 v[72:73], v[68:71], off
	s_nop 1
	v_cvt_f32_f16_e32 v68, v100
	v_cvt_f32_f16_sdwa v69, v100 dst_sel:DWORD dst_unused:UNUSED_PAD src0_sel:WORD_1
	v_pk_mul_f32 v[68:69], v[32:33], v[68:69]
	s_nop 0
	v_pk_fma_f32 v[64:65], v[64:65], s[38:39], v[68:69] op_sel_hi:[1,0,1]
	s_nop 0
	v_mul_f32_e32 v68, 0x3d372713, v64
	v_mul_f32_e32 v69, 0x3d372713, v65
	v_mul_f32_e32 v68, v64, v68
	v_mul_f32_e32 v69, v65, v69
	v_fma_f32 v68, v64, v68, v64
	v_fma_f32 v69, v65, v69, v65
	v_mul_f32_e32 v68, 0x3f4c422a, v68
	v_mul_f32_e32 v69, 0x3f4c422a, v69
	v_mul_f32_e32 v68, -2.0, v68
	v_mul_f32_e32 v69, -2.0, v69
	v_mul_f32_e32 v68, 0x3fb8aa3b, v68
	v_mul_f32_e32 v69, 0x3fb8aa3b, v69
	v_exp_f32_e32 v68, v68
	v_exp_f32_e32 v69, v69
	v_add_f32_e32 v68, 1.0, v68
	v_add_f32_e32 v69, 1.0, v69
	v_rcp_f32_e32 v68, v68
	v_rcp_f32_e32 v69, v69
	s_nop 0
	v_pk_mul_f32 v[64:65], v[64:65], v[68:69]
	s_nop 0
	v_cvt_pk_f16_f32 v68, v64, v65
	v_cvt_f32_f16_e32 v64, v102
	v_cvt_f32_f16_sdwa v65, v102 dst_sel:DWORD dst_unused:UNUSED_PAD src0_sel:WORD_1
	v_pk_mul_f32 v[64:65], v[28:29], v[64:65]
	s_nop 0
	v_pk_fma_f32 v[60:61], v[60:61], s[38:39], v[64:65] op_sel_hi:[1,0,1]
	s_nop 0
	v_mul_f32_e32 v64, 0x3d372713, v60
	v_mul_f32_e32 v65, 0x3d372713, v61
	v_mul_f32_e32 v64, v60, v64
	v_mul_f32_e32 v65, v61, v65
	v_fma_f32 v64, v60, v64, v60
	v_fma_f32 v65, v61, v65, v61
	v_mul_f32_e32 v64, 0x3f4c422a, v64
	v_mul_f32_e32 v65, 0x3f4c422a, v65
	v_mul_f32_e32 v64, -2.0, v64
	v_mul_f32_e32 v65, -2.0, v65
	v_mul_f32_e32 v64, 0x3fb8aa3b, v64
	v_mul_f32_e32 v65, 0x3fb8aa3b, v65
	v_exp_f32_e32 v64, v64
	v_exp_f32_e32 v65, v65
	v_add_f32_e32 v64, 1.0, v64
	v_add_f32_e32 v65, 1.0, v65
	v_rcp_f32_e32 v64, v64
	v_rcp_f32_e32 v65, v65
	s_nop 0
	v_pk_mul_f32 v[60:61], v[60:61], v[64:65]
	s_nop 0
	v_cvt_pk_f16_f32 v69, v60, v61
	v_cvt_f32_f16_e32 v60, v101
	v_cvt_f32_f16_sdwa v61, v101 dst_sel:DWORD dst_unused:UNUSED_PAD src0_sel:WORD_1
	v_pk_mul_f32 v[60:61], v[34:35], v[60:61]
	s_nop 0
	v_pk_fma_f32 v[60:61], v[66:67], s[38:39], v[60:61] op_sel_hi:[1,0,1]
	s_nop 0
	v_mul_f32_e32 v64, 0x3d372713, v60
	v_mul_f32_e32 v65, 0x3d372713, v61
	v_mul_f32_e32 v64, v60, v64
	v_mul_f32_e32 v65, v61, v65
	v_fma_f32 v64, v60, v64, v60
	v_fma_f32 v65, v61, v65, v61
	v_mul_f32_e32 v64, 0x3f4c422a, v64
	v_mul_f32_e32 v65, 0x3f4c422a, v65
	v_mul_f32_e32 v64, -2.0, v64
	v_mul_f32_e32 v65, -2.0, v65
	v_mul_f32_e32 v64, 0x3fb8aa3b, v64
	v_mul_f32_e32 v65, 0x3fb8aa3b, v65
	v_exp_f32_e32 v64, v64
	v_exp_f32_e32 v65, v65
	v_add_f32_e32 v64, 1.0, v64
	v_add_f32_e32 v65, 1.0, v65
	v_rcp_f32_e32 v64, v64
	v_rcp_f32_e32 v65, v65
	s_nop 0
	v_pk_mul_f32 v[60:61], v[60:61], v[64:65]
	s_nop 0
	v_cvt_pk_f16_f32 v64, v60, v61
	v_cvt_f32_f16_e32 v60, v103
	v_cvt_f32_f16_sdwa v61, v103 dst_sel:DWORD dst_unused:UNUSED_PAD src0_sel:WORD_1
	v_pk_mul_f32 v[60:61], v[30:31], v[60:61]
	s_nop 0
	v_pk_fma_f32 v[60:61], v[62:63], s[38:39], v[60:61] op_sel_hi:[1,0,1]
	s_nop 0
	v_mul_f32_e32 v62, 0x3d372713, v60
	v_mul_f32_e32 v63, 0x3d372713, v61
	v_mul_f32_e32 v62, v60, v62
	v_mul_f32_e32 v63, v61, v63
	v_fma_f32 v62, v60, v62, v60
	v_fma_f32 v63, v61, v63, v61
	v_mul_f32_e32 v62, 0x3f4c422a, v62
	v_mul_f32_e32 v63, 0x3f4c422a, v63
	v_mul_f32_e32 v62, -2.0, v62
	v_mul_f32_e32 v63, -2.0, v63
	v_mul_f32_e32 v62, 0x3fb8aa3b, v62
	v_mul_f32_e32 v63, 0x3fb8aa3b, v63
	v_exp_f32_e32 v62, v62
	v_exp_f32_e32 v63, v63
	v_add_f32_e32 v62, 1.0, v62
	v_add_f32_e32 v63, 1.0, v63
	v_rcp_f32_e32 v62, v62
	v_rcp_f32_e32 v63, v63
	s_nop 0
	v_pk_mul_f32 v[60:61], v[60:61], v[62:63]
	s_nop 0
	v_cvt_pk_f16_f32 v63, v60, v61
	v_lshrrev_b32_e32 v61, 4, v64
	v_and_b32_e32 v61, 0x10001, v61
	v_add3_u32 v61, v64, v61, s21
	v_lshrrev_b32_e32 v64, 4, v63
	v_and_b32_e32 v64, 0x10001, v64
	v_add3_u32 v63, v63, v64, s21
	v_add_u32_e32 v64, v140, v104
	v_ashrrev_i32_e32 v65, 31, v64
	v_lshrrev_b32_e32 v60, 4, v68
	v_lshrrev_b32_e32 v62, 4, v69
	v_lshlrev_b64 v[64:65], 10, v[64:65]
	v_and_b32_e32 v60, 0x10001, v60
	v_and_b32_e32 v62, 0x10001, v62
	v_lshl_add_u64 v[64:65], s[16:17], 0, v[64:65]
	v_add3_u32 v60, v68, v60, s21
	v_add3_u32 v62, v69, v62, s21
	v_lshl_add_u64 v[64:65], v[64:65], 0, s[42:43]
	v_and_b32_e32 v60, 0xfff0fff0, v60
	v_and_b32_e32 v61, 0xfff0fff0, v61
	v_and_b32_e32 v62, 0xfff0fff0, v62
	v_and_b32_e32 v63, 0xfff0fff0, v63
	v_lshl_add_u64 v[64:65], v[64:65], 0, v[2:3]
	global_store_dwordx4 v[64:65], v[60:63], off
	s_nop 1
	v_cvt_f32_f16_e32 v62, v96
	v_cvt_f32_f16_sdwa v63, v96 dst_sel:DWORD dst_unused:UNUSED_PAD src0_sel:WORD_1
	v_add_u32_e32 v60, 0x900, v192
	v_pk_mul_f32 v[62:63], v[32:33], v[62:63]
	s_nop 0
	v_pk_fma_f32 v[56:57], v[56:57], s[38:39], v[62:63] op_sel_hi:[1,0,1]
	s_nop 0
	v_mul_f32_e32 v61, 0x3d372713, v56
	v_mul_f32_e32 v61, v56, v61
	v_fma_f32 v61, v56, v61, v56
	v_mul_f32_e32 v61, 0x3f4c422a, v61
	v_mul_f32_e32 v61, -2.0, v61
	v_mul_f32_e32 v61, 0x3fb8aa3b, v61
	v_exp_f32_e32 v61, v61
	s_nop 0
	v_add_f32_e32 v61, 1.0, v61
	v_rcp_f32_e32 v62, v61
	v_mul_f32_e32 v61, 0x3d372713, v57
	v_mul_f32_e32 v61, v57, v61
	v_fma_f32 v61, v57, v61, v57
	v_mul_f32_e32 v61, 0x3f4c422a, v61
	v_mul_f32_e32 v61, -2.0, v61
	v_mul_f32_e32 v61, 0x3fb8aa3b, v61
	v_exp_f32_e32 v61, v61
	s_nop 0
	v_add_f32_e32 v61, 1.0, v61
	v_rcp_f32_e32 v63, v61
	s_nop 0
	v_pk_mul_f32 v[56:57], v[56:57], v[62:63]
	s_nop 0
	v_cvt_pk_f16_f32 v61, v56, v57
	v_cvt_f32_f16_e32 v56, v98
	v_cvt_f32_f16_sdwa v57, v98 dst_sel:DWORD dst_unused:UNUSED_PAD src0_sel:WORD_1
	v_pk_mul_f32 v[56:57], v[28:29], v[56:57]
	s_nop 0
	v_pk_fma_f32 v[52:53], v[52:53], s[38:39], v[56:57] op_sel_hi:[1,0,1]
	s_nop 0
	v_mul_f32_e32 v56, 0x3d372713, v52
	v_mul_f32_e32 v57, 0x3d372713, v53
	v_mul_f32_e32 v56, v52, v56
	v_mul_f32_e32 v57, v53, v57
	v_fma_f32 v56, v52, v56, v52
	v_fma_f32 v57, v53, v57, v53
	v_mul_f32_e32 v56, 0x3f4c422a, v56
	v_mul_f32_e32 v57, 0x3f4c422a, v57
	v_mul_f32_e32 v56, -2.0, v56
	v_mul_f32_e32 v57, -2.0, v57
	v_mul_f32_e32 v56, 0x3fb8aa3b, v56
	v_mul_f32_e32 v57, 0x3fb8aa3b, v57
	v_exp_f32_e32 v56, v56
	v_exp_f32_e32 v57, v57
	v_add_f32_e32 v56, 1.0, v56
	v_add_f32_e32 v57, 1.0, v57
	v_rcp_f32_e32 v56, v56
	v_rcp_f32_e32 v57, v57
	s_nop 0
	v_pk_mul_f32 v[52:53], v[52:53], v[56:57]
	s_nop 0
	v_cvt_pk_f16_f32 v62, v52, v53
	v_cvt_f32_f16_e32 v52, v97
	v_cvt_f32_f16_sdwa v53, v97 dst_sel:DWORD dst_unused:UNUSED_PAD src0_sel:WORD_1
	v_pk_mul_f32 v[52:53], v[34:35], v[52:53]
	s_nop 0
	v_pk_fma_f32 v[52:53], v[58:59], s[38:39], v[52:53] op_sel_hi:[1,0,1]
	s_nop 0
	v_mul_f32_e32 v56, 0x3d372713, v52
	v_mul_f32_e32 v57, 0x3d372713, v53
	v_mul_f32_e32 v56, v52, v56
	v_mul_f32_e32 v57, v53, v57
	v_fma_f32 v56, v52, v56, v52
	v_fma_f32 v57, v53, v57, v53
	v_mul_f32_e32 v56, 0x3f4c422a, v56
	v_mul_f32_e32 v57, 0x3f4c422a, v57
	v_mul_f32_e32 v56, -2.0, v56
	v_mul_f32_e32 v57, -2.0, v57
	v_mul_f32_e32 v56, 0x3fb8aa3b, v56
	v_mul_f32_e32 v57, 0x3fb8aa3b, v57
	v_exp_f32_e32 v56, v56
	v_exp_f32_e32 v57, v57
	v_add_f32_e32 v56, 1.0, v56
	v_add_f32_e32 v57, 1.0, v57
	v_rcp_f32_e32 v56, v56
	v_rcp_f32_e32 v57, v57
	s_nop 0
	v_pk_mul_f32 v[52:53], v[52:53], v[56:57]
	s_nop 0
	v_cvt_pk_f16_f32 v56, v52, v53
	v_cvt_f32_f16_e32 v52, v99
	v_cvt_f32_f16_sdwa v53, v99 dst_sel:DWORD dst_unused:UNUSED_PAD src0_sel:WORD_1
	v_pk_mul_f32 v[52:53], v[30:31], v[52:53]
	s_nop 0
	v_pk_fma_f32 v[52:53], v[54:55], s[38:39], v[52:53] op_sel_hi:[1,0,1]
	s_nop 0
	v_mul_f32_e32 v54, 0x3d372713, v52
	v_mul_f32_e32 v55, 0x3d372713, v53
	v_mul_f32_e32 v54, v52, v54
	v_mul_f32_e32 v55, v53, v55
	v_fma_f32 v54, v52, v54, v52
	v_fma_f32 v55, v53, v55, v53
	v_mul_f32_e32 v54, 0x3f4c422a, v54
	v_mul_f32_e32 v55, 0x3f4c422a, v55
	v_mul_f32_e32 v54, -2.0, v54
	v_mul_f32_e32 v55, -2.0, v55
	v_mul_f32_e32 v54, 0x3fb8aa3b, v54
	v_mul_f32_e32 v55, 0x3fb8aa3b, v55
	v_exp_f32_e32 v54, v54
	v_exp_f32_e32 v55, v55
	v_add_f32_e32 v54, 1.0, v54
	v_add_f32_e32 v55, 1.0, v55
	v_rcp_f32_e32 v54, v54
	v_rcp_f32_e32 v55, v55
	s_nop 0
	v_pk_mul_f32 v[52:53], v[52:53], v[54:55]
	s_nop 0
	v_cvt_pk_f16_f32 v55, v52, v53
	v_lshrrev_b32_e32 v53, 4, v56
	v_and_b32_e32 v53, 0x10001, v53
	v_add3_u32 v53, v56, v53, s21
	v_lshrrev_b32_e32 v56, 4, v55
	v_and_b32_e32 v56, 0x10001, v56
	v_add3_u32 v55, v55, v56, s21
	v_add_u32_e32 v56, v152, v60
	v_ashrrev_i32_e32 v57, 31, v56
	v_lshrrev_b32_e32 v52, 4, v61
	v_lshrrev_b32_e32 v54, 4, v62
	v_lshlrev_b64 v[56:57], 10, v[56:57]
	v_and_b32_e32 v52, 0x10001, v52
	v_and_b32_e32 v54, 0x10001, v54
	v_lshl_add_u64 v[56:57], s[16:17], 0, v[56:57]
	v_add3_u32 v52, v61, v52, s21
	v_add3_u32 v54, v62, v54, s21
	v_lshl_add_u64 v[56:57], v[56:57], 0, s[42:43]
	v_and_b32_e32 v52, 0xfff0fff0, v52
	v_and_b32_e32 v53, 0xfff0fff0, v53
	v_and_b32_e32 v54, 0xfff0fff0, v54
	v_and_b32_e32 v55, 0xfff0fff0, v55
	v_lshl_add_u64 v[56:57], v[56:57], 0, v[2:3]
	global_store_dwordx4 v[56:57], v[52:55], off
	s_nop 1
	v_cvt_f32_f16_e32 v52, v92
	v_cvt_f32_f16_sdwa v53, v92 dst_sel:DWORD dst_unused:UNUSED_PAD src0_sel:WORD_1
	v_pk_mul_f32 v[52:53], v[32:33], v[52:53]
	s_nop 0
	v_pk_fma_f32 v[48:49], v[48:49], s[38:39], v[52:53] op_sel_hi:[1,0,1]
	s_nop 0
	v_mul_f32_e32 v52, 0x3d372713, v48
	v_mul_f32_e32 v53, 0x3d372713, v49
	v_mul_f32_e32 v52, v48, v52
	v_mul_f32_e32 v53, v49, v53
	v_fma_f32 v52, v48, v52, v48
	v_fma_f32 v53, v49, v53, v49
	v_mul_f32_e32 v52, 0x3f4c422a, v52
	v_mul_f32_e32 v53, 0x3f4c422a, v53
	v_mul_f32_e32 v52, -2.0, v52
	v_mul_f32_e32 v53, -2.0, v53
	v_mul_f32_e32 v52, 0x3fb8aa3b, v52
	v_mul_f32_e32 v53, 0x3fb8aa3b, v53
	v_exp_f32_e32 v52, v52
	v_exp_f32_e32 v53, v53
	v_add_f32_e32 v52, 1.0, v52
	v_add_f32_e32 v53, 1.0, v53
	v_rcp_f32_e32 v52, v52
	v_rcp_f32_e32 v53, v53
	s_nop 0
	v_pk_mul_f32 v[48:49], v[48:49], v[52:53]
	s_nop 0
	v_cvt_pk_f16_f32 v52, v48, v49
	v_cvt_f32_f16_e32 v48, v94
	v_cvt_f32_f16_sdwa v49, v94 dst_sel:DWORD dst_unused:UNUSED_PAD src0_sel:WORD_1
	v_pk_mul_f32 v[48:49], v[28:29], v[48:49]
	s_nop 0
	v_pk_fma_f32 v[44:45], v[44:45], s[38:39], v[48:49] op_sel_hi:[1,0,1]
	s_nop 0
	v_mul_f32_e32 v48, 0x3d372713, v44
	v_mul_f32_e32 v49, 0x3d372713, v45
	v_mul_f32_e32 v48, v44, v48
	v_mul_f32_e32 v49, v45, v49
	v_fma_f32 v48, v44, v48, v44
	v_fma_f32 v49, v45, v49, v45
	v_mul_f32_e32 v48, 0x3f4c422a, v48
	v_mul_f32_e32 v49, 0x3f4c422a, v49
	v_mul_f32_e32 v48, -2.0, v48
	v_mul_f32_e32 v49, -2.0, v49
	v_mul_f32_e32 v48, 0x3fb8aa3b, v48
	v_mul_f32_e32 v49, 0x3fb8aa3b, v49
	v_exp_f32_e32 v48, v48
	v_exp_f32_e32 v49, v49
	v_add_f32_e32 v48, 1.0, v48
	v_add_f32_e32 v49, 1.0, v49
	v_rcp_f32_e32 v48, v48
	v_rcp_f32_e32 v49, v49
	s_nop 0
	v_pk_mul_f32 v[44:45], v[44:45], v[48:49]
	s_nop 0
	v_cvt_pk_f16_f32 v53, v44, v45
	v_cvt_f32_f16_e32 v44, v93
	v_cvt_f32_f16_sdwa v45, v93 dst_sel:DWORD dst_unused:UNUSED_PAD src0_sel:WORD_1
	v_pk_mul_f32 v[44:45], v[34:35], v[44:45]
	s_nop 0
	v_pk_fma_f32 v[44:45], v[50:51], s[38:39], v[44:45] op_sel_hi:[1,0,1]
	s_nop 0
	v_mul_f32_e32 v48, 0x3d372713, v44
	v_mul_f32_e32 v49, 0x3d372713, v45
	v_mul_f32_e32 v48, v44, v48
	v_mul_f32_e32 v49, v45, v49
	v_fma_f32 v48, v44, v48, v44
	v_fma_f32 v49, v45, v49, v45
	v_mul_f32_e32 v48, 0x3f4c422a, v48
	v_mul_f32_e32 v49, 0x3f4c422a, v49
	v_mul_f32_e32 v48, -2.0, v48
	v_mul_f32_e32 v49, -2.0, v49
	v_mul_f32_e32 v48, 0x3fb8aa3b, v48
	v_mul_f32_e32 v49, 0x3fb8aa3b, v49
	v_exp_f32_e32 v48, v48
	v_exp_f32_e32 v49, v49
	v_add_f32_e32 v48, 1.0, v48
	v_add_f32_e32 v49, 1.0, v49
	v_rcp_f32_e32 v48, v48
	v_rcp_f32_e32 v49, v49
	s_nop 0
	v_pk_mul_f32 v[44:45], v[44:45], v[48:49]
	s_nop 0
	v_cvt_pk_f16_f32 v48, v44, v45
	v_cvt_f32_f16_e32 v44, v95
	v_cvt_f32_f16_sdwa v45, v95 dst_sel:DWORD dst_unused:UNUSED_PAD src0_sel:WORD_1
	v_pk_mul_f32 v[44:45], v[30:31], v[44:45]
	s_nop 0
	v_pk_fma_f32 v[44:45], v[46:47], s[38:39], v[44:45] op_sel_hi:[1,0,1]
	s_nop 0
	v_mul_f32_e32 v46, 0x3d372713, v44
	v_mul_f32_e32 v47, 0x3d372713, v45
	v_mul_f32_e32 v46, v44, v46
	v_mul_f32_e32 v47, v45, v47
	v_fma_f32 v46, v44, v46, v44
	v_fma_f32 v47, v45, v47, v45
	v_mul_f32_e32 v46, 0x3f4c422a, v46
	v_mul_f32_e32 v47, 0x3f4c422a, v47
	v_mul_f32_e32 v46, -2.0, v46
	v_mul_f32_e32 v47, -2.0, v47
	v_mul_f32_e32 v46, 0x3fb8aa3b, v46
	v_mul_f32_e32 v47, 0x3fb8aa3b, v47
	v_exp_f32_e32 v46, v46
	v_exp_f32_e32 v47, v47
	v_add_f32_e32 v46, 1.0, v46
	v_add_f32_e32 v47, 1.0, v47
	v_rcp_f32_e32 v46, v46
	v_rcp_f32_e32 v47, v47
	s_nop 0
	v_pk_mul_f32 v[44:45], v[44:45], v[46:47]
	s_nop 0
	v_cvt_pk_f16_f32 v47, v44, v45
	v_lshrrev_b32_e32 v45, 4, v48
	v_and_b32_e32 v45, 0x10001, v45
	v_add3_u32 v45, v48, v45, s21
	v_lshrrev_b32_e32 v48, 4, v47
	v_and_b32_e32 v48, 0x10001, v48
	v_add3_u32 v47, v47, v48, s21
	v_add_u32_e32 v48, v140, v60
	v_ashrrev_i32_e32 v49, 31, v48
	v_lshrrev_b32_e32 v44, 4, v52
	v_lshrrev_b32_e32 v46, 4, v53
	v_lshlrev_b64 v[48:49], 10, v[48:49]
	v_and_b32_e32 v44, 0x10001, v44
	v_and_b32_e32 v46, 0x10001, v46
	v_lshl_add_u64 v[48:49], s[16:17], 0, v[48:49]
	v_add3_u32 v44, v52, v44, s21
	v_add3_u32 v46, v53, v46, s21
	v_lshl_add_u64 v[48:49], v[48:49], 0, s[42:43]
	v_and_b32_e32 v44, 0xfff0fff0, v44
	v_and_b32_e32 v45, 0xfff0fff0, v45
	v_and_b32_e32 v46, 0xfff0fff0, v46
	v_and_b32_e32 v47, 0xfff0fff0, v47
	v_lshl_add_u64 v[48:49], v[48:49], 0, v[2:3]
	global_store_dwordx4 v[48:49], v[44:47], off
	s_nop 1
	v_cvt_f32_f16_e32 v46, v88
	v_cvt_f32_f16_sdwa v47, v88 dst_sel:DWORD dst_unused:UNUSED_PAD src0_sel:WORD_1
	v_add_u32_e32 v44, 0xa00, v192
	v_pk_mul_f32 v[46:47], v[32:33], v[46:47]
	s_nop 0
	v_pk_fma_f32 v[40:41], v[40:41], s[38:39], v[46:47] op_sel_hi:[1,0,1]
	s_nop 0
	v_mul_f32_e32 v45, 0x3d372713, v40
	v_mul_f32_e32 v45, v40, v45
	v_fma_f32 v45, v40, v45, v40
	v_mul_f32_e32 v45, 0x3f4c422a, v45
	v_mul_f32_e32 v45, -2.0, v45
	v_mul_f32_e32 v45, 0x3fb8aa3b, v45
	v_exp_f32_e32 v45, v45
	s_nop 0
	v_add_f32_e32 v45, 1.0, v45
	v_rcp_f32_e32 v46, v45
	v_mul_f32_e32 v45, 0x3d372713, v41
	v_mul_f32_e32 v45, v41, v45
	v_fma_f32 v45, v41, v45, v41
	v_mul_f32_e32 v45, 0x3f4c422a, v45
	v_mul_f32_e32 v45, -2.0, v45
	v_mul_f32_e32 v45, 0x3fb8aa3b, v45
	v_exp_f32_e32 v45, v45
	s_nop 0
	v_add_f32_e32 v45, 1.0, v45
	v_rcp_f32_e32 v47, v45
	s_nop 0
	v_pk_mul_f32 v[40:41], v[40:41], v[46:47]
	s_nop 0
	v_cvt_pk_f16_f32 v45, v40, v41
	v_cvt_f32_f16_e32 v40, v90
	v_cvt_f32_f16_sdwa v41, v90 dst_sel:DWORD dst_unused:UNUSED_PAD src0_sel:WORD_1
	v_pk_mul_f32 v[40:41], v[28:29], v[40:41]
	s_nop 0
	v_pk_fma_f32 v[36:37], v[36:37], s[38:39], v[40:41] op_sel_hi:[1,0,1]
	s_nop 0
	v_mul_f32_e32 v40, 0x3d372713, v36
	v_mul_f32_e32 v41, 0x3d372713, v37
	v_mul_f32_e32 v40, v36, v40
	v_mul_f32_e32 v41, v37, v41
	v_fma_f32 v40, v36, v40, v36
	v_fma_f32 v41, v37, v41, v37
	v_mul_f32_e32 v40, 0x3f4c422a, v40
	v_mul_f32_e32 v41, 0x3f4c422a, v41
	v_mul_f32_e32 v40, -2.0, v40
	v_mul_f32_e32 v41, -2.0, v41
	v_mul_f32_e32 v40, 0x3fb8aa3b, v40
	v_mul_f32_e32 v41, 0x3fb8aa3b, v41
	v_exp_f32_e32 v40, v40
	v_exp_f32_e32 v41, v41
	v_add_f32_e32 v40, 1.0, v40
	v_add_f32_e32 v41, 1.0, v41
	v_rcp_f32_e32 v40, v40
	v_rcp_f32_e32 v41, v41
	s_nop 0
	v_pk_mul_f32 v[36:37], v[36:37], v[40:41]
	s_nop 0
	v_cvt_pk_f16_f32 v46, v36, v37
	v_cvt_f32_f16_e32 v36, v89
	v_cvt_f32_f16_sdwa v37, v89 dst_sel:DWORD dst_unused:UNUSED_PAD src0_sel:WORD_1
	v_pk_mul_f32 v[36:37], v[34:35], v[36:37]
	s_nop 0
	v_pk_fma_f32 v[36:37], v[42:43], s[38:39], v[36:37] op_sel_hi:[1,0,1]
	s_nop 0
	v_mul_f32_e32 v40, 0x3d372713, v36
	v_mul_f32_e32 v41, 0x3d372713, v37
	v_mul_f32_e32 v40, v36, v40
	v_mul_f32_e32 v41, v37, v41
	v_fma_f32 v40, v36, v40, v36
	v_fma_f32 v41, v37, v41, v37
	v_mul_f32_e32 v40, 0x3f4c422a, v40
	v_mul_f32_e32 v41, 0x3f4c422a, v41
	v_mul_f32_e32 v40, -2.0, v40
	v_mul_f32_e32 v41, -2.0, v41
	v_mul_f32_e32 v40, 0x3fb8aa3b, v40
	v_mul_f32_e32 v41, 0x3fb8aa3b, v41
	v_exp_f32_e32 v40, v40
	v_exp_f32_e32 v41, v41
	v_add_f32_e32 v40, 1.0, v40
	v_add_f32_e32 v41, 1.0, v41
	v_rcp_f32_e32 v40, v40
	v_rcp_f32_e32 v41, v41
	s_nop 0
	v_pk_mul_f32 v[36:37], v[36:37], v[40:41]
	s_nop 0
	v_cvt_pk_f16_f32 v40, v36, v37
	v_cvt_f32_f16_e32 v36, v91
	v_cvt_f32_f16_sdwa v37, v91 dst_sel:DWORD dst_unused:UNUSED_PAD src0_sel:WORD_1
	v_pk_mul_f32 v[36:37], v[30:31], v[36:37]
	s_nop 0
	v_pk_fma_f32 v[36:37], v[38:39], s[38:39], v[36:37] op_sel_hi:[1,0,1]
	s_nop 0
	v_mul_f32_e32 v38, 0x3d372713, v36
	v_mul_f32_e32 v39, 0x3d372713, v37
	v_mul_f32_e32 v38, v36, v38
	v_mul_f32_e32 v39, v37, v39
	v_fma_f32 v38, v36, v38, v36
	v_fma_f32 v39, v37, v39, v37
	v_mul_f32_e32 v38, 0x3f4c422a, v38
	v_mul_f32_e32 v39, 0x3f4c422a, v39
	v_mul_f32_e32 v38, -2.0, v38
	v_mul_f32_e32 v39, -2.0, v39
	v_mul_f32_e32 v38, 0x3fb8aa3b, v38
	v_mul_f32_e32 v39, 0x3fb8aa3b, v39
	v_exp_f32_e32 v38, v38
	v_exp_f32_e32 v39, v39
	v_add_f32_e32 v38, 1.0, v38
	v_add_f32_e32 v39, 1.0, v39
	v_rcp_f32_e32 v38, v38
	v_rcp_f32_e32 v39, v39
	s_nop 0
	v_pk_mul_f32 v[36:37], v[36:37], v[38:39]
	s_nop 0
	v_cvt_pk_f16_f32 v39, v36, v37
	v_lshrrev_b32_e32 v37, 4, v40
	v_and_b32_e32 v37, 0x10001, v37
	v_add3_u32 v37, v40, v37, s21
	v_lshrrev_b32_e32 v40, 4, v39
	v_and_b32_e32 v40, 0x10001, v40
	v_add3_u32 v39, v39, v40, s21
	v_add_u32_e32 v40, v152, v44
	v_ashrrev_i32_e32 v41, 31, v40
	v_lshrrev_b32_e32 v36, 4, v45
	v_lshrrev_b32_e32 v38, 4, v46
	v_lshlrev_b64 v[40:41], 10, v[40:41]
	v_and_b32_e32 v36, 0x10001, v36
	v_and_b32_e32 v38, 0x10001, v38
	v_lshl_add_u64 v[40:41], s[16:17], 0, v[40:41]
	v_add3_u32 v36, v45, v36, s21
	v_add3_u32 v38, v46, v38, s21
	v_lshl_add_u64 v[40:41], v[40:41], 0, s[42:43]
	v_and_b32_e32 v36, 0xfff0fff0, v36
	v_and_b32_e32 v37, 0xfff0fff0, v37
	v_and_b32_e32 v38, 0xfff0fff0, v38
	v_and_b32_e32 v39, 0xfff0fff0, v39
	v_lshl_add_u64 v[40:41], v[40:41], 0, v[2:3]
	global_store_dwordx4 v[40:41], v[36:39], off
	s_nop 1
	v_cvt_f32_f16_e32 v36, v84
	v_cvt_f32_f16_sdwa v37, v84 dst_sel:DWORD dst_unused:UNUSED_PAD src0_sel:WORD_1
	v_pk_mul_f32 v[36:37], v[32:33], v[36:37]
	s_nop 0
	v_pk_fma_f32 v[24:25], v[24:25], s[38:39], v[36:37] op_sel_hi:[1,0,1]
	s_nop 0
	v_mul_f32_e32 v36, 0x3d372713, v24
	v_mul_f32_e32 v37, 0x3d372713, v25
	v_mul_f32_e32 v36, v24, v36
	v_mul_f32_e32 v37, v25, v37
	v_fma_f32 v36, v24, v36, v24
	v_fma_f32 v37, v25, v37, v25
	v_mul_f32_e32 v36, 0x3f4c422a, v36
	v_mul_f32_e32 v37, 0x3f4c422a, v37
	v_mul_f32_e32 v36, -2.0, v36
	v_mul_f32_e32 v37, -2.0, v37
	v_mul_f32_e32 v36, 0x3fb8aa3b, v36
	v_mul_f32_e32 v37, 0x3fb8aa3b, v37
	v_exp_f32_e32 v36, v36
	v_exp_f32_e32 v37, v37
	v_add_f32_e32 v36, 1.0, v36
	v_add_f32_e32 v37, 1.0, v37
	v_rcp_f32_e32 v36, v36
	v_rcp_f32_e32 v37, v37
	s_nop 0
	v_pk_mul_f32 v[24:25], v[24:25], v[36:37]
	s_nop 0
	v_cvt_pk_f16_f32 v36, v24, v25
	v_cvt_f32_f16_e32 v24, v86
	v_cvt_f32_f16_sdwa v25, v86 dst_sel:DWORD dst_unused:UNUSED_PAD src0_sel:WORD_1
	v_pk_mul_f32 v[24:25], v[28:29], v[24:25]
	s_nop 0
	v_pk_fma_f32 v[20:21], v[20:21], s[38:39], v[24:25] op_sel_hi:[1,0,1]
	s_nop 0
	v_mul_f32_e32 v24, 0x3d372713, v20
	v_mul_f32_e32 v25, 0x3d372713, v21
	v_mul_f32_e32 v24, v20, v24
	v_mul_f32_e32 v25, v21, v25
	v_fma_f32 v24, v20, v24, v20
	v_fma_f32 v25, v21, v25, v21
	v_mul_f32_e32 v24, 0x3f4c422a, v24
	v_mul_f32_e32 v25, 0x3f4c422a, v25
	v_mul_f32_e32 v24, -2.0, v24
	v_mul_f32_e32 v25, -2.0, v25
	v_mul_f32_e32 v24, 0x3fb8aa3b, v24
	v_mul_f32_e32 v25, 0x3fb8aa3b, v25
	v_exp_f32_e32 v24, v24
	v_exp_f32_e32 v25, v25
	v_add_f32_e32 v24, 1.0, v24
	v_add_f32_e32 v25, 1.0, v25
	v_rcp_f32_e32 v24, v24
	v_rcp_f32_e32 v25, v25
	s_nop 0
	v_pk_mul_f32 v[20:21], v[20:21], v[24:25]
	s_nop 0
	v_cvt_pk_f16_f32 v37, v20, v21
	v_cvt_f32_f16_e32 v20, v85
	v_cvt_f32_f16_sdwa v21, v85 dst_sel:DWORD dst_unused:UNUSED_PAD src0_sel:WORD_1
	v_pk_mul_f32 v[20:21], v[34:35], v[20:21]
	s_nop 0
	v_pk_fma_f32 v[20:21], v[26:27], s[38:39], v[20:21] op_sel_hi:[1,0,1]
	s_nop 0
	v_mul_f32_e32 v24, 0x3d372713, v20
	v_mul_f32_e32 v25, 0x3d372713, v21
	v_mul_f32_e32 v24, v20, v24
	v_mul_f32_e32 v25, v21, v25
	v_fma_f32 v24, v20, v24, v20
	v_fma_f32 v25, v21, v25, v21
	v_mul_f32_e32 v24, 0x3f4c422a, v24
	v_mul_f32_e32 v25, 0x3f4c422a, v25
	v_mul_f32_e32 v24, -2.0, v24
	v_mul_f32_e32 v25, -2.0, v25
	v_mul_f32_e32 v24, 0x3fb8aa3b, v24
	v_mul_f32_e32 v25, 0x3fb8aa3b, v25
	v_exp_f32_e32 v24, v24
	v_exp_f32_e32 v25, v25
	v_add_f32_e32 v24, 1.0, v24
	v_add_f32_e32 v25, 1.0, v25
	v_rcp_f32_e32 v24, v24
	v_rcp_f32_e32 v25, v25
	s_nop 0
	v_pk_mul_f32 v[20:21], v[20:21], v[24:25]
	s_nop 0
	v_cvt_pk_f16_f32 v24, v20, v21
	v_cvt_f32_f16_e32 v20, v87
	v_cvt_f32_f16_sdwa v21, v87 dst_sel:DWORD dst_unused:UNUSED_PAD src0_sel:WORD_1
	v_pk_mul_f32 v[20:21], v[30:31], v[20:21]
	s_nop 0
	v_pk_fma_f32 v[20:21], v[22:23], s[38:39], v[20:21] op_sel_hi:[1,0,1]
	s_nop 0
	v_mul_f32_e32 v22, 0x3d372713, v20
	v_mul_f32_e32 v23, 0x3d372713, v21
	v_mul_f32_e32 v22, v20, v22
	v_mul_f32_e32 v23, v21, v23
	v_fma_f32 v22, v20, v22, v20
	v_fma_f32 v23, v21, v23, v21
	v_mul_f32_e32 v22, 0x3f4c422a, v22
	v_mul_f32_e32 v23, 0x3f4c422a, v23
	v_mul_f32_e32 v22, -2.0, v22
	v_mul_f32_e32 v23, -2.0, v23
	v_mul_f32_e32 v22, 0x3fb8aa3b, v22
	v_mul_f32_e32 v23, 0x3fb8aa3b, v23
	v_exp_f32_e32 v22, v22
	v_exp_f32_e32 v23, v23
	v_add_f32_e32 v22, 1.0, v22
	v_add_f32_e32 v23, 1.0, v23
	v_rcp_f32_e32 v22, v22
	v_rcp_f32_e32 v23, v23
	s_nop 0
	v_pk_mul_f32 v[20:21], v[20:21], v[22:23]
	s_nop 0
	v_cvt_pk_f16_f32 v23, v20, v21
	v_lshrrev_b32_e32 v21, 4, v24
	v_and_b32_e32 v21, 0x10001, v21
	v_add3_u32 v21, v24, v21, s21
	v_lshrrev_b32_e32 v24, 4, v23
	v_and_b32_e32 v24, 0x10001, v24
	v_add3_u32 v23, v23, v24, s21
	v_add_u32_e32 v24, v140, v44
	v_ashrrev_i32_e32 v25, 31, v24
	v_lshrrev_b32_e32 v20, 4, v36
	v_lshrrev_b32_e32 v22, 4, v37
	v_lshlrev_b64 v[24:25], 10, v[24:25]
	v_and_b32_e32 v20, 0x10001, v20
	v_and_b32_e32 v22, 0x10001, v22
	v_lshl_add_u64 v[24:25], s[16:17], 0, v[24:25]
	v_add3_u32 v20, v36, v20, s21
	v_add3_u32 v22, v37, v22, s21
	v_lshl_add_u64 v[24:25], v[24:25], 0, s[42:43]
	v_and_b32_e32 v20, 0xfff0fff0, v20
	v_and_b32_e32 v21, 0xfff0fff0, v21
	v_and_b32_e32 v22, 0xfff0fff0, v22
	v_and_b32_e32 v23, 0xfff0fff0, v23
	v_lshl_add_u64 v[24:25], v[24:25], 0, v[2:3]
	global_store_dwordx4 v[24:25], v[20:23], off
	s_nop 1
	v_cvt_f32_f16_e32 v22, v80
	v_cvt_f32_f16_sdwa v23, v80 dst_sel:DWORD dst_unused:UNUSED_PAD src0_sel:WORD_1
	v_add_u32_e32 v20, 0xb00, v192
	v_pk_mul_f32 v[22:23], v[32:33], v[22:23]
	s_nop 0
	v_pk_fma_f32 v[16:17], v[16:17], s[38:39], v[22:23] op_sel_hi:[1,0,1]
	s_nop 0
	v_mul_f32_e32 v21, 0x3d372713, v16
	v_mul_f32_e32 v21, v16, v21
	v_fma_f32 v21, v16, v21, v16
	v_mul_f32_e32 v21, 0x3f4c422a, v21
	v_mul_f32_e32 v21, -2.0, v21
	v_mul_f32_e32 v21, 0x3fb8aa3b, v21
	v_exp_f32_e32 v21, v21
	s_nop 0
	v_add_f32_e32 v21, 1.0, v21
	v_rcp_f32_e32 v22, v21
	v_mul_f32_e32 v21, 0x3d372713, v17
	v_mul_f32_e32 v21, v17, v21
	v_fma_f32 v21, v17, v21, v17
	v_mul_f32_e32 v21, 0x3f4c422a, v21
	v_mul_f32_e32 v21, -2.0, v21
	v_mul_f32_e32 v21, 0x3fb8aa3b, v21
	v_exp_f32_e32 v21, v21
	s_nop 0
	v_add_f32_e32 v21, 1.0, v21
	v_rcp_f32_e32 v23, v21
	s_nop 0
	v_pk_mul_f32 v[16:17], v[16:17], v[22:23]
	s_nop 0
	v_cvt_pk_f16_f32 v21, v16, v17
	v_cvt_f32_f16_e32 v16, v82
	v_cvt_f32_f16_sdwa v17, v82 dst_sel:DWORD dst_unused:UNUSED_PAD src0_sel:WORD_1
	v_pk_mul_f32 v[16:17], v[28:29], v[16:17]
	s_nop 0
	v_pk_fma_f32 v[12:13], v[12:13], s[38:39], v[16:17] op_sel_hi:[1,0,1]
	s_nop 0
	v_mul_f32_e32 v16, 0x3d372713, v12
	v_mul_f32_e32 v17, 0x3d372713, v13
	v_mul_f32_e32 v16, v12, v16
	v_mul_f32_e32 v17, v13, v17
	v_fma_f32 v16, v12, v16, v12
	v_fma_f32 v17, v13, v17, v13
	v_mul_f32_e32 v16, 0x3f4c422a, v16
	v_mul_f32_e32 v17, 0x3f4c422a, v17
	v_mul_f32_e32 v16, -2.0, v16
	v_mul_f32_e32 v17, -2.0, v17
	v_mul_f32_e32 v16, 0x3fb8aa3b, v16
	v_mul_f32_e32 v17, 0x3fb8aa3b, v17
	v_exp_f32_e32 v16, v16
	v_exp_f32_e32 v17, v17
	v_add_f32_e32 v16, 1.0, v16
	v_add_f32_e32 v17, 1.0, v17
	v_rcp_f32_e32 v16, v16
	v_rcp_f32_e32 v17, v17
	s_nop 0
	v_pk_mul_f32 v[12:13], v[12:13], v[16:17]
	s_nop 0
	v_cvt_pk_f16_f32 v22, v12, v13
	v_cvt_f32_f16_e32 v12, v81
	v_cvt_f32_f16_sdwa v13, v81 dst_sel:DWORD dst_unused:UNUSED_PAD src0_sel:WORD_1
	v_pk_mul_f32 v[12:13], v[34:35], v[12:13]
	s_nop 0
	v_pk_fma_f32 v[12:13], v[18:19], s[38:39], v[12:13] op_sel_hi:[1,0,1]
	s_nop 0
	v_mul_f32_e32 v16, 0x3d372713, v12
	v_mul_f32_e32 v17, 0x3d372713, v13
	v_mul_f32_e32 v16, v12, v16
	v_mul_f32_e32 v17, v13, v17
	v_fma_f32 v16, v12, v16, v12
	v_fma_f32 v17, v13, v17, v13
	v_mul_f32_e32 v16, 0x3f4c422a, v16
	v_mul_f32_e32 v17, 0x3f4c422a, v17
	v_mul_f32_e32 v16, -2.0, v16
	v_mul_f32_e32 v17, -2.0, v17
	v_mul_f32_e32 v16, 0x3fb8aa3b, v16
	v_mul_f32_e32 v17, 0x3fb8aa3b, v17
	v_exp_f32_e32 v16, v16
	v_exp_f32_e32 v17, v17
	v_add_f32_e32 v16, 1.0, v16
	v_add_f32_e32 v17, 1.0, v17
	v_rcp_f32_e32 v16, v16
	v_rcp_f32_e32 v17, v17
	s_nop 0
	v_pk_mul_f32 v[12:13], v[12:13], v[16:17]
	s_nop 0
	v_cvt_pk_f16_f32 v16, v12, v13
	v_cvt_f32_f16_e32 v12, v83
	v_cvt_f32_f16_sdwa v13, v83 dst_sel:DWORD dst_unused:UNUSED_PAD src0_sel:WORD_1
	v_pk_mul_f32 v[12:13], v[30:31], v[12:13]
	s_nop 0
	v_pk_fma_f32 v[12:13], v[14:15], s[38:39], v[12:13] op_sel_hi:[1,0,1]
	s_nop 0
	v_mul_f32_e32 v14, 0x3d372713, v12
	v_mul_f32_e32 v15, 0x3d372713, v13
	v_mul_f32_e32 v14, v12, v14
	v_mul_f32_e32 v15, v13, v15
	v_fma_f32 v14, v12, v14, v12
	v_fma_f32 v15, v13, v15, v13
	v_mul_f32_e32 v14, 0x3f4c422a, v14
	v_mul_f32_e32 v15, 0x3f4c422a, v15
	v_mul_f32_e32 v14, -2.0, v14
	v_mul_f32_e32 v15, -2.0, v15
	v_mul_f32_e32 v14, 0x3fb8aa3b, v14
	v_mul_f32_e32 v15, 0x3fb8aa3b, v15
	v_exp_f32_e32 v14, v14
	v_exp_f32_e32 v15, v15
	v_add_f32_e32 v14, 1.0, v14
	v_add_f32_e32 v15, 1.0, v15
	v_rcp_f32_e32 v14, v14
	v_rcp_f32_e32 v15, v15
	s_nop 0
	v_pk_mul_f32 v[12:13], v[12:13], v[14:15]
	s_nop 0
	v_cvt_pk_f16_f32 v15, v12, v13
	v_lshrrev_b32_e32 v13, 4, v16
	v_and_b32_e32 v13, 0x10001, v13
	v_add3_u32 v13, v16, v13, s21
	v_lshrrev_b32_e32 v16, 4, v15
	v_and_b32_e32 v16, 0x10001, v16
	v_add3_u32 v15, v15, v16, s21
	v_add_u32_e32 v16, v152, v20
	v_ashrrev_i32_e32 v17, 31, v16
	v_lshrrev_b32_e32 v12, 4, v21
	v_lshrrev_b32_e32 v14, 4, v22
	v_lshlrev_b64 v[16:17], 10, v[16:17]
	v_and_b32_e32 v12, 0x10001, v12
	v_and_b32_e32 v14, 0x10001, v14
	v_lshl_add_u64 v[16:17], s[16:17], 0, v[16:17]
	v_add3_u32 v12, v21, v12, s21
	v_add3_u32 v14, v22, v14, s21
	v_lshl_add_u64 v[16:17], v[16:17], 0, s[42:43]
	v_and_b32_e32 v12, 0xfff0fff0, v12
	v_and_b32_e32 v13, 0xfff0fff0, v13
	v_and_b32_e32 v14, 0xfff0fff0, v14
	v_and_b32_e32 v15, 0xfff0fff0, v15
	v_lshl_add_u64 v[16:17], v[16:17], 0, v[2:3]
	global_store_dwordx4 v[16:17], v[12:15], off
	s_nop 1
	v_cvt_f32_f16_e32 v12, v76
	v_cvt_f32_f16_sdwa v13, v76 dst_sel:DWORD dst_unused:UNUSED_PAD src0_sel:WORD_1
	v_pk_mul_f32 v[12:13], v[32:33], v[12:13]
	s_nop 0
	v_pk_fma_f32 v[8:9], v[8:9], s[38:39], v[12:13] op_sel_hi:[1,0,1]
	s_nop 0
	v_mul_f32_e32 v12, 0x3d372713, v8
	v_mul_f32_e32 v13, 0x3d372713, v9
	v_mul_f32_e32 v12, v8, v12
	v_mul_f32_e32 v13, v9, v13
	v_fma_f32 v12, v8, v12, v8
	v_fma_f32 v13, v9, v13, v9
	v_mul_f32_e32 v12, 0x3f4c422a, v12
	v_mul_f32_e32 v13, 0x3f4c422a, v13
	v_mul_f32_e32 v12, -2.0, v12
	v_mul_f32_e32 v13, -2.0, v13
	v_mul_f32_e32 v12, 0x3fb8aa3b, v12
	v_mul_f32_e32 v13, 0x3fb8aa3b, v13
	v_exp_f32_e32 v12, v12
	v_exp_f32_e32 v13, v13
	v_add_f32_e32 v12, 1.0, v12
	v_add_f32_e32 v13, 1.0, v13
	v_rcp_f32_e32 v12, v12
	v_rcp_f32_e32 v13, v13
	s_nop 0
	v_pk_mul_f32 v[8:9], v[8:9], v[12:13]
	s_nop 0
	v_cvt_pk_f16_f32 v12, v8, v9
	v_cvt_f32_f16_e32 v8, v78
	v_cvt_f32_f16_sdwa v9, v78 dst_sel:DWORD dst_unused:UNUSED_PAD src0_sel:WORD_1
	v_pk_mul_f32 v[8:9], v[28:29], v[8:9]
	s_nop 0
	v_pk_fma_f32 v[4:5], v[4:5], s[38:39], v[8:9] op_sel_hi:[1,0,1]
	s_nop 0
	v_mul_f32_e32 v8, 0x3d372713, v4
	v_mul_f32_e32 v9, 0x3d372713, v5
	v_mul_f32_e32 v8, v4, v8
	v_mul_f32_e32 v9, v5, v9
	v_fma_f32 v8, v4, v8, v4
	v_fma_f32 v9, v5, v9, v5
	v_mul_f32_e32 v8, 0x3f4c422a, v8
	v_mul_f32_e32 v9, 0x3f4c422a, v9
	v_mul_f32_e32 v8, -2.0, v8
	v_mul_f32_e32 v9, -2.0, v9
	v_mul_f32_e32 v8, 0x3fb8aa3b, v8
	v_mul_f32_e32 v9, 0x3fb8aa3b, v9
	v_exp_f32_e32 v8, v8
	v_exp_f32_e32 v9, v9
	v_add_f32_e32 v8, 1.0, v8
	v_add_f32_e32 v9, 1.0, v9
	v_rcp_f32_e32 v8, v8
	v_rcp_f32_e32 v9, v9
	s_nop 0
	v_pk_mul_f32 v[4:5], v[4:5], v[8:9]
	s_nop 0
	v_cvt_pk_f16_f32 v13, v4, v5
	v_cvt_f32_f16_e32 v4, v77
	v_cvt_f32_f16_sdwa v5, v77 dst_sel:DWORD dst_unused:UNUSED_PAD src0_sel:WORD_1
	v_pk_mul_f32 v[4:5], v[34:35], v[4:5]
	s_nop 0
	v_pk_fma_f32 v[4:5], v[10:11], s[38:39], v[4:5] op_sel_hi:[1,0,1]
	s_nop 0
	v_mul_f32_e32 v8, 0x3d372713, v4
	v_mul_f32_e32 v9, 0x3d372713, v5
	v_mul_f32_e32 v8, v4, v8
	v_mul_f32_e32 v9, v5, v9
	v_fma_f32 v8, v4, v8, v4
	v_fma_f32 v9, v5, v9, v5
	v_mul_f32_e32 v8, 0x3f4c422a, v8
	v_mul_f32_e32 v9, 0x3f4c422a, v9
	v_mul_f32_e32 v8, -2.0, v8
	v_mul_f32_e32 v9, -2.0, v9
	v_mul_f32_e32 v8, 0x3fb8aa3b, v8
	v_mul_f32_e32 v9, 0x3fb8aa3b, v9
	v_exp_f32_e32 v8, v8
	v_exp_f32_e32 v9, v9
	v_add_f32_e32 v8, 1.0, v8
	v_add_f32_e32 v9, 1.0, v9
	v_rcp_f32_e32 v8, v8
	v_rcp_f32_e32 v9, v9
	s_nop 0
	v_pk_mul_f32 v[4:5], v[4:5], v[8:9]
	s_nop 0
	v_cvt_pk_f16_f32 v8, v4, v5
	v_cvt_f32_f16_e32 v4, v79
	v_cvt_f32_f16_sdwa v5, v79 dst_sel:DWORD dst_unused:UNUSED_PAD src0_sel:WORD_1
	v_pk_mul_f32 v[4:5], v[30:31], v[4:5]
	s_nop 0
	v_pk_fma_f32 v[4:5], v[6:7], s[38:39], v[4:5] op_sel_hi:[1,0,1]
	s_mov_b64 s[38:39], s[36:37]
	v_mul_f32_e32 v6, 0x3d372713, v4
	v_mul_f32_e32 v7, 0x3d372713, v5
	v_mul_f32_e32 v6, v4, v6
	v_mul_f32_e32 v7, v5, v7
	v_fma_f32 v6, v4, v6, v4
	v_fma_f32 v7, v5, v7, v5
	v_mul_f32_e32 v6, 0x3f4c422a, v6
	v_mul_f32_e32 v7, 0x3f4c422a, v7
	v_mul_f32_e32 v6, -2.0, v6
	v_mul_f32_e32 v7, -2.0, v7
	v_mul_f32_e32 v6, 0x3fb8aa3b, v6
	v_mul_f32_e32 v7, 0x3fb8aa3b, v7
	v_exp_f32_e32 v6, v6
	v_exp_f32_e32 v7, v7
	v_add_f32_e32 v6, 1.0, v6
	v_add_f32_e32 v7, 1.0, v7
	v_rcp_f32_e32 v6, v6
	v_rcp_f32_e32 v7, v7
	s_nop 0
	v_pk_mul_f32 v[4:5], v[4:5], v[6:7]
	s_nop 0
	v_cvt_pk_f16_f32 v7, v4, v5
	v_lshrrev_b32_e32 v5, 4, v8
	v_and_b32_e32 v5, 0x10001, v5
	v_add3_u32 v5, v8, v5, s21
	v_lshrrev_b32_e32 v8, 4, v7
	v_and_b32_e32 v8, 0x10001, v8
	v_add3_u32 v7, v7, v8, s21
	v_add_u32_e32 v8, v140, v20
	v_ashrrev_i32_e32 v9, 31, v8
	v_lshrrev_b32_e32 v4, 4, v12
	v_lshrrev_b32_e32 v6, 4, v13
	v_lshlrev_b64 v[8:9], 10, v[8:9]
	v_and_b32_e32 v4, 0x10001, v4
	v_and_b32_e32 v6, 0x10001, v6
	v_lshl_add_u64 v[8:9], s[16:17], 0, v[8:9]
	v_add3_u32 v4, v12, v4, s21
	v_add3_u32 v6, v13, v6, s21
	v_lshl_add_u64 v[8:9], v[8:9], 0, s[42:43]
	v_and_b32_e32 v4, 0xfff0fff0, v4
	v_and_b32_e32 v5, 0xfff0fff0, v5
	v_and_b32_e32 v6, 0xfff0fff0, v6
	v_and_b32_e32 v7, 0xfff0fff0, v7
	v_lshl_add_u64 v[8:9], v[8:9], 0, v[2:3]
	global_store_dwordx4 v[8:9], v[4:7], off
	s_mov_b32 s16, s47
	s_cbranch_vccz .LBB0_1338
	s_waitcnt vmcnt(0)
	s_cmpk_gt_u32 s5, 0xff
	s_cbranch_scc1 .LBB0_1345
	s_barrier

.LBB0_1664:
	s_add_u32 s15, s46, 0xfffe0080
	s_addc_u32 s29, s47, -1
	s_add_i32 s30, 0, 0x10000
	v_add_u32_e32 v56, s30, v208
	ds_read_b128 v[32:35], v56
	ds_read_b128 v[40:43], v56 offset:1024
	ds_read_b128 v[48:51], v56 offset:2048
	ds_read_b128 v[56:59], v56 offset:3072
	s_cmp_eq_u32 s14, 4
	s_cselect_b32 s49, s43, s29
	s_cselect_b32 s48, s42, s15
	s_cselect_b32 s39, s45, s11
	s_cselect_b32 s38, s44, s10
	v_lshl_add_u64 v[190:191], s[46:47], 0, v[186:187]
	s_add_i32 m0, s8, 0xc000
	ds_read_b128 v[108:111], v209
	ds_read_b128 v[120:123], v209 offset:1024
	ds_read_b128 v[132:135], v209 offset:2048
	ds_read_b128 v[144:147], v209 offset:3072
	ds_read_b128 v[156:159], v209 offset:4096
	ds_read_b128 v[168:171], v209 offset:5120
	ds_read_b128 v[172:175], v209 offset:6144
	ds_read_b128 v[176:179], v209 offset:7168
	global_load_lds_dwordx4 v[190:191], off
	v_lshl_add_u64 v[190:191], s[46:47], 0, v[188:189]
	s_add_i32 m0, s8, 0xe000
	s_nop 0
	global_load_lds_dwordx4 v[190:191], off
	s_waitcnt lgkmcnt(8)
	s_barrier
	s_waitcnt lgkmcnt(0)
	s_waitcnt lgkmcnt(0)
	v_mfma_f32_16x16x32_f16 v[164:167], v[32:35], v[108:111], v[164:167]
	v_mfma_f32_16x16x32_f16 v[160:163], v[48:51], v[108:111], v[160:163]
	v_mfma_f32_16x16x32_f16 v[140:143], v[32:35], v[132:135], v[140:143]
	v_mfma_f32_16x16x32_f16 v[136:139], v[48:51], v[132:135], v[136:139]
	v_mfma_f32_16x16x32_f16 v[116:119], v[32:35], v[156:159], v[116:119]
	v_mfma_f32_16x16x32_f16 v[112:115], v[48:51], v[156:159], v[112:115]
	v_mfma_f32_16x16x32_f16 v[96:99], v[32:35], v[172:175], v[96:99]
	v_mfma_f32_16x16x32_f16 v[92:95], v[48:51], v[172:175], v[92:95]
	v_mfma_f32_16x16x32_f16 v[164:167], v[40:43], v[120:123], v[164:167]
	v_mfma_f32_16x16x32_f16 v[160:163], v[56:59], v[120:123], v[160:163]
	v_mfma_f32_16x16x32_f16 v[140:143], v[40:43], v[144:147], v[140:143]
	v_mfma_f32_16x16x32_f16 v[136:139], v[56:59], v[144:147], v[136:139]
	v_mfma_f32_16x16x32_f16 v[116:119], v[40:43], v[168:171], v[116:119]
	v_mfma_f32_16x16x32_f16 v[112:115], v[56:59], v[168:171], v[112:115]
	v_mfma_f32_16x16x32_f16 v[96:99], v[40:43], v[176:179], v[96:99]
	v_mfma_f32_16x16x32_f16 v[92:95], v[56:59], v[176:179], v[92:95]
	s_barrier
	s_add_i32 s15, 0, 0x14000
	v_add_u32_e32 v202, s15, v208
	s_add_i32 s29, s30, s7
	ds_read_b128 v[190:193], v202
	ds_read_b128 v[194:197], v202 offset:1024
	ds_read_b128 v[198:201], v202 offset:2048
	ds_read_b128 v[210:213], v202 offset:3072
	v_lshl_add_u64 v[202:203], s[38:39], 0, v[2:3]
	s_mov_b32 m0, s29
	v_lshl_add_u64 v[218:219], s[38:39], 0, v[184:185]
	global_load_lds_dwordx4 v[202:203], off
	s_add_i32 m0, s29, 0x2000
	s_nop 0
	global_load_lds_dwordx4 v[218:219], off
	s_barrier
	s_waitcnt lgkmcnt(0)
	s_waitcnt lgkmcnt(0)
	v_mfma_f32_16x16x32_f16 v[152:155], v[190:193], v[108:111], v[152:155]
	v_mfma_f32_16x16x32_f16 v[108:111], v[198:201], v[108:111], v[148:151]
	v_mfma_f32_16x16x32_f16 v[124:127], v[198:201], v[132:135], v[124:127]
	v_mfma_f32_16x16x32_f16 v[104:107], v[190:193], v[156:159], v[104:107]
	v_mfma_f32_16x16x32_f16 v[100:103], v[198:201], v[156:159], v[100:103]
	v_mfma_f32_16x16x32_f16 v[88:91], v[190:193], v[172:175], v[88:91]
	v_mfma_f32_16x16x32_f16 v[84:87], v[198:201], v[172:175], v[84:87]
	v_mfma_f32_16x16x32_f16 v[152:155], v[194:197], v[120:123], v[152:155]
	v_mfma_f32_16x16x32_f16 v[108:111], v[210:213], v[120:123], v[108:111]
	v_mfma_f32_16x16x32_f16 v[120:123], v[190:193], v[132:135], v[128:131]
	v_mfma_f32_16x16x32_f16 v[124:127], v[210:213], v[144:147], v[124:127]
	v_mfma_f32_16x16x32_f16 v[104:107], v[194:197], v[168:171], v[104:107]
	v_mfma_f32_16x16x32_f16 v[100:103], v[210:213], v[168:171], v[100:103]
	v_mfma_f32_16x16x32_f16 v[88:91], v[194:197], v[176:179], v[88:91]
	v_mfma_f32_16x16x32_f16 v[84:87], v[210:213], v[176:179], v[84:87]
	v_mfma_f32_16x16x32_f16 v[120:123], v[194:197], v[144:147], v[120:123]
	s_mov_b32 m0, s8
	v_lshl_add_u64 v[220:221], s[48:49], 0, v[180:181]
	s_barrier
	ds_read_b128 v[128:131], v209 offset:16384
	ds_read_b128 v[132:135], v209 offset:17408
	ds_read_b128 v[144:147], v209 offset:18432
	ds_read_b128 v[148:151], v209 offset:19456
	ds_read_b128 v[156:159], v209 offset:20480
	ds_read_b128 v[168:171], v209 offset:21504
	ds_read_b128 v[172:175], v209 offset:22528
	ds_read_b128 v[176:179], v209 offset:23552
	global_load_lds_dwordx4 v[220:221], off
	v_lshl_add_u64 v[232:233], s[48:49], 0, v[182:183]
	s_mov_b32 m0, s9
	s_nop 0
	global_load_lds_dwordx4 v[232:233], off
	s_barrier
	s_waitcnt lgkmcnt(0)
	s_waitcnt lgkmcnt(0)
	v_mfma_f32_16x16x32_f16 v[80:83], v[32:35], v[128:131], v[80:83]
	v_mfma_f32_16x16x32_f16 v[76:79], v[48:51], v[128:131], v[76:79]
	v_mfma_f32_16x16x32_f16 v[64:67], v[32:35], v[144:147], v[64:67]
	v_mfma_f32_16x16x32_f16 v[60:63], v[48:51], v[144:147], v[60:63]
	v_mfma_f32_16x16x32_f16 v[36:39], v[32:35], v[156:159], v[36:39]
	v_mfma_f32_16x16x32_f16 v[28:31], v[48:51], v[156:159], v[28:31]
	v_mfma_f32_16x16x32_f16 v[16:19], v[32:35], v[172:175], v[16:19]
	v_mfma_f32_16x16x32_f16 v[12:15], v[48:51], v[172:175], v[12:15]
	v_mfma_f32_16x16x32_f16 v[80:83], v[40:43], v[132:135], v[80:83]
	v_mfma_f32_16x16x32_f16 v[76:79], v[56:59], v[132:135], v[76:79]
	v_mfma_f32_16x16x32_f16 v[64:67], v[40:43], v[148:151], v[64:67]
	v_mfma_f32_16x16x32_f16 v[60:63], v[56:59], v[148:151], v[60:63]
	v_mfma_f32_16x16x32_f16 v[36:39], v[40:43], v[168:171], v[36:39]
	v_mfma_f32_16x16x32_f16 v[28:31], v[56:59], v[168:171], v[28:31]
	v_mfma_f32_16x16x32_f16 v[16:19], v[40:43], v[176:179], v[16:19]
	v_mfma_f32_16x16x32_f16 v[12:15], v[56:59], v[176:179], v[12:15]
	s_barrier
	s_add_u32 s30, s38, 0x20000
	s_addc_u32 s31, s39, 0
	s_add_i32 s15, s15, s7
	v_lshl_add_u64 v[32:33], s[30:31], 0, v[2:3]
	s_mov_b32 m0, s15
	s_nop 0
	global_load_lds_dwordx4 v[32:33], off
	v_lshl_add_u64 v[32:33], s[30:31], 0, v[184:185]
	s_add_i32 m0, s15, 0x2000
	s_nop 0
	global_load_lds_dwordx4 v[32:33], off
	s_waitcnt vmcnt(6)
	s_barrier
	v_mfma_f32_16x16x32_f16 v[44:47], v[198:201], v[144:147], v[44:47]
	v_mfma_f32_16x16x32_f16 v[24:27], v[190:193], v[156:159], v[24:27]
	v_mfma_f32_16x16x32_f16 v[20:23], v[198:201], v[156:159], v[20:23]
	v_mfma_f32_16x16x32_f16 v[8:11], v[190:193], v[172:175], v[8:11]
	v_mfma_f32_16x16x32_f16 v[4:7], v[198:201], v[172:175], v[4:7]
	v_mfma_f32_16x16x32_f16 v[32:35], v[190:193], v[128:131], v[72:75]
	v_mfma_f32_16x16x32_f16 v[40:43], v[198:201], v[128:131], v[68:71]
	v_mfma_f32_16x16x32_f16 v[48:51], v[190:193], v[144:147], v[52:55]
	v_mfma_f32_16x16x32_f16 v[44:47], v[210:213], v[148:151], v[44:47]
	v_mfma_f32_16x16x32_f16 v[24:27], v[194:197], v[168:171], v[24:27]
	v_mfma_f32_16x16x32_f16 v[20:23], v[210:213], v[168:171], v[20:23]
	v_mfma_f32_16x16x32_f16 v[8:11], v[194:197], v[176:179], v[8:11]
	v_mfma_f32_16x16x32_f16 v[4:7], v[210:213], v[176:179], v[4:7]
	v_mfma_f32_16x16x32_f16 v[32:35], v[194:197], v[132:135], v[32:35]
	v_mfma_f32_16x16x32_f16 v[40:43], v[210:213], v[132:135], v[40:43]
	v_mfma_f32_16x16x32_f16 v[48:51], v[194:197], v[148:151], v[48:51]
	s_add_i32 s15, 0, 0x18000
	v_add_u32_e32 v72, s15, v208
	s_barrier
	ds_read_b128 v[52:55], v72
	ds_read_b128 v[56:59], v72 offset:1024
	ds_read_b128 v[68:71], v72 offset:2048
	ds_read_b128 v[72:75], v72 offset:3072
	s_add_u32 s30, s48, 0x20000
	s_addc_u32 s31, s49, 0
	s_mov_b32 m0, s12
	v_lshl_add_u64 v[148:149], s[30:31], 0, v[180:181]
	ds_read_b128 v[128:131], v209 offset:32768
	ds_read_b128 v[132:135], v209 offset:33792
	ds_read_b128 v[144:147], v209 offset:34816
	ds_read_b128 v[156:159], v209 offset:35840
	ds_read_b128 v[168:171], v209 offset:36864
	ds_read_b128 v[172:175], v209 offset:37888
	ds_read_b128 v[176:179], v209 offset:38912
	ds_read_b128 v[190:193], v209 offset:39936
	global_load_lds_dwordx4 v[148:149], off
	v_lshl_add_u64 v[148:149], s[30:31], 0, v[182:183]
	s_mov_b32 m0, s13
	s_nop 0
	global_load_lds_dwordx4 v[148:149], off
	s_waitcnt lgkmcnt(8)
	s_barrier
	s_waitcnt lgkmcnt(0)
	s_waitcnt lgkmcnt(0)
	v_mfma_f32_16x16x32_f16 v[148:151], v[52:55], v[128:131], v[164:167]
	v_mfma_f32_16x16x32_f16 v[164:167], v[56:59], v[132:135], v[148:151]
	v_mfma_f32_16x16x32_f16 v[148:151], v[68:71], v[128:131], v[160:163]
	v_mfma_f32_16x16x32_f16 v[140:143], v[52:55], v[144:147], v[140:143]
	v_mfma_f32_16x16x32_f16 v[136:139], v[68:71], v[144:147], v[136:139]
	v_mfma_f32_16x16x32_f16 v[116:119], v[52:55], v[168:171], v[116:119]
	v_mfma_f32_16x16x32_f16 v[112:115], v[68:71], v[168:171], v[112:115]
	v_mfma_f32_16x16x32_f16 v[96:99], v[52:55], v[176:179], v[96:99]
	v_mfma_f32_16x16x32_f16 v[92:95], v[68:71], v[176:179], v[92:95]
	v_mfma_f32_16x16x32_f16 v[160:163], v[72:75], v[132:135], v[148:151]
	v_mfma_f32_16x16x32_f16 v[140:143], v[56:59], v[156:159], v[140:143]
	v_mfma_f32_16x16x32_f16 v[136:139], v[72:75], v[156:159], v[136:139]
	v_mfma_f32_16x16x32_f16 v[116:119], v[56:59], v[172:175], v[116:119]
	v_mfma_f32_16x16x32_f16 v[112:115], v[72:75], v[172:175], v[112:115]
	v_mfma_f32_16x16x32_f16 v[96:99], v[56:59], v[190:193], v[96:99]
	v_mfma_f32_16x16x32_f16 v[92:95], v[72:75], v[190:193], v[92:95]
	s_barrier
	s_add_i32 s29, 0, 0x1c000
	v_add_u32_e32 v148, s29, v208
	s_add_i32 s15, s15, s7
	ds_read_b128 v[194:197], v148
	ds_read_b128 v[198:201], v148 offset:1024
	ds_read_b128 v[210:213], v148 offset:2048
	ds_read_b128 v[214:217], v148 offset:3072
	v_lshl_add_u64 v[148:149], v[202:203], 0, s[88:89]
	s_mov_b32 m0, s15
	s_nop 0
	global_load_lds_dwordx4 v[148:149], off
	v_lshl_add_u64 v[148:149], v[218:219], 0, s[88:89]
	s_add_i32 m0, s15, 0x2000
	s_nop 0
	global_load_lds_dwordx4 v[148:149], off
	s_barrier
	s_waitcnt lgkmcnt(0)
	s_waitcnt lgkmcnt(0)
	v_mfma_f32_16x16x32_f16 v[148:151], v[194:197], v[128:131], v[152:155]
	v_mfma_f32_16x16x32_f16 v[108:111], v[210:213], v[128:131], v[108:111]
	v_mfma_f32_16x16x32_f16 v[152:155], v[198:201], v[132:135], v[148:151]
	v_mfma_f32_16x16x32_f16 v[148:151], v[214:217], v[132:135], v[108:111]
	v_mfma_f32_16x16x32_f16 v[108:111], v[194:197], v[144:147], v[120:123]
	v_mfma_f32_16x16x32_f16 v[128:131], v[198:201], v[156:159], v[108:111]
	v_mfma_f32_16x16x32_f16 v[108:111], v[210:213], v[144:147], v[124:127]
	v_mfma_f32_16x16x32_f16 v[104:107], v[194:197], v[168:171], v[104:107]
	v_mfma_f32_16x16x32_f16 v[100:103], v[210:213], v[168:171], v[100:103]
	v_mfma_f32_16x16x32_f16 v[88:91], v[194:197], v[176:179], v[88:91]
	v_mfma_f32_16x16x32_f16 v[84:87], v[210:213], v[176:179], v[84:87]
	v_mfma_f32_16x16x32_f16 v[124:127], v[214:217], v[156:159], v[108:111]
	v_mfma_f32_16x16x32_f16 v[104:107], v[198:201], v[172:175], v[104:107]
	v_mfma_f32_16x16x32_f16 v[100:103], v[214:217], v[172:175], v[100:103]
	v_mfma_f32_16x16x32_f16 v[88:91], v[198:201], v[190:193], v[88:91]
	v_mfma_f32_16x16x32_f16 v[84:87], v[214:217], v[190:193], v[84:87]
	s_mov_b32 m0, s50
	v_lshl_add_u64 v[190:191], v[220:221], 0, s[88:89]
	s_barrier
	ds_read_b128 v[108:111], v209 offset:49152
	ds_read_b128 v[120:123], v209 offset:50176
	ds_read_b128 v[132:135], v209 offset:51200
	ds_read_b128 v[144:147], v209 offset:52224
	ds_read_b128 v[156:159], v209 offset:53248
	ds_read_b128 v[168:171], v209 offset:54272
	ds_read_b128 v[172:175], v209 offset:55296
	ds_read_b128 v[176:179], v209 offset:56320
	global_load_lds_dwordx4 v[190:191], off
	v_lshl_add_u64 v[190:191], v[232:233], 0, s[88:89]
	s_mov_b32 m0, s51
	s_nop 0
	global_load_lds_dwordx4 v[190:191], off
	s_barrier
	s_waitcnt lgkmcnt(0)
	s_waitcnt lgkmcnt(0)
	v_mfma_f32_16x16x32_f16 v[80:83], v[52:55], v[108:111], v[80:83]
	v_mfma_f32_16x16x32_f16 v[76:79], v[68:71], v[108:111], v[76:79]
	v_mfma_f32_16x16x32_f16 v[64:67], v[52:55], v[132:135], v[64:67]
	v_mfma_f32_16x16x32_f16 v[60:63], v[68:71], v[132:135], v[60:63]
	v_mfma_f32_16x16x32_f16 v[36:39], v[52:55], v[156:159], v[36:39]
	v_mfma_f32_16x16x32_f16 v[28:31], v[68:71], v[156:159], v[28:31]
	v_mfma_f32_16x16x32_f16 v[16:19], v[52:55], v[172:175], v[16:19]
	v_mfma_f32_16x16x32_f16 v[12:15], v[68:71], v[172:175], v[12:15]
	v_mfma_f32_16x16x32_f16 v[80:83], v[56:59], v[120:123], v[80:83]
	v_mfma_f32_16x16x32_f16 v[76:79], v[72:75], v[120:123], v[76:79]
	v_mfma_f32_16x16x32_f16 v[64:67], v[56:59], v[144:147], v[64:67]
	v_mfma_f32_16x16x32_f16 v[60:63], v[72:75], v[144:147], v[60:63]
	v_mfma_f32_16x16x32_f16 v[36:39], v[56:59], v[168:171], v[36:39]
	v_mfma_f32_16x16x32_f16 v[28:31], v[72:75], v[168:171], v[28:31]
	v_mfma_f32_16x16x32_f16 v[16:19], v[56:59], v[176:179], v[16:19]
	v_mfma_f32_16x16x32_f16 v[12:15], v[72:75], v[176:179], v[12:15]
	s_barrier
	s_add_u32 s30, s38, 0x20080
	s_addc_u32 s31, s39, 0
	s_add_i32 s15, s29, s7
	v_lshl_add_u64 v[52:53], s[30:31], 0, v[2:3]
	s_mov_b32 m0, s15
	s_nop 0
	global_load_lds_dwordx4 v[52:53], off
	v_lshl_add_u64 v[52:53], s[30:31], 0, v[184:185]
	s_add_i32 m0, s15, 0x2000
	s_nop 0
	global_load_lds_dwordx4 v[52:53], off
	s_waitcnt vmcnt(6)
	s_barrier
	v_mfma_f32_16x16x32_f16 v[32:35], v[194:197], v[108:111], v[32:35]
	v_mfma_f32_16x16x32_f16 v[72:75], v[198:201], v[120:123], v[32:35]
	v_mfma_f32_16x16x32_f16 v[32:35], v[210:213], v[108:111], v[40:43]
	v_mfma_f32_16x16x32_f16 v[68:71], v[214:217], v[120:123], v[32:35]
	v_mfma_f32_16x16x32_f16 v[32:35], v[194:197], v[132:135], v[48:51]
	v_mfma_f32_16x16x32_f16 v[52:55], v[198:201], v[144:147], v[32:35]
	v_mfma_f32_16x16x32_f16 v[32:35], v[210:213], v[132:135], v[44:47]
	v_mfma_f32_16x16x32_f16 v[24:27], v[194:197], v[156:159], v[24:27]
	v_mfma_f32_16x16x32_f16 v[20:23], v[210:213], v[156:159], v[20:23]
	v_mfma_f32_16x16x32_f16 v[8:11], v[194:197], v[172:175], v[8:11]
	v_mfma_f32_16x16x32_f16 v[4:7], v[210:213], v[172:175], v[4:7]
	v_mfma_f32_16x16x32_f16 v[44:47], v[214:217], v[144:147], v[32:35]
	v_mfma_f32_16x16x32_f16 v[24:27], v[198:201], v[168:171], v[24:27]
	v_mfma_f32_16x16x32_f16 v[20:23], v[214:217], v[168:171], v[20:23]
	v_mfma_f32_16x16x32_f16 v[8:11], v[198:201], v[176:179], v[8:11]
	v_mfma_f32_16x16x32_f16 v[4:7], v[214:217], v[176:179], v[4:7]
	s_add_i32 s14, s14, 2
	s_add_u32 s46, s46, 0x100
	s_addc_u32 s47, s47, 0
	s_add_u32 s10, s10, 0x100
	s_addc_u32 s11, s11, 0
	s_cmp_gt_u32 s14, 5
	s_barrier
	s_cbranch_scc0 .LBB0_1664
	s_lshl_b32 s11, s16, 8
	v_mov_b32_e32 v110, v206
	v_mov_b32_e32 v32, v207
	s_lshl_b32 s10, s26, 8
	s_or_b32 s11, s11, s27
	s_add_i32 s10, s10, s17
	v_lshl_add_u32 v108, v32, 3, s11
	v_ashrrev_i32_e32 v109, 31, v108
	v_add_u32_e32 v194, s10, v110
	v_readlane_b32 s10, v253, 25
	v_lshlrev_b64 v[190:191], 1, v[108:109]
	v_readlane_b32 s11, v253, 26
	v_ashrrev_i32_e32 v195, 31, v194
	v_add_u32_e32 v200, 16, v194
	v_lshl_add_u64 v[32:33], v[108:109], 2, s[18:19]
	v_lshl_add_u64 v[192:193], s[10:11], 0, v[190:191]
	v_lshlrev_b64 v[108:109], 10, v[194:195]
	v_ashrrev_i32_e32 v201, 31, v200
	v_add_u32_e32 v198, 32, v194
	flat_load_dwordx4 v[56:59], v[32:33]
	flat_load_dwordx4 v[48:51], v[32:33] offset:16
	flat_load_dwordx4 v[40:43], v[32:33] offset:512
	s_nop 0
	flat_load_dwordx4 v[32:35], v[32:33] offset:528
	v_lshl_add_u64 v[176:177], v[192:193], 0, v[108:109]
	v_lshlrev_b64 v[108:109], 10, v[200:201]
	v_ashrrev_i32_e32 v199, 31, v198
	v_add_u32_e32 v196, 48, v194
	v_lshl_add_u64 v[168:169], v[192:193], 0, v[108:109]
	v_lshlrev_b64 v[108:109], 10, v[198:199]
	v_ashrrev_i32_e32 v197, 31, v196
	v_lshl_add_u64 v[144:145], v[192:193], 0, v[108:109]
	v_lshlrev_b64 v[108:109], 10, v[196:197]
	v_lshl_add_u64 v[120:121], v[192:193], 0, v[108:109]
	global_load_dwordx4 v[108:111], v[120:121], off offset:256
	s_nop 0
	global_load_dwordx4 v[120:123], v[120:121], off
	s_nop 0
	global_load_dwordx4 v[132:135], v[144:145], off offset:256
	s_nop 0
	global_load_dwordx4 v[144:147], v[144:145], off
	s_nop 0
	global_load_dwordx4 v[156:159], v[168:169], off offset:256
	s_nop 0
	global_load_dwordx4 v[168:171], v[168:169], off
	s_nop 0
	global_load_dwordx4 v[172:175], v[176:177], off offset:256
	s_nop 0
	global_load_dwordx4 v[176:179], v[176:177], off
	v_readlane_b32 s10, v253, 40
	v_lshlrev_b64 v[202:203], 12, v[194:195]
	v_readlane_b32 s11, v253, 41
	s_and_b64 vcc, exec, s[40:41]
	s_mov_b32 s16, s34
	s_mov_b32 s26, s36
	s_mov_b64 s[48:49], s[44:45]
	s_mov_b64 s[38:39], s[42:43]
	s_waitcnt vmcnt(0)
	s_waitcnt lgkmcnt(0)
	v_add_f32_e32 v164, v164, v56
	v_add_f32_e32 v165, v165, v57
	v_mul_f32_e32 v164, 0xbfb8aa3b, v164
	v_mul_f32_e32 v165, 0xbfb8aa3b, v165
	v_exp_f32_e32 v164, v164
	v_exp_f32_e32 v165, v165
	v_add_f32_e32 v160, v160, v48
	v_add_f32_e32 v161, v161, v49
	v_add_f32_e32 v164, 1.0, v164
	v_mul_f32_e32 v160, 0xbfb8aa3b, v160
	v_add_f32_e32 v165, 1.0, v165
	v_mul_f32_e32 v161, 0xbfb8aa3b, v161
	v_rcp_f32_e32 v164, v164
	v_exp_f32_e32 v160, v160
	v_rcp_f32_e32 v165, v165
	v_cvt_f32_f16_e32 v210, v176
	v_cvt_f32_f16_sdwa v211, v176 dst_sel:DWORD dst_unused:UNUSED_PAD src0_sel:WORD_1
	v_exp_f32_e32 v161, v161
	v_add_f32_e32 v160, 1.0, v160
	v_rcp_f32_e32 v160, v160
	v_pk_mul_f32 v[164:165], v[164:165], v[210:211]
	v_add_f32_e32 v161, 1.0, v161
	v_cvt_pk_f16_f32 v176, v164, v165
	v_rcp_f32_e32 v161, v161
	v_cvt_f32_f16_e32 v164, v178
	v_cvt_f32_f16_sdwa v165, v178 dst_sel:DWORD dst_unused:UNUSED_PAD src0_sel:WORD_1
	v_add_f32_e32 v152, v152, v40
	v_add_f32_e32 v153, v153, v41
	v_mul_f32_e32 v152, 0xbfb8aa3b, v152
	v_pk_mul_f32 v[160:161], v[160:161], v[164:165]
	v_cvt_f32_f16_e32 v164, v177
	v_cvt_pk_f16_f32 v178, v160, v161
	v_add_f32_e32 v161, v162, v50
	v_mul_f32_e32 v161, 0xbfb8aa3b, v161
	v_exp_f32_e32 v161, v161
	v_add_f32_e32 v160, v166, v58
	v_mul_f32_e32 v160, 0xbfb8aa3b, v160
	v_exp_f32_e32 v160, v160
	v_add_f32_e32 v161, 1.0, v161
	v_rcp_f32_e32 v162, v161
	v_add_f32_e32 v161, v167, v59
	v_mul_f32_e32 v161, 0xbfb8aa3b, v161
	v_exp_f32_e32 v161, v161
	v_add_f32_e32 v160, 1.0, v160
	v_rcp_f32_e32 v160, v160
	v_cvt_f32_f16_sdwa v165, v177 dst_sel:DWORD dst_unused:UNUSED_PAD src0_sel:WORD_1
	v_add_f32_e32 v161, 1.0, v161
	v_rcp_f32_e32 v161, v161
	v_mul_f32_e32 v153, 0xbfb8aa3b, v153
	v_exp_f32_e32 v152, v152
	v_exp_f32_e32 v153, v153
	v_pk_mul_f32 v[160:161], v[160:161], v[164:165]
	v_add_f32_e32 v148, v148, v32
	v_cvt_pk_f16_f32 v164, v160, v161
	v_add_f32_e32 v160, v163, v51
	v_mul_f32_e32 v160, 0xbfb8aa3b, v160
	v_exp_f32_e32 v160, v160
	v_cvt_f32_f16_sdwa v161, v179 dst_sel:DWORD dst_unused:UNUSED_PAD src0_sel:WORD_1
	v_add_f32_e32 v149, v149, v33
	v_add_f32_e32 v152, 1.0, v152
	v_add_f32_e32 v160, 1.0, v160
	v_rcp_f32_e32 v163, v160
	v_cvt_f32_f16_e32 v160, v179
	v_mul_f32_e32 v148, 0xbfb8aa3b, v148
	v_add_f32_e32 v153, 1.0, v153
	v_mul_f32_e32 v149, 0xbfb8aa3b, v149
	v_pk_mul_f32 v[160:161], v[162:163], v[160:161]
	v_rcp_f32_e32 v152, v152
	v_cvt_pk_f16_f32 v160, v160, v161
	v_lshrrev_b32_e32 v161, 4, v176
	v_and_b32_e32 v161, 0x10001, v161
	v_add3_u32 v161, v176, v161, s21
	v_and_b32_e32 v162, 0xfff0fff0, v161
	v_lshrrev_b32_e32 v161, 4, v164
	v_and_b32_e32 v161, 0x10001, v161
	v_add3_u32 v161, v164, v161, s21
	v_and_b32_e32 v163, 0xfff0fff0, v161
	v_lshrrev_b32_e32 v161, 4, v178
	v_and_b32_e32 v161, 0x10001, v161
	v_add3_u32 v161, v178, v161, s21
	v_and_b32_e32 v164, 0xfff0fff0, v161
	v_lshrrev_b32_e32 v161, 4, v160
	v_and_b32_e32 v161, 0x10001, v161
	v_add3_u32 v160, v160, v161, s21
	v_and_b32_e32 v165, 0xfff0fff0, v160
	v_lshl_add_u64 v[160:161], s[10:11], 0, v[202:203]
	v_lshl_add_u64 v[160:161], v[160:161], 0, v[190:191]
	global_store_dwordx4 v[160:161], v[162:165], off
	v_exp_f32_e32 v148, v148
	v_rcp_f32_e32 v153, v153
	v_cvt_f32_f16_e32 v162, v172
	v_cvt_f32_f16_sdwa v163, v172 dst_sel:DWORD dst_unused:UNUSED_PAD src0_sel:WORD_1
	v_exp_f32_e32 v149, v149
	v_add_f32_e32 v148, 1.0, v148
	v_rcp_f32_e32 v148, v148
	v_pk_mul_f32 v[152:153], v[152:153], v[162:163]
	v_add_f32_e32 v149, 1.0, v149
	v_cvt_pk_f16_f32 v162, v152, v153
	v_rcp_f32_e32 v149, v149
	v_cvt_f32_f16_e32 v152, v174
	v_cvt_f32_f16_sdwa v153, v174 dst_sel:DWORD dst_unused:UNUSED_PAD src0_sel:WORD_1
	v_add_f32_e32 v140, v140, v56
	v_add_f32_e32 v141, v141, v57
	v_mul_f32_e32 v140, 0xbfb8aa3b, v140
	v_pk_mul_f32 v[148:149], v[148:149], v[152:153]
	v_cvt_f32_f16_e32 v152, v173
	v_cvt_pk_f16_f32 v163, v148, v149
	v_add_f32_e32 v149, v150, v34
	v_mul_f32_e32 v149, 0xbfb8aa3b, v149
	v_exp_f32_e32 v149, v149
	v_add_f32_e32 v148, v154, v42
	v_mul_f32_e32 v148, 0xbfb8aa3b, v148
	v_exp_f32_e32 v148, v148
	v_add_f32_e32 v149, 1.0, v149
	v_rcp_f32_e32 v150, v149
	v_add_f32_e32 v149, v155, v43
	v_mul_f32_e32 v149, 0xbfb8aa3b, v149
	v_exp_f32_e32 v149, v149
	v_add_f32_e32 v148, 1.0, v148
	v_rcp_f32_e32 v148, v148
	v_cvt_f32_f16_sdwa v153, v173 dst_sel:DWORD dst_unused:UNUSED_PAD src0_sel:WORD_1
	v_add_f32_e32 v149, 1.0, v149
	v_rcp_f32_e32 v149, v149
	v_mul_f32_e32 v141, 0xbfb8aa3b, v141
	v_exp_f32_e32 v140, v140
	v_exp_f32_e32 v141, v141
	v_pk_mul_f32 v[148:149], v[148:149], v[152:153]
	v_add_f32_e32 v136, v136, v48
	v_cvt_pk_f16_f32 v152, v148, v149
	v_add_f32_e32 v148, v151, v35
	v_mul_f32_e32 v148, 0xbfb8aa3b, v148
	v_exp_f32_e32 v148, v148
	v_cvt_f32_f16_sdwa v149, v175 dst_sel:DWORD dst_unused:UNUSED_PAD src0_sel:WORD_1
	v_add_f32_e32 v137, v137, v49
	v_add_f32_e32 v140, 1.0, v140
	v_add_f32_e32 v148, 1.0, v148
	v_rcp_f32_e32 v151, v148
	v_cvt_f32_f16_e32 v148, v175
	v_mul_f32_e32 v136, 0xbfb8aa3b, v136
	v_add_f32_e32 v141, 1.0, v141
	v_mul_f32_e32 v137, 0xbfb8aa3b, v137
	v_pk_mul_f32 v[148:149], v[150:151], v[148:149]
	v_lshrrev_b32_e32 v150, 4, v163
	v_cvt_pk_f16_f32 v151, v148, v149
	v_lshrrev_b32_e32 v149, 4, v152
	v_and_b32_e32 v149, 0x10001, v149
	v_lshrrev_b32_e32 v148, 4, v162
	v_add3_u32 v149, v152, v149, s21
	v_lshrrev_b32_e32 v152, 4, v151
	v_and_b32_e32 v148, 0x10001, v148
	v_and_b32_e32 v150, 0x10001, v150
	v_and_b32_e32 v152, 0x10001, v152
	v_add3_u32 v148, v162, v148, s21
	v_add3_u32 v150, v163, v150, s21
	v_add3_u32 v151, v151, v152, s21
	v_and_b32_e32 v148, 0xfff0fff0, v148
	v_and_b32_e32 v149, 0xfff0fff0, v149
	v_and_b32_e32 v150, 0xfff0fff0, v150
	v_and_b32_e32 v151, 0xfff0fff0, v151
	global_store_dwordx4 v[160:161], v[148:151], off offset:256
	v_rcp_f32_e32 v140, v140
	v_exp_f32_e32 v136, v136
	v_rcp_f32_e32 v141, v141
	v_cvt_f32_f16_e32 v150, v168
	v_cvt_f32_f16_sdwa v151, v168 dst_sel:DWORD dst_unused:UNUSED_PAD src0_sel:WORD_1
	v_exp_f32_e32 v137, v137
	v_add_f32_e32 v136, 1.0, v136
	v_rcp_f32_e32 v136, v136
	v_pk_mul_f32 v[140:141], v[140:141], v[150:151]
	v_add_f32_e32 v137, 1.0, v137
	v_cvt_pk_f16_f32 v150, v140, v141
	v_rcp_f32_e32 v137, v137
	v_cvt_f32_f16_e32 v140, v170
	v_cvt_f32_f16_sdwa v141, v170 dst_sel:DWORD dst_unused:UNUSED_PAD src0_sel:WORD_1
	v_add_f32_e32 v128, v128, v40
	v_add_f32_e32 v129, v129, v41
	v_mul_f32_e32 v128, 0xbfb8aa3b, v128
	v_pk_mul_f32 v[136:137], v[136:137], v[140:141]
	v_cvt_f32_f16_e32 v140, v169
	v_cvt_pk_f16_f32 v151, v136, v137
	v_add_f32_e32 v137, v138, v50
	v_mul_f32_e32 v137, 0xbfb8aa3b, v137
	v_exp_f32_e32 v137, v137
	v_add_f32_e32 v136, v142, v58
	v_mul_f32_e32 v136, 0xbfb8aa3b, v136
	v_exp_f32_e32 v136, v136
	v_add_f32_e32 v137, 1.0, v137
	v_rcp_f32_e32 v138, v137
	v_add_f32_e32 v137, v143, v59
	v_mul_f32_e32 v137, 0xbfb8aa3b, v137
	v_exp_f32_e32 v137, v137
	v_add_f32_e32 v136, 1.0, v136
	v_rcp_f32_e32 v136, v136
	v_cvt_f32_f16_sdwa v141, v169 dst_sel:DWORD dst_unused:UNUSED_PAD src0_sel:WORD_1
	v_add_f32_e32 v137, 1.0, v137
	v_rcp_f32_e32 v137, v137
	v_mul_f32_e32 v129, 0xbfb8aa3b, v129
	v_exp_f32_e32 v128, v128
	v_exp_f32_e32 v129, v129
	v_pk_mul_f32 v[136:137], v[136:137], v[140:141]
	v_lshlrev_b64 v[148:149], 12, v[200:201]
	v_cvt_pk_f16_f32 v140, v136, v137
	v_add_f32_e32 v136, v139, v51
	v_mul_f32_e32 v136, 0xbfb8aa3b, v136
	v_exp_f32_e32 v136, v136
	v_cvt_f32_f16_sdwa v137, v171 dst_sel:DWORD dst_unused:UNUSED_PAD src0_sel:WORD_1
	v_add_f32_e32 v124, v124, v32
	v_add_f32_e32 v125, v125, v33
	v_add_f32_e32 v136, 1.0, v136
	v_rcp_f32_e32 v139, v136
	v_cvt_f32_f16_e32 v136, v171
	v_add_f32_e32 v128, 1.0, v128
	v_mul_f32_e32 v124, 0xbfb8aa3b, v124
	v_add_f32_e32 v129, 1.0, v129
	v_pk_mul_f32 v[136:137], v[138:139], v[136:137]
	v_mul_f32_e32 v125, 0xbfb8aa3b, v125
	v_cvt_pk_f16_f32 v136, v136, v137
	v_lshrrev_b32_e32 v137, 4, v150
	v_and_b32_e32 v137, 0x10001, v137
	v_add3_u32 v137, v150, v137, s21
	v_and_b32_e32 v138, 0xfff0fff0, v137
	v_lshrrev_b32_e32 v137, 4, v140
	v_and_b32_e32 v137, 0x10001, v137
	v_add3_u32 v137, v140, v137, s21
	v_and_b32_e32 v139, 0xfff0fff0, v137
	v_lshrrev_b32_e32 v137, 4, v151
	v_and_b32_e32 v137, 0x10001, v137
	v_add3_u32 v137, v151, v137, s21
	v_and_b32_e32 v140, 0xfff0fff0, v137
	v_lshrrev_b32_e32 v137, 4, v136
	v_and_b32_e32 v137, 0x10001, v137
	v_add3_u32 v136, v136, v137, s21
	v_and_b32_e32 v141, 0xfff0fff0, v136
	v_lshl_add_u64 v[136:137], s[10:11], 0, v[148:149]
	v_lshl_add_u64 v[136:137], v[136:137], 0, v[190:191]
	global_store_dwordx4 v[136:137], v[138:141], off
	v_rcp_f32_e32 v128, v128
	v_exp_f32_e32 v124, v124
	v_rcp_f32_e32 v129, v129
	v_cvt_f32_f16_e32 v138, v156
	v_cvt_f32_f16_sdwa v139, v156 dst_sel:DWORD dst_unused:UNUSED_PAD src0_sel:WORD_1
	v_exp_f32_e32 v125, v125
	v_add_f32_e32 v124, 1.0, v124
	v_rcp_f32_e32 v124, v124
	v_pk_mul_f32 v[128:129], v[128:129], v[138:139]
	v_add_f32_e32 v125, 1.0, v125
	v_cvt_pk_f16_f32 v138, v128, v129
	v_rcp_f32_e32 v125, v125
	v_cvt_f32_f16_e32 v128, v158
	v_cvt_f32_f16_sdwa v129, v158 dst_sel:DWORD dst_unused:UNUSED_PAD src0_sel:WORD_1
	v_add_f32_e32 v116, v116, v56
	v_add_f32_e32 v117, v117, v57
	v_mul_f32_e32 v116, 0xbfb8aa3b, v116
	v_pk_mul_f32 v[124:125], v[124:125], v[128:129]
	v_cvt_f32_f16_e32 v128, v157
	v_cvt_pk_f16_f32 v139, v124, v125
	v_add_f32_e32 v125, v126, v34
	v_mul_f32_e32 v125, 0xbfb8aa3b, v125
	v_exp_f32_e32 v125, v125
	v_add_f32_e32 v124, v130, v42
	v_mul_f32_e32 v124, 0xbfb8aa3b, v124
	v_exp_f32_e32 v124, v124
	v_add_f32_e32 v125, 1.0, v125
	v_rcp_f32_e32 v126, v125
	v_add_f32_e32 v125, v131, v43
	v_mul_f32_e32 v125, 0xbfb8aa3b, v125
	v_exp_f32_e32 v125, v125
	v_add_f32_e32 v124, 1.0, v124
	v_rcp_f32_e32 v124, v124
	v_cvt_f32_f16_sdwa v129, v157 dst_sel:DWORD dst_unused:UNUSED_PAD src0_sel:WORD_1
	v_add_f32_e32 v125, 1.0, v125
	v_rcp_f32_e32 v125, v125
	v_mul_f32_e32 v117, 0xbfb8aa3b, v117
	v_exp_f32_e32 v116, v116
	v_exp_f32_e32 v117, v117
	v_pk_mul_f32 v[124:125], v[124:125], v[128:129]
	v_add_f32_e32 v112, v112, v48
	v_cvt_pk_f16_f32 v128, v124, v125
	v_add_f32_e32 v124, v127, v35
	v_mul_f32_e32 v124, 0xbfb8aa3b, v124
	v_exp_f32_e32 v124, v124
	v_cvt_f32_f16_sdwa v125, v159 dst_sel:DWORD dst_unused:UNUSED_PAD src0_sel:WORD_1
	v_add_f32_e32 v113, v113, v49
	v_add_f32_e32 v116, 1.0, v116
	v_add_f32_e32 v124, 1.0, v124
	v_rcp_f32_e32 v127, v124
	v_cvt_f32_f16_e32 v124, v159
	v_mul_f32_e32 v112, 0xbfb8aa3b, v112
	v_add_f32_e32 v117, 1.0, v117
	v_mul_f32_e32 v113, 0xbfb8aa3b, v113
	v_pk_mul_f32 v[124:125], v[126:127], v[124:125]
	v_lshrrev_b32_e32 v126, 4, v139
	v_cvt_pk_f16_f32 v127, v124, v125
	v_lshrrev_b32_e32 v125, 4, v128
	v_and_b32_e32 v125, 0x10001, v125
	v_lshrrev_b32_e32 v124, 4, v138
	v_add3_u32 v125, v128, v125, s21
	v_lshrrev_b32_e32 v128, 4, v127
	v_and_b32_e32 v124, 0x10001, v124
	v_and_b32_e32 v126, 0x10001, v126
	v_and_b32_e32 v128, 0x10001, v128
	v_add3_u32 v124, v138, v124, s21
	v_add3_u32 v126, v139, v126, s21
	v_add3_u32 v127, v127, v128, s21
	v_and_b32_e32 v124, 0xfff0fff0, v124
	v_and_b32_e32 v125, 0xfff0fff0, v125
	v_and_b32_e32 v126, 0xfff0fff0, v126
	v_and_b32_e32 v127, 0xfff0fff0, v127
	global_store_dwordx4 v[136:137], v[124:127], off offset:256
	v_rcp_f32_e32 v116, v116
	v_exp_f32_e32 v112, v112
	v_rcp_f32_e32 v117, v117
	v_cvt_f32_f16_e32 v126, v144
	v_cvt_f32_f16_sdwa v127, v144 dst_sel:DWORD dst_unused:UNUSED_PAD src0_sel:WORD_1
	v_exp_f32_e32 v113, v113
	v_add_f32_e32 v112, 1.0, v112
	v_rcp_f32_e32 v112, v112
	v_pk_mul_f32 v[116:117], v[116:117], v[126:127]
	v_add_f32_e32 v113, 1.0, v113
	v_cvt_pk_f16_f32 v126, v116, v117
	v_rcp_f32_e32 v113, v113
	v_cvt_f32_f16_e32 v116, v146
	v_cvt_f32_f16_sdwa v117, v146 dst_sel:DWORD dst_unused:UNUSED_PAD src0_sel:WORD_1
	v_add_f32_e32 v104, v104, v40
	v_add_f32_e32 v105, v105, v41
	v_mul_f32_e32 v104, 0xbfb8aa3b, v104
	v_pk_mul_f32 v[112:113], v[112:113], v[116:117]
	v_cvt_f32_f16_e32 v116, v145
	v_cvt_pk_f16_f32 v127, v112, v113
	v_add_f32_e32 v113, v114, v50
	v_mul_f32_e32 v113, 0xbfb8aa3b, v113
	v_exp_f32_e32 v113, v113
	v_add_f32_e32 v112, v118, v58
	v_mul_f32_e32 v112, 0xbfb8aa3b, v112
	v_exp_f32_e32 v112, v112
	v_add_f32_e32 v113, 1.0, v113
	v_rcp_f32_e32 v114, v113
	v_add_f32_e32 v113, v119, v59
	v_mul_f32_e32 v113, 0xbfb8aa3b, v113
	v_exp_f32_e32 v113, v113
	v_add_f32_e32 v112, 1.0, v112
	v_rcp_f32_e32 v112, v112
	v_cvt_f32_f16_sdwa v117, v145 dst_sel:DWORD dst_unused:UNUSED_PAD src0_sel:WORD_1
	v_add_f32_e32 v113, 1.0, v113
	v_rcp_f32_e32 v113, v113
	v_mul_f32_e32 v105, 0xbfb8aa3b, v105
	v_exp_f32_e32 v104, v104
	v_exp_f32_e32 v105, v105
	v_pk_mul_f32 v[112:113], v[112:113], v[116:117]
	v_lshlrev_b64 v[124:125], 12, v[198:199]
	v_cvt_pk_f16_f32 v116, v112, v113
	v_add_f32_e32 v112, v115, v51
	v_mul_f32_e32 v112, 0xbfb8aa3b, v112
	v_exp_f32_e32 v112, v112
	v_cvt_f32_f16_sdwa v113, v147 dst_sel:DWORD dst_unused:UNUSED_PAD src0_sel:WORD_1
	v_add_f32_e32 v100, v100, v32
	v_add_f32_e32 v101, v101, v33
	v_add_f32_e32 v112, 1.0, v112
	v_rcp_f32_e32 v115, v112
	v_cvt_f32_f16_e32 v112, v147
	v_add_f32_e32 v104, 1.0, v104
	v_mul_f32_e32 v100, 0xbfb8aa3b, v100
	v_add_f32_e32 v105, 1.0, v105
	v_pk_mul_f32 v[112:113], v[114:115], v[112:113]
	v_mul_f32_e32 v101, 0xbfb8aa3b, v101
	v_cvt_pk_f16_f32 v112, v112, v113
	v_lshrrev_b32_e32 v113, 4, v126
	v_and_b32_e32 v113, 0x10001, v113
	v_add3_u32 v113, v126, v113, s21
	v_and_b32_e32 v114, 0xfff0fff0, v113
	v_lshrrev_b32_e32 v113, 4, v116
	v_and_b32_e32 v113, 0x10001, v113
	v_add3_u32 v113, v116, v113, s21
	v_and_b32_e32 v115, 0xfff0fff0, v113
	v_lshrrev_b32_e32 v113, 4, v127
	v_and_b32_e32 v113, 0x10001, v113
	v_add3_u32 v113, v127, v113, s21
	v_and_b32_e32 v116, 0xfff0fff0, v113
	v_lshrrev_b32_e32 v113, 4, v112
	v_and_b32_e32 v113, 0x10001, v113
	v_add3_u32 v112, v112, v113, s21
	v_and_b32_e32 v117, 0xfff0fff0, v112
	v_lshl_add_u64 v[112:113], s[10:11], 0, v[124:125]
	v_lshl_add_u64 v[112:113], v[112:113], 0, v[190:191]
	global_store_dwordx4 v[112:113], v[114:117], off
	v_rcp_f32_e32 v104, v104
	v_exp_f32_e32 v100, v100
	v_rcp_f32_e32 v105, v105
	v_cvt_f32_f16_e32 v114, v132
	v_cvt_f32_f16_sdwa v115, v132 dst_sel:DWORD dst_unused:UNUSED_PAD src0_sel:WORD_1
	v_exp_f32_e32 v101, v101
	v_add_f32_e32 v100, 1.0, v100
	v_rcp_f32_e32 v100, v100
	v_pk_mul_f32 v[104:105], v[104:105], v[114:115]
	v_add_f32_e32 v101, 1.0, v101
	v_cvt_pk_f16_f32 v114, v104, v105
	v_rcp_f32_e32 v101, v101
	v_cvt_f32_f16_e32 v104, v134
	v_cvt_f32_f16_sdwa v105, v134 dst_sel:DWORD dst_unused:UNUSED_PAD src0_sel:WORD_1
	v_add_f32_e32 v96, v96, v56
	v_add_f32_e32 v97, v97, v57
	v_mul_f32_e32 v96, 0xbfb8aa3b, v96
	v_pk_mul_f32 v[100:101], v[100:101], v[104:105]
	v_cvt_f32_f16_e32 v104, v133
	v_cvt_pk_f16_f32 v115, v100, v101
	v_add_f32_e32 v101, v102, v34
	v_mul_f32_e32 v101, 0xbfb8aa3b, v101
	v_exp_f32_e32 v101, v101
	v_add_f32_e32 v100, v106, v42
	v_mul_f32_e32 v100, 0xbfb8aa3b, v100
	v_exp_f32_e32 v100, v100
	v_add_f32_e32 v101, 1.0, v101
	v_rcp_f32_e32 v102, v101
	v_add_f32_e32 v101, v107, v43
	v_mul_f32_e32 v101, 0xbfb8aa3b, v101
	v_exp_f32_e32 v101, v101
	v_add_f32_e32 v100, 1.0, v100
	v_rcp_f32_e32 v100, v100
	v_cvt_f32_f16_sdwa v105, v133 dst_sel:DWORD dst_unused:UNUSED_PAD src0_sel:WORD_1
	v_add_f32_e32 v101, 1.0, v101
	v_rcp_f32_e32 v101, v101
	v_mul_f32_e32 v97, 0xbfb8aa3b, v97
	v_exp_f32_e32 v96, v96
	v_exp_f32_e32 v97, v97
	v_pk_mul_f32 v[100:101], v[100:101], v[104:105]
	v_add_f32_e32 v92, v92, v48
	v_cvt_pk_f16_f32 v104, v100, v101
	v_add_f32_e32 v100, v103, v35
	v_mul_f32_e32 v100, 0xbfb8aa3b, v100
	v_exp_f32_e32 v100, v100
	v_cvt_f32_f16_sdwa v101, v135 dst_sel:DWORD dst_unused:UNUSED_PAD src0_sel:WORD_1
	v_add_f32_e32 v93, v93, v49
	v_add_f32_e32 v96, 1.0, v96
	v_add_f32_e32 v100, 1.0, v100
	v_rcp_f32_e32 v103, v100
	v_cvt_f32_f16_e32 v100, v135
	v_mul_f32_e32 v92, 0xbfb8aa3b, v92
	v_add_f32_e32 v97, 1.0, v97
	v_mul_f32_e32 v93, 0xbfb8aa3b, v93
	v_pk_mul_f32 v[100:101], v[102:103], v[100:101]
	v_lshrrev_b32_e32 v102, 4, v115
	v_cvt_pk_f16_f32 v103, v100, v101
	v_lshrrev_b32_e32 v101, 4, v104
	v_and_b32_e32 v101, 0x10001, v101
	v_lshrrev_b32_e32 v100, 4, v114
	v_add3_u32 v101, v104, v101, s21
	v_lshrrev_b32_e32 v104, 4, v103
	v_and_b32_e32 v100, 0x10001, v100
	v_and_b32_e32 v102, 0x10001, v102
	v_and_b32_e32 v104, 0x10001, v104
	v_add3_u32 v100, v114, v100, s21
	v_add3_u32 v102, v115, v102, s21
	v_add3_u32 v103, v103, v104, s21
	v_and_b32_e32 v100, 0xfff0fff0, v100
	v_and_b32_e32 v101, 0xfff0fff0, v101
	v_and_b32_e32 v102, 0xfff0fff0, v102
	v_and_b32_e32 v103, 0xfff0fff0, v103
	global_store_dwordx4 v[112:113], v[100:103], off offset:256
	v_rcp_f32_e32 v96, v96
	v_exp_f32_e32 v92, v92
	v_rcp_f32_e32 v97, v97
	v_cvt_f32_f16_e32 v102, v120
	v_cvt_f32_f16_sdwa v103, v120 dst_sel:DWORD dst_unused:UNUSED_PAD src0_sel:WORD_1
	v_exp_f32_e32 v93, v93
	v_add_f32_e32 v92, 1.0, v92
	v_rcp_f32_e32 v92, v92
	v_pk_mul_f32 v[96:97], v[96:97], v[102:103]
	v_add_f32_e32 v93, 1.0, v93
	v_cvt_pk_f16_f32 v102, v96, v97
	v_rcp_f32_e32 v93, v93
	v_cvt_f32_f16_e32 v96, v122
	v_cvt_f32_f16_sdwa v97, v122 dst_sel:DWORD dst_unused:UNUSED_PAD src0_sel:WORD_1
	v_add_f32_e32 v88, v88, v40
	v_add_f32_e32 v89, v89, v41
	v_mul_f32_e32 v88, 0xbfb8aa3b, v88
	v_pk_mul_f32 v[92:93], v[92:93], v[96:97]
	v_cvt_f32_f16_e32 v96, v121
	v_cvt_pk_f16_f32 v103, v92, v93
	v_add_f32_e32 v93, v94, v50
	v_mul_f32_e32 v93, 0xbfb8aa3b, v93
	v_exp_f32_e32 v93, v93
	v_add_f32_e32 v92, v98, v58
	v_mul_f32_e32 v92, 0xbfb8aa3b, v92
	v_exp_f32_e32 v92, v92
	v_add_f32_e32 v93, 1.0, v93
	v_rcp_f32_e32 v94, v93
	v_add_f32_e32 v93, v99, v59
	v_mul_f32_e32 v93, 0xbfb8aa3b, v93
	v_exp_f32_e32 v93, v93
	v_add_f32_e32 v92, 1.0, v92
	v_rcp_f32_e32 v92, v92
	v_cvt_f32_f16_sdwa v97, v121 dst_sel:DWORD dst_unused:UNUSED_PAD src0_sel:WORD_1
	v_add_f32_e32 v93, 1.0, v93
	v_rcp_f32_e32 v93, v93
	v_mul_f32_e32 v89, 0xbfb8aa3b, v89
	v_exp_f32_e32 v88, v88
	v_exp_f32_e32 v89, v89
	v_pk_mul_f32 v[92:93], v[92:93], v[96:97]
	v_lshlrev_b64 v[100:101], 12, v[196:197]
	v_cvt_pk_f16_f32 v96, v92, v93
	v_add_f32_e32 v92, v95, v51
	v_mul_f32_e32 v92, 0xbfb8aa3b, v92
	v_exp_f32_e32 v92, v92
	v_cvt_f32_f16_sdwa v93, v123 dst_sel:DWORD dst_unused:UNUSED_PAD src0_sel:WORD_1
	v_add_f32_e32 v84, v84, v32
	v_add_f32_e32 v85, v85, v33
	v_add_f32_e32 v92, 1.0, v92
	v_rcp_f32_e32 v95, v92
	v_cvt_f32_f16_e32 v92, v123
	v_add_f32_e32 v88, 1.0, v88
	v_mul_f32_e32 v84, 0xbfb8aa3b, v84
	v_add_f32_e32 v89, 1.0, v89
	v_pk_mul_f32 v[92:93], v[94:95], v[92:93]
	v_mul_f32_e32 v85, 0xbfb8aa3b, v85
	v_cvt_pk_f16_f32 v92, v92, v93
	v_lshrrev_b32_e32 v93, 4, v102
	v_and_b32_e32 v93, 0x10001, v93
	v_add3_u32 v93, v102, v93, s21
	v_and_b32_e32 v94, 0xfff0fff0, v93
	v_lshrrev_b32_e32 v93, 4, v96
	v_and_b32_e32 v93, 0x10001, v93
	v_add3_u32 v93, v96, v93, s21
	v_and_b32_e32 v95, 0xfff0fff0, v93
	v_lshrrev_b32_e32 v93, 4, v103
	v_and_b32_e32 v93, 0x10001, v93
	v_add3_u32 v93, v103, v93, s21
	v_and_b32_e32 v96, 0xfff0fff0, v93
	v_lshrrev_b32_e32 v93, 4, v92
	v_and_b32_e32 v93, 0x10001, v93
	v_add3_u32 v92, v92, v93, s21
	v_and_b32_e32 v97, 0xfff0fff0, v92
	v_lshl_add_u64 v[92:93], s[10:11], 0, v[100:101]
	v_lshl_add_u64 v[92:93], v[92:93], 0, v[190:191]
	global_store_dwordx4 v[92:93], v[94:97], off
	v_rcp_f32_e32 v88, v88
	v_exp_f32_e32 v84, v84
	v_rcp_f32_e32 v89, v89
	v_cvt_f32_f16_e32 v94, v108
	v_cvt_f32_f16_sdwa v95, v108 dst_sel:DWORD dst_unused:UNUSED_PAD src0_sel:WORD_1
	v_exp_f32_e32 v85, v85
	v_add_f32_e32 v84, 1.0, v84
	v_rcp_f32_e32 v84, v84
	v_pk_mul_f32 v[88:89], v[88:89], v[94:95]
	v_add_f32_e32 v85, 1.0, v85
	v_cvt_pk_f16_f32 v94, v88, v89
	v_rcp_f32_e32 v85, v85
	v_cvt_f32_f16_e32 v88, v110
	v_cvt_f32_f16_sdwa v89, v110 dst_sel:DWORD dst_unused:UNUSED_PAD src0_sel:WORD_1
	v_add_u32_e32 v118, 0x80, v194
	v_ashrrev_i32_e32 v119, 31, v118
	v_add_u32_e32 v116, 0x90, v194
	v_pk_mul_f32 v[84:85], v[84:85], v[88:89]
	v_cvt_f32_f16_e32 v88, v109
	v_cvt_pk_f16_f32 v95, v84, v85
	v_add_f32_e32 v85, v86, v34
	v_mul_f32_e32 v85, 0xbfb8aa3b, v85
	v_exp_f32_e32 v85, v85
	v_add_f32_e32 v84, v90, v42
	v_mul_f32_e32 v84, 0xbfb8aa3b, v84
	v_exp_f32_e32 v84, v84
	v_add_f32_e32 v85, 1.0, v85
	v_rcp_f32_e32 v86, v85
	v_add_f32_e32 v85, v91, v43
	v_mul_f32_e32 v85, 0xbfb8aa3b, v85
	v_exp_f32_e32 v85, v85
	v_add_f32_e32 v84, 1.0, v84
	v_rcp_f32_e32 v84, v84
	v_cvt_f32_f16_sdwa v89, v109 dst_sel:DWORD dst_unused:UNUSED_PAD src0_sel:WORD_1
	v_add_f32_e32 v85, 1.0, v85
	v_rcp_f32_e32 v85, v85
	v_ashrrev_i32_e32 v117, 31, v116
	v_add_u32_e32 v114, 0xa0, v194
	v_ashrrev_i32_e32 v115, 31, v114
	v_pk_mul_f32 v[84:85], v[84:85], v[88:89]
	v_add_u32_e32 v112, 0xb0, v194
	v_cvt_pk_f16_f32 v88, v84, v85
	v_add_f32_e32 v84, v87, v35
	v_mul_f32_e32 v84, 0xbfb8aa3b, v84
	v_exp_f32_e32 v84, v84
	v_cvt_f32_f16_sdwa v85, v111 dst_sel:DWORD dst_unused:UNUSED_PAD src0_sel:WORD_1
	v_ashrrev_i32_e32 v113, 31, v112
	v_add_f32_e32 v80, v80, v56
	v_add_f32_e32 v84, 1.0, v84
	v_rcp_f32_e32 v87, v84
	v_cvt_f32_f16_e32 v84, v111
	v_add_f32_e32 v81, v81, v57
	v_mul_f32_e32 v80, 0xbfb8aa3b, v80
	v_mul_f32_e32 v81, 0xbfb8aa3b, v81
	v_pk_mul_f32 v[84:85], v[86:87], v[84:85]
	v_lshrrev_b32_e32 v86, 4, v95
	v_cvt_pk_f16_f32 v87, v84, v85
	v_lshrrev_b32_e32 v85, 4, v88
	v_and_b32_e32 v85, 0x10001, v85
	v_lshrrev_b32_e32 v84, 4, v94
	v_add3_u32 v85, v88, v85, s21
	v_lshrrev_b32_e32 v88, 4, v87
	v_and_b32_e32 v84, 0x10001, v84
	v_and_b32_e32 v86, 0x10001, v86
	v_and_b32_e32 v88, 0x10001, v88
	v_add3_u32 v84, v94, v84, s21
	v_add3_u32 v86, v95, v86, s21
	v_add3_u32 v87, v87, v88, s21
	v_and_b32_e32 v84, 0xfff0fff0, v84
	v_and_b32_e32 v85, 0xfff0fff0, v85
	v_and_b32_e32 v86, 0xfff0fff0, v86
	v_and_b32_e32 v87, 0xfff0fff0, v87
	global_store_dwordx4 v[92:93], v[84:87], off offset:256
	v_exp_f32_e32 v80, v80
	v_exp_f32_e32 v81, v81
	v_lshlrev_b64 v[84:85], 10, v[118:119]
	v_lshl_add_u64 v[120:121], v[192:193], 0, v[84:85]
	v_lshlrev_b64 v[84:85], 10, v[116:117]
	v_lshl_add_u64 v[104:105], v[192:193], 0, v[84:85]
	v_lshlrev_b64 v[84:85], 10, v[114:115]
	v_lshl_add_u64 v[96:97], v[192:193], 0, v[84:85]
	v_lshlrev_b64 v[84:85], 10, v[112:113]
	v_lshl_add_u64 v[88:89], v[192:193], 0, v[84:85]
	global_load_dwordx4 v[84:87], v[88:89], off offset:256
	s_nop 0
	global_load_dwordx4 v[88:91], v[88:89], off
	s_nop 0
	global_load_dwordx4 v[92:95], v[96:97], off offset:256
	s_nop 0
	global_load_dwordx4 v[96:99], v[96:97], off
	s_nop 0
	global_load_dwordx4 v[100:103], v[104:105], off offset:256
	s_nop 0
	global_load_dwordx4 v[104:107], v[104:105], off
	s_nop 0
	global_load_dwordx4 v[108:111], v[120:121], off offset:256
	s_nop 0
	global_load_dwordx4 v[120:123], v[120:121], off
	v_add_f32_e32 v76, v76, v48
	v_add_f32_e32 v77, v77, v49
	v_add_f32_e32 v80, 1.0, v80
	v_mul_f32_e32 v76, 0xbfb8aa3b, v76
	v_add_f32_e32 v81, 1.0, v81
	v_mul_f32_e32 v77, 0xbfb8aa3b, v77
	s_waitcnt vmcnt(0)
	v_rcp_f32_e32 v80, v80
	v_exp_f32_e32 v76, v76
	v_rcp_f32_e32 v81, v81
	v_cvt_f32_f16_e32 v124, v120
	v_cvt_f32_f16_sdwa v125, v120 dst_sel:DWORD dst_unused:UNUSED_PAD src0_sel:WORD_1
	v_exp_f32_e32 v77, v77
	v_add_f32_e32 v76, 1.0, v76
	v_rcp_f32_e32 v76, v76
	v_pk_mul_f32 v[80:81], v[80:81], v[124:125]
	v_add_f32_e32 v77, 1.0, v77
	v_cvt_pk_f16_f32 v120, v80, v81
	v_rcp_f32_e32 v77, v77
	v_cvt_f32_f16_e32 v80, v122
	v_cvt_f32_f16_sdwa v81, v122 dst_sel:DWORD dst_unused:UNUSED_PAD src0_sel:WORD_1
	v_add_f32_e32 v72, v72, v40
	v_add_f32_e32 v73, v73, v41
	v_mul_f32_e32 v72, 0xbfb8aa3b, v72
	v_pk_mul_f32 v[76:77], v[76:77], v[80:81]
	v_cvt_f32_f16_e32 v80, v121
	v_cvt_pk_f16_f32 v122, v76, v77
	v_add_f32_e32 v77, v78, v50
	v_mul_f32_e32 v77, 0xbfb8aa3b, v77
	v_exp_f32_e32 v77, v77
	v_add_f32_e32 v76, v82, v58
	v_mul_f32_e32 v76, 0xbfb8aa3b, v76
	v_exp_f32_e32 v76, v76
	v_add_f32_e32 v77, 1.0, v77
	v_rcp_f32_e32 v78, v77
	v_add_f32_e32 v77, v83, v59
	v_mul_f32_e32 v77, 0xbfb8aa3b, v77
	v_exp_f32_e32 v77, v77
	v_add_f32_e32 v76, 1.0, v76
	v_rcp_f32_e32 v76, v76
	v_cvt_f32_f16_sdwa v81, v121 dst_sel:DWORD dst_unused:UNUSED_PAD src0_sel:WORD_1
	v_add_f32_e32 v77, 1.0, v77
	v_rcp_f32_e32 v77, v77
	v_mul_f32_e32 v73, 0xbfb8aa3b, v73
	v_exp_f32_e32 v72, v72
	v_exp_f32_e32 v73, v73
	v_pk_mul_f32 v[76:77], v[76:77], v[80:81]
	v_lshlrev_b64 v[118:119], 12, v[118:119]
	v_cvt_pk_f16_f32 v80, v76, v77
	v_add_f32_e32 v76, v79, v51
	v_mul_f32_e32 v76, 0xbfb8aa3b, v76
	v_exp_f32_e32 v76, v76
	v_cvt_f32_f16_sdwa v77, v123 dst_sel:DWORD dst_unused:UNUSED_PAD src0_sel:WORD_1
	v_add_f32_e32 v68, v68, v32
	v_add_f32_e32 v69, v69, v33
	v_add_f32_e32 v76, 1.0, v76
	v_rcp_f32_e32 v79, v76
	v_cvt_f32_f16_e32 v76, v123
	v_add_f32_e32 v72, 1.0, v72
	v_mul_f32_e32 v68, 0xbfb8aa3b, v68
	v_add_f32_e32 v73, 1.0, v73
	v_pk_mul_f32 v[76:77], v[78:79], v[76:77]
	v_mul_f32_e32 v69, 0xbfb8aa3b, v69
	v_cvt_pk_f16_f32 v76, v76, v77
	v_lshrrev_b32_e32 v77, 4, v120
	v_and_b32_e32 v77, 0x10001, v77
	v_add3_u32 v77, v120, v77, s21
	v_and_b32_e32 v78, 0xfff0fff0, v77
	v_lshrrev_b32_e32 v77, 4, v80
	v_and_b32_e32 v77, 0x10001, v77
	v_add3_u32 v77, v80, v77, s21
	v_and_b32_e32 v79, 0xfff0fff0, v77
	v_lshrrev_b32_e32 v77, 4, v122
	v_and_b32_e32 v77, 0x10001, v77
	v_add3_u32 v77, v122, v77, s21
	v_and_b32_e32 v80, 0xfff0fff0, v77
	v_lshrrev_b32_e32 v77, 4, v76
	v_and_b32_e32 v77, 0x10001, v77
	v_add3_u32 v76, v76, v77, s21
	v_and_b32_e32 v81, 0xfff0fff0, v76
	v_lshl_add_u64 v[76:77], s[10:11], 0, v[118:119]
	v_lshl_add_u64 v[76:77], v[76:77], 0, v[190:191]
	global_store_dwordx4 v[76:77], v[78:81], off
	v_rcp_f32_e32 v72, v72
	v_exp_f32_e32 v68, v68
	v_rcp_f32_e32 v73, v73
	v_cvt_f32_f16_e32 v78, v108
	v_cvt_f32_f16_sdwa v79, v108 dst_sel:DWORD dst_unused:UNUSED_PAD src0_sel:WORD_1
	v_exp_f32_e32 v69, v69
	v_add_f32_e32 v68, 1.0, v68
	v_rcp_f32_e32 v68, v68
	v_pk_mul_f32 v[72:73], v[72:73], v[78:79]
	v_add_f32_e32 v69, 1.0, v69
	v_cvt_pk_f16_f32 v78, v72, v73
	v_rcp_f32_e32 v69, v69
	v_cvt_f32_f16_e32 v72, v110
	v_cvt_f32_f16_sdwa v73, v110 dst_sel:DWORD dst_unused:UNUSED_PAD src0_sel:WORD_1
	v_add_f32_e32 v64, v64, v56
	v_add_f32_e32 v65, v65, v57
	v_mul_f32_e32 v64, 0xbfb8aa3b, v64
	v_pk_mul_f32 v[68:69], v[68:69], v[72:73]
	v_cvt_f32_f16_e32 v72, v109
	v_cvt_pk_f16_f32 v79, v68, v69
	v_add_f32_e32 v69, v70, v34
	v_mul_f32_e32 v69, 0xbfb8aa3b, v69
	v_exp_f32_e32 v69, v69
	v_add_f32_e32 v68, v74, v42
	v_mul_f32_e32 v68, 0xbfb8aa3b, v68
	v_exp_f32_e32 v68, v68
	v_add_f32_e32 v69, 1.0, v69
	v_rcp_f32_e32 v70, v69
	v_add_f32_e32 v69, v75, v43
	v_mul_f32_e32 v69, 0xbfb8aa3b, v69
	v_exp_f32_e32 v69, v69
	v_add_f32_e32 v68, 1.0, v68
	v_rcp_f32_e32 v68, v68
	v_cvt_f32_f16_sdwa v73, v109 dst_sel:DWORD dst_unused:UNUSED_PAD src0_sel:WORD_1
	v_add_f32_e32 v69, 1.0, v69
	v_rcp_f32_e32 v69, v69
	v_mul_f32_e32 v65, 0xbfb8aa3b, v65
	v_exp_f32_e32 v64, v64
	v_exp_f32_e32 v65, v65
	v_pk_mul_f32 v[68:69], v[68:69], v[72:73]
	v_add_f32_e32 v60, v60, v48
	v_cvt_pk_f16_f32 v72, v68, v69
	v_add_f32_e32 v68, v71, v35
	v_mul_f32_e32 v68, 0xbfb8aa3b, v68
	v_exp_f32_e32 v68, v68
	v_cvt_f32_f16_sdwa v69, v111 dst_sel:DWORD dst_unused:UNUSED_PAD src0_sel:WORD_1
	v_add_f32_e32 v61, v61, v49
	v_add_f32_e32 v64, 1.0, v64
	v_add_f32_e32 v68, 1.0, v68
	v_rcp_f32_e32 v71, v68
	v_cvt_f32_f16_e32 v68, v111
	v_mul_f32_e32 v60, 0xbfb8aa3b, v60
	v_add_f32_e32 v65, 1.0, v65
	v_mul_f32_e32 v61, 0xbfb8aa3b, v61
	v_pk_mul_f32 v[68:69], v[70:71], v[68:69]
	v_lshrrev_b32_e32 v70, 4, v79
	v_cvt_pk_f16_f32 v71, v68, v69
	v_lshrrev_b32_e32 v69, 4, v72
	v_and_b32_e32 v69, 0x10001, v69
	v_lshrrev_b32_e32 v68, 4, v78
	v_add3_u32 v69, v72, v69, s21
	v_lshrrev_b32_e32 v72, 4, v71
	v_and_b32_e32 v68, 0x10001, v68
	v_and_b32_e32 v70, 0x10001, v70
	v_and_b32_e32 v72, 0x10001, v72
	v_add3_u32 v68, v78, v68, s21
	v_add3_u32 v70, v79, v70, s21
	v_add3_u32 v71, v71, v72, s21
	v_and_b32_e32 v68, 0xfff0fff0, v68
	v_and_b32_e32 v69, 0xfff0fff0, v69
	v_and_b32_e32 v70, 0xfff0fff0, v70
	v_and_b32_e32 v71, 0xfff0fff0, v71
	global_store_dwordx4 v[76:77], v[68:71], off offset:256
	v_rcp_f32_e32 v64, v64
	v_exp_f32_e32 v60, v60
	v_rcp_f32_e32 v65, v65
	v_cvt_f32_f16_e32 v70, v104
	v_cvt_f32_f16_sdwa v71, v104 dst_sel:DWORD dst_unused:UNUSED_PAD src0_sel:WORD_1
	v_exp_f32_e32 v61, v61
	v_add_f32_e32 v60, 1.0, v60
	v_rcp_f32_e32 v60, v60
	v_pk_mul_f32 v[64:65], v[64:65], v[70:71]
	v_add_f32_e32 v61, 1.0, v61
	v_cvt_pk_f16_f32 v70, v64, v65
	v_rcp_f32_e32 v61, v61
	v_cvt_f32_f16_e32 v64, v106
	v_cvt_f32_f16_sdwa v65, v106 dst_sel:DWORD dst_unused:UNUSED_PAD src0_sel:WORD_1
	v_add_f32_e32 v52, v52, v40
	v_add_f32_e32 v53, v53, v41
	v_mul_f32_e32 v52, 0xbfb8aa3b, v52
	v_pk_mul_f32 v[60:61], v[60:61], v[64:65]
	v_cvt_f32_f16_e32 v64, v105
	v_cvt_pk_f16_f32 v71, v60, v61
	v_add_f32_e32 v61, v62, v50
	v_mul_f32_e32 v61, 0xbfb8aa3b, v61
	v_exp_f32_e32 v61, v61
	v_add_f32_e32 v60, v66, v58
	v_mul_f32_e32 v60, 0xbfb8aa3b, v60
	v_exp_f32_e32 v60, v60
	v_add_f32_e32 v61, 1.0, v61
	v_rcp_f32_e32 v62, v61
	v_add_f32_e32 v61, v67, v59
	v_mul_f32_e32 v61, 0xbfb8aa3b, v61
	v_exp_f32_e32 v61, v61
	v_add_f32_e32 v60, 1.0, v60
	v_rcp_f32_e32 v60, v60
	v_cvt_f32_f16_sdwa v65, v105 dst_sel:DWORD dst_unused:UNUSED_PAD src0_sel:WORD_1
	v_add_f32_e32 v61, 1.0, v61
	v_rcp_f32_e32 v61, v61
	v_mul_f32_e32 v53, 0xbfb8aa3b, v53
	v_exp_f32_e32 v52, v52
	v_exp_f32_e32 v53, v53
	v_pk_mul_f32 v[60:61], v[60:61], v[64:65]
	v_lshlrev_b64 v[68:69], 12, v[116:117]
	v_cvt_pk_f16_f32 v64, v60, v61
	v_add_f32_e32 v60, v63, v51
	v_mul_f32_e32 v60, 0xbfb8aa3b, v60
	v_exp_f32_e32 v60, v60
	v_cvt_f32_f16_sdwa v61, v107 dst_sel:DWORD dst_unused:UNUSED_PAD src0_sel:WORD_1
	v_add_f32_e32 v44, v44, v32
	v_add_f32_e32 v45, v45, v33
	v_add_f32_e32 v60, 1.0, v60
	v_rcp_f32_e32 v63, v60
	v_cvt_f32_f16_e32 v60, v107
	v_add_f32_e32 v52, 1.0, v52
	v_mul_f32_e32 v44, 0xbfb8aa3b, v44
	v_add_f32_e32 v53, 1.0, v53
	v_pk_mul_f32 v[60:61], v[62:63], v[60:61]
	v_mul_f32_e32 v45, 0xbfb8aa3b, v45
	v_cvt_pk_f16_f32 v60, v60, v61
	v_lshrrev_b32_e32 v61, 4, v70
	v_and_b32_e32 v61, 0x10001, v61
	v_add3_u32 v61, v70, v61, s21
	v_and_b32_e32 v62, 0xfff0fff0, v61
	v_lshrrev_b32_e32 v61, 4, v64
	v_and_b32_e32 v61, 0x10001, v61
	v_add3_u32 v61, v64, v61, s21
	v_and_b32_e32 v63, 0xfff0fff0, v61
	v_lshrrev_b32_e32 v61, 4, v71
	v_and_b32_e32 v61, 0x10001, v61
	v_add3_u32 v61, v71, v61, s21
	v_and_b32_e32 v64, 0xfff0fff0, v61
	v_lshrrev_b32_e32 v61, 4, v60
	v_and_b32_e32 v61, 0x10001, v61
	v_add3_u32 v60, v60, v61, s21
	v_and_b32_e32 v65, 0xfff0fff0, v60
	v_lshl_add_u64 v[60:61], s[10:11], 0, v[68:69]
	v_lshl_add_u64 v[60:61], v[60:61], 0, v[190:191]
	global_store_dwordx4 v[60:61], v[62:65], off
	v_rcp_f32_e32 v52, v52
	v_exp_f32_e32 v44, v44
	v_rcp_f32_e32 v53, v53
	v_cvt_f32_f16_e32 v62, v100
	v_cvt_f32_f16_sdwa v63, v100 dst_sel:DWORD dst_unused:UNUSED_PAD src0_sel:WORD_1
	v_exp_f32_e32 v45, v45
	v_add_f32_e32 v44, 1.0, v44
	v_rcp_f32_e32 v44, v44
	v_pk_mul_f32 v[52:53], v[52:53], v[62:63]
	v_add_f32_e32 v45, 1.0, v45
	v_cvt_pk_f16_f32 v62, v52, v53
	v_rcp_f32_e32 v45, v45
	v_cvt_f32_f16_e32 v52, v102
	v_cvt_f32_f16_sdwa v53, v102 dst_sel:DWORD dst_unused:UNUSED_PAD src0_sel:WORD_1
	v_add_f32_e32 v36, v36, v56
	v_add_f32_e32 v37, v37, v57
	v_mul_f32_e32 v36, 0xbfb8aa3b, v36
	v_pk_mul_f32 v[44:45], v[44:45], v[52:53]
	v_cvt_f32_f16_e32 v52, v101
	v_cvt_pk_f16_f32 v63, v44, v45
	v_add_f32_e32 v45, v46, v34
	v_mul_f32_e32 v45, 0xbfb8aa3b, v45
	v_exp_f32_e32 v45, v45
	v_add_f32_e32 v44, v54, v42
	v_mul_f32_e32 v44, 0xbfb8aa3b, v44
	v_exp_f32_e32 v44, v44
	v_add_f32_e32 v45, 1.0, v45
	v_rcp_f32_e32 v46, v45
	v_add_f32_e32 v45, v55, v43
	v_mul_f32_e32 v45, 0xbfb8aa3b, v45
	v_exp_f32_e32 v45, v45
	v_add_f32_e32 v44, 1.0, v44
	v_rcp_f32_e32 v44, v44
	v_cvt_f32_f16_sdwa v53, v101 dst_sel:DWORD dst_unused:UNUSED_PAD src0_sel:WORD_1
	v_add_f32_e32 v45, 1.0, v45
	v_rcp_f32_e32 v45, v45
	v_mul_f32_e32 v37, 0xbfb8aa3b, v37
	v_exp_f32_e32 v36, v36
	v_exp_f32_e32 v37, v37
	v_pk_mul_f32 v[44:45], v[44:45], v[52:53]
	v_add_f32_e32 v28, v28, v48
	v_cvt_pk_f16_f32 v52, v44, v45
	v_add_f32_e32 v44, v47, v35
	v_mul_f32_e32 v44, 0xbfb8aa3b, v44
	v_exp_f32_e32 v44, v44
	v_cvt_f32_f16_sdwa v45, v103 dst_sel:DWORD dst_unused:UNUSED_PAD src0_sel:WORD_1
	v_add_f32_e32 v29, v29, v49
	v_add_f32_e32 v36, 1.0, v36
	v_add_f32_e32 v44, 1.0, v44
	v_rcp_f32_e32 v47, v44
	v_cvt_f32_f16_e32 v44, v103
	v_mul_f32_e32 v28, 0xbfb8aa3b, v28
	v_add_f32_e32 v37, 1.0, v37
	v_mul_f32_e32 v29, 0xbfb8aa3b, v29
	v_pk_mul_f32 v[44:45], v[46:47], v[44:45]
	v_lshrrev_b32_e32 v46, 4, v63
	v_cvt_pk_f16_f32 v47, v44, v45
	v_lshrrev_b32_e32 v45, 4, v52
	v_and_b32_e32 v45, 0x10001, v45
	v_lshrrev_b32_e32 v44, 4, v62
	v_add3_u32 v45, v52, v45, s21
	v_lshrrev_b32_e32 v52, 4, v47
	v_and_b32_e32 v44, 0x10001, v44
	v_and_b32_e32 v46, 0x10001, v46
	v_and_b32_e32 v52, 0x10001, v52
	v_add3_u32 v44, v62, v44, s21
	v_add3_u32 v46, v63, v46, s21
	v_add3_u32 v47, v47, v52, s21
	v_and_b32_e32 v44, 0xfff0fff0, v44
	v_and_b32_e32 v45, 0xfff0fff0, v45
	v_and_b32_e32 v46, 0xfff0fff0, v46
	v_and_b32_e32 v47, 0xfff0fff0, v47
	global_store_dwordx4 v[60:61], v[44:47], off offset:256
	v_rcp_f32_e32 v36, v36
	v_exp_f32_e32 v28, v28
	v_rcp_f32_e32 v37, v37
	v_cvt_f32_f16_e32 v46, v96
	v_cvt_f32_f16_sdwa v47, v96 dst_sel:DWORD dst_unused:UNUSED_PAD src0_sel:WORD_1
	v_exp_f32_e32 v29, v29
	v_add_f32_e32 v28, 1.0, v28
	v_rcp_f32_e32 v28, v28
	v_pk_mul_f32 v[36:37], v[36:37], v[46:47]
	v_add_f32_e32 v29, 1.0, v29
	v_cvt_pk_f16_f32 v46, v36, v37
	v_rcp_f32_e32 v29, v29
	v_cvt_f32_f16_e32 v36, v98
	v_cvt_f32_f16_sdwa v37, v98 dst_sel:DWORD dst_unused:UNUSED_PAD src0_sel:WORD_1
	v_add_f32_e32 v24, v24, v40
	v_add_f32_e32 v25, v25, v41
	v_mul_f32_e32 v24, 0xbfb8aa3b, v24
	v_pk_mul_f32 v[28:29], v[28:29], v[36:37]
	v_cvt_f32_f16_e32 v36, v97
	v_cvt_pk_f16_f32 v47, v28, v29
	v_add_f32_e32 v29, v30, v50
	v_mul_f32_e32 v29, 0xbfb8aa3b, v29
	v_exp_f32_e32 v29, v29
	v_add_f32_e32 v28, v38, v58
	v_mul_f32_e32 v28, 0xbfb8aa3b, v28
	v_exp_f32_e32 v28, v28
	v_add_f32_e32 v29, 1.0, v29
	v_rcp_f32_e32 v30, v29
	v_add_f32_e32 v29, v39, v59
	v_mul_f32_e32 v29, 0xbfb8aa3b, v29
	v_exp_f32_e32 v29, v29
	v_add_f32_e32 v28, 1.0, v28
	v_rcp_f32_e32 v28, v28
	v_cvt_f32_f16_sdwa v37, v97 dst_sel:DWORD dst_unused:UNUSED_PAD src0_sel:WORD_1
	v_add_f32_e32 v29, 1.0, v29
	v_rcp_f32_e32 v29, v29
	v_mul_f32_e32 v25, 0xbfb8aa3b, v25
	v_exp_f32_e32 v24, v24
	v_exp_f32_e32 v25, v25
	v_pk_mul_f32 v[28:29], v[28:29], v[36:37]
	v_add_f32_e32 v20, v20, v32
	v_cvt_pk_f16_f32 v37, v28, v29
	v_add_f32_e32 v28, v31, v51
	v_mul_f32_e32 v28, 0xbfb8aa3b, v28
	v_exp_f32_e32 v28, v28
	v_cvt_f32_f16_sdwa v29, v99 dst_sel:DWORD dst_unused:UNUSED_PAD src0_sel:WORD_1
	v_add_f32_e32 v21, v21, v33
	v_add_f32_e32 v24, 1.0, v24
	v_add_f32_e32 v28, 1.0, v28
	v_rcp_f32_e32 v31, v28
	v_cvt_f32_f16_e32 v28, v99
	v_mul_f32_e32 v20, 0xbfb8aa3b, v20
	v_add_f32_e32 v25, 1.0, v25
	v_mul_f32_e32 v21, 0xbfb8aa3b, v21
	v_pk_mul_f32 v[28:29], v[30:31], v[28:29]
	v_rcp_f32_e32 v24, v24
	v_exp_f32_e32 v20, v20
	v_rcp_f32_e32 v25, v25
	v_cvt_f32_f16_e32 v30, v92
	v_cvt_f32_f16_sdwa v31, v92 dst_sel:DWORD dst_unused:UNUSED_PAD src0_sel:WORD_1
	v_exp_f32_e32 v21, v21
	v_add_f32_e32 v20, 1.0, v20
	v_rcp_f32_e32 v20, v20
	v_pk_mul_f32 v[24:25], v[24:25], v[30:31]
	v_add_f32_e32 v21, 1.0, v21
	v_cvt_pk_f16_f32 v30, v24, v25
	v_rcp_f32_e32 v21, v21
	v_cvt_f32_f16_e32 v24, v94
	v_cvt_f32_f16_sdwa v25, v94 dst_sel:DWORD dst_unused:UNUSED_PAD src0_sel:WORD_1
	v_cvt_pk_f16_f32 v28, v28, v29
	v_lshrrev_b32_e32 v29, 4, v46
	v_and_b32_e32 v29, 0x10001, v29
	v_pk_mul_f32 v[20:21], v[20:21], v[24:25]
	v_cvt_f32_f16_e32 v24, v93
	v_cvt_pk_f16_f32 v31, v20, v21
	v_add_f32_e32 v21, v22, v34
	v_mul_f32_e32 v21, 0xbfb8aa3b, v21
	v_exp_f32_e32 v21, v21
	v_add_f32_e32 v20, v26, v42
	v_mul_f32_e32 v20, 0xbfb8aa3b, v20
	v_exp_f32_e32 v20, v20
	v_add_f32_e32 v21, 1.0, v21
	v_rcp_f32_e32 v22, v21
	v_add_f32_e32 v21, v27, v43
	v_mul_f32_e32 v21, 0xbfb8aa3b, v21
	v_exp_f32_e32 v21, v21
	v_add_f32_e32 v20, 1.0, v20
	v_rcp_f32_e32 v20, v20
	v_cvt_f32_f16_sdwa v25, v93 dst_sel:DWORD dst_unused:UNUSED_PAD src0_sel:WORD_1
	v_add_f32_e32 v21, 1.0, v21
	v_rcp_f32_e32 v21, v21
	v_add3_u32 v29, v46, v29, s21
	v_and_b32_e32 v36, 0xfff0fff0, v29
	v_lshrrev_b32_e32 v29, 4, v37
	v_pk_mul_f32 v[20:21], v[20:21], v[24:25]
	v_and_b32_e32 v29, 0x10001, v29
	v_cvt_pk_f16_f32 v24, v20, v21
	v_add_f32_e32 v20, v23, v35
	v_mul_f32_e32 v20, 0xbfb8aa3b, v20
	v_exp_f32_e32 v20, v20
	v_cvt_f32_f16_sdwa v21, v95 dst_sel:DWORD dst_unused:UNUSED_PAD src0_sel:WORD_1
	v_add3_u32 v29, v37, v29, s21
	v_and_b32_e32 v37, 0xfff0fff0, v29
	v_add_f32_e32 v20, 1.0, v20
	v_rcp_f32_e32 v23, v20
	v_cvt_f32_f16_e32 v20, v95
	v_lshrrev_b32_e32 v29, 4, v47
	v_and_b32_e32 v29, 0x10001, v29
	v_add_f32_e32 v16, v16, v56
	v_pk_mul_f32 v[20:21], v[22:23], v[20:21]
	v_add_f32_e32 v17, v17, v57
	v_add3_u32 v29, v47, v29, s21
	v_cvt_pk_f16_f32 v23, v20, v21
	v_lshrrev_b32_e32 v21, 4, v24
	v_mul_f32_e32 v16, 0xbfb8aa3b, v16
	v_mul_f32_e32 v17, 0xbfb8aa3b, v17
	v_and_b32_e32 v38, 0xfff0fff0, v29
	v_lshrrev_b32_e32 v29, 4, v28
	v_and_b32_e32 v21, 0x10001, v21
	v_exp_f32_e32 v16, v16
	v_exp_f32_e32 v17, v17
	v_and_b32_e32 v29, 0x10001, v29
	v_lshrrev_b32_e32 v20, 4, v30
	v_add3_u32 v21, v24, v21, s21
	v_lshrrev_b32_e32 v22, 4, v31
	v_lshrrev_b32_e32 v24, 4, v23
	v_lshlrev_b64 v[44:45], 12, v[114:115]
	v_add3_u32 v28, v28, v29, s21
	v_and_b32_e32 v20, 0x10001, v20
	v_and_b32_e32 v22, 0x10001, v22
	v_and_b32_e32 v24, 0x10001, v24
	v_and_b32_e32 v39, 0xfff0fff0, v28
	v_lshl_add_u64 v[28:29], s[10:11], 0, v[44:45]
	v_add3_u32 v20, v30, v20, s21
	v_add3_u32 v22, v31, v22, s21
	v_add3_u32 v23, v23, v24, s21
	v_add_f32_e32 v12, v12, v48
	v_add_f32_e32 v13, v13, v49
	v_lshl_add_u64 v[28:29], v[28:29], 0, v[190:191]
	v_and_b32_e32 v20, 0xfff0fff0, v20
	v_and_b32_e32 v21, 0xfff0fff0, v21
	v_and_b32_e32 v22, 0xfff0fff0, v22
	v_and_b32_e32 v23, 0xfff0fff0, v23
	v_add_f32_e32 v16, 1.0, v16
	v_mul_f32_e32 v12, 0xbfb8aa3b, v12
	v_add_f32_e32 v17, 1.0, v17
	v_mul_f32_e32 v13, 0xbfb8aa3b, v13
	global_store_dwordx4 v[28:29], v[20:23], off offset:256
	v_rcp_f32_e32 v16, v16
	v_exp_f32_e32 v12, v12
	v_rcp_f32_e32 v17, v17
	v_cvt_f32_f16_e32 v22, v88
	v_cvt_f32_f16_sdwa v23, v88 dst_sel:DWORD dst_unused:UNUSED_PAD src0_sel:WORD_1
	v_exp_f32_e32 v13, v13
	v_add_f32_e32 v12, 1.0, v12
	v_rcp_f32_e32 v12, v12
	v_pk_mul_f32 v[16:17], v[16:17], v[22:23]
	v_add_f32_e32 v13, 1.0, v13
	v_cvt_pk_f16_f32 v22, v16, v17
	v_rcp_f32_e32 v13, v13
	v_cvt_f32_f16_e32 v16, v90
	v_cvt_f32_f16_sdwa v17, v90 dst_sel:DWORD dst_unused:UNUSED_PAD src0_sel:WORD_1
	v_add_f32_e32 v8, v8, v40
	v_add_f32_e32 v9, v9, v41
	v_mul_f32_e32 v8, 0xbfb8aa3b, v8
	v_pk_mul_f32 v[12:13], v[12:13], v[16:17]
	v_cvt_f32_f16_e32 v16, v89
	v_cvt_pk_f16_f32 v23, v12, v13
	v_add_f32_e32 v13, v14, v50
	v_mul_f32_e32 v13, 0xbfb8aa3b, v13
	v_exp_f32_e32 v13, v13
	v_add_f32_e32 v12, v18, v58
	v_mul_f32_e32 v12, 0xbfb8aa3b, v12
	v_exp_f32_e32 v12, v12
	v_add_f32_e32 v13, 1.0, v13
	v_rcp_f32_e32 v14, v13
	v_add_f32_e32 v13, v19, v59
	v_mul_f32_e32 v13, 0xbfb8aa3b, v13
	v_exp_f32_e32 v13, v13
	v_add_f32_e32 v12, 1.0, v12
	v_rcp_f32_e32 v12, v12
	v_cvt_f32_f16_sdwa v17, v89 dst_sel:DWORD dst_unused:UNUSED_PAD src0_sel:WORD_1
	v_add_f32_e32 v13, 1.0, v13
	v_rcp_f32_e32 v13, v13
	v_mul_f32_e32 v9, 0xbfb8aa3b, v9
	v_exp_f32_e32 v8, v8
	v_exp_f32_e32 v9, v9
	v_pk_mul_f32 v[12:13], v[12:13], v[16:17]
	v_lshlrev_b64 v[20:21], 12, v[112:113]
	v_cvt_pk_f16_f32 v16, v12, v13
	v_add_f32_e32 v12, v15, v51
	v_mul_f32_e32 v12, 0xbfb8aa3b, v12
	v_exp_f32_e32 v12, v12
	v_cvt_f32_f16_sdwa v13, v91 dst_sel:DWORD dst_unused:UNUSED_PAD src0_sel:WORD_1
	v_add_f32_e32 v4, v4, v32
	v_add_f32_e32 v5, v5, v33
	v_add_f32_e32 v12, 1.0, v12
	v_rcp_f32_e32 v15, v12
	v_cvt_f32_f16_e32 v12, v91
	v_add_f32_e32 v8, 1.0, v8
	v_mul_f32_e32 v4, 0xbfb8aa3b, v4
	v_add_f32_e32 v9, 1.0, v9
	v_pk_mul_f32 v[12:13], v[14:15], v[12:13]
	v_mul_f32_e32 v5, 0xbfb8aa3b, v5
	v_cvt_pk_f16_f32 v12, v12, v13
	v_lshrrev_b32_e32 v13, 4, v22
	v_and_b32_e32 v13, 0x10001, v13
	v_add3_u32 v13, v22, v13, s21
	v_and_b32_e32 v14, 0xfff0fff0, v13
	v_lshrrev_b32_e32 v13, 4, v16
	v_and_b32_e32 v13, 0x10001, v13
	v_add3_u32 v13, v16, v13, s21
	v_and_b32_e32 v15, 0xfff0fff0, v13
	v_lshrrev_b32_e32 v13, 4, v23
	v_and_b32_e32 v13, 0x10001, v13
	v_add3_u32 v13, v23, v13, s21
	v_and_b32_e32 v16, 0xfff0fff0, v13
	v_lshrrev_b32_e32 v13, 4, v12
	v_and_b32_e32 v13, 0x10001, v13
	v_add3_u32 v12, v12, v13, s21
	v_and_b32_e32 v17, 0xfff0fff0, v12
	v_lshl_add_u64 v[12:13], s[10:11], 0, v[20:21]
	v_lshl_add_u64 v[12:13], v[12:13], 0, v[190:191]
	global_store_dwordx4 v[12:13], v[14:17], off
	v_rcp_f32_e32 v8, v8
	v_exp_f32_e32 v4, v4
	v_rcp_f32_e32 v9, v9
	v_cvt_f32_f16_e32 v14, v84
	v_cvt_f32_f16_sdwa v15, v84 dst_sel:DWORD dst_unused:UNUSED_PAD src0_sel:WORD_1
	v_exp_f32_e32 v5, v5
	v_add_f32_e32 v4, 1.0, v4
	v_rcp_f32_e32 v4, v4
	v_pk_mul_f32 v[8:9], v[8:9], v[14:15]
	v_add_f32_e32 v5, 1.0, v5
	v_cvt_pk_f16_f32 v14, v8, v9
	v_rcp_f32_e32 v5, v5
	v_cvt_f32_f16_e32 v8, v86
	v_cvt_f32_f16_sdwa v9, v86 dst_sel:DWORD dst_unused:UNUSED_PAD src0_sel:WORD_1
	global_store_dwordx4 v[28:29], v[36:39], off
	v_pk_mul_f32 v[4:5], v[4:5], v[8:9]
	s_nop 0
	v_cvt_pk_f16_f32 v15, v4, v5
	v_add_f32_e32 v5, v6, v34
	v_mul_f32_e32 v5, 0xbfb8aa3b, v5
	v_exp_f32_e32 v5, v5
	v_add_f32_e32 v4, v10, v42
	v_mul_f32_e32 v4, 0xbfb8aa3b, v4
	v_exp_f32_e32 v4, v4
	v_add_f32_e32 v5, 1.0, v5
	v_rcp_f32_e32 v6, v5
	v_add_f32_e32 v5, v11, v43
	v_mul_f32_e32 v5, 0xbfb8aa3b, v5
	v_exp_f32_e32 v5, v5
	v_add_f32_e32 v4, 1.0, v4
	v_rcp_f32_e32 v4, v4
	v_cvt_f32_f16_e32 v8, v85
	v_add_f32_e32 v5, 1.0, v5
	v_rcp_f32_e32 v5, v5
	v_cvt_f32_f16_sdwa v9, v85 dst_sel:DWORD dst_unused:UNUSED_PAD src0_sel:WORD_1
	v_pk_mul_f32 v[4:5], v[4:5], v[8:9]
	s_nop 0
	v_cvt_pk_f16_f32 v8, v4, v5
	v_add_f32_e32 v4, v7, v35
	v_mul_f32_e32 v4, 0xbfb8aa3b, v4
	v_exp_f32_e32 v4, v4
	v_cvt_f32_f16_sdwa v5, v87 dst_sel:DWORD dst_unused:UNUSED_PAD src0_sel:WORD_1
	v_add_f32_e32 v4, 1.0, v4
	v_rcp_f32_e32 v7, v4
	v_cvt_f32_f16_e32 v4, v87
	v_pk_mul_f32 v[4:5], v[6:7], v[4:5]
	s_nop 0
	v_cvt_pk_f16_f32 v7, v4, v5
	v_lshrrev_b32_e32 v5, 4, v8
	v_and_b32_e32 v5, 0x10001, v5
	v_lshrrev_b32_e32 v4, 4, v14
	v_add3_u32 v5, v8, v5, s21
	v_lshrrev_b32_e32 v6, 4, v15
	v_lshrrev_b32_e32 v8, 4, v7
	v_and_b32_e32 v4, 0x10001, v4
	v_and_b32_e32 v6, 0x10001, v6
	v_and_b32_e32 v8, 0x10001, v8
	v_add3_u32 v4, v14, v4, s21
	v_add3_u32 v6, v15, v6, s21
	v_add3_u32 v7, v7, v8, s21
	v_and_b32_e32 v4, 0xfff0fff0, v4
	v_and_b32_e32 v5, 0xfff0fff0, v5
	v_and_b32_e32 v6, 0xfff0fff0, v6
	v_and_b32_e32 v7, 0xfff0fff0, v7
	global_store_dwordx4 v[12:13], v[4:7], off offset:256
	s_cbranch_vccz .LBB0_1657
	s_waitcnt vmcnt(0)
	s_cmpk_gt_u32 s4, 0xff
	s_cbranch_scc1 .LBB0_1668
	s_barrier

.LBB0_1742:
	s_add_i32 s19, 0, 0x10000
	v_add_u32_e32 v237, s19, v235
	ds_read_b128 v[134:137], v237
	ds_read_b128 v[138:141], v237 offset:1024
	ds_read_b128 v[142:145], v237 offset:2048
	ds_read_b128 v[146:149], v237 offset:3072
	v_lshl_add_u64 v[198:199], v[132:133], 0, s[16:17]
	s_add_i32 s14, s7, 0xc000
	v_lshl_add_u64 v[182:183], v[198:199], 0, s[26:27]
	s_mov_b32 m0, s14
	v_lshl_add_u64 v[242:243], v[200:201], 0, s[16:17]
	s_add_i32 s15, s7, 0xe000
	ds_read_b128 v[150:153], v236
	ds_read_b128 v[154:157], v236 offset:1024
	ds_read_b128 v[158:161], v236 offset:2048
	ds_read_b128 v[162:165], v236 offset:3072
	ds_read_b128 v[166:169], v236 offset:4096
	ds_read_b128 v[170:173], v236 offset:5120
	ds_read_b128 v[174:177], v236 offset:6144
	ds_read_b128 v[178:181], v236 offset:7168
	global_load_lds_dwordx4 v[182:183], off
	v_lshl_add_u64 v[182:183], v[242:243], 0, s[26:27]
	s_mov_b32 m0, s15
	s_nop 0
	global_load_lds_dwordx4 v[182:183], off
	s_waitcnt lgkmcnt(8)
	s_barrier
	s_waitcnt lgkmcnt(0)
	s_waitcnt lgkmcnt(0)
	v_mfma_f32_16x16x32_f16 v[80:83], v[134:137], v[150:153], v[80:83]
	v_mfma_f32_16x16x32_f16 v[72:75], v[142:145], v[150:153], v[72:75]
	v_mfma_f32_16x16x32_f16 v[56:59], v[134:137], v[158:161], v[56:59]
	v_mfma_f32_16x16x32_f16 v[68:71], v[142:145], v[158:161], v[68:71]
	v_mfma_f32_16x16x32_f16 v[128:131], v[134:137], v[166:169], v[128:131]
	v_mfma_f32_16x16x32_f16 v[124:127], v[142:145], v[166:169], v[124:127]
	v_mfma_f32_16x16x32_f16 v[116:119], v[134:137], v[174:177], v[116:119]
	v_mfma_f32_16x16x32_f16 v[108:111], v[142:145], v[174:177], v[108:111]
	v_mfma_f32_16x16x32_f16 v[80:83], v[138:141], v[154:157], v[80:83]
	v_mfma_f32_16x16x32_f16 v[72:75], v[146:149], v[154:157], v[72:75]
	v_mfma_f32_16x16x32_f16 v[56:59], v[138:141], v[162:165], v[56:59]
	v_mfma_f32_16x16x32_f16 v[68:71], v[146:149], v[162:165], v[68:71]
	v_mfma_f32_16x16x32_f16 v[128:131], v[138:141], v[170:173], v[128:131]
	v_mfma_f32_16x16x32_f16 v[124:127], v[146:149], v[170:173], v[124:127]
	v_mfma_f32_16x16x32_f16 v[116:119], v[138:141], v[178:181], v[116:119]
	v_mfma_f32_16x16x32_f16 v[108:111], v[146:149], v[178:181], v[108:111]
	s_barrier
	s_add_i32 s63, 0, 0x14000
	v_lshl_add_u64 v[244:245], v[202:203], 0, s[16:17]
	s_add_i32 s19, s19, s5
	v_add_u32_e32 v238, s63, v235
	v_lshl_add_u64 v[240:241], v[244:245], 0, s[30:31]
	s_mov_b32 m0, s19
	v_lshl_add_u64 v[246:247], v[220:221], 0, s[16:17]
	s_add_i32 s37, s19, 0x2000
	ds_read_b128 v[182:185], v238
	ds_read_b128 v[186:189], v238 offset:1024
	ds_read_b128 v[190:193], v238 offset:2048
	ds_read_b128 v[194:197], v238 offset:3072
	global_load_lds_dwordx4 v[240:241], off
	v_lshl_add_u64 v[240:241], v[246:247], 0, s[30:31]
	s_mov_b32 m0, s37
	s_nop 0
	global_load_lds_dwordx4 v[240:241], off
	s_barrier
	s_waitcnt lgkmcnt(0)
	s_waitcnt lgkmcnt(0)
	v_mfma_f32_16x16x32_f16 v[52:55], v[182:185], v[150:153], v[52:55]
	v_mfma_f32_16x16x32_f16 v[40:43], v[190:193], v[150:153], v[40:43]
	v_mfma_f32_16x16x32_f16 v[36:39], v[182:185], v[158:161], v[36:39]
	v_mfma_f32_16x16x32_f16 v[28:31], v[190:193], v[158:161], v[28:31]
	v_mfma_f32_16x16x32_f16 v[120:123], v[182:185], v[166:169], v[120:123]
	v_mfma_f32_16x16x32_f16 v[112:115], v[190:193], v[166:169], v[112:115]
	v_mfma_f32_16x16x32_f16 v[104:107], v[182:185], v[174:177], v[104:107]
	v_mfma_f32_16x16x32_f16 v[100:103], v[190:193], v[174:177], v[100:103]
	v_mfma_f32_16x16x32_f16 v[52:55], v[186:189], v[154:157], v[52:55]
	v_mfma_f32_16x16x32_f16 v[40:43], v[194:197], v[154:157], v[40:43]
	v_mfma_f32_16x16x32_f16 v[36:39], v[186:189], v[162:165], v[36:39]
	v_mfma_f32_16x16x32_f16 v[28:31], v[194:197], v[162:165], v[28:31]
	v_mfma_f32_16x16x32_f16 v[120:123], v[186:189], v[170:173], v[120:123]
	v_mfma_f32_16x16x32_f16 v[112:115], v[194:197], v[170:173], v[112:115]
	v_mfma_f32_16x16x32_f16 v[104:107], v[186:189], v[178:181], v[104:107]
	v_mfma_f32_16x16x32_f16 v[100:103], v[194:197], v[178:181], v[100:103]
	s_mov_b32 m0, s7
	v_lshl_add_u64 v[240:241], v[198:199], 0, s[30:31]
	s_barrier
	ds_read_b128 v[150:153], v236 offset:16384
	ds_read_b128 v[154:157], v236 offset:17408
	ds_read_b128 v[158:161], v236 offset:18432
	ds_read_b128 v[162:165], v236 offset:19456
	ds_read_b128 v[166:169], v236 offset:20480
	ds_read_b128 v[170:173], v236 offset:21504
	ds_read_b128 v[174:177], v236 offset:22528
	ds_read_b128 v[178:181], v236 offset:23552
	global_load_lds_dwordx4 v[240:241], off
	v_lshl_add_u64 v[240:241], v[242:243], 0, s[30:31]
	s_mov_b32 m0, s8
	s_nop 0
	global_load_lds_dwordx4 v[240:241], off
	s_barrier
	s_waitcnt lgkmcnt(0)
	s_waitcnt lgkmcnt(0)
	v_mfma_f32_16x16x32_f16 v[96:99], v[134:137], v[150:153], v[96:99]
	v_mfma_f32_16x16x32_f16 v[92:95], v[142:145], v[150:153], v[92:95]
	v_mfma_f32_16x16x32_f16 v[76:79], v[134:137], v[158:161], v[76:79]
	v_mfma_f32_16x16x32_f16 v[64:67], v[142:145], v[158:161], v[64:67]
	v_mfma_f32_16x16x32_f16 v[44:47], v[134:137], v[166:169], v[44:47]
	v_mfma_f32_16x16x32_f16 v[32:35], v[142:145], v[166:169], v[32:35]
	v_mfma_f32_16x16x32_f16 v[16:19], v[134:137], v[174:177], v[16:19]
	v_mfma_f32_16x16x32_f16 v[12:15], v[142:145], v[174:177], v[12:15]
	v_mfma_f32_16x16x32_f16 v[96:99], v[138:141], v[154:157], v[96:99]
	v_mfma_f32_16x16x32_f16 v[92:95], v[146:149], v[154:157], v[92:95]
	v_mfma_f32_16x16x32_f16 v[76:79], v[138:141], v[162:165], v[76:79]
	v_mfma_f32_16x16x32_f16 v[64:67], v[146:149], v[162:165], v[64:67]
	v_mfma_f32_16x16x32_f16 v[44:47], v[138:141], v[170:173], v[44:47]
	v_mfma_f32_16x16x32_f16 v[32:35], v[146:149], v[170:173], v[32:35]
	v_mfma_f32_16x16x32_f16 v[16:19], v[138:141], v[178:181], v[16:19]
	v_mfma_f32_16x16x32_f16 v[12:15], v[146:149], v[178:181], v[12:15]
	s_barrier
	s_add_i32 s63, s63, s5
	v_lshl_add_u64 v[134:135], v[244:245], 0, s[84:85]
	s_mov_b32 m0, s63
	s_add_i32 s68, s63, 0x2000
	global_load_lds_dwordx4 v[134:135], off
	v_lshl_add_u64 v[134:135], v[246:247], 0, s[84:85]
	s_mov_b32 m0, s68
	s_nop 0
	global_load_lds_dwordx4 v[134:135], off
	s_waitcnt vmcnt(6)
	s_barrier
	v_mfma_f32_16x16x32_f16 v[88:91], v[182:185], v[150:153], v[88:91]
	v_mfma_f32_16x16x32_f16 v[84:87], v[190:193], v[150:153], v[84:87]
	v_mfma_f32_16x16x32_f16 v[60:63], v[182:185], v[158:161], v[60:63]
	v_mfma_f32_16x16x32_f16 v[48:51], v[190:193], v[158:161], v[48:51]
	v_mfma_f32_16x16x32_f16 v[24:27], v[182:185], v[166:169], v[24:27]
	v_mfma_f32_16x16x32_f16 v[20:23], v[190:193], v[166:169], v[20:23]
	v_mfma_f32_16x16x32_f16 v[8:11], v[182:185], v[174:177], v[8:11]
	v_mfma_f32_16x16x32_f16 v[4:7], v[190:193], v[174:177], v[4:7]
	v_mfma_f32_16x16x32_f16 v[88:91], v[186:189], v[154:157], v[88:91]
	v_mfma_f32_16x16x32_f16 v[84:87], v[194:197], v[154:157], v[84:87]
	v_mfma_f32_16x16x32_f16 v[60:63], v[186:189], v[162:165], v[60:63]
	v_mfma_f32_16x16x32_f16 v[48:51], v[194:197], v[162:165], v[48:51]
	v_mfma_f32_16x16x32_f16 v[24:27], v[186:189], v[170:173], v[24:27]
	v_mfma_f32_16x16x32_f16 v[20:23], v[194:197], v[170:173], v[20:23]
	v_mfma_f32_16x16x32_f16 v[8:11], v[186:189], v[178:181], v[8:11]
	v_mfma_f32_16x16x32_f16 v[4:7], v[194:197], v[178:181], v[4:7]
	s_add_i32 s69, 0, 0x18000
	v_add_u32_e32 v239, s69, v235
	s_barrier
	ds_read_b128 v[134:137], v239
	ds_read_b128 v[138:141], v239 offset:1024
	ds_read_b128 v[142:145], v239 offset:2048
	ds_read_b128 v[146:149], v239 offset:3072
	s_mov_b32 m0, s9
	v_lshl_add_u64 v[182:183], v[198:199], 0, s[84:85]
	ds_read_b128 v[150:153], v236 offset:32768
	ds_read_b128 v[154:157], v236 offset:33792
	ds_read_b128 v[158:161], v236 offset:34816
	ds_read_b128 v[162:165], v236 offset:35840
	ds_read_b128 v[166:169], v236 offset:36864
	ds_read_b128 v[170:173], v236 offset:37888
	ds_read_b128 v[174:177], v236 offset:38912
	ds_read_b128 v[178:181], v236 offset:39936
	global_load_lds_dwordx4 v[182:183], off
	v_lshl_add_u64 v[182:183], v[242:243], 0, s[84:85]
	s_mov_b32 m0, s12
	s_nop 0
	global_load_lds_dwordx4 v[182:183], off
	s_waitcnt lgkmcnt(8)
	s_barrier
	s_waitcnt lgkmcnt(0)
	s_waitcnt lgkmcnt(0)
	v_mfma_f32_16x16x32_f16 v[80:83], v[134:137], v[150:153], v[80:83]
	v_mfma_f32_16x16x32_f16 v[72:75], v[142:145], v[150:153], v[72:75]
	v_mfma_f32_16x16x32_f16 v[56:59], v[134:137], v[158:161], v[56:59]
	v_mfma_f32_16x16x32_f16 v[68:71], v[142:145], v[158:161], v[68:71]
	v_mfma_f32_16x16x32_f16 v[128:131], v[134:137], v[166:169], v[128:131]
	v_mfma_f32_16x16x32_f16 v[124:127], v[142:145], v[166:169], v[124:127]
	v_mfma_f32_16x16x32_f16 v[116:119], v[134:137], v[174:177], v[116:119]
	v_mfma_f32_16x16x32_f16 v[108:111], v[142:145], v[174:177], v[108:111]
	v_mfma_f32_16x16x32_f16 v[80:83], v[138:141], v[154:157], v[80:83]
	v_mfma_f32_16x16x32_f16 v[72:75], v[146:149], v[154:157], v[72:75]
	v_mfma_f32_16x16x32_f16 v[56:59], v[138:141], v[162:165], v[56:59]
	v_mfma_f32_16x16x32_f16 v[68:71], v[146:149], v[162:165], v[68:71]
	v_mfma_f32_16x16x32_f16 v[128:131], v[138:141], v[170:173], v[128:131]
	v_mfma_f32_16x16x32_f16 v[124:127], v[146:149], v[170:173], v[124:127]
	v_mfma_f32_16x16x32_f16 v[116:119], v[138:141], v[178:181], v[116:119]
	v_mfma_f32_16x16x32_f16 v[108:111], v[146:149], v[178:181], v[108:111]
	s_barrier
	s_add_i32 s71, 0, 0x1c000
	s_add_i32 s69, s69, s5
	v_add_u32_e32 v240, s71, v235
	v_lshl_add_u64 v[248:249], v[244:245], 0, s[78:79]
	s_mov_b32 m0, s69
	s_add_i32 s70, s69, 0x2000
	ds_read_b128 v[182:185], v240
	ds_read_b128 v[186:189], v240 offset:1024
	ds_read_b128 v[190:193], v240 offset:2048
	ds_read_b128 v[194:197], v240 offset:3072
	global_load_lds_dwordx4 v[248:249], off
	v_lshl_add_u64 v[248:249], v[246:247], 0, s[78:79]
	s_mov_b32 m0, s70
	s_nop 0
	global_load_lds_dwordx4 v[248:249], off
	s_barrier
	s_waitcnt lgkmcnt(0)
	s_waitcnt lgkmcnt(0)
	v_mfma_f32_16x16x32_f16 v[52:55], v[182:185], v[150:153], v[52:55]
	v_mfma_f32_16x16x32_f16 v[40:43], v[190:193], v[150:153], v[40:43]
	v_mfma_f32_16x16x32_f16 v[36:39], v[182:185], v[158:161], v[36:39]
	v_mfma_f32_16x16x32_f16 v[28:31], v[190:193], v[158:161], v[28:31]
	v_mfma_f32_16x16x32_f16 v[120:123], v[182:185], v[166:169], v[120:123]
	v_mfma_f32_16x16x32_f16 v[112:115], v[190:193], v[166:169], v[112:115]
	v_mfma_f32_16x16x32_f16 v[104:107], v[182:185], v[174:177], v[104:107]
	v_mfma_f32_16x16x32_f16 v[100:103], v[190:193], v[174:177], v[100:103]
	v_mfma_f32_16x16x32_f16 v[52:55], v[186:189], v[154:157], v[52:55]
	v_mfma_f32_16x16x32_f16 v[40:43], v[194:197], v[154:157], v[40:43]
	v_mfma_f32_16x16x32_f16 v[36:39], v[186:189], v[162:165], v[36:39]
	v_mfma_f32_16x16x32_f16 v[28:31], v[194:197], v[162:165], v[28:31]
	v_mfma_f32_16x16x32_f16 v[120:123], v[186:189], v[170:173], v[120:123]
	v_mfma_f32_16x16x32_f16 v[112:115], v[194:197], v[170:173], v[112:115]
	v_mfma_f32_16x16x32_f16 v[104:107], v[186:189], v[178:181], v[104:107]
	v_mfma_f32_16x16x32_f16 v[100:103], v[194:197], v[178:181], v[100:103]
	s_mov_b32 m0, s39
	v_lshl_add_u64 v[198:199], v[198:199], 0, s[78:79]
	s_barrier
	ds_read_b128 v[150:153], v236 offset:49152
	ds_read_b128 v[154:157], v236 offset:50176
	ds_read_b128 v[158:161], v236 offset:51200
	ds_read_b128 v[162:165], v236 offset:52224
	ds_read_b128 v[166:169], v236 offset:53248
	ds_read_b128 v[170:173], v236 offset:54272
	ds_read_b128 v[174:177], v236 offset:55296
	ds_read_b128 v[178:181], v236 offset:56320
	global_load_lds_dwordx4 v[198:199], off
	v_lshl_add_u64 v[198:199], v[242:243], 0, s[78:79]
	s_mov_b32 m0, s47
	s_nop 0
	global_load_lds_dwordx4 v[198:199], off
	s_barrier
	s_waitcnt lgkmcnt(0)
	s_waitcnt lgkmcnt(0)
	v_mfma_f32_16x16x32_f16 v[96:99], v[134:137], v[150:153], v[96:99]
	v_mfma_f32_16x16x32_f16 v[92:95], v[142:145], v[150:153], v[92:95]
	v_mfma_f32_16x16x32_f16 v[76:79], v[134:137], v[158:161], v[76:79]
	v_mfma_f32_16x16x32_f16 v[64:67], v[142:145], v[158:161], v[64:67]
	v_mfma_f32_16x16x32_f16 v[44:47], v[134:137], v[166:169], v[44:47]
	v_mfma_f32_16x16x32_f16 v[32:35], v[142:145], v[166:169], v[32:35]
	v_mfma_f32_16x16x32_f16 v[16:19], v[134:137], v[174:177], v[16:19]
	v_mfma_f32_16x16x32_f16 v[12:15], v[142:145], v[174:177], v[12:15]
	v_mfma_f32_16x16x32_f16 v[96:99], v[138:141], v[154:157], v[96:99]
	v_mfma_f32_16x16x32_f16 v[92:95], v[146:149], v[154:157], v[92:95]
	v_mfma_f32_16x16x32_f16 v[76:79], v[138:141], v[162:165], v[76:79]
	v_mfma_f32_16x16x32_f16 v[64:67], v[146:149], v[162:165], v[64:67]
	v_mfma_f32_16x16x32_f16 v[44:47], v[138:141], v[170:173], v[44:47]
	v_mfma_f32_16x16x32_f16 v[32:35], v[146:149], v[170:173], v[32:35]
	v_mfma_f32_16x16x32_f16 v[16:19], v[138:141], v[178:181], v[16:19]
	v_mfma_f32_16x16x32_f16 v[12:15], v[146:149], v[178:181], v[12:15]
	s_barrier
	s_add_i32 s71, s71, s5
	v_lshl_add_u64 v[134:135], v[244:245], 0, vcc
	s_mov_b32 m0, s71
	s_add_i32 s76, s71, 0x2000
	global_load_lds_dwordx4 v[134:135], off
	v_lshl_add_u64 v[134:135], v[246:247], 0, vcc
	s_mov_b32 m0, s76
	s_nop 0
	global_load_lds_dwordx4 v[134:135], off
	s_waitcnt vmcnt(6)
	s_barrier
	v_mfma_f32_16x16x32_f16 v[88:91], v[182:185], v[150:153], v[88:91]
	v_mfma_f32_16x16x32_f16 v[84:87], v[190:193], v[150:153], v[84:87]
	v_mfma_f32_16x16x32_f16 v[60:63], v[182:185], v[158:161], v[60:63]
	v_mfma_f32_16x16x32_f16 v[48:51], v[190:193], v[158:161], v[48:51]
	v_mfma_f32_16x16x32_f16 v[24:27], v[182:185], v[166:169], v[24:27]
	v_mfma_f32_16x16x32_f16 v[20:23], v[190:193], v[166:169], v[20:23]
	v_mfma_f32_16x16x32_f16 v[8:11], v[182:185], v[174:177], v[8:11]
	v_mfma_f32_16x16x32_f16 v[4:7], v[190:193], v[174:177], v[4:7]
	v_mfma_f32_16x16x32_f16 v[88:91], v[186:189], v[154:157], v[88:91]
	v_mfma_f32_16x16x32_f16 v[84:87], v[194:197], v[154:157], v[84:87]
	v_mfma_f32_16x16x32_f16 v[60:63], v[186:189], v[162:165], v[60:63]
	v_mfma_f32_16x16x32_f16 v[48:51], v[194:197], v[162:165], v[48:51]
	v_mfma_f32_16x16x32_f16 v[24:27], v[186:189], v[170:173], v[24:27]
	v_mfma_f32_16x16x32_f16 v[20:23], v[194:197], v[170:173], v[20:23]
	v_mfma_f32_16x16x32_f16 v[8:11], v[186:189], v[178:181], v[8:11]
	v_mfma_f32_16x16x32_f16 v[4:7], v[194:197], v[178:181], v[4:7]
	s_add_i32 s10, s10, 2
	s_add_u32 s16, s16, 0x100
	s_addc_u32 s17, s17, 0
	s_cmp_lt_u32 s10, 6
	s_barrier
	s_cbranch_scc1 .LBB0_1742
	s_ashr_i32 s78, s48, 31
	s_mul_i32 s10, s46, 0x42
	s_mul_hi_i32 s11, s46, 0x42
	s_add_u32 s10, s10, s48
	v_mov_b32_e32 v132, v233
	v_mov_b32_e32 v133, v234
	s_addc_u32 s11, s11, s78
	s_lshl_b64 s[10:11], s[10:11], 17
	v_readlane_b32 s16, v252, 45
	v_lshlrev_b32_e32 v133, 3, v133
	s_add_u32 s16, s16, s10
	v_readlane_b32 s10, v252, 46
	v_lshlrev_b32_e32 v132, 8, v132
	s_addc_u32 s17, s10, s11
	v_add3_u32 v188, v132, s49, v133
	s_add_u32 s26, s16, 0x4200000
	v_ashrrev_i32_e32 v189, 31, v188
	s_addc_u32 s27, s17, 0
	v_lshlrev_b64 v[132:133], 1, v[188:189]
	v_lshl_add_u64 v[134:135], s[16:17], 0, v[132:133]
	v_lshl_add_u64 v[136:137], s[26:27], 0, v[132:133]
	v_add_u32_e32 v132, 0x1000, v188
	v_ashrrev_i32_e32 v133, 31, v132
	v_lshlrev_b64 v[132:133], 1, v[132:133]
	v_lshl_add_u64 v[138:139], s[16:17], 0, v[132:133]
	v_lshl_add_u64 v[176:177], s[26:27], 0, v[132:133]
	v_add_u32_e32 v132, 0x1080, v188
	v_ashrrev_i32_e32 v133, 31, v132
	v_lshlrev_b64 v[132:133], 1, v[132:133]
	v_lshl_add_u64 v[148:149], s[16:17], 0, v[132:133]
	v_lshl_add_u64 v[168:169], s[26:27], 0, v[132:133]
	v_add_u32_e32 v132, 0x2000, v188
	v_ashrrev_i32_e32 v133, 31, v132
	v_lshlrev_b64 v[132:133], 1, v[132:133]
	v_lshl_add_u64 v[144:145], s[16:17], 0, v[132:133]
	v_lshl_add_u64 v[156:157], s[26:27], 0, v[132:133]
	v_add_u32_e32 v132, 0x2080, v188
	v_ashrrev_i32_e32 v133, 31, v132
	v_lshlrev_b64 v[132:133], 1, v[132:133]
	v_lshl_add_u64 v[146:147], s[16:17], 0, v[132:133]
	v_lshl_add_u64 v[158:159], s[26:27], 0, v[132:133]
	v_add_u32_e32 v132, 0x3000, v188
	v_ashrrev_i32_e32 v133, 31, v132
	v_lshlrev_b64 v[132:133], 1, v[132:133]
	v_lshl_add_u64 v[140:141], s[16:17], 0, v[132:133]
	v_lshl_add_u64 v[150:151], s[26:27], 0, v[132:133]
	v_add_u32_e32 v132, 0x3080, v188
	v_ashrrev_i32_e32 v133, 31, v132
	v_lshlrev_b64 v[132:133], 1, v[132:133]
	v_lshl_add_u64 v[142:143], s[16:17], 0, v[132:133]
	v_lshl_add_u64 v[164:165], s[26:27], 0, v[132:133]
	global_load_dwordx4 v[180:183], v[134:135], off offset:256
	global_load_dwordx4 v[190:193], v[134:135], off
	s_nop 0
	global_load_dwordx4 v[132:135], v[142:143], off
	s_nop 0
	global_load_dwordx4 v[140:143], v[140:141], off
	s_nop 0
	global_load_dwordx4 v[152:155], v[146:147], off
	s_nop 0
	global_load_dwordx4 v[144:147], v[144:145], off
	s_nop 0
	global_load_dwordx4 v[160:163], v[148:149], off
	global_load_dwordx4 v[172:175], v[138:139], off
	global_load_dwordx4 v[184:187], v[136:137], off offset:256
	global_load_dwordx4 v[194:197], v[136:137], off
	s_nop 0
	global_load_dwordx4 v[136:139], v[164:165], off
	s_nop 0
	global_load_dwordx4 v[148:151], v[150:151], off
	s_nop 0
	global_load_dwordx4 v[164:167], v[158:159], off
	s_nop 0
	global_load_dwordx4 v[156:159], v[156:157], off
	s_nop 0
	global_load_dwordx4 v[168:171], v[168:169], off
	s_nop 0
	global_load_dwordx4 v[176:179], v[176:177], off
	s_mov_b32 s10, 6
	s_mov_b64 s[30:31], 0x500
	s_mov_b64 s[84:85], 0x80500
	s_mov_b64 vcc, 0x580
	s_mov_b64 s[52:53], 0x80580
	s_waitcnt vmcnt(0)
	s_nop 0
	v_cvt_f32_f16_e32 v189, v190
	v_rcp_f32_e32 v198, v189
	v_cvt_f32_f16_e32 v189, v192
	v_cvt_f32_f16_e32 v244, v194
	v_cvt_f32_f16_sdwa v245, v194 dst_sel:DWORD dst_unused:UNUSED_PAD src0_sel:WORD_1
	v_cvt_f32_f16_e32 v194, v195
	v_rcp_f32_e32 v242, v189
	v_cvt_f32_f16_sdwa v189, v190 dst_sel:DWORD dst_unused:UNUSED_PAD src0_sel:WORD_1
	v_cvt_f32_f16_sdwa v195, v195 dst_sel:DWORD dst_unused:UNUSED_PAD src0_sel:WORD_1
	v_cvt_f32_f16_e32 v246, v196
	v_cvt_f32_f16_sdwa v247, v196 dst_sel:DWORD dst_unused:UNUSED_PAD src0_sel:WORD_1
	v_rcp_f32_e32 v199, v189
	v_cvt_f32_f16_sdwa v189, v192 dst_sel:DWORD dst_unused:UNUSED_PAD src0_sel:WORD_1
	v_cvt_f32_f16_e32 v196, v186
	v_pk_mul_f32 v[198:199], v[198:199], v[244:245]
	v_rcp_f32_e32 v243, v189
	v_cvt_f32_f16_e32 v189, v191
	v_pk_mul_f32 v[80:81], v[80:81], v[198:199]
	v_rcp_f32_e32 v190, v189
	v_cvt_f32_f16_e32 v189, v193
	v_rcp_f32_e32 v192, v189
	v_cvt_f32_f16_sdwa v189, v191 dst_sel:DWORD dst_unused:UNUSED_PAD src0_sel:WORD_1
	v_rcp_f32_e32 v191, v189
	v_cvt_f32_f16_sdwa v189, v193 dst_sel:DWORD dst_unused:UNUSED_PAD src0_sel:WORD_1
	v_pk_mul_f32 v[190:191], v[190:191], v[194:195]
	s_nop 0
	v_pk_mul_f32 v[82:83], v[82:83], v[190:191]
	v_rcp_f32_e32 v193, v189
	v_cvt_f32_f16_e32 v190, v197
	v_cvt_f32_f16_sdwa v191, v197 dst_sel:DWORD dst_unused:UNUSED_PAD src0_sel:WORD_1
	v_cvt_f32_f16_e32 v189, v180
	v_cvt_f32_f16_sdwa v180, v180 dst_sel:DWORD dst_unused:UNUSED_PAD src0_sel:WORD_1
	v_pk_mul_f32 v[194:195], v[242:243], v[246:247]
	v_pk_mul_f32 v[190:191], v[192:193], v[190:191]
	v_pk_mul_f32 v[72:73], v[72:73], v[194:195]
	v_pk_mul_f32 v[74:75], v[74:75], v[190:191]
	v_rcp_f32_e32 v191, v180
	v_cvt_f32_f16_sdwa v180, v182 dst_sel:DWORD dst_unused:UNUSED_PAD src0_sel:WORD_1
	v_cvt_f32_f16_e32 v194, v184
	v_cvt_f32_f16_sdwa v195, v184 dst_sel:DWORD dst_unused:UNUSED_PAD src0_sel:WORD_1
	v_cvt_f32_f16_e32 v184, v185
	v_rcp_f32_e32 v193, v180
	v_cvt_f32_f16_e32 v180, v181
	v_cvt_f32_f16_sdwa v181, v181 dst_sel:DWORD dst_unused:UNUSED_PAD src0_sel:WORD_1
	v_cvt_f32_f16_sdwa v185, v185 dst_sel:DWORD dst_unused:UNUSED_PAD src0_sel:WORD_1
	v_rcp_f32_e32 v190, v189
	v_rcp_f32_e32 v180, v180
	v_rcp_f32_e32 v181, v181
	v_cvt_f32_f16_e32 v189, v182
	v_cvt_f32_f16_e32 v182, v183
	v_cvt_f32_f16_sdwa v197, v186 dst_sel:DWORD dst_unused:UNUSED_PAD src0_sel:WORD_1
	v_pk_mul_f32 v[180:181], v[180:181], v[184:185]
	v_rcp_f32_e32 v192, v189
	v_pk_mul_f32 v[54:55], v[54:55], v[180:181]
	v_cvt_f32_f16_sdwa v180, v183 dst_sel:DWORD dst_unused:UNUSED_PAD src0_sel:WORD_1
	v_rcp_f32_e32 v182, v182
	v_cvt_f32_f16_sdwa v181, v187 dst_sel:DWORD dst_unused:UNUSED_PAD src0_sel:WORD_1
	v_pk_mul_f32 v[184:185], v[192:193], v[196:197]
	v_rcp_f32_e32 v183, v180
	v_cvt_f32_f16_e32 v180, v187
	v_pk_mul_f32 v[40:41], v[40:41], v[184:185]
	v_cvt_f32_f16_e32 v184, v176
	v_cvt_f32_f16_sdwa v185, v176 dst_sel:DWORD dst_unused:UNUSED_PAD src0_sel:WORD_1
	v_pk_mul_f32 v[180:181], v[182:183], v[180:181]
	v_cvt_f32_f16_e32 v176, v177
	v_pk_mul_f32 v[42:43], v[42:43], v[180:181]
	v_cvt_f32_f16_e32 v180, v172
	v_cvt_f32_f16_e32 v181, v174
	v_cvt_f32_f16_sdwa v172, v172 dst_sel:DWORD dst_unused:UNUSED_PAD src0_sel:WORD_1
	v_cvt_f32_f16_sdwa v177, v177 dst_sel:DWORD dst_unused:UNUSED_PAD src0_sel:WORD_1
	v_cvt_f32_f16_e32 v186, v178
	v_rcp_f32_e32 v182, v181
	v_rcp_f32_e32 v181, v172
	v_cvt_f32_f16_sdwa v172, v174 dst_sel:DWORD dst_unused:UNUSED_PAD src0_sel:WORD_1
	v_cvt_f32_f16_e32 v174, v175
	v_cvt_f32_f16_sdwa v187, v178 dst_sel:DWORD dst_unused:UNUSED_PAD src0_sel:WORD_1
	v_cvt_f32_f16_e32 v178, v170
	v_rcp_f32_e32 v183, v172
	v_cvt_f32_f16_e32 v172, v173
	v_cvt_f32_f16_sdwa v173, v173 dst_sel:DWORD dst_unused:UNUSED_PAD src0_sel:WORD_1
	v_rcp_f32_e32 v174, v174
	v_rcp_f32_e32 v180, v180
	v_rcp_f32_e32 v172, v172
	v_rcp_f32_e32 v173, v173
	v_pk_mul_f32 v[190:191], v[190:191], v[194:195]
	v_pk_mul_f32 v[180:181], v[180:181], v[184:185]
	v_pk_mul_f32 v[52:53], v[52:53], v[190:191]
	v_pk_mul_f32 v[172:173], v[172:173], v[176:177]
	v_pk_mul_f32 v[176:177], v[182:183], v[186:187]
	v_pk_mul_f32 v[58:59], v[58:59], v[172:173]
	v_cvt_f32_f16_sdwa v172, v175 dst_sel:DWORD dst_unused:UNUSED_PAD src0_sel:WORD_1
	v_cvt_f32_f16_sdwa v173, v179 dst_sel:DWORD dst_unused:UNUSED_PAD src0_sel:WORD_1
	v_pk_mul_f32 v[68:69], v[68:69], v[176:177]
	v_cvt_f32_f16_e32 v176, v168
	v_rcp_f32_e32 v175, v172
	v_cvt_f32_f16_e32 v172, v179
	v_cvt_f32_f16_sdwa v177, v168 dst_sel:DWORD dst_unused:UNUSED_PAD src0_sel:WORD_1
	v_cvt_f32_f16_e32 v168, v169
	v_cvt_f32_f16_sdwa v169, v169 dst_sel:DWORD dst_unused:UNUSED_PAD src0_sel:WORD_1
	v_pk_mul_f32 v[172:173], v[174:175], v[172:173]
	v_cvt_f32_f16_sdwa v179, v170 dst_sel:DWORD dst_unused:UNUSED_PAD src0_sel:WORD_1
	v_pk_mul_f32 v[70:71], v[70:71], v[172:173]
	v_cvt_f32_f16_e32 v172, v160
	v_cvt_f32_f16_e32 v173, v162
	v_cvt_f32_f16_sdwa v160, v160 dst_sel:DWORD dst_unused:UNUSED_PAD src0_sel:WORD_1
	v_cvt_f32_f16_e32 v170, v158
	v_rcp_f32_e32 v172, v172
	v_rcp_f32_e32 v174, v173
	v_rcp_f32_e32 v173, v160
	v_cvt_f32_f16_sdwa v160, v162 dst_sel:DWORD dst_unused:UNUSED_PAD src0_sel:WORD_1
	v_cvt_f32_f16_e32 v162, v163
	v_pk_mul_f32 v[56:57], v[56:57], v[180:181]
	v_pk_mul_f32 v[172:173], v[172:173], v[176:177]
	v_rcp_f32_e32 v175, v160
	v_cvt_f32_f16_e32 v160, v161
	v_cvt_f32_f16_sdwa v161, v161 dst_sel:DWORD dst_unused:UNUSED_PAD src0_sel:WORD_1
	v_rcp_f32_e32 v162, v162
	v_pk_mul_f32 v[36:37], v[36:37], v[172:173]
	v_rcp_f32_e32 v160, v160
	v_rcp_f32_e32 v161, v161
	s_nop 0
	v_pk_mul_f32 v[160:161], v[160:161], v[168:169]
	s_nop 0
	v_pk_mul_f32 v[38:39], v[38:39], v[160:161]
	v_cvt_f32_f16_sdwa v160, v163 dst_sel:DWORD dst_unused:UNUSED_PAD src0_sel:WORD_1
	v_cvt_f32_f16_sdwa v161, v171 dst_sel:DWORD dst_unused:UNUSED_PAD src0_sel:WORD_1
	v_pk_mul_f32 v[168:169], v[174:175], v[178:179]
	v_rcp_f32_e32 v163, v160
	v_cvt_f32_f16_e32 v160, v171
	v_pk_mul_f32 v[28:29], v[28:29], v[168:169]
	v_cvt_f32_f16_sdwa v171, v158 dst_sel:DWORD dst_unused:UNUSED_PAD src0_sel:WORD_1
	v_pk_mul_f32 v[160:161], v[162:163], v[160:161]
	s_nop 0
	v_pk_mul_f32 v[30:31], v[30:31], v[160:161]
	v_cvt_f32_f16_e32 v160, v144
	v_cvt_f32_f16_e32 v161, v146
	v_cvt_f32_f16_sdwa v144, v144 dst_sel:DWORD dst_unused:UNUSED_PAD src0_sel:WORD_1
	v_cvt_f32_f16_e32 v162, v156
	v_rcp_f32_e32 v160, v160
	v_rcp_f32_e32 v168, v161
	v_rcp_f32_e32 v161, v144
	v_cvt_f32_f16_sdwa v144, v146 dst_sel:DWORD dst_unused:UNUSED_PAD src0_sel:WORD_1
	v_cvt_f32_f16_sdwa v163, v156 dst_sel:DWORD dst_unused:UNUSED_PAD src0_sel:WORD_1
	v_cvt_f32_f16_e32 v156, v157
	v_cvt_f32_f16_sdwa v157, v157 dst_sel:DWORD dst_unused:UNUSED_PAD src0_sel:WORD_1
	v_rcp_f32_e32 v169, v144
	v_cvt_f32_f16_e32 v144, v145
	v_cvt_f32_f16_sdwa v145, v145 dst_sel:DWORD dst_unused:UNUSED_PAD src0_sel:WORD_1
	v_pk_mul_f32 v[160:161], v[160:161], v[162:163]
	v_cvt_f32_f16_e32 v146, v147
	v_rcp_f32_e32 v144, v144
	v_rcp_f32_e32 v145, v145
	v_pk_mul_f32 v[160:161], v[128:129], v[160:161]
	v_cvt_f32_f16_sdwa v128, v147 dst_sel:DWORD dst_unused:UNUSED_PAD src0_sel:WORD_1
	v_rcp_f32_e32 v146, v146
	v_pk_mul_f32 v[144:145], v[144:145], v[156:157]
	v_cvt_f32_f16_sdwa v129, v159 dst_sel:DWORD dst_unused:UNUSED_PAD src0_sel:WORD_1
	v_pk_mul_f32 v[162:163], v[130:131], v[144:145]
	v_rcp_f32_e32 v147, v128
	v_cvt_f32_f16_e32 v128, v159
	v_pk_mul_f32 v[130:131], v[168:169], v[170:171]
	v_cvt_f32_f16_e32 v145, v155
	v_pk_mul_f32 v[156:157], v[124:125], v[130:131]
	v_cvt_f32_f16_e32 v125, v154
	v_pk_mul_f32 v[128:129], v[146:147], v[128:129]
	v_cvt_f32_f16_e32 v124, v152
	v_pk_mul_f32 v[158:159], v[126:127], v[128:129]
	v_rcp_f32_e32 v126, v125
	v_cvt_f32_f16_sdwa v125, v152 dst_sel:DWORD dst_unused:UNUSED_PAD src0_sel:WORD_1
	v_cvt_f32_f16_e32 v144, v153
	v_rcp_f32_e32 v152, v145
	v_cvt_f32_f16_sdwa v145, v153 dst_sel:DWORD dst_unused:UNUSED_PAD src0_sel:WORD_1
	v_rcp_f32_e32 v124, v124
	v_rcp_f32_e32 v125, v125
	v_cvt_f32_f16_e32 v128, v164
	v_cvt_f32_f16_sdwa v129, v164 dst_sel:DWORD dst_unused:UNUSED_PAD src0_sel:WORD_1
	v_cvt_f32_f16_sdwa v127, v154 dst_sel:DWORD dst_unused:UNUSED_PAD src0_sel:WORD_1
	v_rcp_f32_e32 v144, v144
	v_rcp_f32_e32 v145, v145
	v_cvt_f32_f16_e32 v146, v165
	v_cvt_f32_f16_sdwa v147, v165 dst_sel:DWORD dst_unused:UNUSED_PAD src0_sel:WORD_1
	v_pk_mul_f32 v[124:125], v[124:125], v[128:129]
	v_rcp_f32_e32 v127, v127
	v_cvt_f32_f16_e32 v130, v166
	v_cvt_f32_f16_sdwa v131, v166 dst_sel:DWORD dst_unused:UNUSED_PAD src0_sel:WORD_1
	v_pk_mul_f32 v[128:129], v[144:145], v[146:147]
	v_pk_mul_f32 v[144:145], v[120:121], v[124:125]
	v_cvt_f32_f16_sdwa v120, v155 dst_sel:DWORD dst_unused:UNUSED_PAD src0_sel:WORD_1
	v_pk_mul_f32 v[146:147], v[122:123], v[128:129]
	v_cvt_f32_f16_sdwa v121, v167 dst_sel:DWORD dst_unused:UNUSED_PAD src0_sel:WORD_1
	v_pk_mul_f32 v[122:123], v[126:127], v[130:131]
	v_rcp_f32_e32 v153, v120
	v_cvt_f32_f16_e32 v120, v167
	v_pk_mul_f32 v[124:125], v[112:113], v[122:123]
	v_cvt_f32_f16_e32 v113, v142
	v_cvt_f32_f16_e32 v112, v140
	v_pk_mul_f32 v[120:121], v[152:153], v[120:121]
	v_cvt_f32_f16_e32 v129, v143
	v_pk_mul_f32 v[126:127], v[114:115], v[120:121]
	v_rcp_f32_e32 v114, v113
	v_cvt_f32_f16_sdwa v113, v140 dst_sel:DWORD dst_unused:UNUSED_PAD src0_sel:WORD_1
	v_rcp_f32_e32 v112, v112
	v_cvt_f32_f16_e32 v120, v148
	v_cvt_f32_f16_sdwa v121, v148 dst_sel:DWORD dst_unused:UNUSED_PAD src0_sel:WORD_1
	v_rcp_f32_e32 v113, v113
	v_cvt_f32_f16_sdwa v115, v142 dst_sel:DWORD dst_unused:UNUSED_PAD src0_sel:WORD_1
	v_cvt_f32_f16_e32 v122, v150
	v_cvt_f32_f16_sdwa v123, v150 dst_sel:DWORD dst_unused:UNUSED_PAD src0_sel:WORD_1
	v_pk_mul_f32 v[112:113], v[112:113], v[120:121]
	v_rcp_f32_e32 v115, v115
	v_pk_mul_f32 v[152:153], v[116:117], v[112:113]
	v_cvt_f32_f16_sdwa v112, v143 dst_sel:DWORD dst_unused:UNUSED_PAD src0_sel:WORD_1
	v_cvt_f32_f16_e32 v128, v141
	v_rcp_f32_e32 v130, v129
	v_cvt_f32_f16_sdwa v129, v141 dst_sel:DWORD dst_unused:UNUSED_PAD src0_sel:WORD_1
	v_rcp_f32_e32 v131, v112
	v_cvt_f32_f16_e32 v112, v151
	v_cvt_f32_f16_sdwa v113, v151 dst_sel:DWORD dst_unused:UNUSED_PAD src0_sel:WORD_1
	v_pk_mul_f32 v[114:115], v[114:115], v[122:123]
	v_rcp_f32_e32 v128, v128
	v_rcp_f32_e32 v129, v129
	v_cvt_f32_f16_e32 v140, v149
	v_cvt_f32_f16_sdwa v141, v149 dst_sel:DWORD dst_unused:UNUSED_PAD src0_sel:WORD_1
	v_pk_mul_f32 v[148:149], v[108:109], v[114:115]
	v_cvt_f32_f16_e32 v109, v134
	v_cvt_f32_f16_e32 v117, v135
	v_pk_mul_f32 v[112:113], v[130:131], v[112:113]
	v_pk_mul_f32 v[120:121], v[128:129], v[140:141]
	v_pk_mul_f32 v[150:151], v[110:111], v[112:113]
	v_cvt_f32_f16_e32 v108, v132
	v_rcp_f32_e32 v110, v109
	v_cvt_f32_f16_sdwa v109, v132 dst_sel:DWORD dst_unused:UNUSED_PAD src0_sel:WORD_1
	v_pk_mul_f32 v[154:155], v[118:119], v[120:121]
	v_cvt_f32_f16_e32 v116, v133
	v_rcp_f32_e32 v118, v117
	v_cvt_f32_f16_sdwa v117, v133 dst_sel:DWORD dst_unused:UNUSED_PAD src0_sel:WORD_1
	v_rcp_f32_e32 v108, v108
	v_rcp_f32_e32 v109, v109
	v_cvt_f32_f16_e32 v112, v136
	v_cvt_f32_f16_sdwa v113, v136 dst_sel:DWORD dst_unused:UNUSED_PAD src0_sel:WORD_1
	v_rcp_f32_e32 v116, v116
	v_rcp_f32_e32 v117, v117
	v_cvt_f32_f16_e32 v120, v137
	v_cvt_f32_f16_sdwa v121, v137 dst_sel:DWORD dst_unused:UNUSED_PAD src0_sel:WORD_1
	v_cvt_f32_f16_sdwa v111, v134 dst_sel:DWORD dst_unused:UNUSED_PAD src0_sel:WORD_1
	v_pk_mul_f32 v[108:109], v[108:109], v[112:113]
	v_cvt_f32_f16_e32 v114, v138
	v_pk_mul_f32 v[112:113], v[116:117], v[120:121]
	v_pk_mul_f32 v[120:121], v[104:105], v[108:109]
	v_cvt_f32_f16_sdwa v104, v135 dst_sel:DWORD dst_unused:UNUSED_PAD src0_sel:WORD_1
	v_rcp_f32_e32 v111, v111
	v_cvt_f32_f16_sdwa v115, v138 dst_sel:DWORD dst_unused:UNUSED_PAD src0_sel:WORD_1
	v_cvt_f32_f16_sdwa v105, v139 dst_sel:DWORD dst_unused:UNUSED_PAD src0_sel:WORD_1
	v_rcp_f32_e32 v119, v104
	v_cvt_f32_f16_e32 v104, v139
	v_pk_mul_f32 v[122:123], v[106:107], v[112:113]
	v_pk_mul_f32 v[106:107], v[110:111], v[114:115]
	v_pk_mul_f32 v[104:105], v[118:119], v[104:105]
	v_pk_mul_f32 v[116:117], v[100:101], v[106:107]
	v_add_u32_e32 v100, 0x8000, v188
	v_ashrrev_i32_e32 v101, 31, v100
	v_lshlrev_b64 v[100:101], 1, v[100:101]
	v_pk_mul_f32 v[118:119], v[102:103], v[104:105]
	v_lshl_add_u64 v[104:105], s[16:17], 0, v[100:101]
	v_lshl_add_u64 v[112:113], s[26:27], 0, v[100:101]
	v_add_u32_e32 v100, 0x8080, v188
	v_ashrrev_i32_e32 v101, 31, v100
	v_lshlrev_b64 v[100:101], 1, v[100:101]
	v_lshl_add_u64 v[102:103], s[16:17], 0, v[100:101]
	v_lshl_add_u64 v[114:115], s[26:27], 0, v[100:101]
	v_add_u32_e32 v100, 0x9000, v188
	v_ashrrev_i32_e32 v101, 31, v100
	v_lshlrev_b64 v[100:101], 1, v[100:101]
	v_lshl_add_u64 v[106:107], s[16:17], 0, v[100:101]
	v_lshl_add_u64 v[190:191], s[26:27], 0, v[100:101]
	v_add_u32_e32 v100, 0x9080, v188
	v_ashrrev_i32_e32 v101, 31, v100
	v_lshlrev_b64 v[100:101], 1, v[100:101]
	v_lshl_add_u64 v[140:141], s[16:17], 0, v[100:101]
	v_lshl_add_u64 v[180:181], s[26:27], 0, v[100:101]
	v_add_u32_e32 v100, 0xa000, v188
	v_ashrrev_i32_e32 v101, 31, v100
	v_lshlrev_b64 v[100:101], 1, v[100:101]
	v_lshl_add_u64 v[136:137], s[16:17], 0, v[100:101]
	v_lshl_add_u64 v[176:177], s[26:27], 0, v[100:101]
	v_add_u32_e32 v100, 0xa080, v188
	v_ashrrev_i32_e32 v101, 31, v100
	v_lshlrev_b64 v[100:101], 1, v[100:101]
	v_lshl_add_u64 v[132:133], s[16:17], 0, v[100:101]
	v_lshl_add_u64 v[172:173], s[26:27], 0, v[100:101]
	v_add_u32_e32 v100, 0xb000, v188
	v_ashrrev_i32_e32 v101, 31, v100
	v_lshlrev_b64 v[100:101], 1, v[100:101]
	v_lshl_add_u64 v[128:129], s[16:17], 0, v[100:101]
	v_lshl_add_u64 v[168:169], s[26:27], 0, v[100:101]
	v_add_u32_e32 v100, 0xb080, v188
	v_ashrrev_i32_e32 v101, 31, v100
	v_lshlrev_b64 v[100:101], 1, v[100:101]
	v_lshl_add_u64 v[108:109], s[16:17], 0, v[100:101]
	v_lshl_add_u64 v[164:165], s[26:27], 0, v[100:101]
	global_load_dwordx4 v[108:111], v[108:109], off
	s_nop 0
	global_load_dwordx4 v[128:131], v[128:129], off
	s_nop 0
	global_load_dwordx4 v[132:135], v[132:133], off
	s_nop 0
	global_load_dwordx4 v[136:139], v[136:137], off
	s_nop 0
	global_load_dwordx4 v[140:143], v[140:141], off
	s_nop 0
	global_load_dwordx4 v[184:187], v[106:107], off
	s_nop 0
	global_load_dwordx4 v[100:103], v[102:103], off
	s_nop 0
	global_load_dwordx4 v[104:107], v[104:105], off
	s_nop 0
	global_load_dwordx4 v[164:167], v[164:165], off
	s_nop 0
	global_load_dwordx4 v[168:171], v[168:169], off
	s_nop 0
	global_load_dwordx4 v[172:175], v[172:173], off
	s_nop 0
	global_load_dwordx4 v[176:179], v[176:177], off
	s_nop 0
	global_load_dwordx4 v[180:183], v[180:181], off
	s_nop 0
	global_load_dwordx4 v[188:191], v[190:191], off
	s_nop 0
	global_load_dwordx4 v[192:195], v[114:115], off
	global_load_dwordx4 v[196:199], v[112:113], off
	s_waitcnt vmcnt(0)
	s_nop 0
	v_cvt_f32_f16_e32 v112, v104
	v_cvt_f32_f16_e32 v113, v106
	v_cvt_f32_f16_sdwa v104, v104 dst_sel:DWORD dst_unused:UNUSED_PAD src0_sel:WORD_1
	v_rcp_f32_e32 v242, v113
	v_rcp_f32_e32 v113, v104
	v_cvt_f32_f16_sdwa v104, v106 dst_sel:DWORD dst_unused:UNUSED_PAD src0_sel:WORD_1
	v_rcp_f32_e32 v112, v112
	v_cvt_f32_f16_e32 v114, v196
	v_cvt_f32_f16_sdwa v115, v196 dst_sel:DWORD dst_unused:UNUSED_PAD src0_sel:WORD_1
	v_rcp_f32_e32 v243, v104
	v_cvt_f32_f16_e32 v104, v105
	v_cvt_f32_f16_sdwa v105, v105 dst_sel:DWORD dst_unused:UNUSED_PAD src0_sel:WORD_1
	v_cvt_f32_f16_e32 v196, v197
	v_cvt_f32_f16_sdwa v197, v197 dst_sel:DWORD dst_unused:UNUSED_PAD src0_sel:WORD_1
	v_rcp_f32_e32 v104, v104
	v_rcp_f32_e32 v105, v105
	v_pk_mul_f32 v[112:113], v[112:113], v[114:115]
	v_cvt_f32_f16_e32 v244, v198
	v_cvt_f32_f16_sdwa v245, v198 dst_sel:DWORD dst_unused:UNUSED_PAD src0_sel:WORD_1
	v_cvt_f32_f16_e32 v106, v107
	v_pk_mul_f32 v[112:113], v[96:97], v[112:113]
	v_cvt_f32_f16_sdwa v96, v107 dst_sel:DWORD dst_unused:UNUSED_PAD src0_sel:WORD_1
	v_pk_mul_f32 v[104:105], v[104:105], v[196:197]
	v_rcp_f32_e32 v106, v106
	v_pk_mul_f32 v[114:115], v[98:99], v[104:105]
	v_rcp_f32_e32 v107, v96
	v_cvt_f32_f16_e32 v96, v199
	v_cvt_f32_f16_sdwa v97, v199 dst_sel:DWORD dst_unused:UNUSED_PAD src0_sel:WORD_1
	v_pk_mul_f32 v[98:99], v[242:243], v[244:245]
	s_mov_b64 s[16:17], 0
	v_pk_mul_f32 v[104:105], v[92:93], v[98:99]
	v_cvt_f32_f16_e32 v93, v102
	v_pk_mul_f32 v[96:97], v[106:107], v[96:97]
	v_cvt_f32_f16_e32 v92, v100
	v_pk_mul_f32 v[106:107], v[94:95], v[96:97]
	v_rcp_f32_e32 v96, v93
	v_cvt_f32_f16_sdwa v93, v100 dst_sel:DWORD dst_unused:UNUSED_PAD src0_sel:WORD_1
	v_rcp_f32_e32 v92, v92
	v_cvt_f32_f16_e32 v94, v192
	v_cvt_f32_f16_sdwa v95, v192 dst_sel:DWORD dst_unused:UNUSED_PAD src0_sel:WORD_1
	v_rcp_f32_e32 v93, v93
	v_cvt_f32_f16_sdwa v97, v102 dst_sel:DWORD dst_unused:UNUSED_PAD src0_sel:WORD_1
	v_cvt_f32_f16_e32 v102, v103
	v_cvt_f32_f16_e32 v100, v101
	v_pk_mul_f32 v[92:93], v[92:93], v[94:95]
	v_cvt_f32_f16_sdwa v101, v101 dst_sel:DWORD dst_unused:UNUSED_PAD src0_sel:WORD_1
	v_pk_mul_f32 v[92:93], v[88:89], v[92:93]
	v_cvt_f32_f16_sdwa v88, v103 dst_sel:DWORD dst_unused:UNUSED_PAD src0_sel:WORD_1
	v_rcp_f32_e32 v102, v102
	v_cvt_f32_f16_sdwa v89, v195 dst_sel:DWORD dst_unused:UNUSED_PAD src0_sel:WORD_1
	v_rcp_f32_e32 v100, v100
	v_rcp_f32_e32 v103, v88
	v_cvt_f32_f16_e32 v88, v195
	v_rcp_f32_e32 v101, v101
	v_cvt_f32_f16_e32 v192, v193
	v_cvt_f32_f16_sdwa v193, v193 dst_sel:DWORD dst_unused:UNUSED_PAD src0_sel:WORD_1
	v_rcp_f32_e32 v97, v97
	v_cvt_f32_f16_e32 v98, v194
	v_cvt_f32_f16_sdwa v99, v194 dst_sel:DWORD dst_unused:UNUSED_PAD src0_sel:WORD_1
	v_pk_mul_f32 v[88:89], v[102:103], v[88:89]
	v_pk_mul_f32 v[94:95], v[100:101], v[192:193]
	v_pk_mul_f32 v[86:87], v[86:87], v[88:89]
	v_cvt_f32_f16_e32 v89, v186
	v_cvt_f32_f16_e32 v101, v187
	v_pk_mul_f32 v[94:95], v[90:91], v[94:95]
	v_pk_mul_f32 v[90:91], v[96:97], v[98:99]
	v_cvt_f32_f16_e32 v88, v184
	v_pk_mul_f32 v[84:85], v[84:85], v[90:91]
	v_rcp_f32_e32 v90, v89
	v_cvt_f32_f16_sdwa v89, v184 dst_sel:DWORD dst_unused:UNUSED_PAD src0_sel:WORD_1
	v_cvt_f32_f16_e32 v100, v185
	v_rcp_f32_e32 v184, v101
	v_cvt_f32_f16_sdwa v101, v185 dst_sel:DWORD dst_unused:UNUSED_PAD src0_sel:WORD_1
	v_rcp_f32_e32 v88, v88
	v_rcp_f32_e32 v89, v89
	v_cvt_f32_f16_e32 v96, v188
	v_cvt_f32_f16_sdwa v97, v188 dst_sel:DWORD dst_unused:UNUSED_PAD src0_sel:WORD_1
	v_cvt_f32_f16_sdwa v91, v186 dst_sel:DWORD dst_unused:UNUSED_PAD src0_sel:WORD_1
	v_rcp_f32_e32 v100, v100
	v_rcp_f32_e32 v101, v101
	v_cvt_f32_f16_e32 v102, v189
	v_cvt_f32_f16_sdwa v103, v189 dst_sel:DWORD dst_unused:UNUSED_PAD src0_sel:WORD_1
	v_pk_mul_f32 v[88:89], v[88:89], v[96:97]
	v_rcp_f32_e32 v91, v91
	v_cvt_f32_f16_e32 v98, v190
	v_cvt_f32_f16_sdwa v99, v190 dst_sel:DWORD dst_unused:UNUSED_PAD src0_sel:WORD_1
	v_pk_mul_f32 v[96:97], v[100:101], v[102:103]
	v_pk_mul_f32 v[100:101], v[76:77], v[88:89]
	v_cvt_f32_f16_sdwa v76, v187 dst_sel:DWORD dst_unused:UNUSED_PAD src0_sel:WORD_1
	v_pk_mul_f32 v[102:103], v[78:79], v[96:97]
	v_cvt_f32_f16_sdwa v77, v191 dst_sel:DWORD dst_unused:UNUSED_PAD src0_sel:WORD_1
	v_pk_mul_f32 v[78:79], v[90:91], v[98:99]
	v_rcp_f32_e32 v185, v76
	v_cvt_f32_f16_e32 v76, v191
	v_pk_mul_f32 v[96:97], v[64:65], v[78:79]
	v_cvt_f32_f16_e32 v65, v142
	v_cvt_f32_f16_e32 v79, v143
	v_pk_mul_f32 v[76:77], v[184:185], v[76:77]
	v_cvt_f32_f16_e32 v64, v140
	v_pk_mul_f32 v[98:99], v[66:67], v[76:77]
	v_rcp_f32_e32 v66, v65
	v_cvt_f32_f16_sdwa v65, v140 dst_sel:DWORD dst_unused:UNUSED_PAD src0_sel:WORD_1
	v_cvt_f32_f16_e32 v78, v141
	v_rcp_f32_e32 v90, v79
	v_cvt_f32_f16_sdwa v79, v141 dst_sel:DWORD dst_unused:UNUSED_PAD src0_sel:WORD_1
	v_rcp_f32_e32 v64, v64
	v_rcp_f32_e32 v65, v65
	v_cvt_f32_f16_e32 v76, v180
	v_cvt_f32_f16_sdwa v77, v180 dst_sel:DWORD dst_unused:UNUSED_PAD src0_sel:WORD_1
	v_rcp_f32_e32 v78, v78
	v_rcp_f32_e32 v79, v79
	v_cvt_f32_f16_e32 v140, v181
	v_cvt_f32_f16_sdwa v141, v181 dst_sel:DWORD dst_unused:UNUSED_PAD src0_sel:WORD_1
	v_cvt_f32_f16_sdwa v67, v142 dst_sel:DWORD dst_unused:UNUSED_PAD src0_sel:WORD_1
	v_pk_mul_f32 v[64:65], v[64:65], v[76:77]
	v_cvt_f32_f16_e32 v88, v182
	v_pk_mul_f32 v[76:77], v[78:79], v[140:141]
	v_rcp_f32_e32 v67, v67
	v_cvt_f32_f16_sdwa v89, v182 dst_sel:DWORD dst_unused:UNUSED_PAD src0_sel:WORD_1
	v_pk_mul_f32 v[78:79], v[62:63], v[76:77]
	v_pk_mul_f32 v[76:77], v[60:61], v[64:65]
	v_cvt_f32_f16_sdwa v60, v143 dst_sel:DWORD dst_unused:UNUSED_PAD src0_sel:WORD_1
	v_cvt_f32_f16_sdwa v61, v183 dst_sel:DWORD dst_unused:UNUSED_PAD src0_sel:WORD_1
	v_pk_mul_f32 v[62:63], v[66:67], v[88:89]
	v_cvt_f32_f16_e32 v89, v139
	v_rcp_f32_e32 v91, v60
	v_cvt_f32_f16_e32 v60, v183
	v_pk_mul_f32 v[64:65], v[48:49], v[62:63]
	v_cvt_f32_f16_e32 v49, v138
	v_cvt_f32_f16_e32 v48, v136
	v_pk_mul_f32 v[60:61], v[90:91], v[60:61]
	v_cvt_f32_f16_e32 v88, v137
	v_pk_mul_f32 v[66:67], v[50:51], v[60:61]
	v_rcp_f32_e32 v50, v49
	v_cvt_f32_f16_sdwa v49, v136 dst_sel:DWORD dst_unused:UNUSED_PAD src0_sel:WORD_1
	v_rcp_f32_e32 v48, v48
	v_cvt_f32_f16_e32 v60, v176
	v_cvt_f32_f16_sdwa v61, v176 dst_sel:DWORD dst_unused:UNUSED_PAD src0_sel:WORD_1
	v_rcp_f32_e32 v49, v49
	v_rcp_f32_e32 v90, v89
	v_cvt_f32_f16_sdwa v89, v137 dst_sel:DWORD dst_unused:UNUSED_PAD src0_sel:WORD_1
	v_cvt_f32_f16_sdwa v51, v138 dst_sel:DWORD dst_unused:UNUSED_PAD src0_sel:WORD_1
	v_rcp_f32_e32 v88, v88
	v_cvt_f32_f16_e32 v136, v177
	v_rcp_f32_e32 v89, v89
	v_cvt_f32_f16_sdwa v137, v177 dst_sel:DWORD dst_unused:UNUSED_PAD src0_sel:WORD_1
	v_pk_mul_f32 v[48:49], v[48:49], v[60:61]
	v_rcp_f32_e32 v51, v51
	v_cvt_f32_f16_e32 v62, v178
	v_cvt_f32_f16_sdwa v63, v178 dst_sel:DWORD dst_unused:UNUSED_PAD src0_sel:WORD_1
	v_pk_mul_f32 v[140:141], v[44:45], v[48:49]
	v_cvt_f32_f16_sdwa v44, v139 dst_sel:DWORD dst_unused:UNUSED_PAD src0_sel:WORD_1
	v_pk_mul_f32 v[60:61], v[88:89], v[136:137]
	v_cvt_f32_f16_sdwa v45, v179 dst_sel:DWORD dst_unused:UNUSED_PAD src0_sel:WORD_1
	v_pk_mul_f32 v[142:143], v[46:47], v[60:61]
	v_rcp_f32_e32 v91, v44
	v_cvt_f32_f16_e32 v44, v179
	v_pk_mul_f32 v[46:47], v[50:51], v[62:63]
	v_cvt_f32_f16_e32 v49, v135
	v_pk_mul_f32 v[136:137], v[32:33], v[46:47]
	v_cvt_f32_f16_e32 v33, v134
	v_pk_mul_f32 v[44:45], v[90:91], v[44:45]
	v_cvt_f32_f16_e32 v32, v132
	v_pk_mul_f32 v[138:139], v[34:35], v[44:45]
	v_rcp_f32_e32 v34, v33
	v_cvt_f32_f16_sdwa v33, v132 dst_sel:DWORD dst_unused:UNUSED_PAD src0_sel:WORD_1
	v_cvt_f32_f16_e32 v48, v133
	v_rcp_f32_e32 v50, v49
	v_cvt_f32_f16_sdwa v49, v133 dst_sel:DWORD dst_unused:UNUSED_PAD src0_sel:WORD_1
	v_rcp_f32_e32 v32, v32
	v_rcp_f32_e32 v33, v33
	v_cvt_f32_f16_e32 v44, v172
	v_cvt_f32_f16_sdwa v45, v172 dst_sel:DWORD dst_unused:UNUSED_PAD src0_sel:WORD_1
	v_cvt_f32_f16_sdwa v35, v134 dst_sel:DWORD dst_unused:UNUSED_PAD src0_sel:WORD_1
	v_rcp_f32_e32 v48, v48
	v_rcp_f32_e32 v49, v49
	v_cvt_f32_f16_e32 v60, v173
	v_cvt_f32_f16_sdwa v61, v173 dst_sel:DWORD dst_unused:UNUSED_PAD src0_sel:WORD_1
	v_pk_mul_f32 v[32:33], v[32:33], v[44:45]
	v_rcp_f32_e32 v35, v35
	v_cvt_f32_f16_e32 v46, v174
	v_cvt_f32_f16_sdwa v47, v174 dst_sel:DWORD dst_unused:UNUSED_PAD src0_sel:WORD_1
	v_pk_mul_f32 v[44:45], v[48:49], v[60:61]
	v_pk_mul_f32 v[60:61], v[24:25], v[32:33]
	v_cvt_f32_f16_sdwa v24, v135 dst_sel:DWORD dst_unused:UNUSED_PAD src0_sel:WORD_1
	v_pk_mul_f32 v[62:63], v[26:27], v[44:45]
	v_cvt_f32_f16_sdwa v25, v175 dst_sel:DWORD dst_unused:UNUSED_PAD src0_sel:WORD_1
	v_pk_mul_f32 v[26:27], v[34:35], v[46:47]
	v_rcp_f32_e32 v51, v24
	v_cvt_f32_f16_e32 v24, v175
	v_pk_mul_f32 v[48:49], v[20:21], v[26:27]
	v_cvt_f32_f16_e32 v21, v130
	v_cvt_f32_f16_e32 v20, v128
	v_pk_mul_f32 v[24:25], v[50:51], v[24:25]
	v_cvt_f32_f16_e32 v33, v131
	v_pk_mul_f32 v[50:51], v[22:23], v[24:25]
	v_rcp_f32_e32 v22, v21
	v_cvt_f32_f16_sdwa v21, v128 dst_sel:DWORD dst_unused:UNUSED_PAD src0_sel:WORD_1
	v_rcp_f32_e32 v20, v20
	v_cvt_f32_f16_e32 v24, v168
	v_cvt_f32_f16_sdwa v25, v168 dst_sel:DWORD dst_unused:UNUSED_PAD src0_sel:WORD_1
	v_rcp_f32_e32 v21, v21
	v_cvt_f32_f16_e32 v32, v129
	v_rcp_f32_e32 v34, v33
	v_cvt_f32_f16_sdwa v33, v129 dst_sel:DWORD dst_unused:UNUSED_PAD src0_sel:WORD_1
	v_cvt_f32_f16_sdwa v23, v130 dst_sel:DWORD dst_unused:UNUSED_PAD src0_sel:WORD_1
	v_rcp_f32_e32 v32, v32
	v_cvt_f32_f16_e32 v44, v169
	v_rcp_f32_e32 v33, v33
	v_cvt_f32_f16_sdwa v45, v169 dst_sel:DWORD dst_unused:UNUSED_PAD src0_sel:WORD_1
	v_pk_mul_f32 v[20:21], v[20:21], v[24:25]
	v_rcp_f32_e32 v23, v23
	v_cvt_f32_f16_e32 v26, v170
	v_cvt_f32_f16_sdwa v27, v170 dst_sel:DWORD dst_unused:UNUSED_PAD src0_sel:WORD_1
	v_pk_mul_f32 v[132:133], v[16:17], v[20:21]
	v_cvt_f32_f16_sdwa v16, v131 dst_sel:DWORD dst_unused:UNUSED_PAD src0_sel:WORD_1
	v_pk_mul_f32 v[24:25], v[32:33], v[44:45]
	v_cvt_f32_f16_sdwa v17, v171 dst_sel:DWORD dst_unused:UNUSED_PAD src0_sel:WORD_1
	v_pk_mul_f32 v[134:135], v[18:19], v[24:25]
	v_rcp_f32_e32 v35, v16
	v_cvt_f32_f16_e32 v16, v171
	v_pk_mul_f32 v[18:19], v[22:23], v[26:27]
	v_cvt_f32_f16_e32 v21, v111
	v_pk_mul_f32 v[128:129], v[12:13], v[18:19]
	v_cvt_f32_f16_e32 v13, v110
	v_pk_mul_f32 v[16:17], v[34:35], v[16:17]
	v_cvt_f32_f16_e32 v12, v108
	v_pk_mul_f32 v[130:131], v[14:15], v[16:17]
	v_rcp_f32_e32 v14, v13
	v_cvt_f32_f16_sdwa v13, v108 dst_sel:DWORD dst_unused:UNUSED_PAD src0_sel:WORD_1
	v_rcp_f32_e32 v12, v12
	v_cvt_f32_f16_e32 v16, v164
	v_cvt_f32_f16_sdwa v17, v164 dst_sel:DWORD dst_unused:UNUSED_PAD src0_sel:WORD_1
	v_rcp_f32_e32 v13, v13
	v_cvt_f32_f16_e32 v20, v109
	v_rcp_f32_e32 v22, v21
	v_cvt_f32_f16_sdwa v21, v109 dst_sel:DWORD dst_unused:UNUSED_PAD src0_sel:WORD_1
	v_pk_mul_f32 v[12:13], v[12:13], v[16:17]
	v_cvt_f32_f16_sdwa v15, v110 dst_sel:DWORD dst_unused:UNUSED_PAD src0_sel:WORD_1
	v_pk_mul_f32 v[32:33], v[8:9], v[12:13]
	v_cvt_f32_f16_sdwa v8, v111 dst_sel:DWORD dst_unused:UNUSED_PAD src0_sel:WORD_1
	v_rcp_f32_e32 v20, v20
	v_rcp_f32_e32 v21, v21
	v_cvt_f32_f16_e32 v24, v165
	v_cvt_f32_f16_sdwa v25, v165 dst_sel:DWORD dst_unused:UNUSED_PAD src0_sel:WORD_1
	v_rcp_f32_e32 v15, v15
	v_cvt_f32_f16_e32 v18, v166
	v_cvt_f32_f16_sdwa v19, v166 dst_sel:DWORD dst_unused:UNUSED_PAD src0_sel:WORD_1
	v_rcp_f32_e32 v23, v8
	v_cvt_f32_f16_e32 v8, v167
	v_cvt_f32_f16_sdwa v9, v167 dst_sel:DWORD dst_unused:UNUSED_PAD src0_sel:WORD_1
	v_pk_mul_f32 v[16:17], v[20:21], v[24:25]
	s_mov_b64 s[26:27], 0x80480
	v_pk_mul_f32 v[34:35], v[10:11], v[16:17]
	v_pk_mul_f32 v[10:11], v[14:15], v[18:19]
	v_pk_mul_f32 v[8:9], v[22:23], v[8:9]
	v_pk_mul_f32 v[44:45], v[4:5], v[10:11]
	v_pk_mul_f32 v[46:47], v[6:7], v[8:9]
	v_lshl_add_u64 v[4:5], s[34:35], 0, v[210:211]
.LBB0_1744:
	ds_read_b128 v[6:9], v237
	ds_read_b128 v[10:13], v237 offset:1024
	ds_read_b128 v[14:17], v237 offset:2048
	ds_read_b128 v[18:21], v237 offset:3072
	v_lshl_add_u64 v[246:247], v[4:5], 0, s[16:17]
	s_mov_b32 m0, s14
	v_lshl_add_u64 v[26:27], v[246:247], 0, s[26:27]
	v_lshl_add_u64 v[248:249], v[200:201], 0, s[16:17]
	ds_read_b128 v[22:25], v236
	ds_read_b128 v[88:91], v236 offset:1024
	ds_read_b128 v[108:111], v236 offset:2048
	ds_read_b128 v[164:167], v236 offset:3072
	ds_read_b128 v[168:171], v236 offset:4096
	ds_read_b128 v[172:175], v236 offset:5120
	ds_read_b128 v[176:179], v236 offset:6144
	ds_read_b128 v[180:183], v236 offset:7168
	global_load_lds_dwordx4 v[26:27], off
	v_lshl_add_u64 v[26:27], v[248:249], 0, s[26:27]
	s_mov_b32 m0, s15
	s_nop 0
	global_load_lds_dwordx4 v[26:27], off
	s_waitcnt lgkmcnt(8)
	s_barrier
	s_waitcnt lgkmcnt(0)
	s_waitcnt lgkmcnt(0)
	v_mfma_f32_16x16x32_f16 v[80:83], v[6:9], v[22:25], v[80:83]
	v_mfma_f32_16x16x32_f16 v[72:75], v[14:17], v[22:25], v[72:75]
	v_mfma_f32_16x16x32_f16 v[56:59], v[6:9], v[108:111], v[56:59]
	v_mfma_f32_16x16x32_f16 v[68:71], v[14:17], v[108:111], v[68:71]
	v_mfma_f32_16x16x32_f16 v[160:163], v[6:9], v[168:171], v[160:163]
	v_mfma_f32_16x16x32_f16 v[156:159], v[14:17], v[168:171], v[156:159]
	v_mfma_f32_16x16x32_f16 v[152:155], v[6:9], v[176:179], v[152:155]
	v_mfma_f32_16x16x32_f16 v[148:151], v[14:17], v[176:179], v[148:151]
	v_mfma_f32_16x16x32_f16 v[80:83], v[10:13], v[88:91], v[80:83]
	v_mfma_f32_16x16x32_f16 v[72:75], v[18:21], v[88:91], v[72:75]
	v_mfma_f32_16x16x32_f16 v[56:59], v[10:13], v[164:167], v[56:59]
	v_mfma_f32_16x16x32_f16 v[68:71], v[18:21], v[164:167], v[68:71]
	v_mfma_f32_16x16x32_f16 v[160:163], v[10:13], v[172:175], v[160:163]
	v_mfma_f32_16x16x32_f16 v[156:159], v[18:21], v[172:175], v[156:159]
	v_mfma_f32_16x16x32_f16 v[152:155], v[10:13], v[180:183], v[152:155]
	v_mfma_f32_16x16x32_f16 v[148:151], v[18:21], v[180:183], v[148:151]
	s_barrier
	v_lshl_add_u64 v[224:225], v[202:203], 0, s[16:17]
	s_mov_b32 m0, s19
	v_lshl_add_u64 v[26:27], v[224:225], 0, s[30:31]
	v_lshl_add_u64 v[226:227], v[220:221], 0, s[16:17]
	ds_read_b128 v[184:187], v238
	ds_read_b128 v[188:191], v238 offset:1024
	ds_read_b128 v[192:195], v238 offset:2048
	ds_read_b128 v[196:199], v238 offset:3072
	global_load_lds_dwordx4 v[26:27], off
	v_lshl_add_u64 v[26:27], v[226:227], 0, s[30:31]
	s_mov_b32 m0, s37
	s_nop 0
	global_load_lds_dwordx4 v[26:27], off
	s_barrier
	s_waitcnt lgkmcnt(0)
	s_waitcnt lgkmcnt(0)
	v_mfma_f32_16x16x32_f16 v[52:55], v[184:187], v[22:25], v[52:55]
	v_mfma_f32_16x16x32_f16 v[22:25], v[192:195], v[22:25], v[40:43]
	v_mfma_f32_16x16x32_f16 v[40:43], v[184:187], v[168:171], v[144:147]
	v_mfma_f32_16x16x32_f16 v[52:55], v[188:191], v[88:91], v[52:55]
	v_mfma_f32_16x16x32_f16 v[22:25], v[196:199], v[88:91], v[22:25]
	v_mfma_f32_16x16x32_f16 v[88:91], v[188:191], v[172:175], v[40:43]
	v_mfma_f32_16x16x32_f16 v[40:43], v[192:195], v[168:171], v[124:127]
	v_mfma_f32_16x16x32_f16 v[36:39], v[184:187], v[108:111], v[36:39]
	v_mfma_f32_16x16x32_f16 v[26:29], v[192:195], v[108:111], v[28:31]
	v_mfma_f32_16x16x32_f16 v[108:111], v[196:199], v[172:175], v[40:43]
	v_mfma_f32_16x16x32_f16 v[40:43], v[184:187], v[176:179], v[120:123]
	v_mfma_f32_16x16x32_f16 v[120:123], v[188:191], v[180:183], v[40:43]
	v_mfma_f32_16x16x32_f16 v[40:43], v[192:195], v[176:179], v[116:119]
	v_mfma_f32_16x16x32_f16 v[36:39], v[188:191], v[164:167], v[36:39]
	v_mfma_f32_16x16x32_f16 v[26:29], v[196:199], v[164:167], v[26:29]
	v_mfma_f32_16x16x32_f16 v[116:119], v[196:199], v[180:183], v[40:43]
	s_mov_b32 m0, s7
	v_lshl_add_u64 v[30:31], v[246:247], 0, s[30:31]
	s_barrier
	s_nop 0
	ds_read_b128 v[40:43], v236 offset:16384
	ds_read_b128 v[124:127], v236 offset:17408
	ds_read_b128 v[144:147], v236 offset:18432
	ds_read_b128 v[164:167], v236 offset:19456
	ds_read_b128 v[168:171], v236 offset:20480
	ds_read_b128 v[172:175], v236 offset:21504
	ds_read_b128 v[176:179], v236 offset:22528
	ds_read_b128 v[180:183], v236 offset:23552
	global_load_lds_dwordx4 v[30:31], off
	v_lshl_add_u64 v[30:31], v[248:249], 0, s[30:31]
	s_mov_b32 m0, s8
	s_nop 0
	global_load_lds_dwordx4 v[30:31], off
	s_barrier
	s_waitcnt lgkmcnt(0)
	s_waitcnt lgkmcnt(0)
	v_mfma_f32_16x16x32_f16 v[112:115], v[6:9], v[40:43], v[112:115]
	v_mfma_f32_16x16x32_f16 v[104:107], v[14:17], v[40:43], v[104:107]
	v_mfma_f32_16x16x32_f16 v[100:103], v[6:9], v[144:147], v[100:103]
	v_mfma_f32_16x16x32_f16 v[96:99], v[14:17], v[144:147], v[96:99]
	v_mfma_f32_16x16x32_f16 v[140:143], v[6:9], v[168:171], v[140:143]
	v_mfma_f32_16x16x32_f16 v[136:139], v[14:17], v[168:171], v[136:139]
	v_mfma_f32_16x16x32_f16 v[6:9], v[6:9], v[176:179], v[132:135]
	v_mfma_f32_16x16x32_f16 v[112:115], v[10:13], v[124:127], v[112:115]
	v_mfma_f32_16x16x32_f16 v[104:107], v[18:21], v[124:127], v[104:107]
	v_mfma_f32_16x16x32_f16 v[100:103], v[10:13], v[164:167], v[100:103]
	v_mfma_f32_16x16x32_f16 v[96:99], v[18:21], v[164:167], v[96:99]
	v_mfma_f32_16x16x32_f16 v[140:143], v[10:13], v[172:175], v[140:143]
	v_mfma_f32_16x16x32_f16 v[136:139], v[18:21], v[172:175], v[136:139]
	v_mfma_f32_16x16x32_f16 v[6:9], v[10:13], v[180:183], v[6:9]
	v_mfma_f32_16x16x32_f16 v[10:13], v[14:17], v[176:179], v[128:131]
	v_mfma_f32_16x16x32_f16 v[10:13], v[18:21], v[180:183], v[10:13]
	s_barrier
	s_mov_b32 m0, s63
	v_lshl_add_u64 v[14:15], v[224:225], 0, s[84:85]
	global_load_lds_dwordx4 v[14:15], off
	v_lshl_add_u64 v[14:15], v[226:227], 0, s[84:85]
	s_mov_b32 m0, s68
	s_nop 0
	global_load_lds_dwordx4 v[14:15], off
	s_waitcnt vmcnt(6)
	s_barrier
	v_mfma_f32_16x16x32_f16 v[14:17], v[184:187], v[40:43], v[92:95]
	v_mfma_f32_16x16x32_f16 v[18:21], v[192:195], v[40:43], v[84:87]
	v_mfma_f32_16x16x32_f16 v[40:43], v[184:187], v[144:147], v[76:79]
	v_mfma_f32_16x16x32_f16 v[76:79], v[188:191], v[164:167], v[40:43]
	v_mfma_f32_16x16x32_f16 v[40:43], v[192:195], v[144:147], v[64:67]
	v_mfma_f32_16x16x32_f16 v[64:67], v[196:199], v[164:167], v[40:43]
	v_mfma_f32_16x16x32_f16 v[40:43], v[184:187], v[168:171], v[60:63]
	v_mfma_f32_16x16x32_f16 v[60:63], v[188:191], v[172:175], v[40:43]
	v_mfma_f32_16x16x32_f16 v[40:43], v[192:195], v[168:171], v[48:51]
	v_mfma_f32_16x16x32_f16 v[48:51], v[196:199], v[172:175], v[40:43]
	v_mfma_f32_16x16x32_f16 v[30:33], v[184:187], v[176:179], v[32:35]
	v_mfma_f32_16x16x32_f16 v[40:43], v[192:195], v[176:179], v[44:47]
	v_mfma_f32_16x16x32_f16 v[32:35], v[188:191], v[180:183], v[30:33]
	v_mfma_f32_16x16x32_f16 v[44:47], v[196:199], v[180:183], v[40:43]
	v_mfma_f32_16x16x32_f16 v[14:17], v[188:191], v[124:127], v[14:17]
	v_mfma_f32_16x16x32_f16 v[18:21], v[196:199], v[124:127], v[18:21]
	s_barrier
	ds_read_b128 v[84:87], v239
	ds_read_b128 v[92:95], v239 offset:1024
	ds_read_b128 v[128:131], v239 offset:2048
	ds_read_b128 v[164:167], v239 offset:3072
	s_mov_b32 m0, s9
	v_lshl_add_u64 v[30:31], v[246:247], 0, s[84:85]
	ds_read_b128 v[40:43], v236 offset:32768
	ds_read_b128 v[124:127], v236 offset:33792
	ds_read_b128 v[132:135], v236 offset:34816
	ds_read_b128 v[144:147], v236 offset:35840
	ds_read_b128 v[168:171], v236 offset:36864
	ds_read_b128 v[172:175], v236 offset:37888
	ds_read_b128 v[176:179], v236 offset:38912
	ds_read_b128 v[180:183], v236 offset:39936
	global_load_lds_dwordx4 v[30:31], off
	v_lshl_add_u64 v[30:31], v[248:249], 0, s[84:85]
	s_mov_b32 m0, s12
	s_nop 0
	global_load_lds_dwordx4 v[30:31], off
	s_waitcnt lgkmcnt(8)
	s_barrier
	s_waitcnt lgkmcnt(0)
	s_waitcnt lgkmcnt(0)
	v_mfma_f32_16x16x32_f16 v[80:83], v[84:87], v[40:43], v[80:83]
	v_mfma_f32_16x16x32_f16 v[72:75], v[128:131], v[40:43], v[72:75]
	v_mfma_f32_16x16x32_f16 v[56:59], v[84:87], v[132:135], v[56:59]
	v_mfma_f32_16x16x32_f16 v[68:71], v[128:131], v[132:135], v[68:71]
	v_mfma_f32_16x16x32_f16 v[160:163], v[84:87], v[168:171], v[160:163]
	v_mfma_f32_16x16x32_f16 v[156:159], v[128:131], v[168:171], v[156:159]
	v_mfma_f32_16x16x32_f16 v[152:155], v[84:87], v[176:179], v[152:155]
	v_mfma_f32_16x16x32_f16 v[148:151], v[128:131], v[176:179], v[148:151]
	v_mfma_f32_16x16x32_f16 v[80:83], v[92:95], v[124:127], v[80:83]
	v_mfma_f32_16x16x32_f16 v[72:75], v[164:167], v[124:127], v[72:75]
	v_mfma_f32_16x16x32_f16 v[56:59], v[92:95], v[144:147], v[56:59]
	v_mfma_f32_16x16x32_f16 v[68:71], v[164:167], v[144:147], v[68:71]
	v_mfma_f32_16x16x32_f16 v[160:163], v[92:95], v[172:175], v[160:163]
	v_mfma_f32_16x16x32_f16 v[156:159], v[164:167], v[172:175], v[156:159]
	v_mfma_f32_16x16x32_f16 v[152:155], v[92:95], v[180:183], v[152:155]
	v_mfma_f32_16x16x32_f16 v[148:151], v[164:167], v[180:183], v[148:151]
	s_barrier
	s_mov_b32 m0, s69
	v_lshl_add_u64 v[30:31], v[224:225], 0, vcc
	ds_read_b128 v[184:187], v240
	ds_read_b128 v[188:191], v240 offset:1024
	ds_read_b128 v[192:195], v240 offset:2048
	ds_read_b128 v[196:199], v240 offset:3072
	global_load_lds_dwordx4 v[30:31], off
	v_lshl_add_u64 v[30:31], v[226:227], 0, vcc
	s_mov_b32 m0, s70
	s_nop 0
	global_load_lds_dwordx4 v[30:31], off
	s_barrier
	s_waitcnt lgkmcnt(0)
	s_waitcnt lgkmcnt(0)
	v_mfma_f32_16x16x32_f16 v[22:25], v[192:195], v[40:43], v[22:25]
	v_mfma_f32_16x16x32_f16 v[52:55], v[184:187], v[40:43], v[52:55]
	v_mfma_f32_16x16x32_f16 v[40:43], v[196:199], v[124:127], v[22:25]
	v_mfma_f32_16x16x32_f16 v[22:25], v[184:187], v[132:135], v[36:39]
	v_mfma_f32_16x16x32_f16 v[36:39], v[188:191], v[144:147], v[22:25]
	v_mfma_f32_16x16x32_f16 v[22:25], v[192:195], v[132:135], v[26:29]
	v_mfma_f32_16x16x32_f16 v[28:31], v[196:199], v[144:147], v[22:25]
	v_mfma_f32_16x16x32_f16 v[22:25], v[184:187], v[168:171], v[88:91]
	v_mfma_f32_16x16x32_f16 v[144:147], v[188:191], v[172:175], v[22:25]
	v_mfma_f32_16x16x32_f16 v[22:25], v[192:195], v[168:171], v[108:111]
	v_mfma_f32_16x16x32_f16 v[52:55], v[188:191], v[124:127], v[52:55]
	v_mfma_f32_16x16x32_f16 v[124:127], v[196:199], v[172:175], v[22:25]
	v_mfma_f32_16x16x32_f16 v[22:25], v[184:187], v[176:179], v[120:123]
	v_mfma_f32_16x16x32_f16 v[120:123], v[188:191], v[180:183], v[22:25]
	v_mfma_f32_16x16x32_f16 v[22:25], v[192:195], v[176:179], v[116:119]
	v_mfma_f32_16x16x32_f16 v[116:119], v[196:199], v[180:183], v[22:25]
	s_mov_b32 m0, s39
	v_lshl_add_u64 v[26:27], v[246:247], 0, vcc
	s_barrier
	s_nop 2
	ds_read_b128 v[22:25], v236 offset:49152
	ds_read_b128 v[88:91], v236 offset:50176
	ds_read_b128 v[108:111], v236 offset:51200
	ds_read_b128 v[168:171], v236 offset:52224
	ds_read_b128 v[172:175], v236 offset:53248
	ds_read_b128 v[176:179], v236 offset:54272
	ds_read_b128 v[180:183], v236 offset:55296
	ds_read_b128 v[242:245], v236 offset:56320
	global_load_lds_dwordx4 v[26:27], off
	v_lshl_add_u64 v[26:27], v[248:249], 0, vcc
	s_mov_b32 m0, s47
	s_nop 0
	global_load_lds_dwordx4 v[26:27], off
	s_barrier
	s_waitcnt lgkmcnt(0)
	s_waitcnt lgkmcnt(0)
	v_mfma_f32_16x16x32_f16 v[132:135], v[84:87], v[172:175], v[140:143]
	v_mfma_f32_16x16x32_f16 v[140:143], v[92:95], v[176:179], v[132:135]
	v_mfma_f32_16x16x32_f16 v[132:135], v[128:131], v[172:175], v[136:139]
	v_mfma_f32_16x16x32_f16 v[6:9], v[84:87], v[180:183], v[6:9]
	v_mfma_f32_16x16x32_f16 v[112:115], v[84:87], v[22:25], v[112:115]
	v_mfma_f32_16x16x32_f16 v[104:107], v[128:131], v[22:25], v[104:107]
	v_mfma_f32_16x16x32_f16 v[100:103], v[84:87], v[108:111], v[100:103]
	v_mfma_f32_16x16x32_f16 v[96:99], v[128:131], v[108:111], v[96:99]
	v_mfma_f32_16x16x32_f16 v[136:139], v[164:167], v[176:179], v[132:135]
	v_mfma_f32_16x16x32_f16 v[132:135], v[92:95], v[242:245], v[6:9]
	v_mfma_f32_16x16x32_f16 v[6:9], v[128:131], v[180:183], v[10:13]
	v_mfma_f32_16x16x32_f16 v[112:115], v[92:95], v[88:91], v[112:115]
	v_mfma_f32_16x16x32_f16 v[104:107], v[164:167], v[88:91], v[104:107]
	v_mfma_f32_16x16x32_f16 v[100:103], v[92:95], v[168:171], v[100:103]
	v_mfma_f32_16x16x32_f16 v[96:99], v[164:167], v[168:171], v[96:99]
	v_mfma_f32_16x16x32_f16 v[128:131], v[164:167], v[242:245], v[6:9]
	s_barrier
	s_mov_b32 m0, s71
	v_lshl_add_u64 v[6:7], v[224:225], 0, s[52:53]
	global_load_lds_dwordx4 v[6:7], off
	v_lshl_add_u64 v[6:7], v[226:227], 0, s[52:53]
	s_mov_b32 m0, s76
	s_nop 0
	global_load_lds_dwordx4 v[6:7], off
	s_waitcnt vmcnt(6)
	s_barrier
	v_mfma_f32_16x16x32_f16 v[6:9], v[184:187], v[22:25], v[14:17]
	v_mfma_f32_16x16x32_f16 v[92:95], v[188:191], v[88:91], v[6:9]
	v_mfma_f32_16x16x32_f16 v[6:9], v[192:195], v[22:25], v[18:21]
	v_mfma_f32_16x16x32_f16 v[84:87], v[196:199], v[88:91], v[6:9]
	v_mfma_f32_16x16x32_f16 v[6:9], v[184:187], v[108:111], v[76:79]
	v_mfma_f32_16x16x32_f16 v[76:79], v[188:191], v[168:171], v[6:9]
	v_mfma_f32_16x16x32_f16 v[6:9], v[192:195], v[108:111], v[64:67]
	v_mfma_f32_16x16x32_f16 v[64:67], v[196:199], v[168:171], v[6:9]
	v_mfma_f32_16x16x32_f16 v[6:9], v[184:187], v[172:175], v[60:63]
	v_mfma_f32_16x16x32_f16 v[60:63], v[188:191], v[176:179], v[6:9]
	v_mfma_f32_16x16x32_f16 v[6:9], v[192:195], v[172:175], v[48:51]
	v_mfma_f32_16x16x32_f16 v[48:51], v[196:199], v[176:179], v[6:9]
	v_mfma_f32_16x16x32_f16 v[6:9], v[184:187], v[180:183], v[32:35]
	v_mfma_f32_16x16x32_f16 v[32:35], v[188:191], v[242:245], v[6:9]
	v_mfma_f32_16x16x32_f16 v[6:9], v[192:195], v[180:183], v[44:47]
	v_mfma_f32_16x16x32_f16 v[44:47], v[196:199], v[242:245], v[6:9]
	s_add_i32 s10, s10, 2
	s_add_u32 s16, s16, 0x100
	s_addc_u32 s17, s17, 0
	s_cmp_lt_u32 s10, 14
	s_barrier
	s_cbranch_scc1 .LBB0_1744
	s_add_i32 s10, s46, 8
	s_mul_hi_i32 s11, s10, 0x42
	s_mulk_i32 s10, 0x42
	s_add_u32 s10, s10, s48
	v_mov_b32_e32 v4, v233
	v_mov_b32_e32 v5, v234
	s_addc_u32 s11, s11, s78
	s_lshl_b64 s[10:11], s[10:11], 17
	v_readlane_b32 s16, v252, 45
	v_lshlrev_b32_e32 v5, 3, v5
	s_add_u32 s16, s16, s10
	v_readlane_b32 s10, v252, 46
	v_lshlrev_b32_e32 v4, 8, v4
	s_addc_u32 s17, s10, s11
	v_add3_u32 v196, v4, s49, v5
	s_add_u32 s26, s16, 0x4200000
	v_ashrrev_i32_e32 v197, 31, v196
	s_addc_u32 s27, s17, 0
	v_lshlrev_b64 v[4:5], 1, v[196:197]
	v_lshl_add_u64 v[6:7], s[16:17], 0, v[4:5]
	v_lshl_add_u64 v[12:13], s[26:27], 0, v[4:5]
	v_add_u32_e32 v4, 0x1000, v196
	v_ashrrev_i32_e32 v5, 31, v4
	v_lshlrev_b64 v[4:5], 1, v[4:5]
	v_lshl_add_u64 v[14:15], s[16:17], 0, v[4:5]
	v_lshl_add_u64 v[20:21], s[26:27], 0, v[4:5]
	v_add_u32_e32 v4, 0x1080, v196
	v_ashrrev_i32_e32 v5, 31, v4
	v_lshlrev_b64 v[4:5], 1, v[4:5]
	v_lshl_add_u64 v[22:23], s[16:17], 0, v[4:5]
	v_lshl_add_u64 v[26:27], s[26:27], 0, v[4:5]
	v_add_u32_e32 v4, 0x2000, v196
	v_ashrrev_i32_e32 v5, 31, v4
	v_lshlrev_b64 v[4:5], 1, v[4:5]
	v_lshl_add_u64 v[24:25], s[16:17], 0, v[4:5]
	v_lshl_add_u64 v[168:169], s[26:27], 0, v[4:5]
	v_add_u32_e32 v4, 0x2080, v196
	v_ashrrev_i32_e32 v5, 31, v4
	v_lshlrev_b64 v[4:5], 1, v[4:5]
	v_lshl_add_u64 v[16:17], s[16:17], 0, v[4:5]
	v_lshl_add_u64 v[170:171], s[26:27], 0, v[4:5]
	v_add_u32_e32 v4, 0x3000, v196
	v_ashrrev_i32_e32 v5, 31, v4
	v_lshlrev_b64 v[4:5], 1, v[4:5]
	v_lshl_add_u64 v[8:9], s[16:17], 0, v[4:5]
	v_lshl_add_u64 v[176:177], s[26:27], 0, v[4:5]
	v_add_u32_e32 v4, 0x3080, v196
	v_ashrrev_i32_e32 v5, 31, v4
	v_lshlrev_b64 v[4:5], 1, v[4:5]
	v_lshl_add_u64 v[10:11], s[16:17], 0, v[4:5]
	v_lshl_add_u64 v[164:165], s[26:27], 0, v[4:5]
	global_load_dwordx4 v[192:195], v[6:7], off offset:256
	global_load_dwordx4 v[108:111], v[6:7], off
	s_nop 0
	global_load_dwordx4 v[4:7], v[10:11], off
	s_nop 0
	global_load_dwordx4 v[8:11], v[8:9], off
	s_nop 0
	global_load_dwordx4 v[16:19], v[16:17], off
	s_nop 0
	global_load_dwordx4 v[172:175], v[24:25], off
	global_load_dwordx4 v[180:183], v[22:23], off
	global_load_dwordx4 v[188:191], v[14:15], off
	global_load_dwordx4 v[88:91], v[12:13], off offset:256
	global_load_dwordx4 v[198:201], v[12:13], off
	s_nop 0
	global_load_dwordx4 v[164:167], v[164:165], off
	s_nop 0
	global_load_dwordx4 v[12:15], v[176:177], off
	global_load_dwordx4 v[22:25], v[170:171], off
	s_nop 0
	global_load_dwordx4 v[168:171], v[168:169], off
	s_nop 0
	global_load_dwordx4 v[176:179], v[26:27], off
	global_load_dwordx4 v[184:187], v[20:21], off
	s_mov_b32 s29, 14
	s_waitcnt vmcnt(0)
	s_nop 0
	v_cvt_f32_f16_e32 v21, v110
	v_cvt_f32_f16_e32 v20, v108
	v_rcp_f32_e32 v26, v21
	v_cvt_f32_f16_sdwa v21, v108 dst_sel:DWORD dst_unused:UNUSED_PAD src0_sel:WORD_1
	v_rcp_f32_e32 v20, v20
	v_cvt_f32_f16_e32 v202, v198
	v_cvt_f32_f16_sdwa v203, v198 dst_sel:DWORD dst_unused:UNUSED_PAD src0_sel:WORD_1
	v_rcp_f32_e32 v21, v21
	v_cvt_f32_f16_sdwa v27, v110 dst_sel:DWORD dst_unused:UNUSED_PAD src0_sel:WORD_1
	v_cvt_f32_f16_e32 v110, v111
	v_cvt_f32_f16_e32 v108, v109
	v_pk_mul_f32 v[20:21], v[20:21], v[202:203]
	v_cvt_f32_f16_sdwa v109, v109 dst_sel:DWORD dst_unused:UNUSED_PAD src0_sel:WORD_1
	v_pk_mul_f32 v[80:81], v[80:81], v[20:21]
	v_cvt_f32_f16_sdwa v20, v111 dst_sel:DWORD dst_unused:UNUSED_PAD src0_sel:WORD_1
	v_rcp_f32_e32 v110, v110
	v_cvt_f32_f16_sdwa v21, v201 dst_sel:DWORD dst_unused:UNUSED_PAD src0_sel:WORD_1
	v_rcp_f32_e32 v27, v27
	v_rcp_f32_e32 v111, v20
	v_cvt_f32_f16_e32 v20, v201
	v_cvt_f32_f16_e32 v220, v200
	v_cvt_f32_f16_sdwa v221, v200 dst_sel:DWORD dst_unused:UNUSED_PAD src0_sel:WORD_1
	v_rcp_f32_e32 v108, v108
	v_rcp_f32_e32 v109, v109
	v_cvt_f32_f16_e32 v198, v199
	v_cvt_f32_f16_sdwa v199, v199 dst_sel:DWORD dst_unused:UNUSED_PAD src0_sel:WORD_1
	v_pk_mul_f32 v[20:21], v[110:111], v[20:21]
	v_pk_mul_f32 v[26:27], v[26:27], v[220:221]
	v_pk_mul_f32 v[110:111], v[74:75], v[20:21]
	v_cvt_f32_f16_e32 v21, v194
	v_cvt_f32_f16_e32 v75, v195
	v_pk_mul_f32 v[108:109], v[108:109], v[198:199]
	v_cvt_f32_f16_e32 v20, v192
	v_pk_mul_f32 v[82:83], v[82:83], v[108:109]
	v_pk_mul_f32 v[108:109], v[72:73], v[26:27]
	v_rcp_f32_e32 v26, v21
	v_cvt_f32_f16_sdwa v21, v192 dst_sel:DWORD dst_unused:UNUSED_PAD src0_sel:WORD_1
	v_cvt_f32_f16_e32 v72, v88
	v_cvt_f32_f16_sdwa v73, v88 dst_sel:DWORD dst_unused:UNUSED_PAD src0_sel:WORD_1
	v_cvt_f32_f16_e32 v74, v193
	v_rcp_f32_e32 v88, v75
	v_cvt_f32_f16_sdwa v75, v193 dst_sel:DWORD dst_unused:UNUSED_PAD src0_sel:WORD_1
	v_rcp_f32_e32 v20, v20
	v_rcp_f32_e32 v21, v21
	v_rcp_f32_e32 v74, v74
	v_rcp_f32_e32 v75, v75
	v_cvt_f32_f16_e32 v192, v89
	v_cvt_f32_f16_sdwa v193, v89 dst_sel:DWORD dst_unused:UNUSED_PAD src0_sel:WORD_1
	v_pk_mul_f32 v[20:21], v[20:21], v[72:73]
	v_cvt_f32_f16_sdwa v27, v194 dst_sel:DWORD dst_unused:UNUSED_PAD src0_sel:WORD_1
	v_cvt_f32_f16_e32 v198, v90
	v_pk_mul_f32 v[72:73], v[74:75], v[192:193]
	v_cvt_f32_f16_sdwa v199, v90 dst_sel:DWORD dst_unused:UNUSED_PAD src0_sel:WORD_1
	v_pk_mul_f32 v[74:75], v[54:55], v[72:73]
	v_pk_mul_f32 v[72:73], v[52:53], v[20:21]
	v_cvt_f32_f16_sdwa v20, v195 dst_sel:DWORD dst_unused:UNUSED_PAD src0_sel:WORD_1
	v_cvt_f32_f16_sdwa v21, v91 dst_sel:DWORD dst_unused:UNUSED_PAD src0_sel:WORD_1
	v_rcp_f32_e32 v27, v27
	v_cvt_f32_f16_e32 v53, v191
	v_rcp_f32_e32 v89, v20
	v_cvt_f32_f16_e32 v20, v91
	v_pk_mul_f32 v[26:27], v[26:27], v[198:199]
	v_rcp_f32_e32 v54, v53
	v_cvt_f32_f16_e32 v52, v189
	v_pk_mul_f32 v[20:21], v[88:89], v[20:21]
	v_pk_mul_f32 v[88:89], v[40:41], v[26:27]
	v_pk_mul_f32 v[90:91], v[42:43], v[20:21]
	v_cvt_f32_f16_e32 v21, v190
	v_cvt_f32_f16_e32 v20, v188
	v_cvt_f32_f16_e32 v40, v184
	v_cvt_f32_f16_sdwa v41, v184 dst_sel:DWORD dst_unused:UNUSED_PAD src0_sel:WORD_1
	v_rcp_f32_e32 v26, v21
	v_cvt_f32_f16_sdwa v21, v188 dst_sel:DWORD dst_unused:UNUSED_PAD src0_sel:WORD_1
	v_rcp_f32_e32 v20, v20
	v_cvt_f32_f16_sdwa v27, v190 dst_sel:DWORD dst_unused:UNUSED_PAD src0_sel:WORD_1
	v_cvt_f32_f16_e32 v42, v186
	v_rcp_f32_e32 v21, v21
	v_cvt_f32_f16_sdwa v43, v186 dst_sel:DWORD dst_unused:UNUSED_PAD src0_sel:WORD_1
	v_rcp_f32_e32 v27, v27
	v_cvt_f32_f16_sdwa v53, v189 dst_sel:DWORD dst_unused:UNUSED_PAD src0_sel:WORD_1
	v_pk_mul_f32 v[20:21], v[20:21], v[40:41]
	v_rcp_f32_e32 v52, v52
	v_pk_mul_f32 v[56:57], v[56:57], v[20:21]
	v_cvt_f32_f16_sdwa v20, v191 dst_sel:DWORD dst_unused:UNUSED_PAD src0_sel:WORD_1
	v_cvt_f32_f16_sdwa v21, v187 dst_sel:DWORD dst_unused:UNUSED_PAD src0_sel:WORD_1
	v_pk_mul_f32 v[26:27], v[26:27], v[42:43]
	v_cvt_f32_f16_e32 v43, v183
	v_rcp_f32_e32 v55, v20
	v_cvt_f32_f16_e32 v20, v187
	v_rcp_f32_e32 v53, v53
	v_cvt_f32_f16_e32 v184, v185
	v_cvt_f32_f16_sdwa v185, v185 dst_sel:DWORD dst_unused:UNUSED_PAD src0_sel:WORD_1
	v_pk_mul_f32 v[20:21], v[54:55], v[20:21]
	v_pk_mul_f32 v[68:69], v[68:69], v[26:27]
	v_pk_mul_f32 v[70:71], v[70:71], v[20:21]
	v_cvt_f32_f16_e32 v21, v182
	v_cvt_f32_f16_e32 v20, v180
	v_cvt_f32_f16_e32 v42, v181
	v_rcp_f32_e32 v54, v43
	v_rcp_f32_e32 v26, v21
	v_cvt_f32_f16_sdwa v21, v180 dst_sel:DWORD dst_unused:UNUSED_PAD src0_sel:WORD_1
	v_cvt_f32_f16_sdwa v43, v181 dst_sel:DWORD dst_unused:UNUSED_PAD src0_sel:WORD_1
	v_pk_mul_f32 v[40:41], v[52:53], v[184:185]
	v_rcp_f32_e32 v20, v20
	v_pk_mul_f32 v[58:59], v[58:59], v[40:41]
	v_rcp_f32_e32 v21, v21
	v_cvt_f32_f16_e32 v40, v176
	v_cvt_f32_f16_sdwa v41, v176 dst_sel:DWORD dst_unused:UNUSED_PAD src0_sel:WORD_1
	v_rcp_f32_e32 v42, v42
	v_rcp_f32_e32 v43, v43
	v_cvt_f32_f16_e32 v176, v177
	v_cvt_f32_f16_sdwa v177, v177 dst_sel:DWORD dst_unused:UNUSED_PAD src0_sel:WORD_1
	v_pk_mul_f32 v[20:21], v[20:21], v[40:41]
	v_cvt_f32_f16_sdwa v27, v182 dst_sel:DWORD dst_unused:UNUSED_PAD src0_sel:WORD_1
	v_cvt_f32_f16_e32 v52, v178
	v_pk_mul_f32 v[40:41], v[42:43], v[176:177]
	v_cvt_f32_f16_sdwa v53, v178 dst_sel:DWORD dst_unused:UNUSED_PAD src0_sel:WORD_1
	v_pk_mul_f32 v[42:43], v[38:39], v[40:41]
	v_pk_mul_f32 v[40:41], v[36:37], v[20:21]
	v_cvt_f32_f16_sdwa v20, v183 dst_sel:DWORD dst_unused:UNUSED_PAD src0_sel:WORD_1
	v_cvt_f32_f16_sdwa v21, v179 dst_sel:DWORD dst_unused:UNUSED_PAD src0_sel:WORD_1
	v_rcp_f32_e32 v27, v27
	v_cvt_f32_f16_e32 v36, v170
	v_rcp_f32_e32 v55, v20
	v_cvt_f32_f16_e32 v20, v179
	v_pk_mul_f32 v[26:27], v[26:27], v[52:53]
	v_cvt_f32_f16_sdwa v37, v170 dst_sel:DWORD dst_unused:UNUSED_PAD src0_sel:WORD_1
	v_pk_mul_f32 v[52:53], v[28:29], v[26:27]
	v_pk_mul_f32 v[20:21], v[54:55], v[20:21]
	v_cvt_f32_f16_e32 v28, v168
	v_pk_mul_f32 v[54:55], v[30:31], v[20:21]
	v_cvt_f32_f16_e32 v21, v174
	v_cvt_f32_f16_e32 v31, v175
	v_cvt_f32_f16_e32 v20, v172
	v_cvt_f32_f16_e32 v30, v173
	v_rcp_f32_e32 v26, v21
	v_cvt_f32_f16_sdwa v21, v172 dst_sel:DWORD dst_unused:UNUSED_PAD src0_sel:WORD_1
	v_rcp_f32_e32 v38, v31
	v_cvt_f32_f16_sdwa v31, v173 dst_sel:DWORD dst_unused:UNUSED_PAD src0_sel:WORD_1
	v_rcp_f32_e32 v20, v20
	v_rcp_f32_e32 v21, v21
	v_cvt_f32_f16_sdwa v29, v168 dst_sel:DWORD dst_unused:UNUSED_PAD src0_sel:WORD_1
	v_rcp_f32_e32 v30, v30
	v_rcp_f32_e32 v31, v31
	v_cvt_f32_f16_e32 v168, v169
	v_cvt_f32_f16_sdwa v169, v169 dst_sel:DWORD dst_unused:UNUSED_PAD src0_sel:WORD_1
	v_pk_mul_f32 v[20:21], v[20:21], v[28:29]
	v_cvt_f32_f16_sdwa v27, v174 dst_sel:DWORD dst_unused:UNUSED_PAD src0_sel:WORD_1
	v_pk_mul_f32 v[28:29], v[30:31], v[168:169]
	v_rcp_f32_e32 v27, v27
	v_pk_mul_f32 v[30:31], v[162:163], v[28:29]
	v_pk_mul_f32 v[28:29], v[160:161], v[20:21]
	v_cvt_f32_f16_sdwa v20, v175 dst_sel:DWORD dst_unused:UNUSED_PAD src0_sel:WORD_1
	v_cvt_f32_f16_sdwa v21, v171 dst_sel:DWORD dst_unused:UNUSED_PAD src0_sel:WORD_1
	v_pk_mul_f32 v[26:27], v[26:27], v[36:37]
	v_rcp_f32_e32 v39, v20
	v_cvt_f32_f16_e32 v20, v171
	v_pk_mul_f32 v[36:37], v[156:157], v[26:27]
	v_cvt_f32_f16_e32 v156, v22
	v_cvt_f32_f16_sdwa v157, v22 dst_sel:DWORD dst_unused:UNUSED_PAD src0_sel:WORD_1
	v_pk_mul_f32 v[20:21], v[38:39], v[20:21]
	v_cvt_f32_f16_e32 v22, v23
	v_pk_mul_f32 v[38:39], v[158:159], v[20:21]
	v_cvt_f32_f16_e32 v20, v16
	v_cvt_f32_f16_e32 v21, v18
	v_cvt_f32_f16_sdwa v16, v16 dst_sel:DWORD dst_unused:UNUSED_PAD src0_sel:WORD_1
	v_cvt_f32_f16_sdwa v23, v23 dst_sel:DWORD dst_unused:UNUSED_PAD src0_sel:WORD_1
	v_cvt_f32_f16_e32 v158, v24
	v_rcp_f32_e32 v26, v21
	v_rcp_f32_e32 v21, v16
	v_cvt_f32_f16_sdwa v16, v18 dst_sel:DWORD dst_unused:UNUSED_PAD src0_sel:WORD_1
	v_cvt_f32_f16_e32 v18, v19
	v_cvt_f32_f16_sdwa v159, v24 dst_sel:DWORD dst_unused:UNUSED_PAD src0_sel:WORD_1
	v_rcp_f32_e32 v20, v20
	v_rcp_f32_e32 v27, v16
	v_cvt_f32_f16_e32 v16, v17
	v_cvt_f32_f16_sdwa v17, v17 dst_sel:DWORD dst_unused:UNUSED_PAD src0_sel:WORD_1
	v_rcp_f32_e32 v18, v18
	v_pk_mul_f32 v[20:21], v[20:21], v[156:157]
	v_rcp_f32_e32 v16, v16
	v_rcp_f32_e32 v17, v17
	v_pk_mul_f32 v[20:21], v[144:145], v[20:21]
	v_cvt_f32_f16_e32 v144, v165
	v_cvt_f32_f16_sdwa v145, v165 dst_sel:DWORD dst_unused:UNUSED_PAD src0_sel:WORD_1
	v_pk_mul_f32 v[16:17], v[16:17], v[22:23]
	s_nop 0
	v_pk_mul_f32 v[22:23], v[146:147], v[16:17]
	v_cvt_f32_f16_sdwa v16, v19 dst_sel:DWORD dst_unused:UNUSED_PAD src0_sel:WORD_1
	v_cvt_f32_f16_sdwa v17, v25 dst_sel:DWORD dst_unused:UNUSED_PAD src0_sel:WORD_1
	v_rcp_f32_e32 v19, v16
	v_cvt_f32_f16_e32 v16, v25
	v_pk_mul_f32 v[24:25], v[26:27], v[158:159]
	v_pk_mul_f32 v[16:17], v[18:19], v[16:17]
	s_nop 0
	v_pk_mul_f32 v[26:27], v[126:127], v[16:17]
	v_cvt_f32_f16_e32 v16, v8
	v_cvt_f32_f16_e32 v17, v10
	v_cvt_f32_f16_sdwa v8, v8 dst_sel:DWORD dst_unused:UNUSED_PAD src0_sel:WORD_1
	v_pk_mul_f32 v[24:25], v[124:125], v[24:25]
	v_cvt_f32_f16_e32 v18, v12
	v_rcp_f32_e32 v124, v17
	v_rcp_f32_e32 v17, v8
	v_cvt_f32_f16_sdwa v8, v10 dst_sel:DWORD dst_unused:UNUSED_PAD src0_sel:WORD_1
	v_cvt_f32_f16_sdwa v19, v12 dst_sel:DWORD dst_unused:UNUSED_PAD src0_sel:WORD_1
	v_cvt_f32_f16_e32 v12, v13
	v_cvt_f32_f16_sdwa v13, v13 dst_sel:DWORD dst_unused:UNUSED_PAD src0_sel:WORD_1
	v_rcp_f32_e32 v125, v8
	v_cvt_f32_f16_e32 v8, v9
	v_cvt_f32_f16_sdwa v9, v9 dst_sel:DWORD dst_unused:UNUSED_PAD src0_sel:WORD_1
	v_rcp_f32_e32 v16, v16
	v_cvt_f32_f16_e32 v10, v11
	v_rcp_f32_e32 v8, v8
	v_rcp_f32_e32 v9, v9
	v_pk_mul_f32 v[16:17], v[16:17], v[18:19]
	v_rcp_f32_e32 v10, v10
	v_cvt_f32_f16_e32 v126, v14
	v_pk_mul_f32 v[8:9], v[8:9], v[12:13]
	v_cvt_f32_f16_sdwa v127, v14 dst_sel:DWORD dst_unused:UNUSED_PAD src0_sel:WORD_1
	v_pk_mul_f32 v[18:19], v[154:155], v[8:9]
	v_cvt_f32_f16_sdwa v8, v11 dst_sel:DWORD dst_unused:UNUSED_PAD src0_sel:WORD_1
	v_cvt_f32_f16_sdwa v9, v15 dst_sel:DWORD dst_unused:UNUSED_PAD src0_sel:WORD_1
	v_pk_mul_f32 v[12:13], v[124:125], v[126:127]
	v_cvt_f32_f16_e32 v126, v166
	v_rcp_f32_e32 v11, v8
	v_cvt_f32_f16_e32 v8, v15
	v_cvt_f32_f16_sdwa v127, v166 dst_sel:DWORD dst_unused:UNUSED_PAD src0_sel:WORD_1
	v_pk_mul_f32 v[16:17], v[152:153], v[16:17]
	v_pk_mul_f32 v[12:13], v[148:149], v[12:13]
	v_pk_mul_f32 v[8:9], v[10:11], v[8:9]
	v_cvt_f32_f16_e32 v10, v164
	v_pk_mul_f32 v[14:15], v[150:151], v[8:9]
	v_cvt_f32_f16_e32 v8, v4
	v_cvt_f32_f16_e32 v9, v6
	v_cvt_f32_f16_sdwa v4, v4 dst_sel:DWORD dst_unused:UNUSED_PAD src0_sel:WORD_1
	v_cvt_f32_f16_sdwa v11, v164 dst_sel:DWORD dst_unused:UNUSED_PAD src0_sel:WORD_1
	v_rcp_f32_e32 v8, v8
	v_rcp_f32_e32 v124, v9
	v_rcp_f32_e32 v9, v4
	v_cvt_f32_f16_sdwa v4, v6 dst_sel:DWORD dst_unused:UNUSED_PAD src0_sel:WORD_1
	v_cvt_f32_f16_e32 v6, v7
	v_pk_mul_f32 v[8:9], v[8:9], v[10:11]
	v_rcp_f32_e32 v125, v4
	v_cvt_f32_f16_e32 v4, v5
	v_cvt_f32_f16_sdwa v5, v5 dst_sel:DWORD dst_unused:UNUSED_PAD src0_sel:WORD_1
	v_rcp_f32_e32 v6, v6
	v_pk_mul_f32 v[8:9], v[120:121], v[8:9]
	v_rcp_f32_e32 v4, v4
	v_rcp_f32_e32 v5, v5
	v_pk_mul_f32 v[120:121], v[124:125], v[126:127]
	v_pk_mul_f32 v[4:5], v[4:5], v[144:145]
	s_nop 0
	v_pk_mul_f32 v[10:11], v[122:123], v[4:5]
	v_cvt_f32_f16_sdwa v4, v7 dst_sel:DWORD dst_unused:UNUSED_PAD src0_sel:WORD_1
	v_cvt_f32_f16_sdwa v5, v167 dst_sel:DWORD dst_unused:UNUSED_PAD src0_sel:WORD_1
	v_rcp_f32_e32 v7, v4
	v_cvt_f32_f16_e32 v4, v167
	v_pk_mul_f32 v[4:5], v[6:7], v[4:5]
	s_nop 0
	v_pk_mul_f32 v[6:7], v[118:119], v[4:5]
	v_add_u32_e32 v118, 0x8080, v196
	v_ashrrev_i32_e32 v119, 31, v118
	v_lshlrev_b64 v[118:119], 1, v[118:119]
	v_pk_mul_f32 v[4:5], v[116:117], v[120:121]
	v_lshl_add_u64 v[120:121], s[16:17], 0, v[118:119]
	v_lshl_add_u64 v[124:125], s[26:27], 0, v[118:119]
	v_add_u32_e32 v118, 0x9000, v196
	v_ashrrev_i32_e32 v119, 31, v118
	v_lshlrev_b64 v[118:119], 1, v[118:119]
	v_lshl_add_u64 v[126:127], s[16:17], 0, v[118:119]
	v_lshl_add_u64 v[192:193], s[26:27], 0, v[118:119]
	v_add_u32_e32 v118, 0x9080, v196
	v_ashrrev_i32_e32 v119, 31, v118
	v_lshlrev_b64 v[118:119], 1, v[118:119]
	v_lshl_add_u64 v[144:145], s[16:17], 0, v[118:119]
	v_lshl_add_u64 v[184:185], s[26:27], 0, v[118:119]
	v_add_u32_e32 v118, 0xa000, v196
	v_ashrrev_i32_e32 v119, 31, v118
	v_lshlrev_b64 v[118:119], 1, v[118:119]
	v_lshl_add_u64 v[146:147], s[16:17], 0, v[118:119]
	v_lshl_add_u64 v[176:177], s[26:27], 0, v[118:119]
	v_add_u32_e32 v118, 0xa080, v196
	v_ashrrev_i32_e32 v119, 31, v118
	v_lshlrev_b64 v[118:119], 1, v[118:119]
	v_lshl_add_u64 v[152:153], s[16:17], 0, v[118:119]
	v_lshl_add_u64 v[168:169], s[26:27], 0, v[118:119]
	v_add_u32_e32 v118, 0xb000, v196
	v_ashrrev_i32_e32 v119, 31, v118
	v_lshlrev_b64 v[118:119], 1, v[118:119]
	v_lshl_add_u64 v[154:155], s[16:17], 0, v[118:119]
	v_lshl_add_u64 v[160:161], s[26:27], 0, v[118:119]
	v_add_u32_e32 v118, 0xb080, v196
	v_add_u32_e32 v116, 0x8000, v196
	v_ashrrev_i32_e32 v119, 31, v118
	v_ashrrev_i32_e32 v117, 31, v116
	v_lshlrev_b64 v[118:119], 1, v[118:119]
	v_lshlrev_b64 v[116:117], 1, v[116:117]
	v_lshl_add_u64 v[148:149], s[16:17], 0, v[118:119]
	v_lshl_add_u64 v[162:163], s[26:27], 0, v[118:119]
	v_lshl_add_u64 v[122:123], s[16:17], 0, v[116:117]
	v_lshl_add_u64 v[116:117], s[26:27], 0, v[116:117]
	global_load_dwordx4 v[148:151], v[148:149], off
	s_nop 0
	global_load_dwordx4 v[156:159], v[154:155], off
	global_load_dwordx4 v[164:167], v[152:153], off
	global_load_dwordx4 v[172:175], v[146:147], off
	global_load_dwordx4 v[180:183], v[144:145], off
	global_load_dwordx4 v[188:191], v[126:127], off
	s_nop 0
	global_load_dwordx4 v[118:121], v[120:121], off
	s_nop 0
	global_load_dwordx4 v[144:147], v[122:123], off
	global_load_dwordx4 v[152:155], v[162:163], off
	s_nop 0
	global_load_dwordx4 v[160:163], v[160:161], off
	s_nop 0
	global_load_dwordx4 v[168:171], v[168:169], off
	s_nop 0
	global_load_dwordx4 v[176:179], v[176:177], off
	s_nop 0
	global_load_dwordx4 v[184:187], v[184:185], off
	s_nop 0
	global_load_dwordx4 v[192:195], v[192:193], off
	s_nop 0
	global_load_dwordx4 v[196:199], v[124:125], off
	global_load_dwordx4 v[200:203], v[116:117], off
	s_waitcnt vmcnt(0)
	s_nop 0
	v_cvt_f32_f16_e32 v117, v146
	v_cvt_f32_f16_e32 v127, v147
	v_cvt_f32_f16_e32 v116, v144
	v_cvt_f32_f16_e32 v126, v145
	v_rcp_f32_e32 v122, v117
	v_cvt_f32_f16_sdwa v117, v144 dst_sel:DWORD dst_unused:UNUSED_PAD src0_sel:WORD_1
	v_rcp_f32_e32 v144, v127
	v_cvt_f32_f16_sdwa v127, v145 dst_sel:DWORD dst_unused:UNUSED_PAD src0_sel:WORD_1
	v_rcp_f32_e32 v116, v116
	v_rcp_f32_e32 v117, v117
	v_cvt_f32_f16_e32 v124, v200
	v_cvt_f32_f16_sdwa v125, v200 dst_sel:DWORD dst_unused:UNUSED_PAD src0_sel:WORD_1
	v_rcp_f32_e32 v126, v126
	v_rcp_f32_e32 v127, v127
	v_cvt_f32_f16_e32 v200, v201
	v_cvt_f32_f16_sdwa v201, v201 dst_sel:DWORD dst_unused:UNUSED_PAD src0_sel:WORD_1
	v_cvt_f32_f16_sdwa v123, v146 dst_sel:DWORD dst_unused:UNUSED_PAD src0_sel:WORD_1
	v_pk_mul_f32 v[116:117], v[116:117], v[124:125]
	v_cvt_f32_f16_e32 v220, v202
	v_pk_mul_f32 v[124:125], v[126:127], v[200:201]
	v_rcp_f32_e32 v123, v123
	v_pk_mul_f32 v[126:127], v[114:115], v[124:125]
	v_pk_mul_f32 v[124:125], v[112:113], v[116:117]
	v_cvt_f32_f16_sdwa v112, v147 dst_sel:DWORD dst_unused:UNUSED_PAD src0_sel:WORD_1
	v_cvt_f32_f16_sdwa v221, v202 dst_sel:DWORD dst_unused:UNUSED_PAD src0_sel:WORD_1
	v_cvt_f32_f16_sdwa v113, v203 dst_sel:DWORD dst_unused:UNUSED_PAD src0_sel:WORD_1
	v_cvt_f32_f16_e32 v117, v121
	v_rcp_f32_e32 v145, v112
	v_cvt_f32_f16_e32 v112, v203
	v_pk_mul_f32 v[114:115], v[122:123], v[220:221]
	v_cvt_f32_f16_e32 v116, v119
	s_add_u32 s16, s34, 0x80880
	v_pk_mul_f32 v[112:113], v[144:145], v[112:113]
	v_pk_mul_f32 v[144:145], v[104:105], v[114:115]
	v_cvt_f32_f16_e32 v105, v120
	v_pk_mul_f32 v[146:147], v[106:107], v[112:113]
	v_cvt_f32_f16_e32 v104, v118
	v_cvt_f32_f16_sdwa v107, v120 dst_sel:DWORD dst_unused:UNUSED_PAD src0_sel:WORD_1
	v_rcp_f32_e32 v106, v105
	v_cvt_f32_f16_sdwa v105, v118 dst_sel:DWORD dst_unused:UNUSED_PAD src0_sel:WORD_1
	v_rcp_f32_e32 v120, v117
	v_cvt_f32_f16_sdwa v117, v119 dst_sel:DWORD dst_unused:UNUSED_PAD src0_sel:WORD_1
	v_rcp_f32_e32 v104, v104
	v_rcp_f32_e32 v105, v105
	v_cvt_f32_f16_e32 v112, v196
	v_cvt_f32_f16_sdwa v113, v196 dst_sel:DWORD dst_unused:UNUSED_PAD src0_sel:WORD_1
	v_rcp_f32_e32 v116, v116
	v_rcp_f32_e32 v117, v117
	v_cvt_f32_f16_e32 v118, v197
	v_cvt_f32_f16_sdwa v119, v197 dst_sel:DWORD dst_unused:UNUSED_PAD src0_sel:WORD_1
	v_pk_mul_f32 v[104:105], v[104:105], v[112:113]
	v_rcp_f32_e32 v107, v107
	v_cvt_f32_f16_e32 v114, v198
	v_pk_mul_f32 v[112:113], v[116:117], v[118:119]
	v_pk_mul_f32 v[116:117], v[92:93], v[104:105]
	v_cvt_f32_f16_sdwa v92, v121 dst_sel:DWORD dst_unused:UNUSED_PAD src0_sel:WORD_1
	v_cvt_f32_f16_sdwa v115, v198 dst_sel:DWORD dst_unused:UNUSED_PAD src0_sel:WORD_1
	v_cvt_f32_f16_sdwa v93, v199 dst_sel:DWORD dst_unused:UNUSED_PAD src0_sel:WORD_1
	v_pk_mul_f32 v[118:119], v[94:95], v[112:113]
	v_rcp_f32_e32 v121, v92
	v_cvt_f32_f16_e32 v92, v199
	v_pk_mul_f32 v[94:95], v[106:107], v[114:115]
	v_cvt_f32_f16_e32 v105, v191
	v_cvt_f32_f16_e32 v104, v189
	v_pk_mul_f32 v[92:93], v[120:121], v[92:93]
	v_pk_mul_f32 v[120:121], v[84:85], v[94:95]
	v_cvt_f32_f16_e32 v85, v190
	v_pk_mul_f32 v[122:123], v[86:87], v[92:93]
	v_cvt_f32_f16_e32 v84, v188
	v_rcp_f32_e32 v112, v105
	v_rcp_f32_e32 v86, v85
	v_cvt_f32_f16_sdwa v85, v188 dst_sel:DWORD dst_unused:UNUSED_PAD src0_sel:WORD_1
	v_cvt_f32_f16_sdwa v105, v189 dst_sel:DWORD dst_unused:UNUSED_PAD src0_sel:WORD_1
	v_rcp_f32_e32 v84, v84
	v_cvt_f32_f16_e32 v92, v192
	v_rcp_f32_e32 v85, v85
	v_cvt_f32_f16_sdwa v93, v192 dst_sel:DWORD dst_unused:UNUSED_PAD src0_sel:WORD_1
	v_rcp_f32_e32 v104, v104
	v_rcp_f32_e32 v105, v105
	v_cvt_f32_f16_e32 v106, v193
	v_cvt_f32_f16_sdwa v107, v193 dst_sel:DWORD dst_unused:UNUSED_PAD src0_sel:WORD_1
	v_pk_mul_f32 v[84:85], v[84:85], v[92:93]
	v_cvt_f32_f16_sdwa v87, v190 dst_sel:DWORD dst_unused:UNUSED_PAD src0_sel:WORD_1
	v_cvt_f32_f16_e32 v94, v194
	v_pk_mul_f32 v[92:93], v[104:105], v[106:107]
	v_pk_mul_f32 v[104:105], v[100:101], v[84:85]
	v_cvt_f32_f16_sdwa v84, v191 dst_sel:DWORD dst_unused:UNUSED_PAD src0_sel:WORD_1
	v_cvt_f32_f16_sdwa v85, v195 dst_sel:DWORD dst_unused:UNUSED_PAD src0_sel:WORD_1
	v_rcp_f32_e32 v87, v87
	v_cvt_f32_f16_sdwa v95, v194 dst_sel:DWORD dst_unused:UNUSED_PAD src0_sel:WORD_1
	v_rcp_f32_e32 v113, v84
	v_cvt_f32_f16_e32 v84, v195
	v_pk_mul_f32 v[106:107], v[102:103], v[92:93]
	v_pk_mul_f32 v[86:87], v[86:87], v[94:95]
	v_cvt_f32_f16_e32 v92, v184
	v_pk_mul_f32 v[84:85], v[112:113], v[84:85]
	v_pk_mul_f32 v[112:113], v[96:97], v[86:87]
	v_pk_mul_f32 v[114:115], v[98:99], v[84:85]
	v_cvt_f32_f16_e32 v85, v182
	v_cvt_f32_f16_e32 v97, v183
	v_cvt_f32_f16_e32 v84, v180
	v_cvt_f32_f16_e32 v96, v181
	v_rcp_f32_e32 v86, v85
	v_cvt_f32_f16_sdwa v85, v180 dst_sel:DWORD dst_unused:UNUSED_PAD src0_sel:WORD_1
	v_rcp_f32_e32 v100, v97
	v_cvt_f32_f16_sdwa v97, v181 dst_sel:DWORD dst_unused:UNUSED_PAD src0_sel:WORD_1
	v_rcp_f32_e32 v84, v84
	v_rcp_f32_e32 v85, v85
	v_cvt_f32_f16_sdwa v93, v184 dst_sel:DWORD dst_unused:UNUSED_PAD src0_sel:WORD_1
	v_rcp_f32_e32 v96, v96
	v_rcp_f32_e32 v97, v97
	v_cvt_f32_f16_e32 v98, v185
	v_cvt_f32_f16_sdwa v99, v185 dst_sel:DWORD dst_unused:UNUSED_PAD src0_sel:WORD_1
	v_cvt_f32_f16_sdwa v87, v182 dst_sel:DWORD dst_unused:UNUSED_PAD src0_sel:WORD_1
	v_pk_mul_f32 v[84:85], v[84:85], v[92:93]
	v_cvt_f32_f16_e32 v94, v186
	v_pk_mul_f32 v[92:93], v[96:97], v[98:99]
	v_pk_mul_f32 v[96:97], v[76:77], v[84:85]
	v_cvt_f32_f16_sdwa v76, v183 dst_sel:DWORD dst_unused:UNUSED_PAD src0_sel:WORD_1
	v_rcp_f32_e32 v87, v87
	v_cvt_f32_f16_sdwa v95, v186 dst_sel:DWORD dst_unused:UNUSED_PAD src0_sel:WORD_1
	v_cvt_f32_f16_sdwa v77, v187 dst_sel:DWORD dst_unused:UNUSED_PAD src0_sel:WORD_1
	v_rcp_f32_e32 v101, v76
	v_cvt_f32_f16_e32 v76, v187
	v_pk_mul_f32 v[98:99], v[78:79], v[92:93]
	v_pk_mul_f32 v[78:79], v[86:87], v[94:95]
	v_cvt_f32_f16_e32 v85, v175
	v_pk_mul_f32 v[76:77], v[100:101], v[76:77]
	v_pk_mul_f32 v[100:101], v[64:65], v[78:79]
	v_cvt_f32_f16_e32 v65, v174
	v_pk_mul_f32 v[102:103], v[66:67], v[76:77]
	v_cvt_f32_f16_e32 v64, v172
	v_cvt_f32_f16_e32 v84, v173
	v_rcp_f32_e32 v66, v65
	v_cvt_f32_f16_sdwa v65, v172 dst_sel:DWORD dst_unused:UNUSED_PAD src0_sel:WORD_1
	v_rcp_f32_e32 v92, v85
	v_cvt_f32_f16_sdwa v85, v173 dst_sel:DWORD dst_unused:UNUSED_PAD src0_sel:WORD_1
	v_rcp_f32_e32 v64, v64
	v_rcp_f32_e32 v65, v65
	v_cvt_f32_f16_e32 v76, v176
	v_cvt_f32_f16_sdwa v77, v176 dst_sel:DWORD dst_unused:UNUSED_PAD src0_sel:WORD_1
	v_rcp_f32_e32 v84, v84
	v_rcp_f32_e32 v85, v85
	v_cvt_f32_f16_e32 v86, v177
	v_cvt_f32_f16_sdwa v87, v177 dst_sel:DWORD dst_unused:UNUSED_PAD src0_sel:WORD_1
	v_pk_mul_f32 v[64:65], v[64:65], v[76:77]
	v_cvt_f32_f16_sdwa v67, v174 dst_sel:DWORD dst_unused:UNUSED_PAD src0_sel:WORD_1
	v_cvt_f32_f16_e32 v78, v178
	v_pk_mul_f32 v[76:77], v[84:85], v[86:87]
	v_pk_mul_f32 v[84:85], v[140:141], v[64:65]
	v_cvt_f32_f16_sdwa v64, v175 dst_sel:DWORD dst_unused:UNUSED_PAD src0_sel:WORD_1
	v_cvt_f32_f16_sdwa v65, v179 dst_sel:DWORD dst_unused:UNUSED_PAD src0_sel:WORD_1
	v_rcp_f32_e32 v67, v67
	v_cvt_f32_f16_sdwa v79, v178 dst_sel:DWORD dst_unused:UNUSED_PAD src0_sel:WORD_1
	v_rcp_f32_e32 v93, v64
	v_cvt_f32_f16_e32 v64, v179
	v_pk_mul_f32 v[86:87], v[142:143], v[76:77]
	v_pk_mul_f32 v[66:67], v[66:67], v[78:79]
	v_cvt_f32_f16_sdwa v77, v166 dst_sel:DWORD dst_unused:UNUSED_PAD src0_sel:WORD_1
	v_pk_mul_f32 v[64:65], v[92:93], v[64:65]
	v_pk_mul_f32 v[92:93], v[136:137], v[66:67]
	v_pk_mul_f32 v[94:95], v[138:139], v[64:65]
	v_cvt_f32_f16_e32 v65, v166
	v_cvt_f32_f16_e32 v64, v164
	v_cvt_f32_f16_e32 v137, v167
	v_cvt_f32_f16_e32 v66, v168
	v_rcp_f32_e32 v76, v65
	v_cvt_f32_f16_sdwa v65, v164 dst_sel:DWORD dst_unused:UNUSED_PAD src0_sel:WORD_1
	v_rcp_f32_e32 v64, v64
	v_cvt_f32_f16_sdwa v67, v168 dst_sel:DWORD dst_unused:UNUSED_PAD src0_sel:WORD_1
	v_cvt_f32_f16_e32 v136, v165
	v_rcp_f32_e32 v65, v65
	v_rcp_f32_e32 v138, v137
	v_cvt_f32_f16_sdwa v137, v165 dst_sel:DWORD dst_unused:UNUSED_PAD src0_sel:WORD_1
	v_rcp_f32_e32 v136, v136
	v_cvt_f32_f16_e32 v140, v169
	v_cvt_f32_f16_sdwa v141, v169 dst_sel:DWORD dst_unused:UNUSED_PAD src0_sel:WORD_1
	v_rcp_f32_e32 v137, v137
	v_pk_mul_f32 v[64:65], v[64:65], v[66:67]
	v_rcp_f32_e32 v77, v77
	v_cvt_f32_f16_e32 v78, v170
	v_cvt_f32_f16_sdwa v79, v170 dst_sel:DWORD dst_unused:UNUSED_PAD src0_sel:WORD_1
	v_pk_mul_f32 v[64:65], v[60:61], v[64:65]
	v_cvt_f32_f16_sdwa v60, v167 dst_sel:DWORD dst_unused:UNUSED_PAD src0_sel:WORD_1
	v_pk_mul_f32 v[66:67], v[136:137], v[140:141]
	v_cvt_f32_f16_sdwa v61, v171 dst_sel:DWORD dst_unused:UNUSED_PAD src0_sel:WORD_1
	v_pk_mul_f32 v[66:67], v[62:63], v[66:67]
	v_rcp_f32_e32 v139, v60
	v_cvt_f32_f16_e32 v60, v171
	v_pk_mul_f32 v[62:63], v[76:77], v[78:79]
	v_cvt_f32_f16_e32 v137, v159
	v_pk_mul_f32 v[76:77], v[48:49], v[62:63]
	v_cvt_f32_f16_e32 v49, v158
	v_pk_mul_f32 v[60:61], v[138:139], v[60:61]
	v_cvt_f32_f16_e32 v48, v156
	v_pk_mul_f32 v[78:79], v[50:51], v[60:61]
	v_rcp_f32_e32 v60, v49
	v_cvt_f32_f16_sdwa v49, v156 dst_sel:DWORD dst_unused:UNUSED_PAD src0_sel:WORD_1
	v_rcp_f32_e32 v48, v48
	v_cvt_f32_f16_e32 v50, v160
	v_cvt_f32_f16_sdwa v51, v160 dst_sel:DWORD dst_unused:UNUSED_PAD src0_sel:WORD_1
	v_rcp_f32_e32 v49, v49
	v_cvt_f32_f16_sdwa v61, v158 dst_sel:DWORD dst_unused:UNUSED_PAD src0_sel:WORD_1
	v_cvt_f32_f16_e32 v62, v162
	v_cvt_f32_f16_sdwa v63, v162 dst_sel:DWORD dst_unused:UNUSED_PAD src0_sel:WORD_1
	v_pk_mul_f32 v[48:49], v[48:49], v[50:51]
	v_rcp_f32_e32 v61, v61
	v_pk_mul_f32 v[48:49], v[132:133], v[48:49]
	v_cvt_f32_f16_sdwa v132, v159 dst_sel:DWORD dst_unused:UNUSED_PAD src0_sel:WORD_1
	v_rcp_f32_e32 v138, v137
	v_cvt_f32_f16_sdwa v133, v163 dst_sel:DWORD dst_unused:UNUSED_PAD src0_sel:WORD_1
	v_pk_mul_f32 v[60:61], v[60:61], v[62:63]
	v_rcp_f32_e32 v139, v132
	v_cvt_f32_f16_e32 v132, v163
	v_pk_mul_f32 v[60:61], v[128:129], v[60:61]
	v_cvt_f32_f16_e32 v129, v150
	v_cvt_f32_f16_e32 v136, v157
	v_cvt_f32_f16_sdwa v137, v157 dst_sel:DWORD dst_unused:UNUSED_PAD src0_sel:WORD_1
	v_pk_mul_f32 v[62:63], v[138:139], v[132:133]
	v_cvt_f32_f16_e32 v128, v148
	v_pk_mul_f32 v[62:63], v[130:131], v[62:63]
	v_rcp_f32_e32 v130, v129
	v_cvt_f32_f16_sdwa v129, v148 dst_sel:DWORD dst_unused:UNUSED_PAD src0_sel:WORD_1
	v_rcp_f32_e32 v136, v136
	v_rcp_f32_e32 v137, v137
	v_cvt_f32_f16_e32 v140, v161
	v_cvt_f32_f16_sdwa v141, v161 dst_sel:DWORD dst_unused:UNUSED_PAD src0_sel:WORD_1
	v_rcp_f32_e32 v128, v128
	v_rcp_f32_e32 v129, v129
	v_cvt_f32_f16_e32 v132, v152
	v_cvt_f32_f16_sdwa v133, v152 dst_sel:DWORD dst_unused:UNUSED_PAD src0_sel:WORD_1
	v_pk_mul_f32 v[50:51], v[136:137], v[140:141]
	v_cvt_f32_f16_e32 v137, v151
	v_cvt_f32_f16_sdwa v131, v150 dst_sel:DWORD dst_unused:UNUSED_PAD src0_sel:WORD_1
	v_pk_mul_f32 v[128:129], v[128:129], v[132:133]
	v_cvt_f32_f16_e32 v136, v149
	v_rcp_f32_e32 v138, v137
	v_cvt_f32_f16_sdwa v137, v149 dst_sel:DWORD dst_unused:UNUSED_PAD src0_sel:WORD_1
	v_pk_mul_f32 v[32:33], v[32:33], v[128:129]
	v_cvt_f32_f16_sdwa v128, v151 dst_sel:DWORD dst_unused:UNUSED_PAD src0_sel:WORD_1
	v_pk_mul_f32 v[50:51], v[134:135], v[50:51]
	v_rcp_f32_e32 v131, v131
	v_cvt_f32_f16_e32 v134, v154
	v_cvt_f32_f16_sdwa v135, v154 dst_sel:DWORD dst_unused:UNUSED_PAD src0_sel:WORD_1
	v_rcp_f32_e32 v136, v136
	v_rcp_f32_e32 v137, v137
	v_cvt_f32_f16_e32 v140, v153
	v_cvt_f32_f16_sdwa v141, v153 dst_sel:DWORD dst_unused:UNUSED_PAD src0_sel:WORD_1
	v_rcp_f32_e32 v139, v128
	v_cvt_f32_f16_e32 v128, v155
	v_cvt_f32_f16_sdwa v129, v155 dst_sel:DWORD dst_unused:UNUSED_PAD src0_sel:WORD_1
	s_addc_u32 s17, s35, 0
	v_pk_mul_f32 v[132:133], v[136:137], v[140:141]
	v_pk_mul_f32 v[130:131], v[130:131], v[134:135]
	v_pk_mul_f32 v[128:129], v[138:139], v[128:129]
	s_add_u32 s10, s50, 0x900
	v_pk_mul_f32 v[34:35], v[34:35], v[132:133]
	v_pk_mul_f32 v[46:47], v[46:47], v[128:129]
	v_pk_mul_f32 v[44:45], v[44:45], v[130:131]
	s_addc_u32 s11, s51, 0
.LBB0_1746:
	ds_read_b128 v[128:131], v237
	ds_read_b128 v[132:135], v237 offset:1024
	ds_read_b128 v[136:139], v237 offset:2048
	ds_read_b128 v[140:143], v237 offset:3072
	s_add_u32 s26, s16, 0xfff80080
	s_addc_u32 s27, s17, -1
	s_cmp_eq_u32 s29, 28
	s_cselect_b32 s35, s43, s27
	s_cselect_b32 s34, s42, s26
	s_cselect_b32 s27, s45, s11
	s_cselect_b32 s26, s44, s10
	s_mov_b32 m0, s14
	v_lshl_add_u64 v[180:181], s[16:17], 0, v[210:211]
	ds_read_b128 v[148:151], v236
	ds_read_b128 v[152:155], v236 offset:1024
	ds_read_b128 v[156:159], v236 offset:2048
	ds_read_b128 v[160:163], v236 offset:3072
	ds_read_b128 v[164:167], v236 offset:4096
	ds_read_b128 v[168:171], v236 offset:5120
	ds_read_b128 v[172:175], v236 offset:6144
	ds_read_b128 v[176:179], v236 offset:7168
	global_load_lds_dwordx4 v[180:181], off
	v_lshl_add_u64 v[180:181], s[16:17], 0, v[214:215]
	s_mov_b32 m0, s15
	s_nop 0
	global_load_lds_dwordx4 v[180:181], off
	s_waitcnt lgkmcnt(8)
	s_barrier
	s_waitcnt lgkmcnt(0)
	s_waitcnt lgkmcnt(0)
	v_mfma_f32_16x16x32_f16 v[80:83], v[128:131], v[148:151], v[80:83]
	v_mfma_f32_16x16x32_f16 v[108:111], v[136:139], v[148:151], v[108:111]
	v_mfma_f32_16x16x32_f16 v[56:59], v[128:131], v[156:159], v[56:59]
	v_mfma_f32_16x16x32_f16 v[68:71], v[136:139], v[156:159], v[68:71]
	v_mfma_f32_16x16x32_f16 v[28:31], v[128:131], v[164:167], v[28:31]
	v_mfma_f32_16x16x32_f16 v[36:39], v[136:139], v[164:167], v[36:39]
	v_mfma_f32_16x16x32_f16 v[16:19], v[128:131], v[172:175], v[16:19]
	v_mfma_f32_16x16x32_f16 v[12:15], v[136:139], v[172:175], v[12:15]
	v_mfma_f32_16x16x32_f16 v[80:83], v[132:135], v[152:155], v[80:83]
	v_mfma_f32_16x16x32_f16 v[108:111], v[140:143], v[152:155], v[108:111]
	v_mfma_f32_16x16x32_f16 v[56:59], v[132:135], v[160:163], v[56:59]
	v_mfma_f32_16x16x32_f16 v[68:71], v[140:143], v[160:163], v[68:71]
	v_mfma_f32_16x16x32_f16 v[28:31], v[132:135], v[168:171], v[28:31]
	v_mfma_f32_16x16x32_f16 v[36:39], v[140:143], v[168:171], v[36:39]
	v_mfma_f32_16x16x32_f16 v[16:19], v[132:135], v[176:179], v[16:19]
	v_mfma_f32_16x16x32_f16 v[12:15], v[140:143], v[176:179], v[12:15]
	s_barrier
	s_mov_b32 m0, s19
	v_lshl_add_u64 v[196:197], s[26:27], 0, v[2:3]
	ds_read_b128 v[180:183], v238
	ds_read_b128 v[184:187], v238 offset:1024
	ds_read_b128 v[188:191], v238 offset:2048
	ds_read_b128 v[192:195], v238 offset:3072
	global_load_lds_dwordx4 v[196:197], off
	v_lshl_add_u64 v[198:199], s[26:27], 0, v[206:207]
	s_mov_b32 m0, s37
	s_nop 0
	global_load_lds_dwordx4 v[198:199], off
	s_barrier
	s_waitcnt lgkmcnt(0)
	s_waitcnt lgkmcnt(0)
	v_mfma_f32_16x16x32_f16 v[72:75], v[180:183], v[148:151], v[72:75]
	v_mfma_f32_16x16x32_f16 v[88:91], v[188:191], v[148:151], v[88:91]
	v_mfma_f32_16x16x32_f16 v[40:43], v[180:183], v[156:159], v[40:43]
	v_mfma_f32_16x16x32_f16 v[52:55], v[188:191], v[156:159], v[52:55]
	v_mfma_f32_16x16x32_f16 v[20:23], v[180:183], v[164:167], v[20:23]
	v_mfma_f32_16x16x32_f16 v[24:27], v[188:191], v[164:167], v[24:27]
	v_mfma_f32_16x16x32_f16 v[8:11], v[180:183], v[172:175], v[8:11]
	v_mfma_f32_16x16x32_f16 v[4:7], v[188:191], v[172:175], v[4:7]
	v_mfma_f32_16x16x32_f16 v[72:75], v[184:187], v[152:155], v[72:75]
	v_mfma_f32_16x16x32_f16 v[88:91], v[192:195], v[152:155], v[88:91]
	v_mfma_f32_16x16x32_f16 v[40:43], v[184:187], v[160:163], v[40:43]
	v_mfma_f32_16x16x32_f16 v[52:55], v[192:195], v[160:163], v[52:55]
	v_mfma_f32_16x16x32_f16 v[20:23], v[184:187], v[168:171], v[20:23]
	v_mfma_f32_16x16x32_f16 v[24:27], v[192:195], v[168:171], v[24:27]
	v_mfma_f32_16x16x32_f16 v[8:11], v[184:187], v[176:179], v[8:11]
	v_mfma_f32_16x16x32_f16 v[4:7], v[192:195], v[176:179], v[4:7]
	s_mov_b32 m0, s7
	v_lshl_add_u64 v[200:201], s[34:35], 0, v[210:211]
	s_barrier
	ds_read_b128 v[148:151], v236 offset:16384
	ds_read_b128 v[152:155], v236 offset:17408
	ds_read_b128 v[156:159], v236 offset:18432
	ds_read_b128 v[160:163], v236 offset:19456
	ds_read_b128 v[164:167], v236 offset:20480
	ds_read_b128 v[168:171], v236 offset:21504
	ds_read_b128 v[172:175], v236 offset:22528
	ds_read_b128 v[176:179], v236 offset:23552
	global_load_lds_dwordx4 v[200:201], off
	v_lshl_add_u64 v[202:203], s[34:35], 0, v[208:209]
	s_mov_b32 m0, s8
	s_nop 0
	global_load_lds_dwordx4 v[202:203], off
	s_barrier
	s_waitcnt lgkmcnt(0)
	s_waitcnt lgkmcnt(0)
	v_mfma_f32_16x16x32_f16 v[124:127], v[128:131], v[148:151], v[124:127]
	v_mfma_f32_16x16x32_f16 v[144:147], v[136:139], v[148:151], v[144:147]
	v_mfma_f32_16x16x32_f16 v[104:107], v[128:131], v[156:159], v[104:107]
	v_mfma_f32_16x16x32_f16 v[112:115], v[136:139], v[156:159], v[112:115]
	v_mfma_f32_16x16x32_f16 v[84:87], v[128:131], v[164:167], v[84:87]
	v_mfma_f32_16x16x32_f16 v[92:95], v[136:139], v[164:167], v[92:95]
	v_mfma_f32_16x16x32_f16 v[48:51], v[128:131], v[172:175], v[48:51]
	v_mfma_f32_16x16x32_f16 v[60:63], v[136:139], v[172:175], v[60:63]
	v_mfma_f32_16x16x32_f16 v[124:127], v[132:135], v[152:155], v[124:127]
	v_mfma_f32_16x16x32_f16 v[144:147], v[140:143], v[152:155], v[144:147]
	v_mfma_f32_16x16x32_f16 v[104:107], v[132:135], v[160:163], v[104:107]
	v_mfma_f32_16x16x32_f16 v[112:115], v[140:143], v[160:163], v[112:115]
	v_mfma_f32_16x16x32_f16 v[84:87], v[132:135], v[168:171], v[84:87]
	v_mfma_f32_16x16x32_f16 v[92:95], v[140:143], v[168:171], v[92:95]
	v_mfma_f32_16x16x32_f16 v[48:51], v[132:135], v[176:179], v[48:51]
	v_mfma_f32_16x16x32_f16 v[60:63], v[140:143], v[176:179], v[60:63]
	s_barrier
	s_add_u32 s30, s26, 0x80000
	s_addc_u32 s31, s27, 0
	s_mov_b32 m0, s63
	v_lshl_add_u64 v[128:129], s[30:31], 0, v[2:3]
	global_load_lds_dwordx4 v[128:129], off
	v_lshl_add_u64 v[128:129], s[30:31], 0, v[206:207]
	s_mov_b32 m0, s68
	s_nop 0
	global_load_lds_dwordx4 v[128:129], off
	s_waitcnt vmcnt(6)
	s_barrier
	v_mfma_f32_16x16x32_f16 v[116:119], v[180:183], v[148:151], v[116:119]
	v_mfma_f32_16x16x32_f16 v[120:123], v[188:191], v[148:151], v[120:123]
	v_mfma_f32_16x16x32_f16 v[96:99], v[180:183], v[156:159], v[96:99]
	v_mfma_f32_16x16x32_f16 v[100:103], v[188:191], v[156:159], v[100:103]
	v_mfma_f32_16x16x32_f16 v[64:67], v[180:183], v[164:167], v[64:67]
	v_mfma_f32_16x16x32_f16 v[76:79], v[188:191], v[164:167], v[76:79]
	v_mfma_f32_16x16x32_f16 v[32:35], v[180:183], v[172:175], v[32:35]
	v_mfma_f32_16x16x32_f16 v[44:47], v[188:191], v[172:175], v[44:47]
	v_mfma_f32_16x16x32_f16 v[116:119], v[184:187], v[152:155], v[116:119]
	v_mfma_f32_16x16x32_f16 v[120:123], v[192:195], v[152:155], v[120:123]
	v_mfma_f32_16x16x32_f16 v[96:99], v[184:187], v[160:163], v[96:99]
	v_mfma_f32_16x16x32_f16 v[100:103], v[192:195], v[160:163], v[100:103]
	v_mfma_f32_16x16x32_f16 v[64:67], v[184:187], v[168:171], v[64:67]
	v_mfma_f32_16x16x32_f16 v[76:79], v[192:195], v[168:171], v[76:79]
	v_mfma_f32_16x16x32_f16 v[32:35], v[184:187], v[176:179], v[32:35]
	v_mfma_f32_16x16x32_f16 v[44:47], v[192:195], v[176:179], v[44:47]
	s_barrier
	ds_read_b128 v[128:131], v239
	ds_read_b128 v[132:135], v239 offset:1024
	ds_read_b128 v[136:139], v239 offset:2048
	ds_read_b128 v[140:143], v239 offset:3072
	s_add_u32 s30, s34, 0x80000
	s_addc_u32 s31, s35, 0
	s_mov_b32 m0, s9
	v_lshl_add_u64 v[180:181], s[30:31], 0, v[210:211]
	ds_read_b128 v[148:151], v236 offset:32768
	ds_read_b128 v[152:155], v236 offset:33792
	ds_read_b128 v[156:159], v236 offset:34816
	ds_read_b128 v[160:163], v236 offset:35840
	ds_read_b128 v[164:167], v236 offset:36864
	ds_read_b128 v[168:171], v236 offset:37888
	ds_read_b128 v[172:175], v236 offset:38912
	ds_read_b128 v[176:179], v236 offset:39936
	global_load_lds_dwordx4 v[180:181], off
	v_lshl_add_u64 v[180:181], s[30:31], 0, v[208:209]
	s_mov_b32 m0, s12
	s_nop 0
	global_load_lds_dwordx4 v[180:181], off
	s_waitcnt lgkmcnt(8)
	s_barrier
	s_waitcnt lgkmcnt(0)
	s_waitcnt lgkmcnt(0)
	v_mfma_f32_16x16x32_f16 v[80:83], v[128:131], v[148:151], v[80:83]
	v_mfma_f32_16x16x32_f16 v[108:111], v[136:139], v[148:151], v[108:111]
	v_mfma_f32_16x16x32_f16 v[56:59], v[128:131], v[156:159], v[56:59]
	v_mfma_f32_16x16x32_f16 v[68:71], v[136:139], v[156:159], v[68:71]
	v_mfma_f32_16x16x32_f16 v[28:31], v[128:131], v[164:167], v[28:31]
	v_mfma_f32_16x16x32_f16 v[36:39], v[136:139], v[164:167], v[36:39]
	v_mfma_f32_16x16x32_f16 v[16:19], v[128:131], v[172:175], v[16:19]
	v_mfma_f32_16x16x32_f16 v[12:15], v[136:139], v[172:175], v[12:15]
	v_mfma_f32_16x16x32_f16 v[80:83], v[132:135], v[152:155], v[80:83]
	v_mfma_f32_16x16x32_f16 v[108:111], v[140:143], v[152:155], v[108:111]
	v_mfma_f32_16x16x32_f16 v[56:59], v[132:135], v[160:163], v[56:59]
	v_mfma_f32_16x16x32_f16 v[68:71], v[140:143], v[160:163], v[68:71]
	v_mfma_f32_16x16x32_f16 v[28:31], v[132:135], v[168:171], v[28:31]
	v_mfma_f32_16x16x32_f16 v[36:39], v[140:143], v[168:171], v[36:39]
	v_mfma_f32_16x16x32_f16 v[16:19], v[132:135], v[176:179], v[16:19]
	v_mfma_f32_16x16x32_f16 v[12:15], v[140:143], v[176:179], v[12:15]
	s_barrier
	s_mov_b32 m0, s69
	v_lshl_add_u64 v[196:197], v[196:197], 0, s[88:89]
	ds_read_b128 v[180:183], v240
	ds_read_b128 v[184:187], v240 offset:1024
	ds_read_b128 v[188:191], v240 offset:2048
	ds_read_b128 v[192:195], v240 offset:3072
	global_load_lds_dwordx4 v[196:197], off
	v_lshl_add_u64 v[196:197], v[198:199], 0, s[88:89]
	s_mov_b32 m0, s70
	s_nop 0
	global_load_lds_dwordx4 v[196:197], off
	s_barrier
	s_waitcnt lgkmcnt(0)
	s_waitcnt lgkmcnt(0)
	v_mfma_f32_16x16x32_f16 v[72:75], v[180:183], v[148:151], v[72:75]
	v_mfma_f32_16x16x32_f16 v[88:91], v[188:191], v[148:151], v[88:91]
	v_mfma_f32_16x16x32_f16 v[40:43], v[180:183], v[156:159], v[40:43]
	v_mfma_f32_16x16x32_f16 v[52:55], v[188:191], v[156:159], v[52:55]
	v_mfma_f32_16x16x32_f16 v[20:23], v[180:183], v[164:167], v[20:23]
	v_mfma_f32_16x16x32_f16 v[24:27], v[188:191], v[164:167], v[24:27]
	v_mfma_f32_16x16x32_f16 v[8:11], v[180:183], v[172:175], v[8:11]
	v_mfma_f32_16x16x32_f16 v[4:7], v[188:191], v[172:175], v[4:7]
	v_mfma_f32_16x16x32_f16 v[72:75], v[184:187], v[152:155], v[72:75]
	v_mfma_f32_16x16x32_f16 v[88:91], v[192:195], v[152:155], v[88:91]
	v_mfma_f32_16x16x32_f16 v[40:43], v[184:187], v[160:163], v[40:43]
	v_mfma_f32_16x16x32_f16 v[52:55], v[192:195], v[160:163], v[52:55]
	v_mfma_f32_16x16x32_f16 v[20:23], v[184:187], v[168:171], v[20:23]
	v_mfma_f32_16x16x32_f16 v[24:27], v[192:195], v[168:171], v[24:27]
	v_mfma_f32_16x16x32_f16 v[8:11], v[184:187], v[176:179], v[8:11]
	v_mfma_f32_16x16x32_f16 v[4:7], v[192:195], v[176:179], v[4:7]
	s_mov_b32 m0, s39
	v_lshl_add_u64 v[196:197], v[200:201], 0, s[88:89]
	s_barrier
	ds_read_b128 v[148:151], v236 offset:49152
	ds_read_b128 v[152:155], v236 offset:50176
	ds_read_b128 v[156:159], v236 offset:51200
	ds_read_b128 v[160:163], v236 offset:52224
	ds_read_b128 v[164:167], v236 offset:53248
	ds_read_b128 v[168:171], v236 offset:54272
	ds_read_b128 v[172:175], v236 offset:55296
	ds_read_b128 v[176:179], v236 offset:56320
	global_load_lds_dwordx4 v[196:197], off
	v_lshl_add_u64 v[196:197], v[202:203], 0, s[88:89]
	s_mov_b32 m0, s47
	s_nop 0
	global_load_lds_dwordx4 v[196:197], off
	s_barrier
	s_waitcnt lgkmcnt(0)
	s_waitcnt lgkmcnt(0)
	v_mfma_f32_16x16x32_f16 v[124:127], v[128:131], v[148:151], v[124:127]
	v_mfma_f32_16x16x32_f16 v[144:147], v[136:139], v[148:151], v[144:147]
	v_mfma_f32_16x16x32_f16 v[104:107], v[128:131], v[156:159], v[104:107]
	v_mfma_f32_16x16x32_f16 v[112:115], v[136:139], v[156:159], v[112:115]
	v_mfma_f32_16x16x32_f16 v[84:87], v[128:131], v[164:167], v[84:87]
	v_mfma_f32_16x16x32_f16 v[92:95], v[136:139], v[164:167], v[92:95]
	v_mfma_f32_16x16x32_f16 v[48:51], v[128:131], v[172:175], v[48:51]
	v_mfma_f32_16x16x32_f16 v[60:63], v[136:139], v[172:175], v[60:63]
	v_mfma_f32_16x16x32_f16 v[124:127], v[132:135], v[152:155], v[124:127]
	v_mfma_f32_16x16x32_f16 v[144:147], v[140:143], v[152:155], v[144:147]
	v_mfma_f32_16x16x32_f16 v[104:107], v[132:135], v[160:163], v[104:107]
	v_mfma_f32_16x16x32_f16 v[112:115], v[140:143], v[160:163], v[112:115]
	v_mfma_f32_16x16x32_f16 v[84:87], v[132:135], v[168:171], v[84:87]
	v_mfma_f32_16x16x32_f16 v[92:95], v[140:143], v[168:171], v[92:95]
	v_mfma_f32_16x16x32_f16 v[48:51], v[132:135], v[176:179], v[48:51]
	v_mfma_f32_16x16x32_f16 v[60:63], v[140:143], v[176:179], v[60:63]
	s_barrier
	s_add_u32 s26, s26, 0x80080
	s_addc_u32 s27, s27, 0
	s_mov_b32 m0, s71
	v_lshl_add_u64 v[128:129], s[26:27], 0, v[2:3]
	global_load_lds_dwordx4 v[128:129], off
	v_lshl_add_u64 v[128:129], s[26:27], 0, v[206:207]
	s_mov_b32 m0, s76
	s_nop 0
	global_load_lds_dwordx4 v[128:129], off
	s_waitcnt vmcnt(6)
	s_barrier
	v_mfma_f32_16x16x32_f16 v[116:119], v[180:183], v[148:151], v[116:119]
	v_mfma_f32_16x16x32_f16 v[120:123], v[188:191], v[148:151], v[120:123]
	v_mfma_f32_16x16x32_f16 v[96:99], v[180:183], v[156:159], v[96:99]
	v_mfma_f32_16x16x32_f16 v[100:103], v[188:191], v[156:159], v[100:103]
	v_mfma_f32_16x16x32_f16 v[64:67], v[180:183], v[164:167], v[64:67]
	v_mfma_f32_16x16x32_f16 v[76:79], v[188:191], v[164:167], v[76:79]
	v_mfma_f32_16x16x32_f16 v[32:35], v[180:183], v[172:175], v[32:35]
	v_mfma_f32_16x16x32_f16 v[44:47], v[188:191], v[172:175], v[44:47]
	v_mfma_f32_16x16x32_f16 v[116:119], v[184:187], v[152:155], v[116:119]
	v_mfma_f32_16x16x32_f16 v[120:123], v[192:195], v[152:155], v[120:123]
	v_mfma_f32_16x16x32_f16 v[96:99], v[184:187], v[160:163], v[96:99]
	v_mfma_f32_16x16x32_f16 v[100:103], v[192:195], v[160:163], v[100:103]
	v_mfma_f32_16x16x32_f16 v[64:67], v[184:187], v[168:171], v[64:67]
	v_mfma_f32_16x16x32_f16 v[76:79], v[192:195], v[168:171], v[76:79]
	v_mfma_f32_16x16x32_f16 v[32:35], v[184:187], v[176:179], v[32:35]
	v_mfma_f32_16x16x32_f16 v[44:47], v[192:195], v[176:179], v[44:47]
	s_add_i32 s29, s29, 2
	s_add_u32 s16, s16, 0x100
	s_addc_u32 s17, s17, 0
	s_add_u32 s10, s10, 0x100
	s_addc_u32 s11, s11, 0
	s_cmp_lt_u32 s29, 30
	s_barrier
	s_cbranch_scc1 .LBB0_1746
	s_add_i32 s10, s46, 16
	s_mul_hi_i32 s11, s10, 0x42
	s_mulk_i32 s10, 0x42
	s_add_u32 s10, s10, s48
	v_mov_b32_e32 v128, v233
	s_addc_u32 s11, s11, s78
	v_mov_b32_e32 v129, v234
	s_lshl_b64 s[10:11], s[10:11], 17
	v_add_u32_e32 v202, s13, v128
	v_lshlrev_b32_e32 v128, 8, v202
	v_lshlrev_b32_e32 v196, 3, v129
	s_add_u32 s10, s4, s10
	s_addc_u32 s11, s6, s11
	v_ashrrev_i32_e32 v197, 31, v196
	v_add_u32_e32 v140, 0x8000, v128
	v_lshl_add_u64 v[130:131], v[196:197], 1, s[10:11]
	v_ashrrev_i32_e32 v141, 31, v140
	v_lshl_add_u64 v[160:161], v[140:141], 1, v[130:131]
	v_add_u32_e32 v140, 0x9000, v128
	v_ashrrev_i32_e32 v129, 31, v128
	v_ashrrev_i32_e32 v141, 31, v140
	v_lshl_add_u64 v[132:133], v[128:129], 1, v[130:131]
	v_add_u32_e32 v134, 0x1000, v128
	v_add_u32_e32 v136, 0x2000, v128
	v_add_u32_e32 v138, 0x3000, v128
	v_lshl_add_u64 v[152:153], v[140:141], 1, v[130:131]
	v_add_u32_e32 v140, 0xa000, v128
	v_add_u32_e32 v128, 0xb000, v128
	v_ashrrev_i32_e32 v135, 31, v134
	v_ashrrev_i32_e32 v137, 31, v136
	v_ashrrev_i32_e32 v139, 31, v138
	v_ashrrev_i32_e32 v141, 31, v140
	v_ashrrev_i32_e32 v129, 31, v128
	v_lshl_add_u64 v[134:135], v[134:135], 1, v[130:131]
	v_lshl_add_u64 v[136:137], v[136:137], 1, v[130:131]
	v_lshl_add_u64 v[138:139], v[138:139], 1, v[130:131]
	v_lshl_add_u64 v[140:141], v[140:141], 1, v[130:131]
	v_lshl_add_u64 v[142:143], v[128:129], 1, v[130:131]
	global_load_dwordx4 v[164:167], v[138:139], off offset:256
	global_load_dwordx4 v[168:171], v[138:139], off
	global_load_dwordx4 v[172:175], v[136:137], off offset:256
	global_load_dwordx4 v[176:179], v[136:137], off
	global_load_dwordx4 v[180:183], v[134:135], off offset:256
	global_load_dwordx4 v[184:187], v[134:135], off
	global_load_dwordx4 v[188:191], v[132:133], off offset:256
	global_load_dwordx4 v[192:195], v[132:133], off
	global_load_dwordx4 v[128:131], v[142:143], off offset:256
	s_nop 0
	global_load_dwordx4 v[132:135], v[142:143], off
	global_load_dwordx4 v[136:139], v[140:141], off offset:256
	s_nop 0
	global_load_dwordx4 v[140:143], v[140:141], off
	s_nop 0
	global_load_dwordx4 v[148:151], v[152:153], off offset:256
	s_nop 0
	global_load_dwordx4 v[152:155], v[152:153], off
	s_nop 0
	global_load_dwordx4 v[156:159], v[160:161], off offset:256
	s_nop 0
	global_load_dwordx4 v[160:163], v[160:161], off
	v_mov_b32_e32 v199, v82
	v_pk_mov_b32 v[82:83], v[82:83], v[108:109] op_sel:[1,0]
	v_lshl_add_u32 v108, s48, 8, v202
	v_mov_b32_e32 v200, v109
	v_ashrrev_i32_e32 v109, 31, v108
	v_mov_b32_e32 v198, v81
	v_mov_b32_e32 v201, v110
	v_lshlrev_b64 v[202:203], 12, v[108:109]
	s_lshl_b32 s10, s46, 8
	s_or_b32 s10, s10, s38
	v_add_u32_e32 v196, s10, v196
	v_readlane_b32 s10, v254, 26
	v_readlane_b32 s11, v254, 27
	v_ashrrev_i32_e32 v197, 31, v196
	s_mov_b32 s46, s18
	s_mov_b32 s48, s36
	s_mov_b64 s[50:51], s[44:45]
	s_mov_b64 s[34:35], s[42:43]
	s_waitcnt vmcnt(0)
	s_nop 0
	v_cvt_f32_f16_e32 v81, v192
	v_cvt_f32_f16_e32 v108, v194
	v_cvt_f32_f16_sdwa v110, v192 dst_sel:DWORD dst_unused:UNUSED_PAD src0_sel:WORD_1
	v_cvt_f32_f16_e32 v220, v193
	v_cvt_f32_f16_sdwa v224, v193 dst_sel:DWORD dst_unused:UNUSED_PAD src0_sel:WORD_1
	v_cvt_f32_f16_sdwa v194, v194 dst_sel:DWORD dst_unused:UNUSED_PAD src0_sel:WORD_1
	v_cvt_f32_f16_e32 v221, v195
	v_rcp_f32_e32 v81, v81
	v_rcp_f32_e32 v109, v108
	v_rcp_f32_e32 v192, v110
	v_rcp_f32_e32 v193, v220
	v_rcp_f32_e32 v108, v224
	v_cvt_f32_f16_sdwa v225, v195 dst_sel:DWORD dst_unused:UNUSED_PAD src0_sel:WORD_1
	v_rcp_f32_e32 v194, v194
	v_rcp_f32_e32 v195, v221
	v_fma_mixlo_f16 v220, v80, v81, 0
	v_pk_mul_f32 v[80:81], v[198:199], v[192:193]
	v_pk_mul_f32 v[82:83], v[82:83], v[108:109]
	v_cvt_pk_f16_f32 v80, v80, v81
	v_cvt_pk_f16_f32 v82, v82, v83
	v_pack_b32_f16 v83, v220, v80
	v_alignbit_b32 v80, v82, v80, 16
	v_pk_mul_f32 v[192:193], v[200:201], v[194:195]
	v_lshrrev_b32_e32 v109, 4, v80
	v_cvt_pk_f16_f32 v81, v192, v193
	v_and_b32_e32 v109, 0x10001, v109
	v_alignbit_b32 v82, v81, v82, 16
	v_add3_u32 v80, v80, v109, s21
	v_rcp_f32_e32 v110, v225
	v_and_b32_e32 v109, 0xfff0fff0, v80
	v_lshrrev_b32_e32 v80, 4, v82
	v_and_b32_e32 v80, 0x10001, v80
	v_add3_u32 v80, v82, v80, s21
	v_cvt_f32_f16_e32 v82, v188
	v_lshrrev_b32_e32 v81, 16, v81
	v_fma_mixhi_f16 v81, v111, v110, 0
	v_and_b32_e32 v110, 0xfff0fff0, v80
	v_lshrrev_b32_e32 v80, 4, v81
	v_lshrrev_b32_e32 v108, 4, v83
	v_and_b32_e32 v80, 0x10001, v80
	v_rcp_f32_e32 v82, v82
	v_and_b32_e32 v108, 0x10001, v108
	v_add3_u32 v80, v81, v80, s21
	v_add3_u32 v83, v83, v108, s21
	v_and_b32_e32 v111, 0xfff0fff0, v80
	v_lshl_add_u64 v[80:81], s[10:11], 0, v[202:203]
	v_and_b32_e32 v108, 0xfff0fff0, v83
	v_lshl_add_u64 v[80:81], v[196:197], 1, v[80:81]
	global_store_dwordx4 v[80:81], v[108:111], off
	v_fma_mixlo_f16 v82, v72, v82, 0
	v_cvt_f32_f16_e32 v72, v190
	v_cvt_f32_f16_sdwa v108, v188 dst_sel:DWORD dst_unused:UNUSED_PAD src0_sel:WORD_1
	v_cvt_f32_f16_sdwa v109, v190 dst_sel:DWORD dst_unused:UNUSED_PAD src0_sel:WORD_1
	v_cvt_f32_f16_e32 v110, v189
	v_rcp_f32_e32 v83, v72
	v_rcp_f32_e32 v108, v108
	v_rcp_f32_e32 v72, v109
	v_rcp_f32_e32 v109, v110
	v_mov_b32_e32 v110, v73
	v_mov_b32_e32 v111, v74
	v_cvt_f32_f16_e32 v73, v191
	v_pk_mul_f32 v[108:109], v[110:111], v[108:109]
	s_mov_b64 s[10:11], 0x10000
	v_cvt_pk_f16_f32 v74, v108, v109
	v_pack_b32_f16 v110, v82, v74
	v_cvt_f32_f16_sdwa v82, v189 dst_sel:DWORD dst_unused:UNUSED_PAD src0_sel:WORD_1
	v_rcp_f32_e32 v73, v73
	v_mov_b32_e32 v108, v89
	v_mov_b32_e32 v109, v90
	v_rcp_f32_e32 v82, v82
	v_pk_mul_f32 v[72:73], v[108:109], v[72:73]
	v_cvt_f32_f16_sdwa v90, v191 dst_sel:DWORD dst_unused:UNUSED_PAD src0_sel:WORD_1
	v_cvt_pk_f16_f32 v89, v72, v73
	v_pk_mov_b32 v[72:73], v[74:75], v[88:89] op_sel:[1,0]
	s_nop 0
	v_pk_mul_f32 v[72:73], v[72:73], v[82:83]
	v_lshrrev_b32_e32 v82, 16, v89
	v_cvt_pk_f16_f32 v72, v72, v73
	v_rcp_f32_e32 v73, v90
	v_alignbit_b32 v74, v72, v74, 16
	v_alignbit_b32 v75, v89, v72, 16
	v_lshrrev_b32_e32 v72, 4, v110
	v_fma_mixhi_f16 v82, v91, v73, 0
	v_lshrrev_b32_e32 v73, 4, v74
	v_and_b32_e32 v73, 0x10001, v73
	v_add3_u32 v73, v74, v73, s21
	v_lshrrev_b32_e32 v74, 4, v75
	v_and_b32_e32 v74, 0x10001, v74
	v_add3_u32 v74, v75, v74, s21
	v_cvt_f32_f16_e32 v75, v184
	v_lshrrev_b32_e32 v83, 4, v82
	v_and_b32_e32 v72, 0x10001, v72
	v_and_b32_e32 v83, 0x10001, v83
	v_rcp_f32_e32 v88, v75
	v_add3_u32 v72, v110, v72, s21
	v_add3_u32 v75, v82, v83, s21
	v_and_b32_e32 v72, 0xfff0fff0, v72
	v_and_b32_e32 v73, 0xfff0fff0, v73
	v_and_b32_e32 v74, 0xfff0fff0, v74
	v_and_b32_e32 v75, 0xfff0fff0, v75
	global_store_dwordx4 v[80:81], v[72:75], off offset:256
	v_cvt_f32_f16_e32 v82, v185
	v_mov_b32_e32 v83, v58
	v_fma_mixlo_f16 v72, v56, v88, 0
	v_cvt_f32_f16_e32 v56, v186
	v_cvt_f32_f16_sdwa v74, v184 dst_sel:DWORD dst_unused:UNUSED_PAD src0_sel:WORD_1
	v_cvt_f32_f16_sdwa v75, v186 dst_sel:DWORD dst_unused:UNUSED_PAD src0_sel:WORD_1
	v_rcp_f32_e32 v73, v56
	v_rcp_f32_e32 v74, v74
	v_rcp_f32_e32 v56, v75
	v_rcp_f32_e32 v75, v82
	v_mov_b32_e32 v82, v57
	v_cvt_f32_f16_e32 v57, v187
	v_pk_mul_f32 v[74:75], v[82:83], v[74:75]
	s_nop 0
	v_cvt_pk_f16_f32 v58, v74, v75
	v_pack_b32_f16 v82, v72, v58
	v_cvt_f32_f16_sdwa v72, v185 dst_sel:DWORD dst_unused:UNUSED_PAD src0_sel:WORD_1
	v_rcp_f32_e32 v57, v57
	v_mov_b32_e32 v74, v69
	v_mov_b32_e32 v75, v70
	v_rcp_f32_e32 v72, v72
	v_pk_mul_f32 v[56:57], v[74:75], v[56:57]
	v_cvt_f32_f16_sdwa v70, v187 dst_sel:DWORD dst_unused:UNUSED_PAD src0_sel:WORD_1
	v_cvt_pk_f16_f32 v69, v56, v57
	v_pk_mov_b32 v[56:57], v[58:59], v[68:69] op_sel:[1,0]
	v_lshrrev_b32_e32 v68, 16, v69
	v_pk_mul_f32 v[56:57], v[56:57], v[72:73]
	s_nop 0
	v_cvt_pk_f16_f32 v56, v56, v57
	v_rcp_f32_e32 v57, v70
	v_alignbit_b32 v58, v56, v58, 16
	v_alignbit_b32 v59, v69, v56, 16
	v_cvt_f32_f16_e32 v70, v180
	v_fma_mixhi_f16 v68, v71, v57, 0
	v_lshrrev_b32_e32 v57, 4, v58
	v_and_b32_e32 v57, 0x10001, v57
	v_add3_u32 v57, v58, v57, s21
	v_lshrrev_b32_e32 v58, 4, v59
	v_and_b32_e32 v58, 0x10001, v58
	v_add3_u32 v58, v59, v58, s21
	v_lshrrev_b32_e32 v59, 4, v68
	v_lshrrev_b32_e32 v56, 4, v82
	v_and_b32_e32 v59, 0x10001, v59
	v_rcp_f32_e32 v72, v70
	v_and_b32_e32 v56, 0x10001, v56
	v_add3_u32 v59, v68, v59, s21
	v_lshl_add_u64 v[68:69], v[80:81], 0, s[10:11]
	s_mov_b32 s10, 0x10000
	v_add3_u32 v56, v82, v56, s21
	v_add_co_u32_e32 v70, vcc, s10, v80
	v_and_b32_e32 v56, 0xfff0fff0, v56
	v_and_b32_e32 v57, 0xfff0fff0, v57
	v_and_b32_e32 v58, 0xfff0fff0, v58
	v_and_b32_e32 v59, 0xfff0fff0, v59
	v_addc_co_u32_e32 v71, vcc, 0, v81, vcc
	global_store_dwordx4 v[70:71], v[56:59], off
	v_cvt_f32_f16_e32 v70, v181
	v_mov_b32_e32 v71, v42
	v_fma_mixlo_f16 v56, v40, v72, 0
	v_cvt_f32_f16_e32 v40, v182
	v_cvt_f32_f16_sdwa v58, v180 dst_sel:DWORD dst_unused:UNUSED_PAD src0_sel:WORD_1
	v_cvt_f32_f16_sdwa v59, v182 dst_sel:DWORD dst_unused:UNUSED_PAD src0_sel:WORD_1
	s_mov_b64 s[10:11], 0x20000
	v_rcp_f32_e32 v57, v40
	v_rcp_f32_e32 v58, v58
	v_rcp_f32_e32 v40, v59
	v_rcp_f32_e32 v59, v70
	v_mov_b32_e32 v70, v41
	v_cvt_f32_f16_e32 v41, v183
	v_pk_mul_f32 v[58:59], v[70:71], v[58:59]
	s_nop 0
	v_cvt_pk_f16_f32 v42, v58, v59
	v_pack_b32_f16 v70, v56, v42
	v_cvt_f32_f16_sdwa v56, v181 dst_sel:DWORD dst_unused:UNUSED_PAD src0_sel:WORD_1
	v_rcp_f32_e32 v41, v41
	v_mov_b32_e32 v58, v53
	v_mov_b32_e32 v59, v54
	v_rcp_f32_e32 v56, v56
	v_pk_mul_f32 v[40:41], v[58:59], v[40:41]
	v_cvt_f32_f16_sdwa v54, v183 dst_sel:DWORD dst_unused:UNUSED_PAD src0_sel:WORD_1
	v_cvt_pk_f16_f32 v53, v40, v41
	v_pk_mov_b32 v[40:41], v[42:43], v[52:53] op_sel:[1,0]
	v_lshrrev_b32_e32 v52, 16, v53
	v_pk_mul_f32 v[40:41], v[40:41], v[56:57]
	s_nop 0
	v_cvt_pk_f16_f32 v40, v40, v41
	v_rcp_f32_e32 v41, v54
	v_alignbit_b32 v42, v40, v42, 16
	v_alignbit_b32 v43, v53, v40, 16
	v_lshrrev_b32_e32 v40, 4, v70
	v_fma_mixhi_f16 v52, v55, v41, 0
	v_lshrrev_b32_e32 v41, 4, v42
	v_and_b32_e32 v41, 0x10001, v41
	v_add3_u32 v41, v42, v41, s21
	v_lshrrev_b32_e32 v42, 4, v43
	v_and_b32_e32 v42, 0x10001, v42
	v_add3_u32 v42, v43, v42, s21
	v_cvt_f32_f16_e32 v43, v176
	v_lshrrev_b32_e32 v53, 4, v52
	v_and_b32_e32 v40, 0x10001, v40
	v_and_b32_e32 v53, 0x10001, v53
	v_rcp_f32_e32 v54, v43
	v_add3_u32 v40, v70, v40, s21
	v_add3_u32 v43, v52, v53, s21
	v_and_b32_e32 v40, 0xfff0fff0, v40
	v_and_b32_e32 v41, 0xfff0fff0, v41
	v_and_b32_e32 v42, 0xfff0fff0, v42
	v_and_b32_e32 v43, 0xfff0fff0, v43
	global_store_dwordx4 v[68:69], v[40:43], off offset:256
	v_cvt_f32_f16_e32 v52, v177
	v_mov_b32_e32 v53, v30
	v_fma_mixlo_f16 v40, v28, v54, 0
	v_cvt_f32_f16_e32 v28, v178
	v_cvt_f32_f16_sdwa v42, v176 dst_sel:DWORD dst_unused:UNUSED_PAD src0_sel:WORD_1
	v_cvt_f32_f16_sdwa v43, v178 dst_sel:DWORD dst_unused:UNUSED_PAD src0_sel:WORD_1
	v_rcp_f32_e32 v41, v28
	v_rcp_f32_e32 v42, v42
	v_rcp_f32_e32 v28, v43
	v_rcp_f32_e32 v43, v52
	v_mov_b32_e32 v52, v29
	v_cvt_f32_f16_e32 v29, v179
	v_pk_mul_f32 v[42:43], v[52:53], v[42:43]
	s_nop 0
	v_cvt_pk_f16_f32 v30, v42, v43
	v_pack_b32_f16 v52, v40, v30
	v_cvt_f32_f16_sdwa v40, v177 dst_sel:DWORD dst_unused:UNUSED_PAD src0_sel:WORD_1
	v_rcp_f32_e32 v29, v29
	v_mov_b32_e32 v42, v37
	v_mov_b32_e32 v43, v38
	v_rcp_f32_e32 v40, v40
	v_pk_mul_f32 v[28:29], v[42:43], v[28:29]
	v_cvt_f32_f16_sdwa v38, v179 dst_sel:DWORD dst_unused:UNUSED_PAD src0_sel:WORD_1
	v_cvt_pk_f16_f32 v37, v28, v29
	v_pk_mov_b32 v[28:29], v[30:31], v[36:37] op_sel:[1,0]
	v_lshrrev_b32_e32 v36, 16, v37
	v_pk_mul_f32 v[28:29], v[28:29], v[40:41]
	s_nop 0
	v_cvt_pk_f16_f32 v28, v28, v29
	v_rcp_f32_e32 v29, v38
	v_alignbit_b32 v30, v28, v30, 16
	v_alignbit_b32 v31, v37, v28, 16
	v_cvt_f32_f16_e32 v38, v172
	v_fma_mixhi_f16 v36, v39, v29, 0
	v_lshrrev_b32_e32 v29, 4, v30
	v_and_b32_e32 v29, 0x10001, v29
	v_add3_u32 v29, v30, v29, s21
	v_lshrrev_b32_e32 v30, 4, v31
	v_and_b32_e32 v30, 0x10001, v30
	v_add3_u32 v30, v31, v30, s21
	v_lshrrev_b32_e32 v31, 4, v36
	v_lshrrev_b32_e32 v28, 4, v52
	v_and_b32_e32 v31, 0x10001, v31
	v_rcp_f32_e32 v40, v38
	v_and_b32_e32 v28, 0x10001, v28
	v_add3_u32 v31, v36, v31, s21
	v_lshl_add_u64 v[36:37], v[80:81], 0, s[10:11]
	s_mov_b32 s10, 0x20000
	v_add3_u32 v28, v52, v28, s21
	v_add_co_u32_e32 v38, vcc, s10, v80
	v_and_b32_e32 v28, 0xfff0fff0, v28
	v_and_b32_e32 v29, 0xfff0fff0, v29
	v_and_b32_e32 v30, 0xfff0fff0, v30
	v_and_b32_e32 v31, 0xfff0fff0, v31
	v_addc_co_u32_e32 v39, vcc, 0, v81, vcc
	global_store_dwordx4 v[38:39], v[28:31], off
	v_cvt_f32_f16_e32 v38, v173
	v_mov_b32_e32 v39, v22
	v_fma_mixlo_f16 v28, v20, v40, 0
	v_cvt_f32_f16_e32 v20, v174
	v_cvt_f32_f16_sdwa v30, v172 dst_sel:DWORD dst_unused:UNUSED_PAD src0_sel:WORD_1
	v_cvt_f32_f16_sdwa v31, v174 dst_sel:DWORD dst_unused:UNUSED_PAD src0_sel:WORD_1
	s_mov_b64 s[10:11], 0x30000
	v_rcp_f32_e32 v29, v20
	v_rcp_f32_e32 v30, v30
	v_rcp_f32_e32 v20, v31
	v_rcp_f32_e32 v31, v38
	v_mov_b32_e32 v38, v21
	v_cvt_f32_f16_e32 v21, v175
	v_pk_mul_f32 v[30:31], v[38:39], v[30:31]
	s_nop 0
	v_cvt_pk_f16_f32 v22, v30, v31
	v_pack_b32_f16 v38, v28, v22
	v_cvt_f32_f16_sdwa v28, v173 dst_sel:DWORD dst_unused:UNUSED_PAD src0_sel:WORD_1
	v_rcp_f32_e32 v21, v21
	v_mov_b32_e32 v30, v25
	v_mov_b32_e32 v31, v26
	v_rcp_f32_e32 v28, v28
	v_pk_mul_f32 v[20:21], v[30:31], v[20:21]
	v_cvt_f32_f16_sdwa v26, v175 dst_sel:DWORD dst_unused:UNUSED_PAD src0_sel:WORD_1
	v_cvt_pk_f16_f32 v25, v20, v21
	v_pk_mov_b32 v[20:21], v[22:23], v[24:25] op_sel:[1,0]
	v_lshrrev_b32_e32 v24, 16, v25
	v_pk_mul_f32 v[20:21], v[20:21], v[28:29]
	s_nop 0
	v_cvt_pk_f16_f32 v20, v20, v21
	v_rcp_f32_e32 v21, v26
	v_alignbit_b32 v22, v20, v22, 16
	v_alignbit_b32 v23, v25, v20, 16
	v_lshrrev_b32_e32 v20, 4, v38
	v_fma_mixhi_f16 v24, v27, v21, 0
	v_lshrrev_b32_e32 v21, 4, v22
	v_and_b32_e32 v21, 0x10001, v21
	v_add3_u32 v21, v22, v21, s21
	v_lshrrev_b32_e32 v22, 4, v23
	v_and_b32_e32 v22, 0x10001, v22
	v_add3_u32 v22, v23, v22, s21
	v_cvt_f32_f16_e32 v23, v168
	v_lshrrev_b32_e32 v25, 4, v24
	v_and_b32_e32 v20, 0x10001, v20
	v_and_b32_e32 v25, 0x10001, v25
	v_rcp_f32_e32 v26, v23
	v_add3_u32 v20, v38, v20, s21
	v_add3_u32 v23, v24, v25, s21
	v_and_b32_e32 v20, 0xfff0fff0, v20
	v_and_b32_e32 v21, 0xfff0fff0, v21
	v_and_b32_e32 v22, 0xfff0fff0, v22
	v_and_b32_e32 v23, 0xfff0fff0, v23
	global_store_dwordx4 v[36:37], v[20:23], off offset:256
	v_cvt_f32_f16_e32 v24, v169
	v_mov_b32_e32 v25, v18
	v_fma_mixlo_f16 v20, v16, v26, 0
	v_cvt_f32_f16_e32 v16, v170
	v_cvt_f32_f16_sdwa v22, v168 dst_sel:DWORD dst_unused:UNUSED_PAD src0_sel:WORD_1
	v_cvt_f32_f16_sdwa v23, v170 dst_sel:DWORD dst_unused:UNUSED_PAD src0_sel:WORD_1
	v_rcp_f32_e32 v21, v16
	v_rcp_f32_e32 v22, v22
	v_rcp_f32_e32 v16, v23
	v_rcp_f32_e32 v23, v24
	v_mov_b32_e32 v24, v17
	v_cvt_f32_f16_e32 v17, v171
	v_pk_mul_f32 v[22:23], v[24:25], v[22:23]
	s_nop 0
	v_cvt_pk_f16_f32 v18, v22, v23
	v_pack_b32_f16 v24, v20, v18
	v_rcp_f32_e32 v17, v17
	v_cvt_f32_f16_sdwa v20, v169 dst_sel:DWORD dst_unused:UNUSED_PAD src0_sel:WORD_1
	v_mov_b32_e32 v22, v13
	v_mov_b32_e32 v23, v14
	v_pk_mul_f32 v[16:17], v[22:23], v[16:17]
	v_rcp_f32_e32 v20, v20
	v_cvt_pk_f16_f32 v14, v16, v17
	v_cvt_f32_f16_sdwa v16, v171 dst_sel:DWORD dst_unused:UNUSED_PAD src0_sel:WORD_1
	v_pk_mov_b32 v[12:13], v[18:19], v[12:13] op_sel:[1,0]
	s_nop 0
	v_pk_mul_f32 v[12:13], v[12:13], v[20:21]
	s_nop 0
	v_cvt_pk_f16_f32 v12, v12, v13
	v_rcp_f32_e32 v13, v16
	v_alignbit_b32 v16, v12, v18, 16
	v_lshrrev_b32_e32 v18, 16, v14
	v_alignbit_b32 v17, v14, v12, 16
	v_fma_mixhi_f16 v18, v15, v13, 0
	v_lshrrev_b32_e32 v15, 4, v18
	v_and_b32_e32 v15, 0x10001, v15
	v_add3_u32 v15, v18, v15, s21
	v_cvt_f32_f16_e32 v18, v164
	v_lshrrev_b32_e32 v13, 4, v16
	v_lshrrev_b32_e32 v14, 4, v17
	v_lshrrev_b32_e32 v12, 4, v24
	v_and_b32_e32 v13, 0x10001, v13
	v_and_b32_e32 v14, 0x10001, v14
	v_rcp_f32_e32 v20, v18
	v_and_b32_e32 v12, 0x10001, v12
	v_add3_u32 v13, v16, v13, s21
	v_add3_u32 v14, v17, v14, s21
	v_lshl_add_u64 v[16:17], v[80:81], 0, s[10:11]
	s_mov_b32 s10, 0x30000
	v_add3_u32 v12, v24, v12, s21
	v_add_co_u32_e32 v18, vcc, s10, v80
	v_and_b32_e32 v12, 0xfff0fff0, v12
	v_and_b32_e32 v13, 0xfff0fff0, v13
	v_and_b32_e32 v14, 0xfff0fff0, v14
	v_and_b32_e32 v15, 0xfff0fff0, v15
	v_addc_co_u32_e32 v19, vcc, 0, v81, vcc
	global_store_dwordx4 v[18:19], v[12:15], off
	v_cvt_f32_f16_e32 v18, v165
	v_mov_b32_e32 v19, v10
	v_fma_mixlo_f16 v12, v8, v20, 0
	v_cvt_f32_f16_e32 v8, v166
	v_cvt_f32_f16_sdwa v14, v164 dst_sel:DWORD dst_unused:UNUSED_PAD src0_sel:WORD_1
	v_cvt_f32_f16_sdwa v15, v166 dst_sel:DWORD dst_unused:UNUSED_PAD src0_sel:WORD_1
	s_mov_b64 s[10:11], 0x80000
	v_rcp_f32_e32 v13, v8
	v_rcp_f32_e32 v14, v14
	v_rcp_f32_e32 v8, v15
	v_rcp_f32_e32 v15, v18
	v_mov_b32_e32 v18, v9
	v_cvt_f32_f16_e32 v9, v167
	v_pk_mul_f32 v[14:15], v[18:19], v[14:15]
	s_nop 0
	v_cvt_pk_f16_f32 v10, v14, v15
	v_pack_b32_f16 v18, v12, v10
	v_rcp_f32_e32 v9, v9
	v_cvt_f32_f16_sdwa v12, v165 dst_sel:DWORD dst_unused:UNUSED_PAD src0_sel:WORD_1
	v_mov_b32_e32 v14, v5
	v_mov_b32_e32 v15, v6
	v_pk_mul_f32 v[8:9], v[14:15], v[8:9]
	v_rcp_f32_e32 v12, v12
	v_cvt_pk_f16_f32 v6, v8, v9
	v_cvt_f32_f16_sdwa v8, v167 dst_sel:DWORD dst_unused:UNUSED_PAD src0_sel:WORD_1
	v_pk_mov_b32 v[4:5], v[10:11], v[4:5] op_sel:[1,0]
	v_mov_b32_e32 v11, v126
	v_pk_mul_f32 v[4:5], v[4:5], v[12:13]
	v_mov_b32_e32 v13, v118
	v_cvt_pk_f16_f32 v4, v4, v5
	v_rcp_f32_e32 v5, v8
	v_alignbit_b32 v8, v4, v10, 16
	v_lshrrev_b32_e32 v10, 16, v6
	v_alignbit_b32 v9, v6, v4, 16
	v_fma_mixhi_f16 v10, v7, v5, 0
	v_cvt_f32_f16_e32 v7, v160
	v_lshrrev_b32_e32 v5, 4, v8
	v_lshrrev_b32_e32 v6, 4, v9
	v_and_b32_e32 v5, 0x10001, v5
	v_and_b32_e32 v6, 0x10001, v6
	v_lshrrev_b32_e32 v4, 4, v18
	v_add3_u32 v5, v8, v5, s21
	v_add3_u32 v6, v9, v6, s21
	v_lshrrev_b32_e32 v8, 4, v10
	v_rcp_f32_e32 v9, v7
	v_and_b32_e32 v4, 0x10001, v4
	v_and_b32_e32 v8, 0x10001, v8
	v_add3_u32 v4, v18, v4, s21
	v_add3_u32 v8, v10, v8, s21
	v_and_b32_e32 v4, 0xfff0fff0, v4
	v_and_b32_e32 v5, 0xfff0fff0, v5
	v_and_b32_e32 v6, 0xfff0fff0, v6
	v_and_b32_e32 v7, 0xfff0fff0, v8
	global_store_dwordx4 v[16:17], v[4:7], off offset:256
	v_mov_b32_e32 v10, v125
	s_nop 0
	v_fma_mixlo_f16 v4, v124, v9, 0
	v_cvt_f32_f16_sdwa v6, v160 dst_sel:DWORD dst_unused:UNUSED_PAD src0_sel:WORD_1
	v_cvt_f32_f16_sdwa v7, v162 dst_sel:DWORD dst_unused:UNUSED_PAD src0_sel:WORD_1
	v_cvt_f32_f16_e32 v9, v161
	v_cvt_f32_f16_e32 v5, v162
	v_rcp_f32_e32 v6, v6
	v_rcp_f32_e32 v8, v7
	v_rcp_f32_e32 v7, v9
	v_cvt_f32_f16_e32 v9, v163
	v_rcp_f32_e32 v5, v5
	v_pk_mul_f32 v[6:7], v[10:11], v[6:7]
	s_nop 0
	v_cvt_pk_f16_f32 v10, v6, v7
	v_pack_b32_f16 v11, v4, v10
	v_cvt_f32_f16_sdwa v4, v161 dst_sel:DWORD dst_unused:UNUSED_PAD src0_sel:WORD_1
	v_rcp_f32_e32 v9, v9
	v_mov_b32_e32 v6, v145
	v_mov_b32_e32 v7, v146
	v_rcp_f32_e32 v4, v4
	v_pk_mul_f32 v[6:7], v[6:7], v[8:9]
	v_cvt_f32_f16_sdwa v9, v163 dst_sel:DWORD dst_unused:UNUSED_PAD src0_sel:WORD_1
	v_cvt_pk_f16_f32 v8, v6, v7
	v_pk_mov_b32 v[6:7], v[126:127], v[144:145] op_sel:[1,0]
	s_nop 0
	v_pk_mul_f32 v[4:5], v[6:7], v[4:5]
	s_nop 0
	v_cvt_pk_f16_f32 v4, v4, v5
	v_rcp_f32_e32 v5, v9
	v_alignbit_b32 v6, v4, v10, 16
	v_alignbit_b32 v7, v8, v4, 16
	v_lshrrev_b32_e32 v8, 16, v8
	v_fma_mixhi_f16 v8, v147, v5, 0
	v_lshrrev_b32_e32 v5, 4, v6
	v_and_b32_e32 v5, 0x10001, v5
	v_add3_u32 v5, v6, v5, s21
	v_lshrrev_b32_e32 v6, 4, v7
	v_and_b32_e32 v6, 0x10001, v6
	v_cvt_f32_f16_e32 v10, v156
	v_add3_u32 v6, v7, v6, s21
	v_lshrrev_b32_e32 v7, 4, v8
	v_lshrrev_b32_e32 v4, 4, v11
	v_and_b32_e32 v7, 0x10001, v7
	v_and_b32_e32 v4, 0x10001, v4
	v_add3_u32 v7, v8, v7, s21
	v_lshl_add_u64 v[8:9], v[80:81], 0, s[10:11]
	s_mov_b32 s10, 0x80000
	v_add3_u32 v4, v11, v4, s21
	v_rcp_f32_e32 v12, v10
	v_add_co_u32_e32 v10, vcc, s10, v80
	v_and_b32_e32 v4, 0xfff0fff0, v4
	v_and_b32_e32 v5, 0xfff0fff0, v5
	v_and_b32_e32 v6, 0xfff0fff0, v6
	v_and_b32_e32 v7, 0xfff0fff0, v7
	v_addc_co_u32_e32 v11, vcc, 0, v81, vcc
	global_store_dwordx4 v[10:11], v[4:7], off
	v_cvt_f32_f16_e32 v11, v157
	s_mov_b64 s[10:11], 0x90000
	v_cvt_f32_f16_sdwa v6, v156 dst_sel:DWORD dst_unused:UNUSED_PAD src0_sel:WORD_1
	v_cvt_f32_f16_sdwa v7, v158 dst_sel:DWORD dst_unused:UNUSED_PAD src0_sel:WORD_1
	v_fma_mixlo_f16 v4, v116, v12, 0
	v_mov_b32_e32 v12, v117
	v_rcp_f32_e32 v6, v6
	v_rcp_f32_e32 v10, v7
	v_rcp_f32_e32 v7, v11
	v_cvt_f32_f16_e32 v11, v159
	v_cvt_f32_f16_e32 v5, v158
	v_pk_mul_f32 v[6:7], v[12:13], v[6:7]
	s_nop 0
	v_cvt_pk_f16_f32 v12, v6, v7
	v_pack_b32_f16 v13, v4, v12
	v_cvt_f32_f16_sdwa v4, v157 dst_sel:DWORD dst_unused:UNUSED_PAD src0_sel:WORD_1
	v_rcp_f32_e32 v11, v11
	v_rcp_f32_e32 v5, v5
	v_mov_b32_e32 v6, v121
	v_mov_b32_e32 v7, v122
	v_rcp_f32_e32 v4, v4
	v_pk_mul_f32 v[6:7], v[6:7], v[10:11]
	v_cvt_f32_f16_sdwa v11, v159 dst_sel:DWORD dst_unused:UNUSED_PAD src0_sel:WORD_1
	v_cvt_pk_f16_f32 v10, v6, v7
	v_pk_mov_b32 v[6:7], v[118:119], v[120:121] op_sel:[1,0]
	s_nop 0
	v_pk_mul_f32 v[4:5], v[6:7], v[4:5]
	s_nop 0
	v_cvt_pk_f16_f32 v4, v4, v5
	v_rcp_f32_e32 v5, v11
	v_alignbit_b32 v6, v4, v12, 16
	v_alignbit_b32 v7, v10, v4, 16
	v_lshrrev_b32_e32 v10, 16, v10
	v_fma_mixhi_f16 v10, v123, v5, 0
	v_lshrrev_b32_e32 v5, 4, v6
	v_and_b32_e32 v5, 0x10001, v5
	v_add3_u32 v5, v6, v5, s21
	v_lshrrev_b32_e32 v6, 4, v7
	v_and_b32_e32 v6, 0x10001, v6
	v_add3_u32 v6, v7, v6, s21
	v_cvt_f32_f16_e32 v7, v152
	v_lshrrev_b32_e32 v4, 4, v13
	v_lshrrev_b32_e32 v11, 4, v10
	v_and_b32_e32 v4, 0x10001, v4
	v_and_b32_e32 v11, 0x10001, v11
	v_add3_u32 v4, v13, v4, s21
	v_rcp_f32_e32 v12, v7
	v_add3_u32 v7, v10, v11, s21
	v_and_b32_e32 v4, 0xfff0fff0, v4
	v_and_b32_e32 v5, 0xfff0fff0, v5
	v_and_b32_e32 v6, 0xfff0fff0, v6
	v_and_b32_e32 v7, 0xfff0fff0, v7
	global_store_dwordx4 v[8:9], v[4:7], off offset:256
	v_cvt_f32_f16_e32 v9, v153
	v_mov_b32_e32 v10, v105
	v_cvt_f32_f16_sdwa v6, v152 dst_sel:DWORD dst_unused:UNUSED_PAD src0_sel:WORD_1
	v_cvt_f32_f16_sdwa v7, v154 dst_sel:DWORD dst_unused:UNUSED_PAD src0_sel:WORD_1
	v_mov_b32_e32 v11, v106
	v_fma_mixlo_f16 v4, v104, v12, 0
	v_rcp_f32_e32 v6, v6
	v_rcp_f32_e32 v8, v7
	v_rcp_f32_e32 v7, v9
	v_cvt_f32_f16_e32 v9, v155
	v_cvt_f32_f16_e32 v5, v154
	v_mov_b32_e32 v13, v98
	v_pk_mul_f32 v[6:7], v[10:11], v[6:7]
	v_rcp_f32_e32 v9, v9
	v_cvt_pk_f16_f32 v10, v6, v7
	v_pack_b32_f16 v11, v4, v10
	v_cvt_f32_f16_sdwa v4, v153 dst_sel:DWORD dst_unused:UNUSED_PAD src0_sel:WORD_1
	v_rcp_f32_e32 v5, v5
	v_mov_b32_e32 v6, v113
	v_mov_b32_e32 v7, v114
	v_rcp_f32_e32 v4, v4
	v_pk_mul_f32 v[6:7], v[6:7], v[8:9]
	v_cvt_f32_f16_sdwa v9, v155 dst_sel:DWORD dst_unused:UNUSED_PAD src0_sel:WORD_1
	v_cvt_pk_f16_f32 v8, v6, v7
	v_pk_mov_b32 v[6:7], v[106:107], v[112:113] op_sel:[1,0]
	s_nop 0
	v_pk_mul_f32 v[4:5], v[6:7], v[4:5]
	s_nop 0
	v_cvt_pk_f16_f32 v4, v4, v5
	v_rcp_f32_e32 v5, v9
	v_alignbit_b32 v6, v4, v10, 16
	v_alignbit_b32 v7, v8, v4, 16
	v_lshrrev_b32_e32 v8, 16, v8
	v_fma_mixhi_f16 v8, v115, v5, 0
	v_lshrrev_b32_e32 v5, 4, v6
	v_and_b32_e32 v5, 0x10001, v5
	v_add3_u32 v5, v6, v5, s21
	v_lshrrev_b32_e32 v6, 4, v7
	v_and_b32_e32 v6, 0x10001, v6
	v_cvt_f32_f16_e32 v10, v148
	v_add3_u32 v6, v7, v6, s21
	v_lshrrev_b32_e32 v7, 4, v8
	v_lshrrev_b32_e32 v4, 4, v11
	v_and_b32_e32 v7, 0x10001, v7
	v_and_b32_e32 v4, 0x10001, v4
	v_add3_u32 v7, v8, v7, s21
	v_lshl_add_u64 v[8:9], v[80:81], 0, s[10:11]
	s_mov_b32 s10, 0x90000
	v_add3_u32 v4, v11, v4, s21
	v_rcp_f32_e32 v12, v10
	v_add_co_u32_e32 v10, vcc, s10, v80
	v_and_b32_e32 v4, 0xfff0fff0, v4
	v_and_b32_e32 v5, 0xfff0fff0, v5
	v_and_b32_e32 v6, 0xfff0fff0, v6
	v_and_b32_e32 v7, 0xfff0fff0, v7
	v_addc_co_u32_e32 v11, vcc, 0, v81, vcc
	global_store_dwordx4 v[10:11], v[4:7], off
	v_cvt_f32_f16_e32 v11, v149
	s_mov_b64 s[10:11], 0xa0000
	v_cvt_f32_f16_sdwa v6, v148 dst_sel:DWORD dst_unused:UNUSED_PAD src0_sel:WORD_1
	v_cvt_f32_f16_sdwa v7, v150 dst_sel:DWORD dst_unused:UNUSED_PAD src0_sel:WORD_1
	v_fma_mixlo_f16 v4, v96, v12, 0
	v_mov_b32_e32 v12, v97
	v_rcp_f32_e32 v6, v6
	v_rcp_f32_e32 v10, v7
	v_rcp_f32_e32 v7, v11
	v_cvt_f32_f16_e32 v11, v151
	v_cvt_f32_f16_e32 v5, v150
	v_pk_mul_f32 v[6:7], v[12:13], v[6:7]
	s_nop 0
	v_cvt_pk_f16_f32 v12, v6, v7
	v_pack_b32_f16 v13, v4, v12
	v_cvt_f32_f16_sdwa v4, v149 dst_sel:DWORD dst_unused:UNUSED_PAD src0_sel:WORD_1
	v_rcp_f32_e32 v11, v11
	v_rcp_f32_e32 v5, v5
	v_mov_b32_e32 v6, v101
	v_mov_b32_e32 v7, v102
	v_rcp_f32_e32 v4, v4
	v_pk_mul_f32 v[6:7], v[6:7], v[10:11]
	v_cvt_f32_f16_sdwa v11, v151 dst_sel:DWORD dst_unused:UNUSED_PAD src0_sel:WORD_1
	v_cvt_pk_f16_f32 v10, v6, v7
	v_pk_mov_b32 v[6:7], v[98:99], v[100:101] op_sel:[1,0]
	s_nop 0
	v_pk_mul_f32 v[4:5], v[6:7], v[4:5]
	s_nop 0
	v_cvt_pk_f16_f32 v4, v4, v5
	v_rcp_f32_e32 v5, v11
	v_alignbit_b32 v6, v4, v12, 16
	v_alignbit_b32 v7, v10, v4, 16
	v_lshrrev_b32_e32 v10, 16, v10
	v_fma_mixhi_f16 v10, v103, v5, 0
	v_lshrrev_b32_e32 v5, 4, v6
	v_and_b32_e32 v5, 0x10001, v5
	v_add3_u32 v5, v6, v5, s21
	v_lshrrev_b32_e32 v6, 4, v7
	v_and_b32_e32 v6, 0x10001, v6
	v_add3_u32 v6, v7, v6, s21
	v_cvt_f32_f16_e32 v7, v140
	v_lshrrev_b32_e32 v4, 4, v13
	v_lshrrev_b32_e32 v11, 4, v10
	v_and_b32_e32 v4, 0x10001, v4
	v_and_b32_e32 v11, 0x10001, v11
	v_add3_u32 v4, v13, v4, s21
	v_rcp_f32_e32 v12, v7
	v_add3_u32 v7, v10, v11, s21
	v_and_b32_e32 v4, 0xfff0fff0, v4
	v_and_b32_e32 v5, 0xfff0fff0, v5
	v_and_b32_e32 v6, 0xfff0fff0, v6
	v_and_b32_e32 v7, 0xfff0fff0, v7
	global_store_dwordx4 v[8:9], v[4:7], off offset:256
	v_cvt_f32_f16_e32 v9, v141
	v_mov_b32_e32 v10, v85
	v_cvt_f32_f16_sdwa v6, v140 dst_sel:DWORD dst_unused:UNUSED_PAD src0_sel:WORD_1
	v_cvt_f32_f16_sdwa v7, v142 dst_sel:DWORD dst_unused:UNUSED_PAD src0_sel:WORD_1
	v_mov_b32_e32 v11, v86
	v_fma_mixlo_f16 v4, v84, v12, 0
	v_rcp_f32_e32 v6, v6
	v_rcp_f32_e32 v8, v7
	v_rcp_f32_e32 v7, v9
	v_cvt_f32_f16_e32 v9, v143
	v_cvt_f32_f16_e32 v5, v142
	v_mov_b32_e32 v13, v66
	v_pk_mul_f32 v[6:7], v[10:11], v[6:7]
	v_rcp_f32_e32 v9, v9
	v_cvt_pk_f16_f32 v10, v6, v7
	v_pack_b32_f16 v11, v4, v10
	v_cvt_f32_f16_sdwa v4, v141 dst_sel:DWORD dst_unused:UNUSED_PAD src0_sel:WORD_1
	v_rcp_f32_e32 v5, v5
	v_mov_b32_e32 v6, v93
	v_mov_b32_e32 v7, v94
	v_rcp_f32_e32 v4, v4
	v_pk_mul_f32 v[6:7], v[6:7], v[8:9]
	v_cvt_f32_f16_sdwa v9, v143 dst_sel:DWORD dst_unused:UNUSED_PAD src0_sel:WORD_1
	v_cvt_pk_f16_f32 v8, v6, v7
	v_pk_mov_b32 v[6:7], v[86:87], v[92:93] op_sel:[1,0]
	s_nop 0
	v_pk_mul_f32 v[4:5], v[6:7], v[4:5]
	s_nop 0
	v_cvt_pk_f16_f32 v4, v4, v5
	v_rcp_f32_e32 v5, v9
	v_alignbit_b32 v6, v4, v10, 16
	v_alignbit_b32 v7, v8, v4, 16
	v_lshrrev_b32_e32 v8, 16, v8
	v_fma_mixhi_f16 v8, v95, v5, 0
	v_lshrrev_b32_e32 v5, 4, v6
	v_and_b32_e32 v5, 0x10001, v5
	v_add3_u32 v5, v6, v5, s21
	v_lshrrev_b32_e32 v6, 4, v7
	v_and_b32_e32 v6, 0x10001, v6
	v_cvt_f32_f16_e32 v10, v136
	v_add3_u32 v6, v7, v6, s21
	v_lshrrev_b32_e32 v7, 4, v8
	v_lshrrev_b32_e32 v4, 4, v11
	v_and_b32_e32 v7, 0x10001, v7
	v_and_b32_e32 v4, 0x10001, v4
	v_add3_u32 v7, v8, v7, s21
	v_lshl_add_u64 v[8:9], v[80:81], 0, s[10:11]
	s_mov_b32 s10, 0xa0000
	v_add3_u32 v4, v11, v4, s21
	v_rcp_f32_e32 v12, v10
	v_add_co_u32_e32 v10, vcc, s10, v80
	v_and_b32_e32 v4, 0xfff0fff0, v4
	v_and_b32_e32 v5, 0xfff0fff0, v5
	v_and_b32_e32 v6, 0xfff0fff0, v6
	v_and_b32_e32 v7, 0xfff0fff0, v7
	v_addc_co_u32_e32 v11, vcc, 0, v81, vcc
	global_store_dwordx4 v[10:11], v[4:7], off
	v_cvt_f32_f16_e32 v11, v137
	s_mov_b64 s[10:11], 0xb0000
	v_cvt_f32_f16_sdwa v6, v136 dst_sel:DWORD dst_unused:UNUSED_PAD src0_sel:WORD_1
	v_cvt_f32_f16_sdwa v7, v138 dst_sel:DWORD dst_unused:UNUSED_PAD src0_sel:WORD_1
	v_fma_mixlo_f16 v4, v64, v12, 0
	v_mov_b32_e32 v12, v65
	v_rcp_f32_e32 v6, v6
	v_rcp_f32_e32 v10, v7
	v_rcp_f32_e32 v7, v11
	v_cvt_f32_f16_e32 v11, v139
	v_cvt_f32_f16_e32 v5, v138
	v_pk_mul_f32 v[6:7], v[12:13], v[6:7]
	s_nop 0
	v_cvt_pk_f16_f32 v12, v6, v7
	v_pack_b32_f16 v13, v4, v12
	v_cvt_f32_f16_sdwa v4, v137 dst_sel:DWORD dst_unused:UNUSED_PAD src0_sel:WORD_1
	v_rcp_f32_e32 v11, v11
	v_rcp_f32_e32 v5, v5
	v_mov_b32_e32 v6, v77
	v_mov_b32_e32 v7, v78
	v_rcp_f32_e32 v4, v4
	v_pk_mul_f32 v[6:7], v[6:7], v[10:11]
	v_cvt_f32_f16_sdwa v11, v139 dst_sel:DWORD dst_unused:UNUSED_PAD src0_sel:WORD_1
	v_cvt_pk_f16_f32 v10, v6, v7
	v_pk_mov_b32 v[6:7], v[66:67], v[76:77] op_sel:[1,0]
	s_nop 0
	v_pk_mul_f32 v[4:5], v[6:7], v[4:5]
	s_nop 0
	v_cvt_pk_f16_f32 v4, v4, v5
	v_rcp_f32_e32 v5, v11
	v_alignbit_b32 v6, v4, v12, 16
	v_alignbit_b32 v7, v10, v4, 16
	v_lshrrev_b32_e32 v10, 16, v10
	v_fma_mixhi_f16 v10, v79, v5, 0
	v_lshrrev_b32_e32 v5, 4, v6
	v_and_b32_e32 v5, 0x10001, v5
	v_add3_u32 v5, v6, v5, s21
	v_lshrrev_b32_e32 v6, 4, v7
	v_and_b32_e32 v6, 0x10001, v6
	v_add3_u32 v6, v7, v6, s21
	v_cvt_f32_f16_e32 v7, v132
	v_lshrrev_b32_e32 v4, 4, v13
	v_lshrrev_b32_e32 v11, 4, v10
	v_and_b32_e32 v4, 0x10001, v4
	v_and_b32_e32 v11, 0x10001, v11
	v_add3_u32 v4, v13, v4, s21
	v_rcp_f32_e32 v12, v7
	v_add3_u32 v7, v10, v11, s21
	v_and_b32_e32 v4, 0xfff0fff0, v4
	v_and_b32_e32 v5, 0xfff0fff0, v5
	v_and_b32_e32 v6, 0xfff0fff0, v6
	v_and_b32_e32 v7, 0xfff0fff0, v7
	global_store_dwordx4 v[8:9], v[4:7], off offset:256
	v_cvt_f32_f16_e32 v9, v133
	v_mov_b32_e32 v10, v49
	v_cvt_f32_f16_sdwa v6, v132 dst_sel:DWORD dst_unused:UNUSED_PAD src0_sel:WORD_1
	v_cvt_f32_f16_sdwa v7, v134 dst_sel:DWORD dst_unused:UNUSED_PAD src0_sel:WORD_1
	v_mov_b32_e32 v11, v50
	v_fma_mixlo_f16 v4, v48, v12, 0
	v_rcp_f32_e32 v6, v6
	v_rcp_f32_e32 v8, v7
	v_rcp_f32_e32 v7, v9
	v_cvt_f32_f16_e32 v9, v135
	v_cvt_f32_f16_e32 v5, v134
	v_mov_b32_e32 v13, v34
	v_pk_mul_f32 v[6:7], v[10:11], v[6:7]
	v_rcp_f32_e32 v9, v9
	v_cvt_pk_f16_f32 v10, v6, v7
	v_pack_b32_f16 v11, v4, v10
	v_cvt_f32_f16_sdwa v4, v133 dst_sel:DWORD dst_unused:UNUSED_PAD src0_sel:WORD_1
	v_rcp_f32_e32 v5, v5
	v_mov_b32_e32 v6, v61
	v_mov_b32_e32 v7, v62
	v_rcp_f32_e32 v4, v4
	v_pk_mul_f32 v[6:7], v[6:7], v[8:9]
	v_cvt_f32_f16_sdwa v9, v135 dst_sel:DWORD dst_unused:UNUSED_PAD src0_sel:WORD_1
	v_cvt_pk_f16_f32 v8, v6, v7
	v_pk_mov_b32 v[6:7], v[50:51], v[60:61] op_sel:[1,0]
	s_nop 0
	v_pk_mul_f32 v[4:5], v[6:7], v[4:5]
	s_nop 0
	v_cvt_pk_f16_f32 v4, v4, v5
	v_rcp_f32_e32 v5, v9
	v_alignbit_b32 v6, v4, v10, 16
	v_alignbit_b32 v7, v8, v4, 16
	v_lshrrev_b32_e32 v8, 16, v8
	v_fma_mixhi_f16 v8, v63, v5, 0
	v_lshrrev_b32_e32 v5, 4, v6
	v_and_b32_e32 v5, 0x10001, v5
	v_add3_u32 v5, v6, v5, s21
	v_lshrrev_b32_e32 v6, 4, v7
	v_and_b32_e32 v6, 0x10001, v6
	v_cvt_f32_f16_e32 v10, v128
	v_add3_u32 v6, v7, v6, s21
	v_lshrrev_b32_e32 v7, 4, v8
	v_lshrrev_b32_e32 v4, 4, v11
	v_and_b32_e32 v7, 0x10001, v7
	v_and_b32_e32 v4, 0x10001, v4
	v_add3_u32 v7, v8, v7, s21
	v_lshl_add_u64 v[8:9], v[80:81], 0, s[10:11]
	s_mov_b32 s10, 0xb0000
	v_add3_u32 v4, v11, v4, s21
	v_rcp_f32_e32 v12, v10
	v_add_co_u32_e32 v10, vcc, s10, v80
	v_and_b32_e32 v4, 0xfff0fff0, v4
	v_and_b32_e32 v5, 0xfff0fff0, v5
	v_and_b32_e32 v6, 0xfff0fff0, v6
	v_and_b32_e32 v7, 0xfff0fff0, v7
	v_addc_co_u32_e32 v11, vcc, 0, v81, vcc
	global_store_dwordx4 v[10:11], v[4:7], off
	v_cvt_f32_f16_e32 v11, v129
	s_andn2_b64 vcc, exec, s[40:41]
	v_cvt_f32_f16_sdwa v6, v128 dst_sel:DWORD dst_unused:UNUSED_PAD src0_sel:WORD_1
	v_cvt_f32_f16_sdwa v7, v130 dst_sel:DWORD dst_unused:UNUSED_PAD src0_sel:WORD_1
	v_fma_mixlo_f16 v4, v32, v12, 0
	v_mov_b32_e32 v12, v33
	v_rcp_f32_e32 v6, v6
	v_rcp_f32_e32 v10, v7
	v_rcp_f32_e32 v7, v11
	v_cvt_f32_f16_e32 v11, v131
	v_cvt_f32_f16_e32 v5, v130
	v_pk_mul_f32 v[6:7], v[12:13], v[6:7]
	s_nop 0
	v_cvt_pk_f16_f32 v12, v6, v7
	v_pack_b32_f16 v13, v4, v12
	v_cvt_f32_f16_sdwa v4, v129 dst_sel:DWORD dst_unused:UNUSED_PAD src0_sel:WORD_1
	v_rcp_f32_e32 v11, v11
	v_rcp_f32_e32 v5, v5
	v_mov_b32_e32 v6, v45
	v_mov_b32_e32 v7, v46
	v_rcp_f32_e32 v4, v4
	v_pk_mul_f32 v[6:7], v[6:7], v[10:11]
	v_cvt_f32_f16_sdwa v11, v131 dst_sel:DWORD dst_unused:UNUSED_PAD src0_sel:WORD_1
	v_cvt_pk_f16_f32 v10, v6, v7
	v_pk_mov_b32 v[6:7], v[34:35], v[44:45] op_sel:[1,0]
	s_nop 0
	v_pk_mul_f32 v[4:5], v[6:7], v[4:5]
	s_nop 0
	v_cvt_pk_f16_f32 v4, v4, v5
	v_rcp_f32_e32 v5, v11
	v_alignbit_b32 v6, v4, v12, 16
	v_alignbit_b32 v7, v10, v4, 16
	v_lshrrev_b32_e32 v10, 16, v10
	v_fma_mixhi_f16 v10, v47, v5, 0
	v_lshrrev_b32_e32 v5, 4, v6
	v_and_b32_e32 v5, 0x10001, v5
	v_add3_u32 v5, v6, v5, s21
	v_lshrrev_b32_e32 v6, 4, v7
	v_and_b32_e32 v6, 0x10001, v6
	v_lshrrev_b32_e32 v4, 4, v13
	v_add3_u32 v6, v7, v6, s21
	v_lshrrev_b32_e32 v7, 4, v10
	v_and_b32_e32 v4, 0x10001, v4
	v_and_b32_e32 v7, 0x10001, v7
	v_add3_u32 v4, v13, v4, s21
	v_add3_u32 v7, v10, v7, s21
	v_and_b32_e32 v4, 0xfff0fff0, v4
	v_and_b32_e32 v5, 0xfff0fff0, v5
	v_and_b32_e32 v6, 0xfff0fff0, v6
	v_and_b32_e32 v7, 0xfff0fff0, v7
	global_store_dwordx4 v[8:9], v[4:7], off offset:256
	s_cbranch_vccnz .LBB0_1739
	s_waitcnt vmcnt(0)
	v_readlane_b32 s4, v251, 63
	s_cmpk_gt_u32 s4, 0xff
	s_cbranch_scc1 .LBB0_1750
	s_barrier

.LBB0_2120:
	s_add_u32 s27, s42, 0xfff80080
	s_addc_u32 s38, s43, -1
	s_add_i32 s46, 0, 0x10000
	v_add_u32_e32 v128, s46, v198
	ds_read_b128 v[108:111], v128
	ds_read_b128 v[112:115], v128 offset:1024
	ds_read_b128 v[120:123], v128 offset:2048
	ds_read_b128 v[128:131], v128 offset:3072
	s_cmp_eq_u32 s17, 28
	s_cselect_b32 s45, s35, s38
	s_cselect_b32 s44, s34, s27
	s_cselect_b32 s39, s37, s15
	s_cselect_b32 s38, s36, s14
	v_lshl_add_u64 v[186:187], s[42:43], 0, v[182:183]
	s_add_i32 m0, s6, 0xc000
	ds_read_b128 v[148:151], v199
	ds_read_b128 v[152:155], v199 offset:1024
	ds_read_b128 v[156:159], v199 offset:2048
	ds_read_b128 v[160:163], v199 offset:3072
	ds_read_b128 v[164:167], v199 offset:4096
	ds_read_b128 v[168:171], v199 offset:5120
	ds_read_b128 v[172:175], v199 offset:6144
	ds_read_b128 v[176:179], v199 offset:7168
	global_load_lds_dwordx4 v[186:187], off
	v_lshl_add_u64 v[186:187], s[42:43], 0, v[184:185]
	s_add_i32 m0, s6, 0xe000
	s_nop 0
	global_load_lds_dwordx4 v[186:187], off
	s_waitcnt lgkmcnt(8)
	s_barrier
	s_waitcnt lgkmcnt(0)
	s_waitcnt lgkmcnt(0)
	v_mfma_f32_16x16x32_f16 v[144:147], v[108:111], v[148:151], v[144:147]
	v_mfma_f32_16x16x32_f16 v[140:143], v[120:123], v[148:151], v[140:143]
	v_mfma_f32_16x16x32_f16 v[124:127], v[108:111], v[156:159], v[124:127]
	v_mfma_f32_16x16x32_f16 v[116:119], v[120:123], v[156:159], v[116:119]
	v_mfma_f32_16x16x32_f16 v[96:99], v[108:111], v[164:167], v[96:99]
	v_mfma_f32_16x16x32_f16 v[92:95], v[120:123], v[164:167], v[92:95]
	v_mfma_f32_16x16x32_f16 v[88:91], v[108:111], v[172:175], v[88:91]
	v_mfma_f32_16x16x32_f16 v[80:83], v[120:123], v[172:175], v[80:83]
	v_mfma_f32_16x16x32_f16 v[144:147], v[112:115], v[152:155], v[144:147]
	v_mfma_f32_16x16x32_f16 v[140:143], v[128:131], v[152:155], v[140:143]
	v_mfma_f32_16x16x32_f16 v[124:127], v[112:115], v[160:163], v[124:127]
	v_mfma_f32_16x16x32_f16 v[116:119], v[128:131], v[160:163], v[116:119]
	v_mfma_f32_16x16x32_f16 v[96:99], v[112:115], v[168:171], v[96:99]
	v_mfma_f32_16x16x32_f16 v[92:95], v[128:131], v[168:171], v[92:95]
	v_mfma_f32_16x16x32_f16 v[88:91], v[112:115], v[176:179], v[88:91]
	v_mfma_f32_16x16x32_f16 v[80:83], v[128:131], v[176:179], v[80:83]
	s_barrier
	s_add_i32 s27, 0, 0x14000
	v_add_u32_e32 v194, s27, v198
	s_add_i32 s46, s46, s5
	ds_read_b128 v[186:189], v194
	ds_read_b128 v[190:193], v194 offset:1024
	ds_read_b128 v[200:203], v194 offset:2048
	ds_read_b128 v[206:209], v194 offset:3072
	v_lshl_add_u64 v[194:195], s[38:39], 0, v[2:3]
	s_mov_b32 m0, s46
	v_lshl_add_u64 v[210:211], s[38:39], 0, v[180:181]
	global_load_lds_dwordx4 v[194:195], off
	s_add_i32 m0, s46, 0x2000
	s_nop 0
	global_load_lds_dwordx4 v[210:211], off
	s_barrier
	s_waitcnt lgkmcnt(0)
	s_waitcnt lgkmcnt(0)
	v_mfma_f32_16x16x32_f16 v[136:139], v[186:189], v[148:151], v[136:139]
	v_mfma_f32_16x16x32_f16 v[132:135], v[200:203], v[148:151], v[132:135]
	v_mfma_f32_16x16x32_f16 v[104:107], v[186:189], v[156:159], v[104:107]
	v_mfma_f32_16x16x32_f16 v[100:103], v[200:203], v[156:159], v[100:103]
	v_mfma_f32_16x16x32_f16 v[84:87], v[186:189], v[164:167], v[84:87]
	v_mfma_f32_16x16x32_f16 v[76:79], v[200:203], v[164:167], v[76:79]
	v_mfma_f32_16x16x32_f16 v[72:75], v[186:189], v[172:175], v[72:75]
	v_mfma_f32_16x16x32_f16 v[68:71], v[200:203], v[172:175], v[68:71]
	v_mfma_f32_16x16x32_f16 v[136:139], v[190:193], v[152:155], v[136:139]
	v_mfma_f32_16x16x32_f16 v[132:135], v[206:209], v[152:155], v[132:135]
	v_mfma_f32_16x16x32_f16 v[104:107], v[190:193], v[160:163], v[104:107]
	v_mfma_f32_16x16x32_f16 v[100:103], v[206:209], v[160:163], v[100:103]
	v_mfma_f32_16x16x32_f16 v[84:87], v[190:193], v[168:171], v[84:87]
	v_mfma_f32_16x16x32_f16 v[76:79], v[206:209], v[168:171], v[76:79]
	v_mfma_f32_16x16x32_f16 v[72:75], v[190:193], v[176:179], v[72:75]
	v_mfma_f32_16x16x32_f16 v[68:71], v[206:209], v[176:179], v[68:71]
	s_mov_b32 m0, s6
	v_lshl_add_u64 v[212:213], s[44:45], 0, v[2:3]
	s_barrier
	ds_read_b128 v[148:151], v199 offset:16384
	ds_read_b128 v[152:155], v199 offset:17408
	ds_read_b128 v[156:159], v199 offset:18432
	ds_read_b128 v[160:163], v199 offset:19456
	ds_read_b128 v[164:167], v199 offset:20480
	ds_read_b128 v[168:171], v199 offset:21504
	ds_read_b128 v[172:175], v199 offset:22528
	ds_read_b128 v[176:179], v199 offset:23552
	global_load_lds_dwordx4 v[212:213], off
	v_lshl_add_u64 v[214:215], s[44:45], 0, v[180:181]
	s_mov_b32 m0, s7
	s_nop 0
	global_load_lds_dwordx4 v[214:215], off
	s_barrier
	s_waitcnt lgkmcnt(0)
	s_waitcnt lgkmcnt(0)
	v_mfma_f32_16x16x32_f16 v[64:67], v[108:111], v[148:151], v[64:67]
	v_mfma_f32_16x16x32_f16 v[60:63], v[120:123], v[148:151], v[60:63]
	v_mfma_f32_16x16x32_f16 v[48:51], v[108:111], v[156:159], v[48:51]
	v_mfma_f32_16x16x32_f16 v[44:47], v[120:123], v[156:159], v[44:47]
	v_mfma_f32_16x16x32_f16 v[32:35], v[108:111], v[164:167], v[32:35]
	v_mfma_f32_16x16x32_f16 v[28:31], v[120:123], v[164:167], v[28:31]
	v_mfma_f32_16x16x32_f16 v[20:23], v[108:111], v[172:175], v[20:23]
	v_mfma_f32_16x16x32_f16 v[12:15], v[120:123], v[172:175], v[12:15]
	v_mfma_f32_16x16x32_f16 v[64:67], v[112:115], v[152:155], v[64:67]
	v_mfma_f32_16x16x32_f16 v[60:63], v[128:131], v[152:155], v[60:63]
	v_mfma_f32_16x16x32_f16 v[48:51], v[112:115], v[160:163], v[48:51]
	v_mfma_f32_16x16x32_f16 v[44:47], v[128:131], v[160:163], v[44:47]
	v_mfma_f32_16x16x32_f16 v[32:35], v[112:115], v[168:171], v[32:35]
	v_mfma_f32_16x16x32_f16 v[28:31], v[128:131], v[168:171], v[28:31]
	v_mfma_f32_16x16x32_f16 v[20:23], v[112:115], v[176:179], v[20:23]
	v_mfma_f32_16x16x32_f16 v[12:15], v[128:131], v[176:179], v[12:15]
	s_barrier
	s_add_u32 s46, s38, 0x80000
	s_addc_u32 s47, s39, 0
	s_add_i32 s27, s27, s5
	v_lshl_add_u64 v[108:109], s[46:47], 0, v[2:3]
	s_mov_b32 m0, s27
	s_nop 0
	global_load_lds_dwordx4 v[108:109], off
	v_lshl_add_u64 v[108:109], s[46:47], 0, v[180:181]
	s_add_i32 m0, s27, 0x2000
	s_nop 0
	global_load_lds_dwordx4 v[108:109], off
	s_waitcnt vmcnt(6)
	s_barrier
	v_mfma_f32_16x16x32_f16 v[56:59], v[186:189], v[148:151], v[56:59]
	v_mfma_f32_16x16x32_f16 v[52:55], v[200:203], v[148:151], v[52:55]
	v_mfma_f32_16x16x32_f16 v[40:43], v[186:189], v[156:159], v[40:43]
	v_mfma_f32_16x16x32_f16 v[36:39], v[200:203], v[156:159], v[36:39]
	v_mfma_f32_16x16x32_f16 v[24:27], v[186:189], v[164:167], v[24:27]
	v_mfma_f32_16x16x32_f16 v[16:19], v[200:203], v[164:167], v[16:19]
	v_mfma_f32_16x16x32_f16 v[8:11], v[186:189], v[172:175], v[8:11]
	v_mfma_f32_16x16x32_f16 v[4:7], v[200:203], v[172:175], v[4:7]
	v_mfma_f32_16x16x32_f16 v[56:59], v[190:193], v[152:155], v[56:59]
	v_mfma_f32_16x16x32_f16 v[52:55], v[206:209], v[152:155], v[52:55]
	v_mfma_f32_16x16x32_f16 v[40:43], v[190:193], v[160:163], v[40:43]
	v_mfma_f32_16x16x32_f16 v[36:39], v[206:209], v[160:163], v[36:39]
	v_mfma_f32_16x16x32_f16 v[24:27], v[190:193], v[168:171], v[24:27]
	v_mfma_f32_16x16x32_f16 v[16:19], v[206:209], v[168:171], v[16:19]
	v_mfma_f32_16x16x32_f16 v[8:11], v[190:193], v[176:179], v[8:11]
	v_mfma_f32_16x16x32_f16 v[4:7], v[206:209], v[176:179], v[4:7]
	s_add_i32 s27, 0, 0x18000
	v_add_u32_e32 v128, s27, v198
	s_barrier
	ds_read_b128 v[108:111], v128
	ds_read_b128 v[112:115], v128 offset:1024
	ds_read_b128 v[120:123], v128 offset:2048
	ds_read_b128 v[128:131], v128 offset:3072
	s_add_u32 s44, s44, 0x80000
	s_addc_u32 s45, s45, 0
	s_mov_b32 m0, s8
	v_lshl_add_u64 v[186:187], s[44:45], 0, v[2:3]
	ds_read_b128 v[148:151], v199 offset:32768
	ds_read_b128 v[152:155], v199 offset:33792
	ds_read_b128 v[156:159], v199 offset:34816
	ds_read_b128 v[160:163], v199 offset:35840
	ds_read_b128 v[164:167], v199 offset:36864
	ds_read_b128 v[168:171], v199 offset:37888
	ds_read_b128 v[172:175], v199 offset:38912
	ds_read_b128 v[176:179], v199 offset:39936
	global_load_lds_dwordx4 v[186:187], off
	v_lshl_add_u64 v[186:187], s[44:45], 0, v[180:181]
	s_mov_b32 m0, s9
	s_nop 0
	global_load_lds_dwordx4 v[186:187], off
	s_waitcnt lgkmcnt(8)
	s_barrier
	s_waitcnt lgkmcnt(0)
	s_waitcnt lgkmcnt(0)
	v_mfma_f32_16x16x32_f16 v[144:147], v[108:111], v[148:151], v[144:147]
	v_mfma_f32_16x16x32_f16 v[140:143], v[120:123], v[148:151], v[140:143]
	v_mfma_f32_16x16x32_f16 v[124:127], v[108:111], v[156:159], v[124:127]
	v_mfma_f32_16x16x32_f16 v[116:119], v[120:123], v[156:159], v[116:119]
	v_mfma_f32_16x16x32_f16 v[96:99], v[108:111], v[164:167], v[96:99]
	v_mfma_f32_16x16x32_f16 v[92:95], v[120:123], v[164:167], v[92:95]
	v_mfma_f32_16x16x32_f16 v[88:91], v[108:111], v[172:175], v[88:91]
	v_mfma_f32_16x16x32_f16 v[80:83], v[120:123], v[172:175], v[80:83]
	v_mfma_f32_16x16x32_f16 v[144:147], v[112:115], v[152:155], v[144:147]
	v_mfma_f32_16x16x32_f16 v[140:143], v[128:131], v[152:155], v[140:143]
	v_mfma_f32_16x16x32_f16 v[124:127], v[112:115], v[160:163], v[124:127]
	v_mfma_f32_16x16x32_f16 v[116:119], v[128:131], v[160:163], v[116:119]
	v_mfma_f32_16x16x32_f16 v[96:99], v[112:115], v[168:171], v[96:99]
	v_mfma_f32_16x16x32_f16 v[92:95], v[128:131], v[168:171], v[92:95]
	v_mfma_f32_16x16x32_f16 v[88:91], v[112:115], v[176:179], v[88:91]
	v_mfma_f32_16x16x32_f16 v[80:83], v[128:131], v[176:179], v[80:83]
	s_barrier
	s_add_i32 s44, 0, 0x1c000
	s_add_i32 s27, s27, s5
	v_add_u32_e32 v206, s44, v198
	v_lshl_add_u64 v[194:195], v[194:195], 0, s[88:89]
	s_mov_b32 m0, s27
	ds_read_b128 v[186:189], v206
	ds_read_b128 v[190:193], v206 offset:1024
	ds_read_b128 v[200:203], v206 offset:2048
	ds_read_b128 v[206:209], v206 offset:3072
	global_load_lds_dwordx4 v[194:195], off
	v_lshl_add_u64 v[194:195], v[210:211], 0, s[88:89]
	s_add_i32 m0, s27, 0x2000
	s_nop 0
	global_load_lds_dwordx4 v[194:195], off
	s_barrier
	s_waitcnt lgkmcnt(0)
	s_waitcnt lgkmcnt(0)
	v_mfma_f32_16x16x32_f16 v[136:139], v[186:189], v[148:151], v[136:139]
	v_mfma_f32_16x16x32_f16 v[132:135], v[200:203], v[148:151], v[132:135]
	v_mfma_f32_16x16x32_f16 v[104:107], v[186:189], v[156:159], v[104:107]
	v_mfma_f32_16x16x32_f16 v[100:103], v[200:203], v[156:159], v[100:103]
	v_mfma_f32_16x16x32_f16 v[84:87], v[186:189], v[164:167], v[84:87]
	v_mfma_f32_16x16x32_f16 v[76:79], v[200:203], v[164:167], v[76:79]
	v_mfma_f32_16x16x32_f16 v[72:75], v[186:189], v[172:175], v[72:75]
	v_mfma_f32_16x16x32_f16 v[68:71], v[200:203], v[172:175], v[68:71]
	v_mfma_f32_16x16x32_f16 v[136:139], v[190:193], v[152:155], v[136:139]
	v_mfma_f32_16x16x32_f16 v[132:135], v[206:209], v[152:155], v[132:135]
	v_mfma_f32_16x16x32_f16 v[104:107], v[190:193], v[160:163], v[104:107]
	v_mfma_f32_16x16x32_f16 v[100:103], v[206:209], v[160:163], v[100:103]
	v_mfma_f32_16x16x32_f16 v[84:87], v[190:193], v[168:171], v[84:87]
	v_mfma_f32_16x16x32_f16 v[76:79], v[206:209], v[168:171], v[76:79]
	v_mfma_f32_16x16x32_f16 v[72:75], v[190:193], v[176:179], v[72:75]
	v_mfma_f32_16x16x32_f16 v[68:71], v[206:209], v[176:179], v[68:71]
	s_mov_b32 m0, s10
	v_lshl_add_u64 v[194:195], v[212:213], 0, s[88:89]
	s_barrier
	ds_read_b128 v[148:151], v199 offset:49152
	ds_read_b128 v[152:155], v199 offset:50176
	ds_read_b128 v[156:159], v199 offset:51200
	ds_read_b128 v[160:163], v199 offset:52224
	ds_read_b128 v[164:167], v199 offset:53248
	ds_read_b128 v[168:171], v199 offset:54272
	ds_read_b128 v[172:175], v199 offset:55296
	ds_read_b128 v[176:179], v199 offset:56320
	global_load_lds_dwordx4 v[194:195], off
	v_lshl_add_u64 v[194:195], v[214:215], 0, s[88:89]
	s_mov_b32 m0, s11
	s_nop 0
	global_load_lds_dwordx4 v[194:195], off
	s_barrier
	s_waitcnt lgkmcnt(0)
	s_waitcnt lgkmcnt(0)
	v_mfma_f32_16x16x32_f16 v[64:67], v[108:111], v[148:151], v[64:67]
	v_mfma_f32_16x16x32_f16 v[60:63], v[120:123], v[148:151], v[60:63]
	v_mfma_f32_16x16x32_f16 v[48:51], v[108:111], v[156:159], v[48:51]
	v_mfma_f32_16x16x32_f16 v[44:47], v[120:123], v[156:159], v[44:47]
	v_mfma_f32_16x16x32_f16 v[32:35], v[108:111], v[164:167], v[32:35]
	v_mfma_f32_16x16x32_f16 v[28:31], v[120:123], v[164:167], v[28:31]
	v_mfma_f32_16x16x32_f16 v[20:23], v[108:111], v[172:175], v[20:23]
	v_mfma_f32_16x16x32_f16 v[12:15], v[120:123], v[172:175], v[12:15]
	v_mfma_f32_16x16x32_f16 v[64:67], v[112:115], v[152:155], v[64:67]
	v_mfma_f32_16x16x32_f16 v[60:63], v[128:131], v[152:155], v[60:63]
	v_mfma_f32_16x16x32_f16 v[48:51], v[112:115], v[160:163], v[48:51]
	v_mfma_f32_16x16x32_f16 v[44:47], v[128:131], v[160:163], v[44:47]
	v_mfma_f32_16x16x32_f16 v[32:35], v[112:115], v[168:171], v[32:35]
	v_mfma_f32_16x16x32_f16 v[28:31], v[128:131], v[168:171], v[28:31]
	v_mfma_f32_16x16x32_f16 v[20:23], v[112:115], v[176:179], v[20:23]
	v_mfma_f32_16x16x32_f16 v[12:15], v[128:131], v[176:179], v[12:15]
	s_barrier
	s_add_u32 s38, s38, 0x80080
	s_addc_u32 s39, s39, 0
	s_add_i32 s27, s44, s5
	v_lshl_add_u64 v[108:109], s[38:39], 0, v[2:3]
	s_mov_b32 m0, s27
	s_nop 0
	global_load_lds_dwordx4 v[108:109], off
	v_lshl_add_u64 v[108:109], s[38:39], 0, v[180:181]
	s_add_i32 m0, s27, 0x2000
	s_nop 0
	global_load_lds_dwordx4 v[108:109], off
	s_waitcnt vmcnt(6)
	s_barrier
	v_mfma_f32_16x16x32_f16 v[56:59], v[186:189], v[148:151], v[56:59]
	v_mfma_f32_16x16x32_f16 v[52:55], v[200:203], v[148:151], v[52:55]
	v_mfma_f32_16x16x32_f16 v[40:43], v[186:189], v[156:159], v[40:43]
	v_mfma_f32_16x16x32_f16 v[36:39], v[200:203], v[156:159], v[36:39]
	v_mfma_f32_16x16x32_f16 v[24:27], v[186:189], v[164:167], v[24:27]
	v_mfma_f32_16x16x32_f16 v[16:19], v[200:203], v[164:167], v[16:19]
	v_mfma_f32_16x16x32_f16 v[8:11], v[186:189], v[172:175], v[8:11]
	v_mfma_f32_16x16x32_f16 v[4:7], v[200:203], v[172:175], v[4:7]
	v_mfma_f32_16x16x32_f16 v[56:59], v[190:193], v[152:155], v[56:59]
	v_mfma_f32_16x16x32_f16 v[52:55], v[206:209], v[152:155], v[52:55]
	v_mfma_f32_16x16x32_f16 v[40:43], v[190:193], v[160:163], v[40:43]
	v_mfma_f32_16x16x32_f16 v[36:39], v[206:209], v[160:163], v[36:39]
	v_mfma_f32_16x16x32_f16 v[24:27], v[190:193], v[168:171], v[24:27]
	v_mfma_f32_16x16x32_f16 v[16:19], v[206:209], v[168:171], v[16:19]
	v_mfma_f32_16x16x32_f16 v[8:11], v[190:193], v[176:179], v[8:11]
	v_mfma_f32_16x16x32_f16 v[4:7], v[206:209], v[176:179], v[4:7]
	s_add_i32 s17, s17, 2
	s_add_u32 s42, s42, 0x100
	s_addc_u32 s43, s43, 0
	s_add_u32 s14, s14, 0x100
	s_addc_u32 s15, s15, 0
	s_cmp_gt_u32 s17, 29
	s_barrier
	s_cbranch_scc0 .LBB0_2120
	s_lshl_b32 s14, s30, 8
	v_mov_b32_e32 v148, v196
	v_mov_b32_e32 v108, v197
	s_add_i32 s17, s14, s12
	s_lshl_b32 s14, s31, 8
	s_or_b32 s14, s14, s13
	v_lshl_add_u32 v108, v108, 2, s14
	s_cmp_lt_i32 s30, 64
	s_movk_i32 s14, 0x3000
	s_cselect_b32 s14, s14, 0x6000
	s_cmp_gt_i32 s30, 31
	s_cselect_b32 s14, s14, 0
	s_lshl_b32 s14, s14, 2
	v_readlane_b32 s15, v251, 41
	s_add_u32 s14, s15, s14
	v_readlane_b32 s15, v251, 42
	v_ashrrev_i32_e32 v109, 31, v108
	s_addc_u32 s15, s15, 0
	v_lshlrev_b64 v[186:187], 2, v[108:109]
	v_lshl_add_u64 v[108:109], s[14:15], 0, v[186:187]
	s_mov_b64 s[14:15], 0x4000
	v_add_u32_e32 v148, s17, v148
	v_lshl_add_u64 v[110:111], v[108:109], 0, s[14:15]
	s_movk_i32 s14, 0x4000
	v_ashrrev_i32_e32 v149, 31, v148
	v_add_co_u32_e32 v108, vcc, s14, v108
	v_lshlrev_b64 v[190:191], 13, v[148:149]
	s_mov_b64 s[14:15], 0x20000
	v_lshl_add_u64 v[224:225], v[190:191], 0, s[14:15]
	s_mov_b64 s[14:15], 0x40000
	v_lshl_add_u64 v[194:195], v[190:191], 0, s[14:15]
	s_mov_b64 s[14:15], 0x60000
	v_addc_co_u32_e32 v109, vcc, 0, v109, vcc
	v_lshl_add_u64 v[188:189], s[18:19], 0, v[186:187]
	v_lshl_add_u64 v[192:193], v[190:191], 0, s[14:15]
	global_load_dwordx4 v[128:131], v[108:109], off
	global_load_dwordx4 v[120:123], v[110:111], off offset:64
	global_load_dwordx4 v[112:115], v[110:111], off offset:512
	s_nop 0
	global_load_dwordx4 v[108:111], v[110:111], off offset:576
	v_lshl_add_u64 v[148:149], v[188:189], 0, v[190:191]
	v_lshl_add_u64 v[150:151], v[188:189], 0, v[224:225]
	v_lshl_add_u64 v[176:177], v[188:189], 0, v[194:195]
	v_lshl_add_u64 v[160:161], v[188:189], 0, v[192:193]
	flat_load_dwordx4 v[200:203], v[150:151] offset:576
	flat_load_dwordx4 v[206:209], v[150:151] offset:512
	flat_load_dwordx4 v[210:213], v[150:151] offset:64
	flat_load_dwordx4 v[214:217], v[150:151]
	flat_load_dwordx4 v[218:221], v[148:149] offset:576
	flat_load_dwordx4 v[232:235], v[148:149] offset:512
	flat_load_dwordx4 v[236:239], v[148:149] offset:64
	flat_load_dwordx4 v[240:243], v[148:149]
	s_nop 0
	flat_load_dwordx4 v[148:151], v[160:161] offset:576
	flat_load_dwordx4 v[152:155], v[160:161] offset:512
	flat_load_dwordx4 v[156:159], v[160:161] offset:64
	s_nop 0
	flat_load_dwordx4 v[160:163], v[160:161]
	s_nop 0
	flat_load_dwordx4 v[164:167], v[176:177] offset:576
	flat_load_dwordx4 v[168:171], v[176:177] offset:512
	flat_load_dwordx4 v[172:175], v[176:177] offset:64
	s_nop 0
	flat_load_dwordx4 v[176:179], v[176:177]
	v_readlane_b32 s14, v250, 25
	v_readlane_b32 s15, v250, 26
	s_mov_b64 s[30:31], 0x100000
	s_and_b64 vcc, exec, s[40:41]
	v_lshl_add_u64 v[226:227], s[14:15], 0, v[190:191]
	v_lshl_add_u64 v[226:227], v[226:227], 0, v[186:187]
	s_mov_b64 s[38:39], s[36:37]
	s_mov_b64 s[42:43], s[34:35]
	s_waitcnt vmcnt(0) lgkmcnt(0)
	s_nop 0
	v_pk_fma_f32 v[134:135], v[134:135], v[110:111], v[220:221]
	v_pk_fma_f32 v[132:133], v[132:133], v[108:109], v[218:219]
	global_store_dwordx4 v[226:227], v[132:135], off offset:576
	v_pk_fma_f32 v[102:103], v[102:103], v[110:111], v[202:203]
	v_pk_fma_f32 v[100:101], v[100:101], v[108:109], v[200:201]
	v_lshl_add_u64 v[132:133], s[14:15], 0, v[224:225]
	v_lshl_add_u64 v[132:133], v[132:133], 0, v[186:187]
	global_store_dwordx4 v[132:133], v[100:103], off offset:576
	v_pk_fma_f32 v[106:107], v[106:107], v[114:115], v[208:209]
	v_pk_fma_f32 v[104:105], v[104:105], v[112:113], v[206:207]
	v_lshl_add_u64 v[100:101], s[14:15], 0, v[194:195]
	v_lshl_add_u64 v[100:101], v[100:101], 0, v[186:187]
	v_pk_fma_f32 v[78:79], v[78:79], v[110:111], v[166:167]
	v_pk_fma_f32 v[76:77], v[76:77], v[108:109], v[164:165]
	global_store_dwordx4 v[132:133], v[104:107], off offset:512
	v_pk_fma_f32 v[86:87], v[86:87], v[114:115], v[170:171]
	v_pk_fma_f32 v[84:85], v[84:85], v[112:113], v[168:169]
	global_store_dwordx4 v[100:101], v[76:79], off offset:576
	v_lshl_add_u64 v[106:107], v[190:191], 0, s[30:31]
	s_mov_b64 s[30:31], 0x120000
	v_lshl_add_u64 v[76:77], s[14:15], 0, v[192:193]
	global_store_dwordx4 v[100:101], v[84:87], off offset:512
	v_pk_fma_f32 v[78:79], v[90:91], v[130:131], v[162:163]
	v_pk_fma_f32 v[72:73], v[72:73], v[112:113], v[152:153]
	v_lshl_add_u64 v[84:85], v[76:77], 0, v[186:187]
	v_pk_fma_f32 v[76:77], v[88:89], v[128:129], v[160:161]
	v_lshl_add_u64 v[152:153], v[190:191], 0, s[30:31]
	s_mov_b64 s[30:31], 0x140000
	v_pk_fma_f32 v[146:147], v[146:147], v[130:131], v[242:243]
	v_pk_fma_f32 v[144:145], v[144:145], v[128:129], v[240:241]
	v_pk_fma_f32 v[142:143], v[142:143], v[122:123], v[238:239]
	v_pk_fma_f32 v[140:141], v[140:141], v[120:121], v[236:237]
	v_pk_fma_f32 v[138:139], v[138:139], v[114:115], v[234:235]
	v_pk_fma_f32 v[136:137], v[136:137], v[112:113], v[232:233]
	v_pk_fma_f32 v[126:127], v[126:127], v[130:131], v[216:217]
	v_pk_fma_f32 v[124:125], v[124:125], v[128:129], v[214:215]
	v_pk_fma_f32 v[118:119], v[118:119], v[122:123], v[212:213]
	v_pk_fma_f32 v[116:117], v[116:117], v[120:121], v[210:211]
	v_pk_fma_f32 v[98:99], v[98:99], v[130:131], v[178:179]
	v_pk_fma_f32 v[96:97], v[96:97], v[128:129], v[176:177]
	v_pk_fma_f32 v[94:95], v[94:95], v[122:123], v[174:175]
	v_pk_fma_f32 v[92:93], v[92:93], v[120:121], v[172:173]
	global_store_dwordx4 v[84:85], v[76:79], off
	v_pk_fma_f32 v[74:75], v[74:75], v[114:115], v[154:155]
	v_pk_fma_f32 v[70:71], v[70:71], v[110:111], v[150:151]
	v_pk_fma_f32 v[78:79], v[82:83], v[122:123], v[158:159]
	v_pk_fma_f32 v[76:77], v[80:81], v[120:121], v[156:157]
	v_pk_fma_f32 v[68:69], v[68:69], v[108:109], v[148:149]
	v_lshl_add_u64 v[154:155], v[190:191], 0, s[30:31]
	s_mov_b64 s[30:31], 0x160000
	global_store_dwordx4 v[226:227], v[144:147], off
	global_store_dwordx4 v[226:227], v[140:143], off offset:64
	global_store_dwordx4 v[226:227], v[136:139], off offset:512
	global_store_dwordx4 v[132:133], v[124:127], off
	global_store_dwordx4 v[132:133], v[116:119], off offset:64
	global_store_dwordx4 v[100:101], v[96:99], off
	global_store_dwordx4 v[100:101], v[92:95], off offset:64
	global_store_dwordx4 v[84:85], v[76:79], off offset:64
	global_store_dwordx4 v[84:85], v[72:75], off offset:512
	global_store_dwordx4 v[84:85], v[68:71], off offset:576
	v_lshl_add_u64 v[100:101], v[190:191], 0, s[30:31]
	v_lshl_add_u64 v[96:97], v[188:189], 0, v[154:155]
	v_lshl_add_u64 v[68:69], v[188:189], 0, v[106:107]
	v_lshl_add_u64 v[70:71], v[188:189], 0, v[152:153]
	v_lshl_add_u64 v[80:81], v[188:189], 0, v[100:101]
	flat_load_dwordx4 v[102:105], v[70:71] offset:576
	flat_load_dwordx4 v[116:119], v[70:71] offset:512
	flat_load_dwordx4 v[124:127], v[70:71] offset:64
	flat_load_dwordx4 v[132:135], v[70:71]
	flat_load_dwordx4 v[136:139], v[68:69] offset:576
	flat_load_dwordx4 v[140:143], v[68:69] offset:512
	flat_load_dwordx4 v[144:147], v[68:69] offset:64
	flat_load_dwordx4 v[148:151], v[68:69]
	s_nop 0
	flat_load_dwordx4 v[68:71], v[80:81] offset:576
	flat_load_dwordx4 v[72:75], v[80:81] offset:512
	flat_load_dwordx4 v[76:79], v[80:81] offset:64
	s_nop 0
	flat_load_dwordx4 v[80:83], v[80:81]
	s_nop 0
	flat_load_dwordx4 v[84:87], v[96:97] offset:576
	flat_load_dwordx4 v[88:91], v[96:97] offset:512
	flat_load_dwordx4 v[92:95], v[96:97] offset:64
	s_nop 0
	flat_load_dwordx4 v[96:99], v[96:97]
	v_lshl_add_u64 v[106:107], s[14:15], 0, v[106:107]
	s_waitcnt vmcnt(0) lgkmcnt(0)
	v_lshl_add_u64 v[106:107], v[106:107], 0, v[186:187]
	v_pk_fma_f32 v[54:55], v[54:55], v[110:111], v[138:139]
	v_pk_fma_f32 v[52:53], v[52:53], v[108:109], v[136:137]
	global_store_dwordx4 v[106:107], v[52:55], off offset:576
	v_pk_fma_f32 v[38:39], v[38:39], v[110:111], v[104:105]
	v_pk_fma_f32 v[36:37], v[36:37], v[108:109], v[102:103]
	v_lshl_add_u64 v[52:53], s[14:15], 0, v[152:153]
	v_lshl_add_u64 v[52:53], v[52:53], 0, v[186:187]
	global_store_dwordx4 v[52:53], v[36:39], off offset:576
	v_pk_fma_f32 v[18:19], v[18:19], v[110:111], v[86:87]
	v_pk_fma_f32 v[16:17], v[16:17], v[108:109], v[84:85]
	v_lshl_add_u64 v[36:37], s[14:15], 0, v[154:155]
	v_lshl_add_u64 v[36:37], v[36:37], 0, v[186:187]
	v_pk_fma_f32 v[26:27], v[26:27], v[114:115], v[90:91]
	v_pk_fma_f32 v[24:25], v[24:25], v[112:113], v[88:89]
	global_store_dwordx4 v[36:37], v[16:19], off offset:576
	v_pk_fma_f32 v[66:67], v[66:67], v[130:131], v[150:151]
	v_pk_fma_f32 v[64:65], v[64:65], v[128:129], v[148:149]
	v_lshl_add_u64 v[16:17], s[14:15], 0, v[100:101]
	v_pk_fma_f32 v[62:63], v[62:63], v[122:123], v[146:147]
	v_pk_fma_f32 v[60:61], v[60:61], v[120:121], v[144:145]
	v_pk_fma_f32 v[58:59], v[58:59], v[114:115], v[142:143]
	v_pk_fma_f32 v[56:57], v[56:57], v[112:113], v[140:141]
	v_pk_fma_f32 v[50:51], v[50:51], v[130:131], v[134:135]
	v_pk_fma_f32 v[48:49], v[48:49], v[128:129], v[132:133]
	v_pk_fma_f32 v[46:47], v[46:47], v[122:123], v[126:127]
	v_pk_fma_f32 v[44:45], v[44:45], v[120:121], v[124:125]
	v_pk_fma_f32 v[42:43], v[42:43], v[114:115], v[118:119]
	v_pk_fma_f32 v[40:41], v[40:41], v[112:113], v[116:117]
	v_pk_fma_f32 v[34:35], v[34:35], v[130:131], v[98:99]
	v_pk_fma_f32 v[32:33], v[32:33], v[128:129], v[96:97]
	v_pk_fma_f32 v[30:31], v[30:31], v[122:123], v[94:95]
	v_pk_fma_f32 v[28:29], v[28:29], v[120:121], v[92:93]
	global_store_dwordx4 v[36:37], v[24:27], off offset:512
	v_pk_fma_f32 v[18:19], v[22:23], v[130:131], v[82:83]
	v_pk_fma_f32 v[14:15], v[14:15], v[122:123], v[78:79]
	v_lshl_add_u64 v[24:25], v[16:17], 0, v[186:187]
	v_pk_fma_f32 v[16:17], v[20:21], v[128:129], v[80:81]
	v_pk_fma_f32 v[12:13], v[12:13], v[120:121], v[76:77]
	v_pk_fma_f32 v[10:11], v[10:11], v[114:115], v[74:75]
	v_pk_fma_f32 v[8:9], v[8:9], v[112:113], v[72:73]
	v_pk_fma_f32 v[6:7], v[6:7], v[110:111], v[70:71]
	v_pk_fma_f32 v[4:5], v[4:5], v[108:109], v[68:69]
	global_store_dwordx4 v[106:107], v[64:67], off
	global_store_dwordx4 v[106:107], v[60:63], off offset:64
	global_store_dwordx4 v[106:107], v[56:59], off offset:512
	global_store_dwordx4 v[52:53], v[48:51], off
	global_store_dwordx4 v[52:53], v[44:47], off offset:64
	global_store_dwordx4 v[52:53], v[40:43], off offset:512
	global_store_dwordx4 v[36:37], v[32:35], off
	global_store_dwordx4 v[36:37], v[28:31], off offset:64
	global_store_dwordx4 v[24:25], v[16:19], off
	global_store_dwordx4 v[24:25], v[12:15], off offset:64
	global_store_dwordx4 v[24:25], v[8:11], off offset:512
	global_store_dwordx4 v[24:25], v[4:7], off offset:576
	s_mov_b32 s31, s16
	s_mov_b32 s30, s26
	s_cbranch_vccz .LBB0_2113
	s_waitcnt vmcnt(0)
	s_cmpk_gt_u32 s4, 0xff
	s_cbranch_scc1 .LBB0_2124
	s_barrier

.LBB0_2133:
	s_add_u32 s38, s40, 0xfff80080
	s_addc_u32 s39, s41, -1
	s_add_i32 s45, 0, 0x10000
	v_add_u32_e32 v144, s45, v158
	ds_read_b128 v[132:135], v144
	ds_read_b128 v[136:139], v144 offset:1024
	ds_read_b128 v[140:143], v144 offset:2048
	ds_read_b128 v[144:147], v144 offset:3072
	s_cmp_eq_u32 s44, 4
	s_cselect_b32 s43, s27, s39
	s_cselect_b32 s42, s26, s38
	s_cselect_b32 s39, s35, s31
	s_cselect_b32 s38, s34, s19
	v_lshl_add_u64 v[154:155], s[40:41], 0, v[150:151]
	s_add_i32 m0, s6, 0xc000
	ds_read_b128 v[160:163], v159
	ds_read_b128 v[164:167], v159 offset:1024
	ds_read_b128 v[168:171], v159 offset:2048
	ds_read_b128 v[172:175], v159 offset:3072
	ds_read_b128 v[176:179], v159 offset:4096
	ds_read_b128 v[180:183], v159 offset:5120
	ds_read_b128 v[184:187], v159 offset:6144
	ds_read_b128 v[188:191], v159 offset:7168
	global_load_lds_dwordx4 v[154:155], off
	v_lshl_add_u64 v[154:155], s[40:41], 0, v[152:153]
	s_add_i32 m0, s6, 0xe000
	s_nop 0
	global_load_lds_dwordx4 v[154:155], off
	s_waitcnt lgkmcnt(8)
	s_barrier
	s_waitcnt lgkmcnt(0)
	s_waitcnt lgkmcnt(0)
	v_mfma_f32_16x16x32_f16 v[128:131], v[132:135], v[160:163], v[128:131]
	v_mfma_f32_16x16x32_f16 v[124:127], v[140:143], v[160:163], v[124:127]
	v_mfma_f32_16x16x32_f16 v[112:115], v[132:135], v[168:171], v[112:115]
	v_mfma_f32_16x16x32_f16 v[108:111], v[140:143], v[168:171], v[108:111]
	v_mfma_f32_16x16x32_f16 v[96:99], v[132:135], v[176:179], v[96:99]
	v_mfma_f32_16x16x32_f16 v[92:95], v[140:143], v[176:179], v[92:95]
	v_mfma_f32_16x16x32_f16 v[80:83], v[132:135], v[184:187], v[80:83]
	v_mfma_f32_16x16x32_f16 v[76:79], v[140:143], v[184:187], v[76:79]
	v_mfma_f32_16x16x32_f16 v[128:131], v[136:139], v[164:167], v[128:131]
	v_mfma_f32_16x16x32_f16 v[124:127], v[144:147], v[164:167], v[124:127]
	v_mfma_f32_16x16x32_f16 v[112:115], v[136:139], v[172:175], v[112:115]
	v_mfma_f32_16x16x32_f16 v[108:111], v[144:147], v[172:175], v[108:111]
	v_mfma_f32_16x16x32_f16 v[96:99], v[136:139], v[180:183], v[96:99]
	v_mfma_f32_16x16x32_f16 v[92:95], v[144:147], v[180:183], v[92:95]
	v_mfma_f32_16x16x32_f16 v[80:83], v[136:139], v[188:191], v[80:83]
	v_mfma_f32_16x16x32_f16 v[76:79], v[144:147], v[188:191], v[76:79]
	s_barrier
	s_add_i32 s48, 0, 0x14000
	v_add_u32_e32 v154, s48, v158
	s_add_i32 s45, s45, s5
	ds_read_b128 v[192:195], v154
	ds_read_b128 v[196:199], v154 offset:1024
	ds_read_b128 v[200:203], v154 offset:2048
	ds_read_b128 v[206:209], v154 offset:3072
	v_lshl_add_u64 v[154:155], s[38:39], 0, v[2:3]
	s_mov_b32 m0, s45
	v_lshl_add_u64 v[210:211], s[38:39], 0, v[148:149]
	global_load_lds_dwordx4 v[154:155], off
	s_add_i32 m0, s45, 0x2000
	s_nop 0
	global_load_lds_dwordx4 v[210:211], off
	s_barrier
	s_waitcnt lgkmcnt(0)
	s_waitcnt lgkmcnt(0)
	v_mfma_f32_16x16x32_f16 v[120:123], v[192:195], v[160:163], v[120:123]
	v_mfma_f32_16x16x32_f16 v[116:119], v[200:203], v[160:163], v[116:119]
	v_mfma_f32_16x16x32_f16 v[104:107], v[192:195], v[168:171], v[104:107]
	v_mfma_f32_16x16x32_f16 v[100:103], v[200:203], v[168:171], v[100:103]
	v_mfma_f32_16x16x32_f16 v[88:91], v[192:195], v[176:179], v[88:91]
	v_mfma_f32_16x16x32_f16 v[84:87], v[200:203], v[176:179], v[84:87]
	v_mfma_f32_16x16x32_f16 v[72:75], v[192:195], v[184:187], v[72:75]
	v_mfma_f32_16x16x32_f16 v[68:71], v[200:203], v[184:187], v[68:71]
	v_mfma_f32_16x16x32_f16 v[120:123], v[196:199], v[164:167], v[120:123]
	v_mfma_f32_16x16x32_f16 v[116:119], v[206:209], v[164:167], v[116:119]
	v_mfma_f32_16x16x32_f16 v[104:107], v[196:199], v[172:175], v[104:107]
	v_mfma_f32_16x16x32_f16 v[100:103], v[206:209], v[172:175], v[100:103]
	v_mfma_f32_16x16x32_f16 v[88:91], v[196:199], v[180:183], v[88:91]
	v_mfma_f32_16x16x32_f16 v[84:87], v[206:209], v[180:183], v[84:87]
	v_mfma_f32_16x16x32_f16 v[72:75], v[196:199], v[188:191], v[72:75]
	v_mfma_f32_16x16x32_f16 v[68:71], v[206:209], v[188:191], v[68:71]
	s_mov_b32 m0, s6
	v_lshl_add_u64 v[212:213], s[42:43], 0, v[2:3]
	s_barrier
	ds_read_b128 v[160:163], v159 offset:16384
	ds_read_b128 v[164:167], v159 offset:17408
	ds_read_b128 v[168:171], v159 offset:18432
	ds_read_b128 v[172:175], v159 offset:19456
	ds_read_b128 v[176:179], v159 offset:20480
	ds_read_b128 v[180:183], v159 offset:21504
	ds_read_b128 v[184:187], v159 offset:22528
	ds_read_b128 v[188:191], v159 offset:23552
	global_load_lds_dwordx4 v[212:213], off
	v_lshl_add_u64 v[214:215], s[42:43], 0, v[148:149]
	s_mov_b32 m0, s7
	s_nop 0
	global_load_lds_dwordx4 v[214:215], off
	s_barrier
	s_waitcnt lgkmcnt(0)
	s_waitcnt lgkmcnt(0)
	v_mfma_f32_16x16x32_f16 v[64:67], v[132:135], v[160:163], v[64:67]
	v_mfma_f32_16x16x32_f16 v[60:63], v[140:143], v[160:163], v[60:63]
	v_mfma_f32_16x16x32_f16 v[56:59], v[132:135], v[168:171], v[56:59]
	v_mfma_f32_16x16x32_f16 v[44:47], v[140:143], v[168:171], v[44:47]
	v_mfma_f32_16x16x32_f16 v[40:43], v[132:135], v[176:179], v[40:43]
	v_mfma_f32_16x16x32_f16 v[28:31], v[140:143], v[176:179], v[28:31]
	v_mfma_f32_16x16x32_f16 v[24:27], v[132:135], v[184:187], v[24:27]
	v_mfma_f32_16x16x32_f16 v[12:15], v[140:143], v[184:187], v[12:15]
	v_mfma_f32_16x16x32_f16 v[64:67], v[136:139], v[164:167], v[64:67]
	v_mfma_f32_16x16x32_f16 v[60:63], v[144:147], v[164:167], v[60:63]
	v_mfma_f32_16x16x32_f16 v[56:59], v[136:139], v[172:175], v[56:59]
	v_mfma_f32_16x16x32_f16 v[44:47], v[144:147], v[172:175], v[44:47]
	v_mfma_f32_16x16x32_f16 v[40:43], v[136:139], v[180:183], v[40:43]
	v_mfma_f32_16x16x32_f16 v[28:31], v[144:147], v[180:183], v[28:31]
	v_mfma_f32_16x16x32_f16 v[24:27], v[136:139], v[188:191], v[24:27]
	v_mfma_f32_16x16x32_f16 v[12:15], v[144:147], v[188:191], v[12:15]
	s_barrier
	s_add_u32 s46, s38, 0x80000
	s_addc_u32 s47, s39, 0
	s_add_i32 s45, s48, s5
	v_lshl_add_u64 v[132:133], s[46:47], 0, v[2:3]
	s_mov_b32 m0, s45
	s_nop 0
	global_load_lds_dwordx4 v[132:133], off
	v_lshl_add_u64 v[132:133], s[46:47], 0, v[148:149]
	s_add_i32 m0, s45, 0x2000
	s_nop 0
	global_load_lds_dwordx4 v[132:133], off
	s_waitcnt vmcnt(6)
	s_barrier
	v_mfma_f32_16x16x32_f16 v[52:55], v[192:195], v[160:163], v[52:55]
	v_mfma_f32_16x16x32_f16 v[48:51], v[200:203], v[160:163], v[48:51]
	v_mfma_f32_16x16x32_f16 v[36:39], v[192:195], v[168:171], v[36:39]
	v_mfma_f32_16x16x32_f16 v[32:35], v[200:203], v[168:171], v[32:35]
	v_mfma_f32_16x16x32_f16 v[20:23], v[192:195], v[176:179], v[20:23]
	v_mfma_f32_16x16x32_f16 v[16:19], v[200:203], v[176:179], v[16:19]
	v_mfma_f32_16x16x32_f16 v[8:11], v[192:195], v[184:187], v[8:11]
	v_mfma_f32_16x16x32_f16 v[4:7], v[200:203], v[184:187], v[4:7]
	v_mfma_f32_16x16x32_f16 v[52:55], v[196:199], v[164:167], v[52:55]
	v_mfma_f32_16x16x32_f16 v[48:51], v[206:209], v[164:167], v[48:51]
	v_mfma_f32_16x16x32_f16 v[36:39], v[196:199], v[172:175], v[36:39]
	v_mfma_f32_16x16x32_f16 v[32:35], v[206:209], v[172:175], v[32:35]
	v_mfma_f32_16x16x32_f16 v[20:23], v[196:199], v[180:183], v[20:23]
	v_mfma_f32_16x16x32_f16 v[16:19], v[206:209], v[180:183], v[16:19]
	v_mfma_f32_16x16x32_f16 v[8:11], v[196:199], v[188:191], v[8:11]
	v_mfma_f32_16x16x32_f16 v[4:7], v[206:209], v[188:191], v[4:7]
	s_add_i32 s45, 0, 0x18000
	v_add_u32_e32 v144, s45, v158
	s_barrier
	ds_read_b128 v[132:135], v144
	ds_read_b128 v[136:139], v144 offset:1024
	ds_read_b128 v[140:143], v144 offset:2048
	ds_read_b128 v[144:147], v144 offset:3072
	s_add_u32 s42, s42, 0x80000
	s_addc_u32 s43, s43, 0
	s_mov_b32 m0, s8
	v_lshl_add_u64 v[192:193], s[42:43], 0, v[2:3]
	ds_read_b128 v[160:163], v159 offset:32768
	ds_read_b128 v[164:167], v159 offset:33792
	ds_read_b128 v[168:171], v159 offset:34816
	ds_read_b128 v[172:175], v159 offset:35840
	ds_read_b128 v[176:179], v159 offset:36864
	ds_read_b128 v[180:183], v159 offset:37888
	ds_read_b128 v[184:187], v159 offset:38912
	ds_read_b128 v[188:191], v159 offset:39936
	global_load_lds_dwordx4 v[192:193], off
	v_lshl_add_u64 v[192:193], s[42:43], 0, v[148:149]
	s_mov_b32 m0, s9
	s_nop 0
	global_load_lds_dwordx4 v[192:193], off
	s_waitcnt lgkmcnt(8)
	s_barrier
	s_waitcnt lgkmcnt(0)
	s_waitcnt lgkmcnt(0)
	v_mfma_f32_16x16x32_f16 v[128:131], v[132:135], v[160:163], v[128:131]
	v_mfma_f32_16x16x32_f16 v[124:127], v[140:143], v[160:163], v[124:127]
	v_mfma_f32_16x16x32_f16 v[112:115], v[132:135], v[168:171], v[112:115]
	v_mfma_f32_16x16x32_f16 v[108:111], v[140:143], v[168:171], v[108:111]
	v_mfma_f32_16x16x32_f16 v[96:99], v[132:135], v[176:179], v[96:99]
	v_mfma_f32_16x16x32_f16 v[92:95], v[140:143], v[176:179], v[92:95]
	v_mfma_f32_16x16x32_f16 v[80:83], v[132:135], v[184:187], v[80:83]
	v_mfma_f32_16x16x32_f16 v[76:79], v[140:143], v[184:187], v[76:79]
	v_mfma_f32_16x16x32_f16 v[128:131], v[136:139], v[164:167], v[128:131]
	v_mfma_f32_16x16x32_f16 v[124:127], v[144:147], v[164:167], v[124:127]
	v_mfma_f32_16x16x32_f16 v[112:115], v[136:139], v[172:175], v[112:115]
	v_mfma_f32_16x16x32_f16 v[108:111], v[144:147], v[172:175], v[108:111]
	v_mfma_f32_16x16x32_f16 v[96:99], v[136:139], v[180:183], v[96:99]
	v_mfma_f32_16x16x32_f16 v[92:95], v[144:147], v[180:183], v[92:95]
	v_mfma_f32_16x16x32_f16 v[80:83], v[136:139], v[188:191], v[80:83]
	v_mfma_f32_16x16x32_f16 v[76:79], v[144:147], v[188:191], v[76:79]
	s_barrier
	s_add_i32 s42, 0, 0x1c000
	s_add_i32 s43, s45, s5
	v_add_u32_e32 v206, s42, v158
	v_lshl_add_u64 v[154:155], v[154:155], 0, s[88:89]
	s_mov_b32 m0, s43
	ds_read_b128 v[192:195], v206
	ds_read_b128 v[196:199], v206 offset:1024
	ds_read_b128 v[200:203], v206 offset:2048
	ds_read_b128 v[206:209], v206 offset:3072
	global_load_lds_dwordx4 v[154:155], off
	v_lshl_add_u64 v[154:155], v[210:211], 0, s[88:89]
	s_add_i32 m0, s43, 0x2000
	s_nop 0
	global_load_lds_dwordx4 v[154:155], off
	s_barrier
	s_waitcnt lgkmcnt(0)
	s_waitcnt lgkmcnt(0)
	v_mfma_f32_16x16x32_f16 v[120:123], v[192:195], v[160:163], v[120:123]
	v_mfma_f32_16x16x32_f16 v[116:119], v[200:203], v[160:163], v[116:119]
	v_mfma_f32_16x16x32_f16 v[104:107], v[192:195], v[168:171], v[104:107]
	v_mfma_f32_16x16x32_f16 v[100:103], v[200:203], v[168:171], v[100:103]
	v_mfma_f32_16x16x32_f16 v[88:91], v[192:195], v[176:179], v[88:91]
	v_mfma_f32_16x16x32_f16 v[84:87], v[200:203], v[176:179], v[84:87]
	v_mfma_f32_16x16x32_f16 v[72:75], v[192:195], v[184:187], v[72:75]
	v_mfma_f32_16x16x32_f16 v[68:71], v[200:203], v[184:187], v[68:71]
	v_mfma_f32_16x16x32_f16 v[120:123], v[196:199], v[164:167], v[120:123]
	v_mfma_f32_16x16x32_f16 v[116:119], v[206:209], v[164:167], v[116:119]
	v_mfma_f32_16x16x32_f16 v[104:107], v[196:199], v[172:175], v[104:107]
	v_mfma_f32_16x16x32_f16 v[100:103], v[206:209], v[172:175], v[100:103]
	v_mfma_f32_16x16x32_f16 v[88:91], v[196:199], v[180:183], v[88:91]
	v_mfma_f32_16x16x32_f16 v[84:87], v[206:209], v[180:183], v[84:87]
	v_mfma_f32_16x16x32_f16 v[72:75], v[196:199], v[188:191], v[72:75]
	v_mfma_f32_16x16x32_f16 v[68:71], v[206:209], v[188:191], v[68:71]
	s_mov_b32 m0, s10
	v_lshl_add_u64 v[154:155], v[212:213], 0, s[88:89]
	s_barrier
	ds_read_b128 v[160:163], v159 offset:49152
	ds_read_b128 v[164:167], v159 offset:50176
	ds_read_b128 v[168:171], v159 offset:51200
	ds_read_b128 v[172:175], v159 offset:52224
	ds_read_b128 v[176:179], v159 offset:53248
	ds_read_b128 v[180:183], v159 offset:54272
	ds_read_b128 v[184:187], v159 offset:55296
	ds_read_b128 v[188:191], v159 offset:56320
	global_load_lds_dwordx4 v[154:155], off
	v_lshl_add_u64 v[154:155], v[214:215], 0, s[88:89]
	s_mov_b32 m0, s11
	s_nop 0
	global_load_lds_dwordx4 v[154:155], off
	s_barrier
	s_waitcnt lgkmcnt(0)
	s_waitcnt lgkmcnt(0)
	v_mfma_f32_16x16x32_f16 v[64:67], v[132:135], v[160:163], v[64:67]
	v_mfma_f32_16x16x32_f16 v[60:63], v[140:143], v[160:163], v[60:63]
	v_mfma_f32_16x16x32_f16 v[56:59], v[132:135], v[168:171], v[56:59]
	v_mfma_f32_16x16x32_f16 v[44:47], v[140:143], v[168:171], v[44:47]
	v_mfma_f32_16x16x32_f16 v[40:43], v[132:135], v[176:179], v[40:43]
	v_mfma_f32_16x16x32_f16 v[28:31], v[140:143], v[176:179], v[28:31]
	v_mfma_f32_16x16x32_f16 v[24:27], v[132:135], v[184:187], v[24:27]
	v_mfma_f32_16x16x32_f16 v[12:15], v[140:143], v[184:187], v[12:15]
	v_mfma_f32_16x16x32_f16 v[64:67], v[136:139], v[164:167], v[64:67]
	v_mfma_f32_16x16x32_f16 v[60:63], v[144:147], v[164:167], v[60:63]
	v_mfma_f32_16x16x32_f16 v[56:59], v[136:139], v[172:175], v[56:59]
	v_mfma_f32_16x16x32_f16 v[44:47], v[144:147], v[172:175], v[44:47]
	v_mfma_f32_16x16x32_f16 v[40:43], v[136:139], v[180:183], v[40:43]
	v_mfma_f32_16x16x32_f16 v[28:31], v[144:147], v[180:183], v[28:31]
	v_mfma_f32_16x16x32_f16 v[24:27], v[136:139], v[188:191], v[24:27]
	v_mfma_f32_16x16x32_f16 v[12:15], v[144:147], v[188:191], v[12:15]
	s_barrier
	s_add_u32 s38, s38, 0x80080
	s_addc_u32 s39, s39, 0
	s_add_i32 s42, s42, s5
	v_lshl_add_u64 v[132:133], s[38:39], 0, v[2:3]
	s_mov_b32 m0, s42
	s_nop 0
	global_load_lds_dwordx4 v[132:133], off
	v_lshl_add_u64 v[132:133], s[38:39], 0, v[148:149]
	s_add_i32 m0, s42, 0x2000
	s_nop 0
	global_load_lds_dwordx4 v[132:133], off
	s_waitcnt vmcnt(6)
	s_barrier
	v_mfma_f32_16x16x32_f16 v[52:55], v[192:195], v[160:163], v[52:55]
	v_mfma_f32_16x16x32_f16 v[48:51], v[200:203], v[160:163], v[48:51]
	v_mfma_f32_16x16x32_f16 v[36:39], v[192:195], v[168:171], v[36:39]
	v_mfma_f32_16x16x32_f16 v[32:35], v[200:203], v[168:171], v[32:35]
	v_mfma_f32_16x16x32_f16 v[20:23], v[192:195], v[176:179], v[20:23]
	v_mfma_f32_16x16x32_f16 v[16:19], v[200:203], v[176:179], v[16:19]
	v_mfma_f32_16x16x32_f16 v[8:11], v[192:195], v[184:187], v[8:11]
	v_mfma_f32_16x16x32_f16 v[4:7], v[200:203], v[184:187], v[4:7]
	v_mfma_f32_16x16x32_f16 v[52:55], v[196:199], v[164:167], v[52:55]
	v_mfma_f32_16x16x32_f16 v[48:51], v[206:209], v[164:167], v[48:51]
	v_mfma_f32_16x16x32_f16 v[36:39], v[196:199], v[172:175], v[36:39]
	v_mfma_f32_16x16x32_f16 v[32:35], v[206:209], v[172:175], v[32:35]
	v_mfma_f32_16x16x32_f16 v[20:23], v[196:199], v[180:183], v[20:23]
	v_mfma_f32_16x16x32_f16 v[16:19], v[206:209], v[180:183], v[16:19]
	v_mfma_f32_16x16x32_f16 v[8:11], v[196:199], v[188:191], v[8:11]
	v_mfma_f32_16x16x32_f16 v[4:7], v[206:209], v[188:191], v[4:7]
	s_add_i32 s44, s44, 2
	s_add_u32 s40, s40, 0x100
	s_addc_u32 s41, s41, 0
	s_add_u32 s19, s19, 0x100
	s_addc_u32 s31, s31, 0
	s_cmp_gt_u32 s44, 5
	s_barrier
	s_cbranch_scc0 .LBB0_2133
	s_lshl_b32 s19, s30, 8
	s_lshl_b32 s30, s29, 8
	v_mov_b32_e32 v160, v156
	v_mov_b32_e32 v132, v157
	s_and_b32 s30, s30, 0xff00
	s_or_b32 s30, s30, s12
	v_lshl_add_u32 v132, v132, 2, s30
	v_ashrrev_i32_e32 v133, 31, v132
	v_lshlrev_b64 v[154:155], 2, v[132:133]
	v_lshl_add_u64 v[132:133], s[16:17], 0, v[154:155]
	global_load_dwordx4 v[144:147], v[132:133], off
	global_load_dwordx4 v[140:143], v[132:133], off offset:64
	global_load_dwordx4 v[136:139], v[132:133], off offset:512
	s_nop 0
	global_load_dwordx4 v[132:135], v[132:133], off offset:576
	s_ashr_i32 s30, s29, 8
	s_ashr_i32 s31, s30, 31
	s_add_i32 s19, s13, s19
	s_lshl_b64 s[30:31], s[30:31], 22
	v_readlane_b32 s38, v250, 27
	v_add_u32_e32 v160, s19, v160
	v_readlane_b32 s39, v250, 28
	s_add_u32 s30, s38, s30
	s_addc_u32 s31, s39, s31
	v_ashrrev_i32_e32 v161, 31, v160
	v_lshl_add_u64 v[154:155], s[30:31], 0, v[154:155]
	v_lshlrev_b64 v[160:161], 13, v[160:161]
	v_lshl_add_u64 v[154:155], v[154:155], 0, v[160:161]
	s_mov_b32 s19, 0x20000
	s_mov_b64 s[30:31], 0x20000
	s_mov_b32 s29, s15
	s_mov_b64 s[38:39], s[34:35]
	s_mov_b64 s[40:41], s[26:27]
	s_waitcnt vmcnt(0)
	v_pk_mul_f32 v[130:131], v[130:131], v[146:147]
	v_pk_mul_f32 v[128:129], v[128:129], v[144:145]
	v_pk_mul_f32 v[54:55], v[54:55], v[138:139]
	v_pk_mul_f32 v[118:119], v[118:119], v[134:135]
	v_pk_mul_f32 v[116:117], v[116:117], v[132:133]
	global_store_dwordx4 v[154:155], v[116:119], off offset:576
	v_pk_mul_f32 v[102:103], v[102:103], v[134:135]
	v_pk_mul_f32 v[100:101], v[100:101], v[132:133]
	v_add_co_u32_e32 v118, vcc, s19, v154
	v_lshl_add_u64 v[116:117], v[154:155], 0, s[30:31]
	s_nop 0
	v_addc_co_u32_e32 v119, vcc, 0, v155, vcc
	s_mov_b32 s19, 0x40000
	global_store_dwordx4 v[116:117], v[100:103], off offset:576
	s_mov_b64 s[30:31], 0x40000
	v_pk_mul_f32 v[86:87], v[86:87], v[134:135]
	v_add_co_u32_e32 v102, vcc, s19, v154
	v_lshl_add_u64 v[100:101], v[154:155], 0, s[30:31]
	s_nop 0
	v_addc_co_u32_e32 v103, vcc, 0, v155, vcc
	v_pk_mul_f32 v[84:85], v[84:85], v[132:133]
	s_mov_b32 s19, 0x60000
	global_store_dwordx4 v[100:101], v[84:87], off offset:576
	s_mov_b64 s[30:31], 0x60000
	v_pk_mul_f32 v[70:71], v[70:71], v[134:135]
	v_add_co_u32_e32 v86, vcc, s19, v154
	v_lshl_add_u64 v[84:85], v[154:155], 0, s[30:31]
	s_nop 0
	v_addc_co_u32_e32 v87, vcc, 0, v155, vcc
	v_pk_mul_f32 v[68:69], v[68:69], v[132:133]
	s_mov_b32 s19, 0x100000
	global_store_dwordx4 v[84:85], v[68:71], off offset:576
	s_mov_b64 s[30:31], 0x100000
	v_pk_mul_f32 v[52:53], v[52:53], v[136:137]
	v_add_co_u32_e32 v70, vcc, s19, v154
	v_lshl_add_u64 v[68:69], v[154:155], 0, s[30:31]
	s_nop 0
	v_addc_co_u32_e32 v71, vcc, 0, v155, vcc
	s_mov_b32 s19, 0x120000
	global_store_dwordx4 v[68:69], v[52:55], off offset:512
	s_mov_b64 s[30:31], 0x120000
	v_pk_mul_f32 v[38:39], v[38:39], v[138:139]
	v_add_co_u32_e32 v54, vcc, s19, v154
	v_lshl_add_u64 v[52:53], v[154:155], 0, s[30:31]
	s_nop 0
	v_addc_co_u32_e32 v55, vcc, 0, v155, vcc
	v_pk_mul_f32 v[36:37], v[36:37], v[136:137]
	s_mov_b32 s19, 0x140000
	global_store_dwordx4 v[52:53], v[36:39], off offset:512
	s_mov_b64 s[30:31], 0x140000
	v_pk_mul_f32 v[22:23], v[22:23], v[138:139]
	v_add_co_u32_e32 v38, vcc, s19, v154
	v_lshl_add_u64 v[36:37], v[154:155], 0, s[30:31]
	s_nop 0
	v_addc_co_u32_e32 v39, vcc, 0, v155, vcc
	v_pk_mul_f32 v[20:21], v[20:21], v[136:137]
	s_mov_b32 s19, 0x160000
	global_store_dwordx4 v[36:37], v[20:23], off offset:512
	v_pk_mul_f32 v[50:51], v[50:51], v[134:135]
	v_pk_mul_f32 v[48:49], v[48:49], v[132:133]
	v_add_co_u32_e32 v22, vcc, s19, v154
	v_pk_mul_f32 v[34:35], v[34:35], v[134:135]
	v_pk_mul_f32 v[32:33], v[32:33], v[132:133]
	v_pk_mul_f32 v[18:19], v[18:19], v[134:135]
	v_pk_mul_f32 v[16:17], v[16:17], v[132:133]
	s_mov_b64 s[30:31], 0x160000
	v_addc_co_u32_e32 v23, vcc, 0, v155, vcc
	v_pk_mul_f32 v[126:127], v[126:127], v[142:143]
	v_pk_mul_f32 v[124:125], v[124:125], v[140:141]
	v_pk_mul_f32 v[122:123], v[122:123], v[138:139]
	v_pk_mul_f32 v[120:121], v[120:121], v[136:137]
	v_pk_mul_f32 v[114:115], v[114:115], v[146:147]
	v_pk_mul_f32 v[112:113], v[112:113], v[144:145]
	v_pk_mul_f32 v[110:111], v[110:111], v[142:143]
	v_pk_mul_f32 v[108:109], v[108:109], v[140:141]
	v_pk_mul_f32 v[106:107], v[106:107], v[138:139]
	v_pk_mul_f32 v[104:105], v[104:105], v[136:137]
	v_pk_mul_f32 v[98:99], v[98:99], v[146:147]
	v_pk_mul_f32 v[96:97], v[96:97], v[144:145]
	v_pk_mul_f32 v[94:95], v[94:95], v[142:143]
	v_pk_mul_f32 v[92:93], v[92:93], v[140:141]
	v_pk_mul_f32 v[90:91], v[90:91], v[138:139]
	v_pk_mul_f32 v[88:89], v[88:89], v[136:137]
	v_pk_mul_f32 v[82:83], v[82:83], v[146:147]
	v_pk_mul_f32 v[80:81], v[80:81], v[144:145]
	v_pk_mul_f32 v[78:79], v[78:79], v[142:143]
	v_pk_mul_f32 v[76:77], v[76:77], v[140:141]
	v_pk_mul_f32 v[74:75], v[74:75], v[138:139]
	v_pk_mul_f32 v[72:73], v[72:73], v[136:137]
	v_pk_mul_f32 v[66:67], v[66:67], v[146:147]
	v_pk_mul_f32 v[64:65], v[64:65], v[144:145]
	v_pk_mul_f32 v[62:63], v[62:63], v[142:143]
	v_pk_mul_f32 v[60:61], v[60:61], v[140:141]
	global_store_dwordx4 v[68:69], v[48:51], off offset:576
	v_pk_mul_f32 v[46:47], v[46:47], v[142:143]
	v_pk_mul_f32 v[44:45], v[44:45], v[140:141]
	v_pk_mul_f32 v[50:51], v[58:59], v[146:147]
	v_pk_mul_f32 v[48:49], v[56:57], v[144:145]
	global_store_dwordx4 v[52:53], v[32:35], off offset:576
	v_pk_mul_f32 v[30:31], v[30:31], v[142:143]
	v_pk_mul_f32 v[28:29], v[28:29], v[140:141]
	v_pk_mul_f32 v[34:35], v[42:43], v[146:147]
	v_pk_mul_f32 v[32:33], v[40:41], v[144:145]
	global_store_dwordx4 v[36:37], v[16:19], off offset:576
	v_lshl_add_u64 v[20:21], v[154:155], 0, s[30:31]
	v_pk_mul_f32 v[14:15], v[14:15], v[142:143]
	v_pk_mul_f32 v[18:19], v[26:27], v[146:147]
	v_pk_mul_f32 v[16:17], v[24:25], v[144:145]
	v_pk_mul_f32 v[12:13], v[12:13], v[140:141]
	v_pk_mul_f32 v[10:11], v[10:11], v[138:139]
	v_pk_mul_f32 v[8:9], v[8:9], v[136:137]
	v_pk_mul_f32 v[6:7], v[6:7], v[134:135]
	v_pk_mul_f32 v[4:5], v[4:5], v[132:133]
	s_and_b64 vcc, exec, s[36:37]
	s_mov_b32 s30, s18
	global_store_dwordx4 v[154:155], v[128:131], off
	global_store_dwordx4 v[154:155], v[124:127], off offset:64
	global_store_dwordx4 v[154:155], v[120:123], off offset:512
	global_store_dwordx4 v[118:119], v[112:115], off
	global_store_dwordx4 v[116:117], v[108:111], off offset:64
	global_store_dwordx4 v[116:117], v[104:107], off offset:512
	global_store_dwordx4 v[102:103], v[96:99], off
	global_store_dwordx4 v[100:101], v[92:95], off offset:64
	global_store_dwordx4 v[100:101], v[88:91], off offset:512
	global_store_dwordx4 v[86:87], v[80:83], off
	global_store_dwordx4 v[84:85], v[76:79], off offset:64
	global_store_dwordx4 v[84:85], v[72:75], off offset:512
	global_store_dwordx4 v[70:71], v[64:67], off
	global_store_dwordx4 v[68:69], v[60:63], off offset:64
	global_store_dwordx4 v[54:55], v[48:51], off
	global_store_dwordx4 v[52:53], v[44:47], off offset:64
	global_store_dwordx4 v[38:39], v[32:35], off
	global_store_dwordx4 v[36:37], v[28:31], off offset:64
	global_store_dwordx4 v[22:23], v[16:19], off
	global_store_dwordx4 v[20:21], v[12:15], off offset:64
	global_store_dwordx4 v[20:21], v[8:11], off offset:512
	global_store_dwordx4 v[20:21], v[4:7], off offset:576
	s_cbranch_vccz .LBB0_2130
	s_waitcnt vmcnt(0)
	s_cmpk_gt_u32 s4, 0xff
	s_cbranch_scc1 .LBB0_2137
	s_barrier

.LBB0_2566:
	s_add_u32 s15, s44, 0xfff80080
	s_addc_u32 s17, s45, -1
	s_add_i32 s29, 0, 0x10000
	v_add_u32_e32 v2, s29, v202
	ds_read_b128 v[132:135], v2
	ds_read_b128 v[136:139], v2 offset:1024
	ds_read_b128 v[140:143], v2 offset:2048
	ds_read_b128 v[144:147], v2 offset:3072
	s_cmp_eq_u32 s14, 28
	s_cselect_b32 s47, s85, s17
	s_cselect_b32 s46, s84, s15
	s_cselect_b32 s39, s27, s11
	s_cselect_b32 s38, s26, s10
	v_lshl_add_u64 v[192:193], s[44:45], 0, v[184:185]
	s_add_i32 m0, s6, 0xc000
	ds_read_b128 v[148:151], v208
	ds_read_b128 v[152:155], v208 offset:1024
	ds_read_b128 v[156:159], v208 offset:2048
	ds_read_b128 v[160:163], v208 offset:3072
	ds_read_b128 v[164:167], v208 offset:4096
	ds_read_b128 v[168:171], v208 offset:5120
	ds_read_b128 v[172:175], v208 offset:6144
	ds_read_b128 v[188:191], v208 offset:7168
	global_load_lds_dwordx4 v[192:193], off
	v_lshl_add_u64 v[192:193], s[44:45], 0, v[186:187]
	s_add_i32 m0, s6, 0xe000
	s_nop 0
	global_load_lds_dwordx4 v[192:193], off
	s_waitcnt lgkmcnt(8)
	s_barrier
	s_waitcnt lgkmcnt(0)
	s_waitcnt lgkmcnt(0)
	v_mfma_f32_16x16x32_f16 v[128:131], v[132:135], v[148:151], v[128:131]
	v_mfma_f32_16x16x32_f16 v[88:91], v[140:143], v[148:151], v[88:91]
	v_mfma_f32_16x16x32_f16 v[120:123], v[132:135], v[156:159], v[120:123]
	v_mfma_f32_16x16x32_f16 v[92:95], v[140:143], v[156:159], v[92:95]
	v_mfma_f32_16x16x32_f16 v[112:115], v[132:135], v[164:167], v[112:115]
	v_mfma_f32_16x16x32_f16 v[80:83], v[140:143], v[164:167], v[80:83]
	v_mfma_f32_16x16x32_f16 v[104:107], v[132:135], v[172:175], v[104:107]
	v_mfma_f32_16x16x32_f16 v[68:71], v[140:143], v[172:175], v[68:71]
	v_mfma_f32_16x16x32_f16 v[128:131], v[136:139], v[152:155], v[128:131]
	v_mfma_f32_16x16x32_f16 v[88:91], v[144:147], v[152:155], v[88:91]
	v_mfma_f32_16x16x32_f16 v[120:123], v[136:139], v[160:163], v[120:123]
	v_mfma_f32_16x16x32_f16 v[92:95], v[144:147], v[160:163], v[92:95]
	v_mfma_f32_16x16x32_f16 v[112:115], v[136:139], v[168:171], v[112:115]
	v_mfma_f32_16x16x32_f16 v[80:83], v[144:147], v[168:171], v[80:83]
	v_mfma_f32_16x16x32_f16 v[104:107], v[136:139], v[188:191], v[104:107]
	v_mfma_f32_16x16x32_f16 v[68:71], v[144:147], v[188:191], v[68:71]
	s_barrier
	s_add_i32 s15, 0, 0x14000
	s_add_i32 s17, s29, s5
	v_add_u32_e32 v2, s15, v202
	v_lshl_add_u64 v[218:219], s[38:39], 0, v[178:179]
	s_mov_b32 m0, s17
	ds_read_b128 v[192:195], v2
	ds_read_b128 v[196:199], v2 offset:1024
	ds_read_b128 v[210:213], v2 offset:2048
	ds_read_b128 v[214:217], v2 offset:3072
	global_load_lds_dwordx4 v[218:219], off
	v_lshl_add_u64 v[220:221], s[38:39], 0, v[182:183]
	s_add_i32 m0, s17, 0x2000
	s_nop 0
	global_load_lds_dwordx4 v[220:221], off
	s_barrier
	s_waitcnt lgkmcnt(0)
	s_waitcnt lgkmcnt(0)
	v_mfma_f32_16x16x32_f16 v[124:127], v[192:195], v[148:151], v[124:127]
	v_mfma_f32_16x16x32_f16 v[96:99], v[210:213], v[148:151], v[96:99]
	v_mfma_f32_16x16x32_f16 v[116:119], v[192:195], v[156:159], v[116:119]
	v_mfma_f32_16x16x32_f16 v[84:87], v[210:213], v[156:159], v[84:87]
	v_mfma_f32_16x16x32_f16 v[108:111], v[192:195], v[164:167], v[108:111]
	v_mfma_f32_16x16x32_f16 v[76:79], v[210:213], v[164:167], v[76:79]
	v_mfma_f32_16x16x32_f16 v[100:103], v[192:195], v[172:175], v[100:103]
	v_mfma_f32_16x16x32_f16 v[72:75], v[210:213], v[172:175], v[72:75]
	v_mfma_f32_16x16x32_f16 v[124:127], v[196:199], v[152:155], v[124:127]
	v_mfma_f32_16x16x32_f16 v[96:99], v[214:217], v[152:155], v[96:99]
	v_mfma_f32_16x16x32_f16 v[116:119], v[196:199], v[160:163], v[116:119]
	v_mfma_f32_16x16x32_f16 v[84:87], v[214:217], v[160:163], v[84:87]
	v_mfma_f32_16x16x32_f16 v[108:111], v[196:199], v[168:171], v[108:111]
	v_mfma_f32_16x16x32_f16 v[76:79], v[214:217], v[168:171], v[76:79]
	v_mfma_f32_16x16x32_f16 v[100:103], v[196:199], v[188:191], v[100:103]
	v_mfma_f32_16x16x32_f16 v[72:75], v[214:217], v[188:191], v[72:75]
	s_mov_b32 m0, s6
	v_lshl_add_u64 v[224:225], s[46:47], 0, v[176:177]
	s_barrier
	ds_read_b128 v[148:151], v208 offset:16384
	ds_read_b128 v[152:155], v208 offset:17408
	ds_read_b128 v[156:159], v208 offset:18432
	ds_read_b128 v[160:163], v208 offset:19456
	ds_read_b128 v[164:167], v208 offset:20480
	ds_read_b128 v[168:171], v208 offset:21504
	ds_read_b128 v[172:175], v208 offset:22528
	ds_read_b128 v[188:191], v208 offset:23552
	global_load_lds_dwordx4 v[224:225], off
	v_lshl_add_u64 v[226:227], s[46:47], 0, v[180:181]
	s_mov_b32 m0, s7
	s_nop 0
	global_load_lds_dwordx4 v[226:227], off
	s_barrier
	s_waitcnt lgkmcnt(0)
	s_waitcnt lgkmcnt(0)
	v_mfma_f32_16x16x32_f16 v[64:67], v[132:135], v[148:151], v[64:67]
	v_mfma_f32_16x16x32_f16 v[48:51], v[140:143], v[148:151], v[48:51]
	v_mfma_f32_16x16x32_f16 v[56:59], v[132:135], v[156:159], v[56:59]
	v_mfma_f32_16x16x32_f16 v[40:43], v[140:143], v[156:159], v[40:43]
	v_mfma_f32_16x16x32_f16 v[28:31], v[132:135], v[164:167], v[28:31]
	v_mfma_f32_16x16x32_f16 v[20:23], v[140:143], v[164:167], v[20:23]
	v_mfma_f32_16x16x32_f16 v[32:35], v[132:135], v[172:175], v[32:35]
	v_mfma_f32_16x16x32_f16 v[8:11], v[140:143], v[172:175], v[8:11]
	v_mfma_f32_16x16x32_f16 v[64:67], v[136:139], v[152:155], v[64:67]
	v_mfma_f32_16x16x32_f16 v[48:51], v[144:147], v[152:155], v[48:51]
	v_mfma_f32_16x16x32_f16 v[56:59], v[136:139], v[160:163], v[56:59]
	v_mfma_f32_16x16x32_f16 v[40:43], v[144:147], v[160:163], v[40:43]
	v_mfma_f32_16x16x32_f16 v[28:31], v[136:139], v[168:171], v[28:31]
	v_mfma_f32_16x16x32_f16 v[20:23], v[144:147], v[168:171], v[20:23]
	v_mfma_f32_16x16x32_f16 v[32:35], v[136:139], v[188:191], v[32:35]
	v_mfma_f32_16x16x32_f16 v[8:11], v[144:147], v[188:191], v[8:11]
	s_barrier
	s_add_u32 s30, s38, 0x80000
	s_addc_u32 s31, s39, 0
	s_add_i32 s15, s15, s5
	v_lshl_add_u64 v[132:133], s[30:31], 0, v[178:179]
	s_mov_b32 m0, s15
	s_nop 0
	global_load_lds_dwordx4 v[132:133], off
	v_lshl_add_u64 v[132:133], s[30:31], 0, v[182:183]
	s_add_i32 m0, s15, 0x2000
	s_nop 0
	global_load_lds_dwordx4 v[132:133], off
	s_waitcnt vmcnt(6)
	s_barrier
	v_mfma_f32_16x16x32_f16 v[60:63], v[192:195], v[148:151], v[60:63]
	v_mfma_f32_16x16x32_f16 v[44:47], v[210:213], v[148:151], v[44:47]
	v_mfma_f32_16x16x32_f16 v[52:55], v[192:195], v[156:159], v[52:55]
	v_mfma_f32_16x16x32_f16 v[36:39], v[210:213], v[156:159], v[36:39]
	v_mfma_f32_16x16x32_f16 v[16:19], v[192:195], v[164:167], v[16:19]
	v_mfma_f32_16x16x32_f16 v[12:15], v[210:213], v[164:167], v[12:15]
	v_mfma_f32_16x16x32_f16 v[24:27], v[192:195], v[172:175], v[24:27]
	v_mfma_f32_16x16x32_f16 v[4:7], v[210:213], v[172:175], v[4:7]
	v_mfma_f32_16x16x32_f16 v[60:63], v[196:199], v[152:155], v[60:63]
	v_mfma_f32_16x16x32_f16 v[44:47], v[214:217], v[152:155], v[44:47]
	v_mfma_f32_16x16x32_f16 v[52:55], v[196:199], v[160:163], v[52:55]
	v_mfma_f32_16x16x32_f16 v[36:39], v[214:217], v[160:163], v[36:39]
	v_mfma_f32_16x16x32_f16 v[16:19], v[196:199], v[168:171], v[16:19]
	v_mfma_f32_16x16x32_f16 v[12:15], v[214:217], v[168:171], v[12:15]
	v_mfma_f32_16x16x32_f16 v[24:27], v[196:199], v[188:191], v[24:27]
	v_mfma_f32_16x16x32_f16 v[4:7], v[214:217], v[188:191], v[4:7]
	s_add_i32 s15, 0, 0x18000
	v_add_u32_e32 v2, s15, v202
	s_barrier
	ds_read_b128 v[132:135], v2
	ds_read_b128 v[136:139], v2 offset:1024
	ds_read_b128 v[140:143], v2 offset:2048
	ds_read_b128 v[144:147], v2 offset:3072
	s_add_u32 s30, s46, 0x80000
	s_addc_u32 s31, s47, 0
	s_mov_b32 m0, s8
	v_lshl_add_u64 v[192:193], s[30:31], 0, v[176:177]
	ds_read_b128 v[148:151], v208 offset:32768
	ds_read_b128 v[152:155], v208 offset:33792
	ds_read_b128 v[156:159], v208 offset:34816
	ds_read_b128 v[160:163], v208 offset:35840
	ds_read_b128 v[164:167], v208 offset:36864
	ds_read_b128 v[168:171], v208 offset:37888
	ds_read_b128 v[172:175], v208 offset:38912
	ds_read_b128 v[188:191], v208 offset:39936
	global_load_lds_dwordx4 v[192:193], off
	v_lshl_add_u64 v[192:193], s[30:31], 0, v[180:181]
	s_mov_b32 m0, s9
	s_nop 0
	global_load_lds_dwordx4 v[192:193], off
	s_waitcnt lgkmcnt(8)
	s_barrier
	s_waitcnt lgkmcnt(0)
	s_waitcnt lgkmcnt(0)
	v_mfma_f32_16x16x32_f16 v[128:131], v[132:135], v[148:151], v[128:131]
	v_mfma_f32_16x16x32_f16 v[88:91], v[140:143], v[148:151], v[88:91]
	v_mfma_f32_16x16x32_f16 v[120:123], v[132:135], v[156:159], v[120:123]
	v_mfma_f32_16x16x32_f16 v[92:95], v[140:143], v[156:159], v[92:95]
	v_mfma_f32_16x16x32_f16 v[112:115], v[132:135], v[164:167], v[112:115]
	v_mfma_f32_16x16x32_f16 v[80:83], v[140:143], v[164:167], v[80:83]
	v_mfma_f32_16x16x32_f16 v[104:107], v[132:135], v[172:175], v[104:107]
	v_mfma_f32_16x16x32_f16 v[68:71], v[140:143], v[172:175], v[68:71]
	v_mfma_f32_16x16x32_f16 v[128:131], v[136:139], v[152:155], v[128:131]
	v_mfma_f32_16x16x32_f16 v[88:91], v[144:147], v[152:155], v[88:91]
	v_mfma_f32_16x16x32_f16 v[120:123], v[136:139], v[160:163], v[120:123]
	v_mfma_f32_16x16x32_f16 v[92:95], v[144:147], v[160:163], v[92:95]
	v_mfma_f32_16x16x32_f16 v[112:115], v[136:139], v[168:171], v[112:115]
	v_mfma_f32_16x16x32_f16 v[80:83], v[144:147], v[168:171], v[80:83]
	v_mfma_f32_16x16x32_f16 v[104:107], v[136:139], v[188:191], v[104:107]
	v_mfma_f32_16x16x32_f16 v[68:71], v[144:147], v[188:191], v[68:71]
	s_barrier
	s_add_i32 s17, 0, 0x1c000
	s_add_i32 s15, s15, s5
	v_add_u32_e32 v2, s17, v202
	v_lshl_add_u64 v[218:219], v[218:219], 0, s[88:89]
	s_mov_b32 m0, s15
	ds_read_b128 v[192:195], v2
	ds_read_b128 v[196:199], v2 offset:1024
	ds_read_b128 v[210:213], v2 offset:2048
	ds_read_b128 v[214:217], v2 offset:3072
	global_load_lds_dwordx4 v[218:219], off
	v_lshl_add_u64 v[218:219], v[220:221], 0, s[88:89]
	s_add_i32 m0, s15, 0x2000
	s_nop 0
	global_load_lds_dwordx4 v[218:219], off
	s_barrier
	s_waitcnt lgkmcnt(0)
	s_waitcnt lgkmcnt(0)
	v_mfma_f32_16x16x32_f16 v[124:127], v[192:195], v[148:151], v[124:127]
	v_mfma_f32_16x16x32_f16 v[96:99], v[210:213], v[148:151], v[96:99]
	v_mfma_f32_16x16x32_f16 v[116:119], v[192:195], v[156:159], v[116:119]
	v_mfma_f32_16x16x32_f16 v[84:87], v[210:213], v[156:159], v[84:87]
	v_mfma_f32_16x16x32_f16 v[108:111], v[192:195], v[164:167], v[108:111]
	v_mfma_f32_16x16x32_f16 v[76:79], v[210:213], v[164:167], v[76:79]
	v_mfma_f32_16x16x32_f16 v[100:103], v[192:195], v[172:175], v[100:103]
	v_mfma_f32_16x16x32_f16 v[72:75], v[210:213], v[172:175], v[72:75]
	v_mfma_f32_16x16x32_f16 v[124:127], v[196:199], v[152:155], v[124:127]
	v_mfma_f32_16x16x32_f16 v[96:99], v[214:217], v[152:155], v[96:99]
	v_mfma_f32_16x16x32_f16 v[116:119], v[196:199], v[160:163], v[116:119]
	v_mfma_f32_16x16x32_f16 v[84:87], v[214:217], v[160:163], v[84:87]
	v_mfma_f32_16x16x32_f16 v[108:111], v[196:199], v[168:171], v[108:111]
	v_mfma_f32_16x16x32_f16 v[76:79], v[214:217], v[168:171], v[76:79]
	v_mfma_f32_16x16x32_f16 v[100:103], v[196:199], v[188:191], v[100:103]
	v_mfma_f32_16x16x32_f16 v[72:75], v[214:217], v[188:191], v[72:75]
	s_mov_b32 m0, s69
	v_lshl_add_u64 v[218:219], v[224:225], 0, s[88:89]
	s_barrier
	ds_read_b128 v[148:151], v208 offset:49152
	ds_read_b128 v[152:155], v208 offset:50176
	ds_read_b128 v[156:159], v208 offset:51200
	ds_read_b128 v[160:163], v208 offset:52224
	ds_read_b128 v[164:167], v208 offset:53248
	ds_read_b128 v[168:171], v208 offset:54272
	ds_read_b128 v[172:175], v208 offset:55296
	ds_read_b128 v[188:191], v208 offset:56320
	global_load_lds_dwordx4 v[218:219], off
	v_lshl_add_u64 v[218:219], v[226:227], 0, s[88:89]
	s_mov_b32 m0, s70
	s_nop 0
	global_load_lds_dwordx4 v[218:219], off
	s_barrier
	s_waitcnt lgkmcnt(0)
	s_waitcnt lgkmcnt(0)
	v_mfma_f32_16x16x32_f16 v[64:67], v[132:135], v[148:151], v[64:67]
	v_mfma_f32_16x16x32_f16 v[48:51], v[140:143], v[148:151], v[48:51]
	v_mfma_f32_16x16x32_f16 v[56:59], v[132:135], v[156:159], v[56:59]
	v_mfma_f32_16x16x32_f16 v[40:43], v[140:143], v[156:159], v[40:43]
	v_mfma_f32_16x16x32_f16 v[28:31], v[132:135], v[164:167], v[28:31]
	v_mfma_f32_16x16x32_f16 v[20:23], v[140:143], v[164:167], v[20:23]
	v_mfma_f32_16x16x32_f16 v[32:35], v[132:135], v[172:175], v[32:35]
	v_mfma_f32_16x16x32_f16 v[8:11], v[140:143], v[172:175], v[8:11]
	v_mfma_f32_16x16x32_f16 v[64:67], v[136:139], v[152:155], v[64:67]
	v_mfma_f32_16x16x32_f16 v[48:51], v[144:147], v[152:155], v[48:51]
	v_mfma_f32_16x16x32_f16 v[56:59], v[136:139], v[160:163], v[56:59]
	v_mfma_f32_16x16x32_f16 v[40:43], v[144:147], v[160:163], v[40:43]
	v_mfma_f32_16x16x32_f16 v[28:31], v[136:139], v[168:171], v[28:31]
	v_mfma_f32_16x16x32_f16 v[20:23], v[144:147], v[168:171], v[20:23]
	v_mfma_f32_16x16x32_f16 v[32:35], v[136:139], v[188:191], v[32:35]
	v_mfma_f32_16x16x32_f16 v[8:11], v[144:147], v[188:191], v[8:11]
	s_barrier
	s_add_u32 s30, s38, 0x80080
	s_addc_u32 s31, s39, 0
	s_add_i32 s15, s17, s5
	v_lshl_add_u64 v[132:133], s[30:31], 0, v[178:179]
	s_mov_b32 m0, s15
	s_nop 0
	global_load_lds_dwordx4 v[132:133], off
	v_lshl_add_u64 v[132:133], s[30:31], 0, v[182:183]
	s_add_i32 m0, s15, 0x2000
	s_nop 0
	global_load_lds_dwordx4 v[132:133], off
	s_waitcnt vmcnt(6)
	s_barrier
	v_mfma_f32_16x16x32_f16 v[60:63], v[192:195], v[148:151], v[60:63]
	v_mfma_f32_16x16x32_f16 v[44:47], v[210:213], v[148:151], v[44:47]
	v_mfma_f32_16x16x32_f16 v[52:55], v[192:195], v[156:159], v[52:55]
	v_mfma_f32_16x16x32_f16 v[36:39], v[210:213], v[156:159], v[36:39]
	v_mfma_f32_16x16x32_f16 v[16:19], v[192:195], v[164:167], v[16:19]
	v_mfma_f32_16x16x32_f16 v[12:15], v[210:213], v[164:167], v[12:15]
	v_mfma_f32_16x16x32_f16 v[24:27], v[192:195], v[172:175], v[24:27]
	v_mfma_f32_16x16x32_f16 v[4:7], v[210:213], v[172:175], v[4:7]
	v_mfma_f32_16x16x32_f16 v[60:63], v[196:199], v[152:155], v[60:63]
	v_mfma_f32_16x16x32_f16 v[44:47], v[214:217], v[152:155], v[44:47]
	v_mfma_f32_16x16x32_f16 v[52:55], v[196:199], v[160:163], v[52:55]
	v_mfma_f32_16x16x32_f16 v[36:39], v[214:217], v[160:163], v[36:39]
	v_mfma_f32_16x16x32_f16 v[16:19], v[196:199], v[168:171], v[16:19]
	v_mfma_f32_16x16x32_f16 v[12:15], v[214:217], v[168:171], v[12:15]
	v_mfma_f32_16x16x32_f16 v[24:27], v[196:199], v[188:191], v[24:27]
	v_mfma_f32_16x16x32_f16 v[4:7], v[214:217], v[188:191], v[4:7]
	s_add_i32 s14, s14, 2
	s_add_u32 s44, s44, 0x100
	s_addc_u32 s45, s45, 0
	s_add_u32 s10, s10, 0x100
	s_addc_u32 s11, s11, 0
	s_cmp_gt_u32 s14, 29
	s_barrier
	s_cbranch_scc0 .LBB0_2566
	v_mov_b32_e32 v209, v200
	v_mov_b32_e32 v2, v201
	s_mov_b64 s[38:39], 0
	v_lshlrev_b32_e32 v136, 5, v2
	v_add_u32_e32 v137, s92, v136
	v_cmp_lt_i32_e32 vcc, 14, v209
	s_and_saveexec_b64 s[10:11], vcc
	s_xor_b64 s[14:15], exec, s[10:11]
	s_cbranch_execz .LBB0_2571
	v_cmp_eq_u32_e32 vcc, 15, v209
	s_and_saveexec_b64 s[44:45], vcc
	s_mov_b64 s[38:39], exec
	ds_write_b128 v137, v[104:107] offset:128
	s_or_b64 exec, exec, s[44:45]
	s_and_b64 s[38:39], s[38:39], exec

.LBB0_3035:
	s_add_u32 s34, s26, 0x100
	s_addc_u32 s35, s27, 0
	s_add_i32 s45, 0, 0x10000
	v_add_u32_e32 v128, s45, v198
	ds_read_b128 v[108:111], v128
	ds_read_b128 v[112:115], v128 offset:1024
	ds_read_b128 v[120:123], v128 offset:2048
	ds_read_b128 v[128:131], v128 offset:3072
	s_cmpk_eq_i32 s44, 0x54
	s_cselect_b32 s39, s17, s35
	s_cselect_b32 s38, s16, s34
	s_cselect_b32 s37, s19, s15
	s_cselect_b32 s36, s18, s14
	v_lshl_add_u64 v[186:187], s[26:27], 0, v[182:183]
	s_add_i32 m0, s6, 0xc000
	ds_read_b128 v[148:151], v199
	ds_read_b128 v[152:155], v199 offset:1024
	ds_read_b128 v[156:159], v199 offset:2048
	ds_read_b128 v[160:163], v199 offset:3072
	ds_read_b128 v[164:167], v199 offset:4096
	ds_read_b128 v[168:171], v199 offset:5120
	ds_read_b128 v[172:175], v199 offset:6144
	ds_read_b128 v[176:179], v199 offset:7168
	global_load_lds_dwordx4 v[186:187], off
	v_lshl_add_u64 v[186:187], s[26:27], 0, v[184:185]
	s_add_i32 m0, s6, 0xe000
	s_nop 0
	global_load_lds_dwordx4 v[186:187], off
	s_waitcnt lgkmcnt(8)
	s_barrier
	s_waitcnt lgkmcnt(0)
	s_waitcnt lgkmcnt(0)
	v_mfma_f32_16x16x32_f16 v[144:147], v[108:111], v[148:151], v[144:147]
	v_mfma_f32_16x16x32_f16 v[140:143], v[120:123], v[148:151], v[140:143]
	v_mfma_f32_16x16x32_f16 v[124:127], v[108:111], v[156:159], v[124:127]
	v_mfma_f32_16x16x32_f16 v[116:119], v[120:123], v[156:159], v[116:119]
	v_mfma_f32_16x16x32_f16 v[96:99], v[108:111], v[164:167], v[96:99]
	v_mfma_f32_16x16x32_f16 v[92:95], v[120:123], v[164:167], v[92:95]
	v_mfma_f32_16x16x32_f16 v[88:91], v[108:111], v[172:175], v[88:91]
	v_mfma_f32_16x16x32_f16 v[80:83], v[120:123], v[172:175], v[80:83]
	v_mfma_f32_16x16x32_f16 v[144:147], v[112:115], v[152:155], v[144:147]
	v_mfma_f32_16x16x32_f16 v[140:143], v[128:131], v[152:155], v[140:143]
	v_mfma_f32_16x16x32_f16 v[124:127], v[112:115], v[160:163], v[124:127]
	v_mfma_f32_16x16x32_f16 v[116:119], v[128:131], v[160:163], v[116:119]
	v_mfma_f32_16x16x32_f16 v[96:99], v[112:115], v[168:171], v[96:99]
	v_mfma_f32_16x16x32_f16 v[92:95], v[128:131], v[168:171], v[92:95]
	v_mfma_f32_16x16x32_f16 v[88:91], v[112:115], v[176:179], v[88:91]
	v_mfma_f32_16x16x32_f16 v[80:83], v[128:131], v[176:179], v[80:83]
	s_barrier
	s_add_i32 s46, 0, 0x14000
	v_add_u32_e32 v194, s46, v198
	s_add_i32 s26, s45, s5
	ds_read_b128 v[186:189], v194
	ds_read_b128 v[190:193], v194 offset:1024
	ds_read_b128 v[200:203], v194 offset:2048
	ds_read_b128 v[206:209], v194 offset:3072
	v_lshl_add_u64 v[194:195], s[36:37], 0, v[2:3]
	s_mov_b32 m0, s26
	v_lshl_add_u64 v[210:211], s[36:37], 0, v[180:181]
	global_load_lds_dwordx4 v[194:195], off
	s_add_i32 m0, s26, 0x2000
	s_nop 0
	global_load_lds_dwordx4 v[210:211], off
	s_barrier
	s_waitcnt lgkmcnt(0)
	s_waitcnt lgkmcnt(0)
	v_mfma_f32_16x16x32_f16 v[136:139], v[186:189], v[148:151], v[136:139]
	v_mfma_f32_16x16x32_f16 v[132:135], v[200:203], v[148:151], v[132:135]
	v_mfma_f32_16x16x32_f16 v[104:107], v[186:189], v[156:159], v[104:107]
	v_mfma_f32_16x16x32_f16 v[100:103], v[200:203], v[156:159], v[100:103]
	v_mfma_f32_16x16x32_f16 v[84:87], v[186:189], v[164:167], v[84:87]
	v_mfma_f32_16x16x32_f16 v[76:79], v[200:203], v[164:167], v[76:79]
	v_mfma_f32_16x16x32_f16 v[72:75], v[186:189], v[172:175], v[72:75]
	v_mfma_f32_16x16x32_f16 v[68:71], v[200:203], v[172:175], v[68:71]
	v_mfma_f32_16x16x32_f16 v[136:139], v[190:193], v[152:155], v[136:139]
	v_mfma_f32_16x16x32_f16 v[132:135], v[206:209], v[152:155], v[132:135]
	v_mfma_f32_16x16x32_f16 v[104:107], v[190:193], v[160:163], v[104:107]
	v_mfma_f32_16x16x32_f16 v[100:103], v[206:209], v[160:163], v[100:103]
	v_mfma_f32_16x16x32_f16 v[84:87], v[190:193], v[168:171], v[84:87]
	v_mfma_f32_16x16x32_f16 v[76:79], v[206:209], v[168:171], v[76:79]
	v_mfma_f32_16x16x32_f16 v[72:75], v[190:193], v[176:179], v[72:75]
	v_mfma_f32_16x16x32_f16 v[68:71], v[206:209], v[176:179], v[68:71]
	s_mov_b32 m0, s6
	v_lshl_add_u64 v[212:213], s[38:39], 0, v[2:3]
	s_barrier
	ds_read_b128 v[148:151], v199 offset:16384
	ds_read_b128 v[152:155], v199 offset:17408
	ds_read_b128 v[156:159], v199 offset:18432
	ds_read_b128 v[160:163], v199 offset:19456
	ds_read_b128 v[164:167], v199 offset:20480
	ds_read_b128 v[168:171], v199 offset:21504
	ds_read_b128 v[172:175], v199 offset:22528
	ds_read_b128 v[176:179], v199 offset:23552
	global_load_lds_dwordx4 v[212:213], off
	v_lshl_add_u64 v[214:215], s[38:39], 0, v[180:181]
	s_mov_b32 m0, s7
	s_nop 0
	global_load_lds_dwordx4 v[214:215], off
	s_barrier
	s_waitcnt lgkmcnt(0)
	s_waitcnt lgkmcnt(0)
	v_mfma_f32_16x16x32_f16 v[64:67], v[108:111], v[148:151], v[64:67]
	v_mfma_f32_16x16x32_f16 v[60:63], v[120:123], v[148:151], v[60:63]
	v_mfma_f32_16x16x32_f16 v[48:51], v[108:111], v[156:159], v[48:51]
	v_mfma_f32_16x16x32_f16 v[44:47], v[120:123], v[156:159], v[44:47]
	v_mfma_f32_16x16x32_f16 v[32:35], v[108:111], v[164:167], v[32:35]
	v_mfma_f32_16x16x32_f16 v[28:31], v[120:123], v[164:167], v[28:31]
	v_mfma_f32_16x16x32_f16 v[20:23], v[108:111], v[172:175], v[20:23]
	v_mfma_f32_16x16x32_f16 v[12:15], v[120:123], v[172:175], v[12:15]
	v_mfma_f32_16x16x32_f16 v[64:67], v[112:115], v[152:155], v[64:67]
	v_mfma_f32_16x16x32_f16 v[60:63], v[128:131], v[152:155], v[60:63]
	v_mfma_f32_16x16x32_f16 v[48:51], v[112:115], v[160:163], v[48:51]
	v_mfma_f32_16x16x32_f16 v[44:47], v[128:131], v[160:163], v[44:47]
	v_mfma_f32_16x16x32_f16 v[32:35], v[112:115], v[168:171], v[32:35]
	v_mfma_f32_16x16x32_f16 v[28:31], v[128:131], v[168:171], v[28:31]
	v_mfma_f32_16x16x32_f16 v[20:23], v[112:115], v[176:179], v[20:23]
	v_mfma_f32_16x16x32_f16 v[12:15], v[128:131], v[176:179], v[12:15]
	s_barrier
	s_add_u32 s26, s36, 0x160000
	s_addc_u32 s27, s37, 0
	s_add_i32 s45, s46, s5
	v_lshl_add_u64 v[108:109], s[26:27], 0, v[2:3]
	s_mov_b32 m0, s45
	s_nop 0
	global_load_lds_dwordx4 v[108:109], off
	v_lshl_add_u64 v[108:109], s[26:27], 0, v[180:181]
	s_add_i32 m0, s45, 0x2000
	s_nop 0
	global_load_lds_dwordx4 v[108:109], off
	s_waitcnt vmcnt(6)
	s_barrier
	v_mfma_f32_16x16x32_f16 v[56:59], v[186:189], v[148:151], v[56:59]
	v_mfma_f32_16x16x32_f16 v[52:55], v[200:203], v[148:151], v[52:55]
	v_mfma_f32_16x16x32_f16 v[40:43], v[186:189], v[156:159], v[40:43]
	v_mfma_f32_16x16x32_f16 v[36:39], v[200:203], v[156:159], v[36:39]
	v_mfma_f32_16x16x32_f16 v[24:27], v[186:189], v[164:167], v[24:27]
	v_mfma_f32_16x16x32_f16 v[16:19], v[200:203], v[164:167], v[16:19]
	v_mfma_f32_16x16x32_f16 v[8:11], v[186:189], v[172:175], v[8:11]
	v_mfma_f32_16x16x32_f16 v[4:7], v[200:203], v[172:175], v[4:7]
	v_mfma_f32_16x16x32_f16 v[56:59], v[190:193], v[152:155], v[56:59]
	v_mfma_f32_16x16x32_f16 v[52:55], v[206:209], v[152:155], v[52:55]
	v_mfma_f32_16x16x32_f16 v[40:43], v[190:193], v[160:163], v[40:43]
	v_mfma_f32_16x16x32_f16 v[36:39], v[206:209], v[160:163], v[36:39]
	v_mfma_f32_16x16x32_f16 v[24:27], v[190:193], v[168:171], v[24:27]
	v_mfma_f32_16x16x32_f16 v[16:19], v[206:209], v[168:171], v[16:19]
	v_mfma_f32_16x16x32_f16 v[8:11], v[190:193], v[176:179], v[8:11]
	v_mfma_f32_16x16x32_f16 v[4:7], v[206:209], v[176:179], v[4:7]
	s_add_i32 s45, 0, 0x18000
	v_add_u32_e32 v128, s45, v198
	s_barrier
	ds_read_b128 v[108:111], v128
	ds_read_b128 v[112:115], v128 offset:1024
	ds_read_b128 v[120:123], v128 offset:2048
	ds_read_b128 v[128:131], v128 offset:3072
	s_add_u32 s26, s38, 0x160000
	s_addc_u32 s27, s39, 0
	s_mov_b32 m0, s8
	v_lshl_add_u64 v[186:187], s[26:27], 0, v[2:3]
	ds_read_b128 v[148:151], v199 offset:32768
	ds_read_b128 v[152:155], v199 offset:33792
	ds_read_b128 v[156:159], v199 offset:34816
	ds_read_b128 v[160:163], v199 offset:35840
	ds_read_b128 v[164:167], v199 offset:36864
	ds_read_b128 v[168:171], v199 offset:37888
	ds_read_b128 v[172:175], v199 offset:38912
	ds_read_b128 v[176:179], v199 offset:39936
	global_load_lds_dwordx4 v[186:187], off
	v_lshl_add_u64 v[186:187], s[26:27], 0, v[180:181]
	s_mov_b32 m0, s9
	s_nop 0
	global_load_lds_dwordx4 v[186:187], off
	s_waitcnt lgkmcnt(8)
	s_barrier
	s_waitcnt lgkmcnt(0)
	s_waitcnt lgkmcnt(0)
	v_mfma_f32_16x16x32_f16 v[144:147], v[108:111], v[148:151], v[144:147]
	v_mfma_f32_16x16x32_f16 v[140:143], v[120:123], v[148:151], v[140:143]
	v_mfma_f32_16x16x32_f16 v[124:127], v[108:111], v[156:159], v[124:127]
	v_mfma_f32_16x16x32_f16 v[116:119], v[120:123], v[156:159], v[116:119]
	v_mfma_f32_16x16x32_f16 v[96:99], v[108:111], v[164:167], v[96:99]
	v_mfma_f32_16x16x32_f16 v[92:95], v[120:123], v[164:167], v[92:95]
	v_mfma_f32_16x16x32_f16 v[88:91], v[108:111], v[172:175], v[88:91]
	v_mfma_f32_16x16x32_f16 v[80:83], v[120:123], v[172:175], v[80:83]
	v_mfma_f32_16x16x32_f16 v[144:147], v[112:115], v[152:155], v[144:147]
	v_mfma_f32_16x16x32_f16 v[140:143], v[128:131], v[152:155], v[140:143]
	v_mfma_f32_16x16x32_f16 v[124:127], v[112:115], v[160:163], v[124:127]
	v_mfma_f32_16x16x32_f16 v[116:119], v[128:131], v[160:163], v[116:119]
	v_mfma_f32_16x16x32_f16 v[96:99], v[112:115], v[168:171], v[96:99]
	v_mfma_f32_16x16x32_f16 v[92:95], v[128:131], v[168:171], v[92:95]
	v_mfma_f32_16x16x32_f16 v[88:91], v[112:115], v[176:179], v[88:91]
	v_mfma_f32_16x16x32_f16 v[80:83], v[128:131], v[176:179], v[80:83]
	s_barrier
	s_add_i32 s38, 0, 0x1c000
	s_add_i32 s26, s45, s5
	v_add_u32_e32 v206, s38, v198
	v_lshl_add_u64 v[194:195], v[194:195], 0, s[88:89]
	s_mov_b32 m0, s26
	ds_read_b128 v[186:189], v206
	ds_read_b128 v[190:193], v206 offset:1024
	ds_read_b128 v[200:203], v206 offset:2048
	ds_read_b128 v[206:209], v206 offset:3072
	global_load_lds_dwordx4 v[194:195], off
	v_lshl_add_u64 v[194:195], v[210:211], 0, s[88:89]
	s_add_i32 m0, s26, 0x2000
	s_nop 0
	global_load_lds_dwordx4 v[194:195], off
	s_barrier
	s_waitcnt lgkmcnt(0)
	s_waitcnt lgkmcnt(0)
	v_mfma_f32_16x16x32_f16 v[136:139], v[186:189], v[148:151], v[136:139]
	v_mfma_f32_16x16x32_f16 v[132:135], v[200:203], v[148:151], v[132:135]
	v_mfma_f32_16x16x32_f16 v[104:107], v[186:189], v[156:159], v[104:107]
	v_mfma_f32_16x16x32_f16 v[100:103], v[200:203], v[156:159], v[100:103]
	v_mfma_f32_16x16x32_f16 v[84:87], v[186:189], v[164:167], v[84:87]
	v_mfma_f32_16x16x32_f16 v[76:79], v[200:203], v[164:167], v[76:79]
	v_mfma_f32_16x16x32_f16 v[72:75], v[186:189], v[172:175], v[72:75]
	v_mfma_f32_16x16x32_f16 v[68:71], v[200:203], v[172:175], v[68:71]
	v_mfma_f32_16x16x32_f16 v[136:139], v[190:193], v[152:155], v[136:139]
	v_mfma_f32_16x16x32_f16 v[132:135], v[206:209], v[152:155], v[132:135]
	v_mfma_f32_16x16x32_f16 v[104:107], v[190:193], v[160:163], v[104:107]
	v_mfma_f32_16x16x32_f16 v[100:103], v[206:209], v[160:163], v[100:103]
	v_mfma_f32_16x16x32_f16 v[84:87], v[190:193], v[168:171], v[84:87]
	v_mfma_f32_16x16x32_f16 v[76:79], v[206:209], v[168:171], v[76:79]
	v_mfma_f32_16x16x32_f16 v[72:75], v[190:193], v[176:179], v[72:75]
	v_mfma_f32_16x16x32_f16 v[68:71], v[206:209], v[176:179], v[68:71]
	s_mov_b32 m0, s10
	v_lshl_add_u64 v[194:195], v[212:213], 0, s[88:89]
	s_barrier
	ds_read_b128 v[148:151], v199 offset:49152
	ds_read_b128 v[152:155], v199 offset:50176
	ds_read_b128 v[156:159], v199 offset:51200
	ds_read_b128 v[160:163], v199 offset:52224
	ds_read_b128 v[164:167], v199 offset:53248
	ds_read_b128 v[168:171], v199 offset:54272
	ds_read_b128 v[172:175], v199 offset:55296
	ds_read_b128 v[176:179], v199 offset:56320
	global_load_lds_dwordx4 v[194:195], off
	v_lshl_add_u64 v[194:195], v[214:215], 0, s[88:89]
	s_mov_b32 m0, s11
	s_nop 0
	global_load_lds_dwordx4 v[194:195], off
	s_barrier
	s_waitcnt lgkmcnt(0)
	s_waitcnt lgkmcnt(0)
	v_mfma_f32_16x16x32_f16 v[64:67], v[108:111], v[148:151], v[64:67]
	v_mfma_f32_16x16x32_f16 v[60:63], v[120:123], v[148:151], v[60:63]
	v_mfma_f32_16x16x32_f16 v[48:51], v[108:111], v[156:159], v[48:51]
	v_mfma_f32_16x16x32_f16 v[44:47], v[120:123], v[156:159], v[44:47]
	v_mfma_f32_16x16x32_f16 v[32:35], v[108:111], v[164:167], v[32:35]
	v_mfma_f32_16x16x32_f16 v[28:31], v[120:123], v[164:167], v[28:31]
	v_mfma_f32_16x16x32_f16 v[20:23], v[108:111], v[172:175], v[20:23]
	v_mfma_f32_16x16x32_f16 v[12:15], v[120:123], v[172:175], v[12:15]
	v_mfma_f32_16x16x32_f16 v[64:67], v[112:115], v[152:155], v[64:67]
	v_mfma_f32_16x16x32_f16 v[60:63], v[128:131], v[152:155], v[60:63]
	v_mfma_f32_16x16x32_f16 v[48:51], v[112:115], v[160:163], v[48:51]
	v_mfma_f32_16x16x32_f16 v[44:47], v[128:131], v[160:163], v[44:47]
	v_mfma_f32_16x16x32_f16 v[32:35], v[112:115], v[168:171], v[32:35]
	v_mfma_f32_16x16x32_f16 v[28:31], v[128:131], v[168:171], v[28:31]
	v_mfma_f32_16x16x32_f16 v[20:23], v[112:115], v[176:179], v[20:23]
	v_mfma_f32_16x16x32_f16 v[12:15], v[128:131], v[176:179], v[12:15]
	s_barrier
	s_add_u32 s26, s36, 0x160080
	s_addc_u32 s27, s37, 0
	s_add_i32 s36, s38, s5
	v_lshl_add_u64 v[108:109], s[26:27], 0, v[2:3]
	s_mov_b32 m0, s36
	s_nop 0
	global_load_lds_dwordx4 v[108:109], off
	v_lshl_add_u64 v[108:109], s[26:27], 0, v[180:181]
	s_add_i32 m0, s36, 0x2000
	s_nop 0
	global_load_lds_dwordx4 v[108:109], off
	s_waitcnt vmcnt(6)
	s_barrier
	v_mfma_f32_16x16x32_f16 v[56:59], v[186:189], v[148:151], v[56:59]
	v_mfma_f32_16x16x32_f16 v[52:55], v[200:203], v[148:151], v[52:55]
	v_mfma_f32_16x16x32_f16 v[40:43], v[186:189], v[156:159], v[40:43]
	v_mfma_f32_16x16x32_f16 v[36:39], v[200:203], v[156:159], v[36:39]
	v_mfma_f32_16x16x32_f16 v[24:27], v[186:189], v[164:167], v[24:27]
	v_mfma_f32_16x16x32_f16 v[16:19], v[200:203], v[164:167], v[16:19]
	v_mfma_f32_16x16x32_f16 v[8:11], v[186:189], v[172:175], v[8:11]
	v_mfma_f32_16x16x32_f16 v[4:7], v[200:203], v[172:175], v[4:7]
	v_mfma_f32_16x16x32_f16 v[56:59], v[190:193], v[152:155], v[56:59]
	v_mfma_f32_16x16x32_f16 v[52:55], v[206:209], v[152:155], v[52:55]
	v_mfma_f32_16x16x32_f16 v[40:43], v[190:193], v[160:163], v[40:43]
	v_mfma_f32_16x16x32_f16 v[36:39], v[206:209], v[160:163], v[36:39]
	v_mfma_f32_16x16x32_f16 v[24:27], v[190:193], v[168:171], v[24:27]
	v_mfma_f32_16x16x32_f16 v[16:19], v[206:209], v[168:171], v[16:19]
	v_mfma_f32_16x16x32_f16 v[8:11], v[190:193], v[176:179], v[8:11]
	v_mfma_f32_16x16x32_f16 v[4:7], v[206:209], v[176:179], v[4:7]
	s_add_i32 s44, s44, 2
	s_add_u32 s14, s14, 0x100
	s_addc_u32 s15, s15, 0
	s_cmpk_gt_u32 s44, 0x55
	s_mov_b64 s[26:27], s[34:35]
	s_barrier
	s_cbranch_scc0 .LBB0_3035
	s_lshl_b32 s14, s42, 8
	v_mov_b32_e32 v148, v196
	v_mov_b32_e32 v108, v197
	s_add_i32 s26, s14, s12
	s_lshl_b32 s14, s43, 8
	s_or_b32 s14, s14, s13
	v_lshl_add_u32 v108, v108, 2, s14
	s_cmp_lt_i32 s42, 64
	s_movk_i32 s14, 0x3000
	s_cselect_b32 s14, s14, 0x6000
	s_cmp_gt_i32 s42, 31
	s_cselect_b32 s14, s14, 0
	s_lshl_b32 s14, s14, 2
	v_readlane_b32 s15, v251, 41
	s_add_u32 s14, s15, s14
	v_readlane_b32 s15, v251, 42
	v_ashrrev_i32_e32 v109, 31, v108
	s_addc_u32 s15, s15, 0
	v_lshlrev_b64 v[186:187], 2, v[108:109]
	v_add_u32_e32 v148, s26, v148
	v_lshl_add_u64 v[108:109], s[14:15], 0, v[186:187]
	s_mov_b64 s[14:15], 0xa000
	v_ashrrev_i32_e32 v149, 31, v148
	v_lshl_add_u64 v[110:111], v[108:109], 0, s[14:15]
	s_mov_b32 s14, 0xa000
	v_lshlrev_b64 v[190:191], 13, v[148:149]
	s_mov_b64 s[26:27], 0x20000
	v_add_co_u32_e32 v108, vcc, s14, v108
	v_readlane_b32 s14, v250, 25
	v_lshl_add_u64 v[224:225], v[190:191], 0, s[26:27]
	s_mov_b64 s[26:27], 0x40000
	v_readlane_b32 s15, v250, 26
	v_lshl_add_u64 v[194:195], v[190:191], 0, s[26:27]
	s_mov_b64 s[26:27], 0x60000
	v_addc_co_u32_e32 v109, vcc, 0, v109, vcc
	v_lshl_add_u64 v[188:189], s[14:15], 0, v[186:187]
	v_lshl_add_u64 v[192:193], v[190:191], 0, s[26:27]
	global_load_dwordx4 v[128:131], v[108:109], off
	global_load_dwordx4 v[120:123], v[110:111], off offset:64
	global_load_dwordx4 v[112:115], v[110:111], off offset:512
	s_nop 0
	global_load_dwordx4 v[108:111], v[110:111], off offset:576
	v_lshl_add_u64 v[148:149], v[188:189], 0, v[190:191]
	v_lshl_add_u64 v[150:151], v[188:189], 0, v[224:225]
	v_lshl_add_u64 v[176:177], v[188:189], 0, v[194:195]
	v_lshl_add_u64 v[160:161], v[188:189], 0, v[192:193]
	global_load_dwordx4 v[200:203], v[150:151], off offset:576
	global_load_dwordx4 v[206:209], v[150:151], off offset:512
	global_load_dwordx4 v[210:213], v[150:151], off offset:64
	global_load_dwordx4 v[214:217], v[150:151], off
	global_load_dwordx4 v[218:221], v[148:149], off offset:576
	global_load_dwordx4 v[232:235], v[148:149], off offset:512
	global_load_dwordx4 v[236:239], v[148:149], off offset:64
	global_load_dwordx4 v[240:243], v[148:149], off
	s_nop 0
	global_load_dwordx4 v[148:151], v[160:161], off offset:576
	global_load_dwordx4 v[152:155], v[160:161], off offset:512
	global_load_dwordx4 v[156:159], v[160:161], off offset:64
	s_nop 0
	global_load_dwordx4 v[160:163], v[160:161], off
	s_nop 0
	global_load_dwordx4 v[164:167], v[176:177], off offset:576
	global_load_dwordx4 v[168:171], v[176:177], off offset:512
	global_load_dwordx4 v[172:175], v[176:177], off offset:64
	s_nop 0
	global_load_dwordx4 v[176:179], v[176:177], off
	v_lshl_add_u64 v[226:227], s[14:15], 0, v[190:191]
	v_lshl_add_u64 v[226:227], v[226:227], 0, v[186:187]
	s_mov_b64 s[26:27], 0x100000
	s_and_b64 vcc, exec, s[40:41]
	s_mov_b32 s43, s30
	s_mov_b32 s42, s31
	s_mov_b64 s[34:35], s[18:19]
	s_waitcnt vmcnt(0)
	s_nop 0
	v_pk_fma_f32 v[134:135], v[134:135], v[110:111], v[220:221]
	v_pk_fma_f32 v[132:133], v[132:133], v[108:109], v[218:219]
	global_store_dwordx4 v[226:227], v[132:135], off offset:576
	v_pk_fma_f32 v[102:103], v[102:103], v[110:111], v[202:203]
	v_pk_fma_f32 v[100:101], v[100:101], v[108:109], v[200:201]
	v_lshl_add_u64 v[132:133], s[14:15], 0, v[224:225]
	v_lshl_add_u64 v[132:133], v[132:133], 0, v[186:187]
	global_store_dwordx4 v[132:133], v[100:103], off offset:576
	v_pk_fma_f32 v[106:107], v[106:107], v[114:115], v[208:209]
	v_pk_fma_f32 v[104:105], v[104:105], v[112:113], v[206:207]
	v_lshl_add_u64 v[100:101], s[14:15], 0, v[194:195]
	v_lshl_add_u64 v[100:101], v[100:101], 0, v[186:187]
	v_pk_fma_f32 v[78:79], v[78:79], v[110:111], v[166:167]
	v_pk_fma_f32 v[76:77], v[76:77], v[108:109], v[164:165]
	global_store_dwordx4 v[132:133], v[104:107], off offset:512
	v_pk_fma_f32 v[86:87], v[86:87], v[114:115], v[170:171]
	v_pk_fma_f32 v[84:85], v[84:85], v[112:113], v[168:169]
	global_store_dwordx4 v[100:101], v[76:79], off offset:576
	v_lshl_add_u64 v[106:107], v[190:191], 0, s[26:27]
	s_mov_b64 s[26:27], 0x120000
	v_lshl_add_u64 v[76:77], s[14:15], 0, v[192:193]
	global_store_dwordx4 v[100:101], v[84:87], off offset:512
	v_pk_fma_f32 v[78:79], v[90:91], v[130:131], v[162:163]
	v_pk_fma_f32 v[72:73], v[72:73], v[112:113], v[152:153]
	v_lshl_add_u64 v[84:85], v[76:77], 0, v[186:187]
	v_pk_fma_f32 v[76:77], v[88:89], v[128:129], v[160:161]
	v_lshl_add_u64 v[152:153], v[190:191], 0, s[26:27]
	s_mov_b64 s[26:27], 0x140000
	v_pk_fma_f32 v[146:147], v[146:147], v[130:131], v[242:243]
	v_pk_fma_f32 v[144:145], v[144:145], v[128:129], v[240:241]
	v_pk_fma_f32 v[142:143], v[142:143], v[122:123], v[238:239]
	v_pk_fma_f32 v[140:141], v[140:141], v[120:121], v[236:237]
	v_pk_fma_f32 v[138:139], v[138:139], v[114:115], v[234:235]
	v_pk_fma_f32 v[136:137], v[136:137], v[112:113], v[232:233]
	v_pk_fma_f32 v[126:127], v[126:127], v[130:131], v[216:217]
	v_pk_fma_f32 v[124:125], v[124:125], v[128:129], v[214:215]
	v_pk_fma_f32 v[118:119], v[118:119], v[122:123], v[212:213]
	v_pk_fma_f32 v[116:117], v[116:117], v[120:121], v[210:211]
	v_pk_fma_f32 v[98:99], v[98:99], v[130:131], v[178:179]
	v_pk_fma_f32 v[96:97], v[96:97], v[128:129], v[176:177]
	v_pk_fma_f32 v[94:95], v[94:95], v[122:123], v[174:175]
	v_pk_fma_f32 v[92:93], v[92:93], v[120:121], v[172:173]
	global_store_dwordx4 v[84:85], v[76:79], off
	v_pk_fma_f32 v[74:75], v[74:75], v[114:115], v[154:155]
	v_pk_fma_f32 v[70:71], v[70:71], v[110:111], v[150:151]
	v_pk_fma_f32 v[78:79], v[82:83], v[122:123], v[158:159]
	v_pk_fma_f32 v[76:77], v[80:81], v[120:121], v[156:157]
	v_pk_fma_f32 v[68:69], v[68:69], v[108:109], v[148:149]
	v_lshl_add_u64 v[154:155], v[190:191], 0, s[26:27]
	s_mov_b64 s[26:27], 0x160000
	global_store_dwordx4 v[226:227], v[144:147], off
	global_store_dwordx4 v[226:227], v[140:143], off offset:64
	global_store_dwordx4 v[226:227], v[136:139], off offset:512
	global_store_dwordx4 v[132:133], v[124:127], off
	global_store_dwordx4 v[132:133], v[116:119], off offset:64
	global_store_dwordx4 v[100:101], v[96:99], off
	global_store_dwordx4 v[100:101], v[92:95], off offset:64
	global_store_dwordx4 v[84:85], v[76:79], off offset:64
	global_store_dwordx4 v[84:85], v[72:75], off offset:512
	global_store_dwordx4 v[84:85], v[68:71], off offset:576
	v_lshl_add_u64 v[100:101], v[190:191], 0, s[26:27]
	v_lshl_add_u64 v[96:97], v[188:189], 0, v[154:155]
	v_lshl_add_u64 v[68:69], v[188:189], 0, v[106:107]
	v_lshl_add_u64 v[70:71], v[188:189], 0, v[152:153]
	v_lshl_add_u64 v[80:81], v[188:189], 0, v[100:101]
	global_load_dwordx4 v[102:105], v[70:71], off offset:576
	global_load_dwordx4 v[116:119], v[70:71], off offset:512
	global_load_dwordx4 v[124:127], v[70:71], off offset:64
	global_load_dwordx4 v[132:135], v[70:71], off
	global_load_dwordx4 v[136:139], v[68:69], off offset:576
	global_load_dwordx4 v[140:143], v[68:69], off offset:512
	global_load_dwordx4 v[144:147], v[68:69], off offset:64
	global_load_dwordx4 v[148:151], v[68:69], off
	s_nop 0
	global_load_dwordx4 v[68:71], v[80:81], off offset:576
	global_load_dwordx4 v[72:75], v[80:81], off offset:512
	global_load_dwordx4 v[76:79], v[80:81], off offset:64
	s_nop 0
	global_load_dwordx4 v[80:83], v[80:81], off
	s_nop 0
	global_load_dwordx4 v[84:87], v[96:97], off offset:576
	global_load_dwordx4 v[88:91], v[96:97], off offset:512
	global_load_dwordx4 v[92:95], v[96:97], off offset:64
	s_nop 0
	global_load_dwordx4 v[96:99], v[96:97], off
	v_lshl_add_u64 v[106:107], s[14:15], 0, v[106:107]
	s_waitcnt vmcnt(0)
	v_lshl_add_u64 v[106:107], v[106:107], 0, v[186:187]
	v_pk_fma_f32 v[54:55], v[54:55], v[110:111], v[138:139]
	v_pk_fma_f32 v[52:53], v[52:53], v[108:109], v[136:137]
	global_store_dwordx4 v[106:107], v[52:55], off offset:576
	v_pk_fma_f32 v[38:39], v[38:39], v[110:111], v[104:105]
	v_pk_fma_f32 v[36:37], v[36:37], v[108:109], v[102:103]
	v_lshl_add_u64 v[52:53], s[14:15], 0, v[152:153]
	v_lshl_add_u64 v[52:53], v[52:53], 0, v[186:187]
	global_store_dwordx4 v[52:53], v[36:39], off offset:576
	v_pk_fma_f32 v[18:19], v[18:19], v[110:111], v[86:87]
	v_pk_fma_f32 v[16:17], v[16:17], v[108:109], v[84:85]
	v_lshl_add_u64 v[36:37], s[14:15], 0, v[154:155]
	v_lshl_add_u64 v[36:37], v[36:37], 0, v[186:187]
	v_pk_fma_f32 v[26:27], v[26:27], v[114:115], v[90:91]
	v_pk_fma_f32 v[24:25], v[24:25], v[112:113], v[88:89]
	global_store_dwordx4 v[36:37], v[16:19], off offset:576
	v_pk_fma_f32 v[66:67], v[66:67], v[130:131], v[150:151]
	v_pk_fma_f32 v[64:65], v[64:65], v[128:129], v[148:149]
	v_lshl_add_u64 v[16:17], s[14:15], 0, v[100:101]
	v_pk_fma_f32 v[62:63], v[62:63], v[122:123], v[146:147]
	v_pk_fma_f32 v[60:61], v[60:61], v[120:121], v[144:145]
	v_pk_fma_f32 v[58:59], v[58:59], v[114:115], v[142:143]
	v_pk_fma_f32 v[56:57], v[56:57], v[112:113], v[140:141]
	v_pk_fma_f32 v[50:51], v[50:51], v[130:131], v[134:135]
	v_pk_fma_f32 v[48:49], v[48:49], v[128:129], v[132:133]
	v_pk_fma_f32 v[46:47], v[46:47], v[122:123], v[126:127]
	v_pk_fma_f32 v[44:45], v[44:45], v[120:121], v[124:125]
	v_pk_fma_f32 v[42:43], v[42:43], v[114:115], v[118:119]
	v_pk_fma_f32 v[40:41], v[40:41], v[112:113], v[116:117]
	v_pk_fma_f32 v[34:35], v[34:35], v[130:131], v[98:99]
	v_pk_fma_f32 v[32:33], v[32:33], v[128:129], v[96:97]
	v_pk_fma_f32 v[30:31], v[30:31], v[122:123], v[94:95]
	v_pk_fma_f32 v[28:29], v[28:29], v[120:121], v[92:93]
	global_store_dwordx4 v[36:37], v[24:27], off offset:512
	v_pk_fma_f32 v[18:19], v[22:23], v[130:131], v[82:83]
	v_pk_fma_f32 v[14:15], v[14:15], v[122:123], v[78:79]
	v_lshl_add_u64 v[24:25], v[16:17], 0, v[186:187]
	v_pk_fma_f32 v[16:17], v[20:21], v[128:129], v[80:81]
	v_pk_fma_f32 v[12:13], v[12:13], v[120:121], v[76:77]
	v_pk_fma_f32 v[10:11], v[10:11], v[114:115], v[74:75]
	v_pk_fma_f32 v[8:9], v[8:9], v[112:113], v[72:73]
	v_pk_fma_f32 v[6:7], v[6:7], v[110:111], v[70:71]
	v_pk_fma_f32 v[4:5], v[4:5], v[108:109], v[68:69]
	global_store_dwordx4 v[106:107], v[64:67], off
	global_store_dwordx4 v[106:107], v[60:63], off offset:64
	global_store_dwordx4 v[106:107], v[56:59], off offset:512
	global_store_dwordx4 v[52:53], v[48:51], off
	global_store_dwordx4 v[52:53], v[44:47], off offset:64
	global_store_dwordx4 v[52:53], v[40:43], off offset:512
	global_store_dwordx4 v[36:37], v[32:35], off
	global_store_dwordx4 v[36:37], v[28:31], off offset:64
	global_store_dwordx4 v[24:25], v[16:19], off
	global_store_dwordx4 v[24:25], v[12:15], off offset:64
	global_store_dwordx4 v[24:25], v[8:11], off offset:512
	global_store_dwordx4 v[24:25], v[4:7], off offset:576
	s_mov_b64 s[26:27], s[16:17]
	s_cbranch_vccz .LBB0_3028
	s_waitcnt vmcnt(0)
	s_cmpk_gt_u32 s4, 0xff
	s_cbranch_scc1 .LBB0_3039
	s_barrier

.LBB0_3048:
	s_add_u32 s40, s36, 0x100
	s_addc_u32 s41, s37, 0
	s_add_i32 s47, 0, 0x10000
	v_add_u32_e32 v144, s47, v158
	ds_read_b128 v[132:135], v144
	ds_read_b128 v[136:139], v144 offset:1024
	ds_read_b128 v[140:143], v144 offset:2048
	ds_read_b128 v[144:147], v144 offset:3072
	s_cmp_eq_u32 s46, 4
	s_cselect_b32 s43, s19, s41
	s_cselect_b32 s42, s18, s40
	s_cselect_b32 s39, s27, s45
	s_cselect_b32 s38, s26, s44
	v_lshl_add_u64 v[154:155], s[36:37], 0, v[150:151]
	s_add_i32 m0, s6, 0xc000
	ds_read_b128 v[160:163], v159
	ds_read_b128 v[164:167], v159 offset:1024
	ds_read_b128 v[168:171], v159 offset:2048
	ds_read_b128 v[172:175], v159 offset:3072
	ds_read_b128 v[176:179], v159 offset:4096
	ds_read_b128 v[180:183], v159 offset:5120
	ds_read_b128 v[184:187], v159 offset:6144
	ds_read_b128 v[188:191], v159 offset:7168
	global_load_lds_dwordx4 v[154:155], off
	v_lshl_add_u64 v[154:155], s[36:37], 0, v[152:153]
	s_add_i32 m0, s6, 0xe000
	s_nop 0
	global_load_lds_dwordx4 v[154:155], off
	s_waitcnt lgkmcnt(8)
	s_barrier
	s_waitcnt lgkmcnt(0)
	s_waitcnt lgkmcnt(0)
	v_mfma_f32_16x16x32_f16 v[128:131], v[132:135], v[160:163], v[128:131]
	v_mfma_f32_16x16x32_f16 v[124:127], v[140:143], v[160:163], v[124:127]
	v_mfma_f32_16x16x32_f16 v[112:115], v[132:135], v[168:171], v[112:115]
	v_mfma_f32_16x16x32_f16 v[108:111], v[140:143], v[168:171], v[108:111]
	v_mfma_f32_16x16x32_f16 v[96:99], v[132:135], v[176:179], v[96:99]
	v_mfma_f32_16x16x32_f16 v[92:95], v[140:143], v[176:179], v[92:95]
	v_mfma_f32_16x16x32_f16 v[80:83], v[132:135], v[184:187], v[80:83]
	v_mfma_f32_16x16x32_f16 v[76:79], v[140:143], v[184:187], v[76:79]
	v_mfma_f32_16x16x32_f16 v[128:131], v[136:139], v[164:167], v[128:131]
	v_mfma_f32_16x16x32_f16 v[124:127], v[144:147], v[164:167], v[124:127]
	v_mfma_f32_16x16x32_f16 v[112:115], v[136:139], v[172:175], v[112:115]
	v_mfma_f32_16x16x32_f16 v[108:111], v[144:147], v[172:175], v[108:111]
	v_mfma_f32_16x16x32_f16 v[96:99], v[136:139], v[180:183], v[96:99]
	v_mfma_f32_16x16x32_f16 v[92:95], v[144:147], v[180:183], v[92:95]
	v_mfma_f32_16x16x32_f16 v[80:83], v[136:139], v[188:191], v[80:83]
	v_mfma_f32_16x16x32_f16 v[76:79], v[144:147], v[188:191], v[76:79]
	s_barrier
	s_add_i32 s48, 0, 0x14000
	v_add_u32_e32 v154, s48, v158
	s_add_i32 s36, s47, s5
	ds_read_b128 v[192:195], v154
	ds_read_b128 v[196:199], v154 offset:1024
	ds_read_b128 v[200:203], v154 offset:2048
	ds_read_b128 v[206:209], v154 offset:3072
	v_lshl_add_u64 v[154:155], s[38:39], 0, v[2:3]
	s_mov_b32 m0, s36
	v_lshl_add_u64 v[210:211], s[38:39], 0, v[148:149]
	global_load_lds_dwordx4 v[154:155], off
	s_add_i32 m0, s36, 0x2000
	s_nop 0
	global_load_lds_dwordx4 v[210:211], off
	s_barrier
	s_waitcnt lgkmcnt(0)
	s_waitcnt lgkmcnt(0)
	v_mfma_f32_16x16x32_f16 v[120:123], v[192:195], v[160:163], v[120:123]
	v_mfma_f32_16x16x32_f16 v[116:119], v[200:203], v[160:163], v[116:119]
	v_mfma_f32_16x16x32_f16 v[104:107], v[192:195], v[168:171], v[104:107]
	v_mfma_f32_16x16x32_f16 v[100:103], v[200:203], v[168:171], v[100:103]
	v_mfma_f32_16x16x32_f16 v[88:91], v[192:195], v[176:179], v[88:91]
	v_mfma_f32_16x16x32_f16 v[84:87], v[200:203], v[176:179], v[84:87]
	v_mfma_f32_16x16x32_f16 v[72:75], v[192:195], v[184:187], v[72:75]
	v_mfma_f32_16x16x32_f16 v[68:71], v[200:203], v[184:187], v[68:71]
	v_mfma_f32_16x16x32_f16 v[120:123], v[196:199], v[164:167], v[120:123]
	v_mfma_f32_16x16x32_f16 v[116:119], v[206:209], v[164:167], v[116:119]
	v_mfma_f32_16x16x32_f16 v[104:107], v[196:199], v[172:175], v[104:107]
	v_mfma_f32_16x16x32_f16 v[100:103], v[206:209], v[172:175], v[100:103]
	v_mfma_f32_16x16x32_f16 v[88:91], v[196:199], v[180:183], v[88:91]
	v_mfma_f32_16x16x32_f16 v[84:87], v[206:209], v[180:183], v[84:87]
	v_mfma_f32_16x16x32_f16 v[72:75], v[196:199], v[188:191], v[72:75]
	v_mfma_f32_16x16x32_f16 v[68:71], v[206:209], v[188:191], v[68:71]
	s_mov_b32 m0, s6
	v_lshl_add_u64 v[212:213], s[42:43], 0, v[2:3]
	s_barrier
	ds_read_b128 v[160:163], v159 offset:16384
	ds_read_b128 v[164:167], v159 offset:17408
	ds_read_b128 v[168:171], v159 offset:18432
	ds_read_b128 v[172:175], v159 offset:19456
	ds_read_b128 v[176:179], v159 offset:20480
	ds_read_b128 v[180:183], v159 offset:21504
	ds_read_b128 v[184:187], v159 offset:22528
	ds_read_b128 v[188:191], v159 offset:23552
	global_load_lds_dwordx4 v[212:213], off
	v_lshl_add_u64 v[214:215], s[42:43], 0, v[148:149]
	s_mov_b32 m0, s7
	s_nop 0
	global_load_lds_dwordx4 v[214:215], off
	s_barrier
	s_waitcnt lgkmcnt(0)
	s_waitcnt lgkmcnt(0)
	v_mfma_f32_16x16x32_f16 v[64:67], v[132:135], v[160:163], v[64:67]
	v_mfma_f32_16x16x32_f16 v[60:63], v[140:143], v[160:163], v[60:63]
	v_mfma_f32_16x16x32_f16 v[56:59], v[132:135], v[168:171], v[56:59]
	v_mfma_f32_16x16x32_f16 v[44:47], v[140:143], v[168:171], v[44:47]
	v_mfma_f32_16x16x32_f16 v[40:43], v[132:135], v[176:179], v[40:43]
	v_mfma_f32_16x16x32_f16 v[28:31], v[140:143], v[176:179], v[28:31]
	v_mfma_f32_16x16x32_f16 v[24:27], v[132:135], v[184:187], v[24:27]
	v_mfma_f32_16x16x32_f16 v[12:15], v[140:143], v[184:187], v[12:15]
	v_mfma_f32_16x16x32_f16 v[64:67], v[136:139], v[164:167], v[64:67]
	v_mfma_f32_16x16x32_f16 v[60:63], v[144:147], v[164:167], v[60:63]
	v_mfma_f32_16x16x32_f16 v[56:59], v[136:139], v[172:175], v[56:59]
	v_mfma_f32_16x16x32_f16 v[44:47], v[144:147], v[172:175], v[44:47]
	v_mfma_f32_16x16x32_f16 v[40:43], v[136:139], v[180:183], v[40:43]
	v_mfma_f32_16x16x32_f16 v[28:31], v[144:147], v[180:183], v[28:31]
	v_mfma_f32_16x16x32_f16 v[24:27], v[136:139], v[188:191], v[24:27]
	v_mfma_f32_16x16x32_f16 v[12:15], v[144:147], v[188:191], v[12:15]
	s_barrier
	s_add_u32 s36, s38, 0x160000
	s_addc_u32 s37, s39, 0
	s_add_i32 s47, s48, s5
	v_lshl_add_u64 v[132:133], s[36:37], 0, v[2:3]
	s_mov_b32 m0, s47
	s_nop 0
	global_load_lds_dwordx4 v[132:133], off
	v_lshl_add_u64 v[132:133], s[36:37], 0, v[148:149]
	s_add_i32 m0, s47, 0x2000
	s_nop 0
	global_load_lds_dwordx4 v[132:133], off
	s_waitcnt vmcnt(6)
	s_barrier
	v_mfma_f32_16x16x32_f16 v[52:55], v[192:195], v[160:163], v[52:55]
	v_mfma_f32_16x16x32_f16 v[48:51], v[200:203], v[160:163], v[48:51]
	v_mfma_f32_16x16x32_f16 v[36:39], v[192:195], v[168:171], v[36:39]
	v_mfma_f32_16x16x32_f16 v[32:35], v[200:203], v[168:171], v[32:35]
	v_mfma_f32_16x16x32_f16 v[20:23], v[192:195], v[176:179], v[20:23]
	v_mfma_f32_16x16x32_f16 v[16:19], v[200:203], v[176:179], v[16:19]
	v_mfma_f32_16x16x32_f16 v[8:11], v[192:195], v[184:187], v[8:11]
	v_mfma_f32_16x16x32_f16 v[4:7], v[200:203], v[184:187], v[4:7]
	v_mfma_f32_16x16x32_f16 v[52:55], v[196:199], v[164:167], v[52:55]
	v_mfma_f32_16x16x32_f16 v[48:51], v[206:209], v[164:167], v[48:51]
	v_mfma_f32_16x16x32_f16 v[36:39], v[196:199], v[172:175], v[36:39]
	v_mfma_f32_16x16x32_f16 v[32:35], v[206:209], v[172:175], v[32:35]
	v_mfma_f32_16x16x32_f16 v[20:23], v[196:199], v[180:183], v[20:23]
	v_mfma_f32_16x16x32_f16 v[16:19], v[206:209], v[180:183], v[16:19]
	v_mfma_f32_16x16x32_f16 v[8:11], v[196:199], v[188:191], v[8:11]
	v_mfma_f32_16x16x32_f16 v[4:7], v[206:209], v[188:191], v[4:7]
	s_add_i32 s47, 0, 0x18000
	v_add_u32_e32 v144, s47, v158
	s_barrier
	ds_read_b128 v[132:135], v144
	ds_read_b128 v[136:139], v144 offset:1024
	ds_read_b128 v[140:143], v144 offset:2048
	ds_read_b128 v[144:147], v144 offset:3072
	s_add_u32 s36, s42, 0x160000
	s_addc_u32 s37, s43, 0
	s_mov_b32 m0, s8
	v_lshl_add_u64 v[192:193], s[36:37], 0, v[2:3]
	ds_read_b128 v[160:163], v159 offset:32768
	ds_read_b128 v[164:167], v159 offset:33792
	ds_read_b128 v[168:171], v159 offset:34816
	ds_read_b128 v[172:175], v159 offset:35840
	ds_read_b128 v[176:179], v159 offset:36864
	ds_read_b128 v[180:183], v159 offset:37888
	ds_read_b128 v[184:187], v159 offset:38912
	ds_read_b128 v[188:191], v159 offset:39936
	global_load_lds_dwordx4 v[192:193], off
	v_lshl_add_u64 v[192:193], s[36:37], 0, v[148:149]
	s_mov_b32 m0, s9
	s_nop 0
	global_load_lds_dwordx4 v[192:193], off
	s_waitcnt lgkmcnt(8)
	s_barrier
	s_waitcnt lgkmcnt(0)
	s_waitcnt lgkmcnt(0)
	v_mfma_f32_16x16x32_f16 v[128:131], v[132:135], v[160:163], v[128:131]
	v_mfma_f32_16x16x32_f16 v[124:127], v[140:143], v[160:163], v[124:127]
	v_mfma_f32_16x16x32_f16 v[112:115], v[132:135], v[168:171], v[112:115]
	v_mfma_f32_16x16x32_f16 v[108:111], v[140:143], v[168:171], v[108:111]
	v_mfma_f32_16x16x32_f16 v[96:99], v[132:135], v[176:179], v[96:99]
	v_mfma_f32_16x16x32_f16 v[92:95], v[140:143], v[176:179], v[92:95]
	v_mfma_f32_16x16x32_f16 v[80:83], v[132:135], v[184:187], v[80:83]
	v_mfma_f32_16x16x32_f16 v[76:79], v[140:143], v[184:187], v[76:79]
	v_mfma_f32_16x16x32_f16 v[128:131], v[136:139], v[164:167], v[128:131]
	v_mfma_f32_16x16x32_f16 v[124:127], v[144:147], v[164:167], v[124:127]
	v_mfma_f32_16x16x32_f16 v[112:115], v[136:139], v[172:175], v[112:115]
	v_mfma_f32_16x16x32_f16 v[108:111], v[144:147], v[172:175], v[108:111]
	v_mfma_f32_16x16x32_f16 v[96:99], v[136:139], v[180:183], v[96:99]
	v_mfma_f32_16x16x32_f16 v[92:95], v[144:147], v[180:183], v[92:95]
	v_mfma_f32_16x16x32_f16 v[80:83], v[136:139], v[188:191], v[80:83]
	v_mfma_f32_16x16x32_f16 v[76:79], v[144:147], v[188:191], v[76:79]
	s_barrier
	s_add_i32 s42, 0, 0x1c000
	s_add_i32 s36, s47, s5
	v_add_u32_e32 v206, s42, v158
	v_lshl_add_u64 v[154:155], v[154:155], 0, s[88:89]
	s_mov_b32 m0, s36
	ds_read_b128 v[192:195], v206
	ds_read_b128 v[196:199], v206 offset:1024
	ds_read_b128 v[200:203], v206 offset:2048
	ds_read_b128 v[206:209], v206 offset:3072
	global_load_lds_dwordx4 v[154:155], off
	v_lshl_add_u64 v[154:155], v[210:211], 0, s[88:89]
	s_add_i32 m0, s36, 0x2000
	s_nop 0
	global_load_lds_dwordx4 v[154:155], off
	s_barrier
	s_waitcnt lgkmcnt(0)
	s_waitcnt lgkmcnt(0)
	v_mfma_f32_16x16x32_f16 v[120:123], v[192:195], v[160:163], v[120:123]
	v_mfma_f32_16x16x32_f16 v[116:119], v[200:203], v[160:163], v[116:119]
	v_mfma_f32_16x16x32_f16 v[104:107], v[192:195], v[168:171], v[104:107]
	v_mfma_f32_16x16x32_f16 v[100:103], v[200:203], v[168:171], v[100:103]
	v_mfma_f32_16x16x32_f16 v[88:91], v[192:195], v[176:179], v[88:91]
	v_mfma_f32_16x16x32_f16 v[84:87], v[200:203], v[176:179], v[84:87]
	v_mfma_f32_16x16x32_f16 v[72:75], v[192:195], v[184:187], v[72:75]
	v_mfma_f32_16x16x32_f16 v[68:71], v[200:203], v[184:187], v[68:71]
	v_mfma_f32_16x16x32_f16 v[120:123], v[196:199], v[164:167], v[120:123]
	v_mfma_f32_16x16x32_f16 v[116:119], v[206:209], v[164:167], v[116:119]
	v_mfma_f32_16x16x32_f16 v[104:107], v[196:199], v[172:175], v[104:107]
	v_mfma_f32_16x16x32_f16 v[100:103], v[206:209], v[172:175], v[100:103]
	v_mfma_f32_16x16x32_f16 v[88:91], v[196:199], v[180:183], v[88:91]
	v_mfma_f32_16x16x32_f16 v[84:87], v[206:209], v[180:183], v[84:87]
	v_mfma_f32_16x16x32_f16 v[72:75], v[196:199], v[188:191], v[72:75]
	v_mfma_f32_16x16x32_f16 v[68:71], v[206:209], v[188:191], v[68:71]
	s_mov_b32 m0, s10
	v_lshl_add_u64 v[154:155], v[212:213], 0, s[88:89]
	s_barrier
	ds_read_b128 v[160:163], v159 offset:49152
	ds_read_b128 v[164:167], v159 offset:50176
	ds_read_b128 v[168:171], v159 offset:51200
	ds_read_b128 v[172:175], v159 offset:52224
	ds_read_b128 v[176:179], v159 offset:53248
	ds_read_b128 v[180:183], v159 offset:54272
	ds_read_b128 v[184:187], v159 offset:55296
	ds_read_b128 v[188:191], v159 offset:56320
	global_load_lds_dwordx4 v[154:155], off
	v_lshl_add_u64 v[154:155], v[214:215], 0, s[88:89]
	s_mov_b32 m0, s11
	s_nop 0
	global_load_lds_dwordx4 v[154:155], off
	s_barrier
	s_waitcnt lgkmcnt(0)
	s_waitcnt lgkmcnt(0)
	v_mfma_f32_16x16x32_f16 v[64:67], v[132:135], v[160:163], v[64:67]
	v_mfma_f32_16x16x32_f16 v[60:63], v[140:143], v[160:163], v[60:63]
	v_mfma_f32_16x16x32_f16 v[56:59], v[132:135], v[168:171], v[56:59]
	v_mfma_f32_16x16x32_f16 v[44:47], v[140:143], v[168:171], v[44:47]
	v_mfma_f32_16x16x32_f16 v[40:43], v[132:135], v[176:179], v[40:43]
	v_mfma_f32_16x16x32_f16 v[28:31], v[140:143], v[176:179], v[28:31]
	v_mfma_f32_16x16x32_f16 v[24:27], v[132:135], v[184:187], v[24:27]
	v_mfma_f32_16x16x32_f16 v[12:15], v[140:143], v[184:187], v[12:15]
	v_mfma_f32_16x16x32_f16 v[64:67], v[136:139], v[164:167], v[64:67]
	v_mfma_f32_16x16x32_f16 v[60:63], v[144:147], v[164:167], v[60:63]
	v_mfma_f32_16x16x32_f16 v[56:59], v[136:139], v[172:175], v[56:59]
	v_mfma_f32_16x16x32_f16 v[44:47], v[144:147], v[172:175], v[44:47]
	v_mfma_f32_16x16x32_f16 v[40:43], v[136:139], v[180:183], v[40:43]
	v_mfma_f32_16x16x32_f16 v[28:31], v[144:147], v[180:183], v[28:31]
	v_mfma_f32_16x16x32_f16 v[24:27], v[136:139], v[188:191], v[24:27]
	v_mfma_f32_16x16x32_f16 v[12:15], v[144:147], v[188:191], v[12:15]
	s_barrier
	s_add_u32 s36, s38, 0x160080
	s_addc_u32 s37, s39, 0
	s_add_i32 s38, s42, s5
	v_lshl_add_u64 v[132:133], s[36:37], 0, v[2:3]
	s_mov_b32 m0, s38
	s_nop 0
	global_load_lds_dwordx4 v[132:133], off
	v_lshl_add_u64 v[132:133], s[36:37], 0, v[148:149]
	s_add_i32 m0, s38, 0x2000
	s_nop 0
	global_load_lds_dwordx4 v[132:133], off
	s_waitcnt vmcnt(6)
	s_barrier
	v_mfma_f32_16x16x32_f16 v[52:55], v[192:195], v[160:163], v[52:55]
	v_mfma_f32_16x16x32_f16 v[48:51], v[200:203], v[160:163], v[48:51]
	v_mfma_f32_16x16x32_f16 v[36:39], v[192:195], v[168:171], v[36:39]
	v_mfma_f32_16x16x32_f16 v[32:35], v[200:203], v[168:171], v[32:35]
	v_mfma_f32_16x16x32_f16 v[20:23], v[192:195], v[176:179], v[20:23]
	v_mfma_f32_16x16x32_f16 v[16:19], v[200:203], v[176:179], v[16:19]
	v_mfma_f32_16x16x32_f16 v[8:11], v[192:195], v[184:187], v[8:11]
	v_mfma_f32_16x16x32_f16 v[4:7], v[200:203], v[184:187], v[4:7]
	v_mfma_f32_16x16x32_f16 v[52:55], v[196:199], v[164:167], v[52:55]
	v_mfma_f32_16x16x32_f16 v[48:51], v[206:209], v[164:167], v[48:51]
	v_mfma_f32_16x16x32_f16 v[36:39], v[196:199], v[172:175], v[36:39]
	v_mfma_f32_16x16x32_f16 v[32:35], v[206:209], v[172:175], v[32:35]
	v_mfma_f32_16x16x32_f16 v[20:23], v[196:199], v[180:183], v[20:23]
	v_mfma_f32_16x16x32_f16 v[16:19], v[206:209], v[180:183], v[16:19]
	v_mfma_f32_16x16x32_f16 v[8:11], v[196:199], v[188:191], v[8:11]
	v_mfma_f32_16x16x32_f16 v[4:7], v[206:209], v[188:191], v[4:7]
	s_add_i32 s46, s46, 2
	s_add_u32 s44, s44, 0x100
	s_addc_u32 s45, s45, 0
	s_cmp_gt_u32 s46, 5
	s_mov_b64 s[36:37], s[40:41]
	s_barrier
	s_cbranch_scc0 .LBB0_3048
	s_lshl_b32 s36, s30, 8
	v_mov_b32_e32 v160, v156
	v_mov_b32_e32 v132, v157
	s_and_b32 s36, s36, 0xff00
	s_or_b32 s36, s36, s12
	v_lshl_add_u32 v132, v132, 2, s36
	v_ashrrev_i32_e32 v133, 31, v132
	v_lshlrev_b64 v[154:155], 2, v[132:133]
	v_lshl_add_u64 v[132:133], s[16:17], 0, v[154:155]
	global_load_dwordx4 v[144:147], v[132:133], off
	global_load_dwordx4 v[140:143], v[132:133], off offset:64
	global_load_dwordx4 v[136:139], v[132:133], off offset:512
	s_nop 0
	global_load_dwordx4 v[132:135], v[132:133], off offset:576
	s_lshl_b32 s31, s31, 8
	s_ashr_i32 s30, s30, 8
	s_add_i32 s31, s13, s31
	v_add_u32_e32 v160, s31, v160
	s_ashr_i32 s31, s30, 31
	s_lshl_b64 s[30:31], s[30:31], 22
	v_readlane_b32 s36, v250, 27
	v_readlane_b32 s37, v250, 28
	s_add_u32 s30, s36, s30
	s_addc_u32 s31, s37, s31
	v_ashrrev_i32_e32 v161, 31, v160
	v_lshl_add_u64 v[154:155], s[30:31], 0, v[154:155]
	v_lshlrev_b64 v[160:161], 13, v[160:161]
	v_lshl_add_u64 v[154:155], v[154:155], 0, v[160:161]
	s_mov_b64 s[30:31], 0x20000
	s_mov_b64 s[38:39], s[26:27]
	s_mov_b64 s[36:37], s[18:19]
	s_waitcnt vmcnt(0)
	v_pk_mul_f32 v[130:131], v[130:131], v[146:147]
	v_pk_mul_f32 v[128:129], v[128:129], v[144:145]
	v_pk_mul_f32 v[54:55], v[54:55], v[138:139]
	v_pk_mul_f32 v[118:119], v[118:119], v[134:135]
	v_pk_mul_f32 v[116:117], v[116:117], v[132:133]
	global_store_dwordx4 v[154:155], v[116:119], off offset:576
	v_pk_mul_f32 v[102:103], v[102:103], v[134:135]
	v_pk_mul_f32 v[100:101], v[100:101], v[132:133]
	v_lshl_add_u64 v[116:117], v[154:155], 0, s[30:31]
	s_mov_b32 s30, 0x20000
	v_add_co_u32_e32 v118, vcc, s30, v154
	s_mov_b64 s[30:31], 0x40000
	s_nop 0
	v_addc_co_u32_e32 v119, vcc, 0, v155, vcc
	global_store_dwordx4 v[116:117], v[100:103], off offset:576
	v_pk_mul_f32 v[86:87], v[86:87], v[134:135]
	v_pk_mul_f32 v[84:85], v[84:85], v[132:133]
	v_lshl_add_u64 v[100:101], v[154:155], 0, s[30:31]
	s_mov_b32 s30, 0x40000
	v_add_co_u32_e32 v102, vcc, s30, v154
	s_mov_b64 s[30:31], 0x60000
	s_nop 0
	v_addc_co_u32_e32 v103, vcc, 0, v155, vcc
	global_store_dwordx4 v[100:101], v[84:87], off offset:576
	v_pk_mul_f32 v[70:71], v[70:71], v[134:135]
	v_pk_mul_f32 v[68:69], v[68:69], v[132:133]
	v_lshl_add_u64 v[84:85], v[154:155], 0, s[30:31]
	s_mov_b32 s30, 0x60000
	v_add_co_u32_e32 v86, vcc, s30, v154
	s_mov_b64 s[30:31], 0x100000
	s_nop 0
	v_addc_co_u32_e32 v87, vcc, 0, v155, vcc
	global_store_dwordx4 v[84:85], v[68:71], off offset:576
	v_pk_mul_f32 v[52:53], v[52:53], v[136:137]
	v_pk_mul_f32 v[38:39], v[38:39], v[138:139]
	v_lshl_add_u64 v[68:69], v[154:155], 0, s[30:31]
	s_mov_b32 s30, 0x100000
	v_add_co_u32_e32 v70, vcc, s30, v154
	s_mov_b64 s[30:31], 0x120000
	s_nop 0
	v_addc_co_u32_e32 v71, vcc, 0, v155, vcc
	global_store_dwordx4 v[68:69], v[52:55], off offset:512
	v_pk_mul_f32 v[36:37], v[36:37], v[136:137]
	v_pk_mul_f32 v[22:23], v[22:23], v[138:139]
	v_lshl_add_u64 v[52:53], v[154:155], 0, s[30:31]
	s_mov_b32 s30, 0x120000
	v_add_co_u32_e32 v54, vcc, s30, v154
	s_mov_b64 s[30:31], 0x140000
	s_nop 0
	v_addc_co_u32_e32 v55, vcc, 0, v155, vcc
	global_store_dwordx4 v[52:53], v[36:39], off offset:512
	v_pk_mul_f32 v[20:21], v[20:21], v[136:137]
	v_pk_mul_f32 v[50:51], v[50:51], v[134:135]
	v_lshl_add_u64 v[36:37], v[154:155], 0, s[30:31]
	s_mov_b32 s30, 0x140000
	v_add_co_u32_e32 v38, vcc, s30, v154
	s_mov_b64 s[30:31], 0x160000
	s_nop 0
	v_addc_co_u32_e32 v39, vcc, 0, v155, vcc
	global_store_dwordx4 v[36:37], v[20:23], off offset:512
	v_pk_mul_f32 v[48:49], v[48:49], v[132:133]
	v_pk_mul_f32 v[34:35], v[34:35], v[134:135]
	v_lshl_add_u64 v[20:21], v[154:155], 0, s[30:31]
	s_mov_b32 s30, 0x160000
	v_add_co_u32_e32 v22, vcc, s30, v154
	v_pk_mul_f32 v[32:33], v[32:33], v[132:133]
	v_pk_mul_f32 v[18:19], v[18:19], v[134:135]
	v_pk_mul_f32 v[16:17], v[16:17], v[132:133]
	v_addc_co_u32_e32 v23, vcc, 0, v155, vcc
	v_pk_mul_f32 v[126:127], v[126:127], v[142:143]
	v_pk_mul_f32 v[124:125], v[124:125], v[140:141]
	v_pk_mul_f32 v[122:123], v[122:123], v[138:139]
	v_pk_mul_f32 v[120:121], v[120:121], v[136:137]
	v_pk_mul_f32 v[114:115], v[114:115], v[146:147]
	v_pk_mul_f32 v[112:113], v[112:113], v[144:145]
	v_pk_mul_f32 v[110:111], v[110:111], v[142:143]
	v_pk_mul_f32 v[108:109], v[108:109], v[140:141]
	v_pk_mul_f32 v[106:107], v[106:107], v[138:139]
	v_pk_mul_f32 v[104:105], v[104:105], v[136:137]
	v_pk_mul_f32 v[98:99], v[98:99], v[146:147]
	v_pk_mul_f32 v[96:97], v[96:97], v[144:145]
	v_pk_mul_f32 v[94:95], v[94:95], v[142:143]
	v_pk_mul_f32 v[92:93], v[92:93], v[140:141]
	v_pk_mul_f32 v[90:91], v[90:91], v[138:139]
	v_pk_mul_f32 v[88:89], v[88:89], v[136:137]
	v_pk_mul_f32 v[82:83], v[82:83], v[146:147]
	v_pk_mul_f32 v[80:81], v[80:81], v[144:145]
	v_pk_mul_f32 v[78:79], v[78:79], v[142:143]
	v_pk_mul_f32 v[76:77], v[76:77], v[140:141]
	v_pk_mul_f32 v[74:75], v[74:75], v[138:139]
	v_pk_mul_f32 v[72:73], v[72:73], v[136:137]
	v_pk_mul_f32 v[66:67], v[66:67], v[146:147]
	v_pk_mul_f32 v[64:65], v[64:65], v[144:145]
	v_pk_mul_f32 v[62:63], v[62:63], v[142:143]
	v_pk_mul_f32 v[60:61], v[60:61], v[140:141]
	global_store_dwordx4 v[68:69], v[48:51], off offset:576
	v_pk_mul_f32 v[46:47], v[46:47], v[142:143]
	v_pk_mul_f32 v[44:45], v[44:45], v[140:141]
	v_pk_mul_f32 v[50:51], v[58:59], v[146:147]
	v_pk_mul_f32 v[48:49], v[56:57], v[144:145]
	global_store_dwordx4 v[52:53], v[32:35], off offset:576
	v_pk_mul_f32 v[30:31], v[30:31], v[142:143]
	v_pk_mul_f32 v[28:29], v[28:29], v[140:141]
	v_pk_mul_f32 v[34:35], v[42:43], v[146:147]
	v_pk_mul_f32 v[32:33], v[40:41], v[144:145]
	global_store_dwordx4 v[36:37], v[16:19], off offset:576
	v_pk_mul_f32 v[14:15], v[14:15], v[142:143]
	v_pk_mul_f32 v[12:13], v[12:13], v[140:141]
	v_pk_mul_f32 v[18:19], v[26:27], v[146:147]
	v_pk_mul_f32 v[16:17], v[24:25], v[144:145]
	v_pk_mul_f32 v[10:11], v[10:11], v[138:139]
	v_pk_mul_f32 v[8:9], v[8:9], v[136:137]
	v_pk_mul_f32 v[6:7], v[6:7], v[134:135]
	v_pk_mul_f32 v[4:5], v[4:5], v[132:133]
	s_and_b64 vcc, exec, s[34:35]
	s_mov_b32 s30, s29
	s_mov_b32 s31, s15
	global_store_dwordx4 v[154:155], v[128:131], off
	global_store_dwordx4 v[154:155], v[124:127], off offset:64
	global_store_dwordx4 v[154:155], v[120:123], off offset:512
	global_store_dwordx4 v[118:119], v[112:115], off
	global_store_dwordx4 v[116:117], v[108:111], off offset:64
	global_store_dwordx4 v[116:117], v[104:107], off offset:512
	global_store_dwordx4 v[102:103], v[96:99], off
	global_store_dwordx4 v[100:101], v[92:95], off offset:64
	global_store_dwordx4 v[100:101], v[88:91], off offset:512
	global_store_dwordx4 v[86:87], v[80:83], off
	global_store_dwordx4 v[84:85], v[76:79], off offset:64
	global_store_dwordx4 v[84:85], v[72:75], off offset:512
	global_store_dwordx4 v[70:71], v[64:67], off
	global_store_dwordx4 v[68:69], v[60:63], off offset:64
	global_store_dwordx4 v[54:55], v[48:51], off
	global_store_dwordx4 v[52:53], v[44:47], off offset:64
	global_store_dwordx4 v[38:39], v[32:35], off
	global_store_dwordx4 v[36:37], v[28:31], off offset:64
	global_store_dwordx4 v[22:23], v[16:19], off
	global_store_dwordx4 v[20:21], v[12:15], off offset:64
	global_store_dwordx4 v[20:21], v[8:11], off offset:512
	global_store_dwordx4 v[20:21], v[4:7], off offset:576
	s_cbranch_vccz .LBB0_3045
	s_waitcnt vmcnt(0)
	s_cmpk_gt_u32 s4, 0xff
	s_cbranch_scc1 .LBB0_3052
	s_barrier
